# speedup vs baseline: 1.0169x; 1.0058x over previous
; #define WAIT_V(n) asm volatile("s_waitcnt vmcnt(" #n ")" ::: "memory")
; #define WAIT_L(n) asm volatile("s_waitcnt lgkmcnt(" #n ")" ::: "memory")
; #define BAR __builtin_amdgcn_s_barrier()
; #define SCHED __builtin_amdgcn_sched_barrier(0)
; #define LDA(dst, b, h)                                                                            \
;   _Pragma("unroll") for (int m = 0; m < 4; ++m) _Pragma("unroll") for (int k = 0; k < 2; ++k)                                         \
;     dst[m][k] = *reinterpret_cast<const bf16x8*>((char*)SA(b, h) + lds_byte(wr * 64 + m * 16 + fr, k * 32 + fq * 8))
; #define LDB(dst, b, h)                                                                            \
;   _Pragma("unroll") for (int n = 0; n < 2; ++n) _Pragma("unroll") for (int k = 0; k < 2; ++k)                                         \
;     dst[n][k] = *reinterpret_cast<const bf16x8*>((char*)SB(b, h) + lds_byte(wc * 32 + n * 16 + fr, k * 32 + fq * 8))
; template <int K, bool SWAP>
; __device__ __forceinline__ void gemm_kloop(const bf16* __restrict__ A, const bf16* __restrict__ Bt,
;                                            f32x4 (&acc)[2][2][4][2], bool pref = false) {
;     ...
;     LDB(B0, 0, 0); SCHED; LDA(At, 0, 0); STAGE(SA(1, 1), A, HALF, t + 1);
;     WAIT_L(8); BAR; WAIT_L(0); MMA(0, 0, At, B0); BAR; SCHED;
;     LDB(B1, 0, 1); STAGE(SB(0, 0), Bt, 0, t + 2);
;     BAR; WAIT_L(0); MMA(0, 1, At, B1); BAR;
;     LDA(At, 0, 1); STAGE(SA(0, 0), A, 0, t + 2);
;     BAR; WAIT_L(0); MMA(1, 0, At, B0); BAR; SCHED;
;     STAGE(SB(0, 1), Bt, HALF, t + 2);
;     WAIT_V(6); BAR; MMA(1, 1, At, B1); BAR;
.LBB0_271:
	ds_read_b128 v[162:165], v159
	ds_read_b128 v[166:169], v159 offset:1024
	ds_read_b128 v[170:173], v159 offset:2048
	ds_read_b128 v[174:177], v159 offset:3072
	v_add_u32_e32 v160, 0xc000, v146
	v_lshl_add_u64 v[178:179], s[58:59], 0, v[140:141]
	v_readfirstlane_b32 s5, v160
	v_lshl_add_u64 v[188:189], v[178:179], 0, s[42:43]
	s_mov_b32 m0, s5
	v_add_u32_e32 v161, 0xe000, v146
	ds_read_b128 v[198:201], v151
	ds_read_b128 v[202:205], v151 offset:1024
	ds_read_b128 v[206:209], v150
	ds_read_b128 v[210:213], v150 offset:1024
	ds_read_b128 v[214:217], v149
	ds_read_b128 v[218:221], v149 offset:1024
	ds_read_b128 v[222:225], v148
	ds_read_b128 v[226:229], v148 offset:1024
	global_load_lds_dwordx4 v[188:189], off
	v_lshl_add_u64 v[188:189], s[58:59], 0, v[142:143]
	v_readfirstlane_b32 s5, v161
	v_lshl_add_u64 v[230:231], v[188:189], 0, s[42:43]
	s_mov_b32 m0, s5
	s_nop 0
	global_load_lds_dwordx4 v[230:231], off
	s_waitcnt lgkmcnt(8)
	s_barrier
	s_waitcnt lgkmcnt(0)
	s_waitcnt lgkmcnt(0)
	v_mfma_f32_16x16x32_bf16 v[124:127], v[198:201], v[162:165], v[124:127]
	v_mfma_f32_16x16x32_bf16 v[120:123], v[198:201], v[170:173], v[120:123]
	v_mfma_f32_16x16x32_bf16 v[112:115], v[206:209], v[170:173], v[112:115]
	v_mfma_f32_16x16x32_bf16 v[116:119], v[206:209], v[162:165], v[116:119]
	v_mfma_f32_16x16x32_bf16 v[108:111], v[214:217], v[162:165], v[108:111]
	v_mfma_f32_16x16x32_bf16 v[104:107], v[214:217], v[170:173], v[104:107]
	v_mfma_f32_16x16x32_bf16 v[96:99], v[222:225], v[170:173], v[96:99]
	v_mfma_f32_16x16x32_bf16 v[100:103], v[222:225], v[162:165], v[100:103]
	v_mfma_f32_16x16x32_bf16 v[124:127], v[202:205], v[166:169], v[124:127]
	v_mfma_f32_16x16x32_bf16 v[120:123], v[202:205], v[174:177], v[120:123]
	v_mfma_f32_16x16x32_bf16 v[112:115], v[210:213], v[174:177], v[112:115]
	v_mfma_f32_16x16x32_bf16 v[116:119], v[210:213], v[166:169], v[116:119]
	v_mfma_f32_16x16x32_bf16 v[108:111], v[218:221], v[166:169], v[108:111]
	v_mfma_f32_16x16x32_bf16 v[104:107], v[218:221], v[174:177], v[104:107]
	v_mfma_f32_16x16x32_bf16 v[96:99], v[226:229], v[174:177], v[96:99]
	v_mfma_f32_16x16x32_bf16 v[100:103], v[226:229], v[166:169], v[100:103]
	s_barrier
	v_add_u32_e32 v186, s7, v145
	v_lshl_add_u64 v[246:247], s[58:59], 0, v[136:137]
	v_readfirstlane_b32 s5, v186
	v_lshl_add_u64 v[248:249], v[246:247], 0, s[44:45]
	s_mov_b32 m0, s5
	v_add_u32_e32 v186, 0x2000, v186
	ds_read_b128 v[230:233], v158
	ds_read_b128 v[234:237], v158 offset:1024
	ds_read_b128 v[238:241], v158 offset:2048
	ds_read_b128 v[242:245], v158 offset:3072
	global_load_lds_dwordx4 v[248:249], off
	v_lshl_add_u64 v[248:249], s[58:59], 0, v[138:139]
	v_readfirstlane_b32 s5, v186
	v_lshl_add_u64 v[250:251], v[248:249], 0, s[44:45]
	s_mov_b32 m0, s5
	s_nop 0
	global_load_lds_dwordx4 v[250:251], off
	s_barrier
	s_waitcnt lgkmcnt(0)
	s_waitcnt lgkmcnt(0)
	v_mfma_f32_16x16x32_bf16 v[92:95], v[198:201], v[230:233], v[92:95]
	v_mfma_f32_16x16x32_bf16 v[88:91], v[198:201], v[238:241], v[88:91]
	v_mfma_f32_16x16x32_bf16 v[80:83], v[206:209], v[238:241], v[80:83]
	v_mfma_f32_16x16x32_bf16 v[84:87], v[206:209], v[230:233], v[84:87]
	v_mfma_f32_16x16x32_bf16 v[76:79], v[214:217], v[230:233], v[76:79]
	v_mfma_f32_16x16x32_bf16 v[72:75], v[214:217], v[238:241], v[72:75]
	v_mfma_f32_16x16x32_bf16 v[64:67], v[222:225], v[238:241], v[64:67]
	v_mfma_f32_16x16x32_bf16 v[68:71], v[222:225], v[230:233], v[68:71]
	v_mfma_f32_16x16x32_bf16 v[92:95], v[202:205], v[234:237], v[92:95]
	v_mfma_f32_16x16x32_bf16 v[88:91], v[202:205], v[242:245], v[88:91]
	v_mfma_f32_16x16x32_bf16 v[80:83], v[210:213], v[242:245], v[80:83]
	v_mfma_f32_16x16x32_bf16 v[84:87], v[210:213], v[234:237], v[84:87]
	v_mfma_f32_16x16x32_bf16 v[76:79], v[218:221], v[234:237], v[76:79]
	v_mfma_f32_16x16x32_bf16 v[72:75], v[218:221], v[242:245], v[72:75]
	v_mfma_f32_16x16x32_bf16 v[64:67], v[226:229], v[242:245], v[64:67]
	v_mfma_f32_16x16x32_bf16 v[68:71], v[226:229], v[234:237], v[68:71]
	v_readfirstlane_b32 s5, v146
	v_add_u32_e32 v186, 0x2000, v146
	v_lshl_add_u64 v[250:251], v[178:179], 0, s[46:47]
	s_mov_b32 m0, s5
	v_readfirstlane_b32 s5, v186
	s_barrier
	ds_read_b128 v[198:201], v151 offset:16384
	ds_read_b128 v[202:205], v151 offset:17408
	ds_read_b128 v[206:209], v150 offset:16384
	ds_read_b128 v[210:213], v150 offset:17408
	ds_read_b128 v[214:217], v149 offset:16384
	ds_read_b128 v[218:221], v149 offset:17408
	ds_read_b128 v[222:225], v148 offset:16384
	ds_read_b128 v[226:229], v148 offset:17408
	global_load_lds_dwordx4 v[250:251], off
	v_lshl_add_u64 v[250:251], v[188:189], 0, s[46:47]
	s_mov_b32 m0, s5
	s_nop 0
	global_load_lds_dwordx4 v[250:251], off
	s_barrier
	s_waitcnt lgkmcnt(0)
	s_waitcnt lgkmcnt(0)
	v_mfma_f32_16x16x32_bf16 v[60:63], v[198:201], v[162:165], v[60:63]
	v_mfma_f32_16x16x32_bf16 v[56:59], v[198:201], v[170:173], v[56:59]
	v_mfma_f32_16x16x32_bf16 v[48:51], v[206:209], v[170:173], v[48:51]
	v_mfma_f32_16x16x32_bf16 v[52:55], v[206:209], v[162:165], v[52:55]
	v_mfma_f32_16x16x32_bf16 v[44:47], v[214:217], v[162:165], v[44:47]
	v_mfma_f32_16x16x32_bf16 v[40:43], v[214:217], v[170:173], v[40:43]
	v_mfma_f32_16x16x32_bf16 v[32:35], v[222:225], v[170:173], v[32:35]
	v_mfma_f32_16x16x32_bf16 v[36:39], v[222:225], v[162:165], v[36:39]
	v_mfma_f32_16x16x32_bf16 v[60:63], v[202:205], v[166:169], v[60:63]
	v_mfma_f32_16x16x32_bf16 v[56:59], v[202:205], v[174:177], v[56:59]
	v_mfma_f32_16x16x32_bf16 v[48:51], v[210:213], v[174:177], v[48:51]
	v_mfma_f32_16x16x32_bf16 v[52:55], v[210:213], v[166:169], v[52:55]
	v_mfma_f32_16x16x32_bf16 v[44:47], v[218:221], v[166:169], v[44:47]
	v_mfma_f32_16x16x32_bf16 v[40:43], v[218:221], v[174:177], v[40:43]
	v_mfma_f32_16x16x32_bf16 v[32:35], v[226:229], v[174:177], v[32:35]
	v_mfma_f32_16x16x32_bf16 v[36:39], v[226:229], v[166:169], v[36:39]
	s_barrier
; #define WAIT_V(n) asm volatile("s_waitcnt vmcnt(" #n ")" ::: "memory")
; #define WAIT_L(n) asm volatile("s_waitcnt lgkmcnt(" #n ")" ::: "memory")
; #define BAR __builtin_amdgcn_s_barrier()
; #define SCHED __builtin_amdgcn_sched_barrier(0)
; #define LDA(dst, b, h)                                                                            \
;   _Pragma("unroll") for (int m = 0; m < 4; ++m) _Pragma("unroll") for (int k = 0; k < 2; ++k)                                         \
;     dst[m][k] = *reinterpret_cast<const bf16x8*>((char*)SA(b, h) + lds_byte(wr * 64 + m * 16 + fr, k * 32 + fq * 8))
; #define LDB(dst, b, h)                                                                            \
;   _Pragma("unroll") for (int n = 0; n < 2; ++n) _Pragma("unroll") for (int k = 0; k < 2; ++k)                                         \
;     dst[n][k] = *reinterpret_cast<const bf16x8*>((char*)SB(b, h) + lds_byte(wc * 32 + n * 16 + fr, k * 32 + fq * 8))
; template <int K, bool SWAP>
; __device__ __forceinline__ void gemm_kloop(const bf16* __restrict__ A, const bf16* __restrict__ Bt,
;                                            f32x4 (&acc)[2][2][4][2], bool pref = false) {
;     ...
;     STAGE(SB(0, 1), Bt, HALF, t + 2);
;     WAIT_V(6); BAR; MMA(1, 1, At, B1); BAR;
;     LDB(B0, 1, 0); SCHED; LDA(At, 1, 0); STAGE(SA(0, 1), A, HALF, t + 2);
;     WAIT_L(8); BAR; WAIT_L(0); MMA(0, 0, At, B0); BAR; SCHED;
;     LDB(B1, 1, 1); STAGE(SB(1, 0), Bt, 0, t + 3);
;     BAR; WAIT_L(0); MMA(0, 1, At, B1); BAR;
;     LDA(At, 1, 1); STAGE(SA(1, 0), A, 0, t + 3);
	v_readfirstlane_b32 s5, v147
	v_add_u32_e32 v164, 0x2000, v147
	v_lshl_add_u64 v[162:163], v[246:247], 0, s[48:49]
	s_mov_b32 m0, s5
	v_readfirstlane_b32 s5, v164
	global_load_lds_dwordx4 v[162:163], off
	v_lshl_add_u64 v[162:163], v[248:249], 0, s[48:49]
	s_mov_b32 m0, s5
	s_nop 0
	global_load_lds_dwordx4 v[162:163], off
	s_waitcnt vmcnt(6)
	s_barrier
	v_mfma_f32_16x16x32_bf16 v[28:31], v[198:201], v[230:233], v[28:31]
	v_mfma_f32_16x16x32_bf16 v[24:27], v[198:201], v[238:241], v[24:27]
	v_mfma_f32_16x16x32_bf16 v[16:19], v[206:209], v[238:241], v[16:19]
	v_mfma_f32_16x16x32_bf16 v[20:23], v[206:209], v[230:233], v[20:23]
	v_mfma_f32_16x16x32_bf16 v[12:15], v[214:217], v[230:233], v[12:15]
	v_mfma_f32_16x16x32_bf16 v[8:11], v[214:217], v[238:241], v[8:11]
	v_mfma_f32_16x16x32_bf16 v[0:3], v[222:225], v[238:241], v[0:3]
	v_mfma_f32_16x16x32_bf16 v[4:7], v[222:225], v[230:233], v[4:7]
	v_mfma_f32_16x16x32_bf16 v[28:31], v[202:205], v[234:237], v[28:31]
	v_mfma_f32_16x16x32_bf16 v[24:27], v[202:205], v[242:245], v[24:27]
	v_mfma_f32_16x16x32_bf16 v[16:19], v[210:213], v[242:245], v[16:19]
	v_mfma_f32_16x16x32_bf16 v[20:23], v[210:213], v[234:237], v[20:23]
	v_mfma_f32_16x16x32_bf16 v[12:15], v[218:221], v[234:237], v[12:15]
	v_mfma_f32_16x16x32_bf16 v[8:11], v[218:221], v[242:245], v[8:11]
	v_mfma_f32_16x16x32_bf16 v[0:3], v[226:229], v[242:245], v[0:3]
	v_mfma_f32_16x16x32_bf16 v[4:7], v[226:229], v[234:237], v[4:7]
	s_barrier
	ds_read_b128 v[162:165], v153
	ds_read_b128 v[166:169], v153 offset:1024
	ds_read_b128 v[170:173], v153 offset:2048
	ds_read_b128 v[174:177], v153 offset:3072
	v_add_u32_e32 v186, 0x4000, v146
	v_lshl_add_u64 v[230:231], v[178:179], 0, s[50:51]
	v_readfirstlane_b32 s5, v186
	v_add_u32_e32 v186, 0x6000, v146
	s_mov_b32 m0, s5
	v_readfirstlane_b32 s5, v186
	ds_read_b128 v[198:201], v151 offset:32768
	ds_read_b128 v[202:205], v151 offset:33792
	ds_read_b128 v[206:209], v150 offset:32768
	ds_read_b128 v[210:213], v150 offset:33792
	ds_read_b128 v[214:217], v149 offset:32768
	ds_read_b128 v[218:221], v149 offset:33792
	ds_read_b128 v[222:225], v148 offset:32768
	ds_read_b128 v[226:229], v148 offset:33792
	global_load_lds_dwordx4 v[230:231], off
	v_lshl_add_u64 v[230:231], v[188:189], 0, s[50:51]
	s_mov_b32 m0, s5
	s_nop 0
	global_load_lds_dwordx4 v[230:231], off
	s_waitcnt lgkmcnt(8)
	s_barrier
	s_waitcnt lgkmcnt(0)
	s_waitcnt lgkmcnt(0)
	v_mfma_f32_16x16x32_bf16 v[124:127], v[198:201], v[162:165], v[124:127]
	v_mfma_f32_16x16x32_bf16 v[120:123], v[198:201], v[170:173], v[120:123]
	v_mfma_f32_16x16x32_bf16 v[112:115], v[206:209], v[170:173], v[112:115]
	v_mfma_f32_16x16x32_bf16 v[116:119], v[206:209], v[162:165], v[116:119]
	v_mfma_f32_16x16x32_bf16 v[108:111], v[214:217], v[162:165], v[108:111]
	v_mfma_f32_16x16x32_bf16 v[104:107], v[214:217], v[170:173], v[104:107]
	v_mfma_f32_16x16x32_bf16 v[96:99], v[222:225], v[170:173], v[96:99]
	v_mfma_f32_16x16x32_bf16 v[100:103], v[222:225], v[162:165], v[100:103]
	v_mfma_f32_16x16x32_bf16 v[124:127], v[202:205], v[166:169], v[124:127]
	v_mfma_f32_16x16x32_bf16 v[120:123], v[202:205], v[174:177], v[120:123]
	v_mfma_f32_16x16x32_bf16 v[112:115], v[210:213], v[174:177], v[112:115]
	v_mfma_f32_16x16x32_bf16 v[116:119], v[210:213], v[166:169], v[116:119]
	v_mfma_f32_16x16x32_bf16 v[108:111], v[218:221], v[166:169], v[108:111]
	v_mfma_f32_16x16x32_bf16 v[104:107], v[218:221], v[174:177], v[104:107]
	v_mfma_f32_16x16x32_bf16 v[96:99], v[226:229], v[174:177], v[96:99]
	v_mfma_f32_16x16x32_bf16 v[100:103], v[226:229], v[166:169], v[100:103]
	s_barrier
	v_readfirstlane_b32 s5, v154
	v_add_u32_e32 v186, 0x2000, v154
	v_lshl_add_u64 v[250:251], v[246:247], 0, s[52:53]
	s_mov_b32 m0, s5
	v_readfirstlane_b32 s5, v186
	ds_read_b128 v[230:233], v152
	ds_read_b128 v[234:237], v152 offset:1024
	ds_read_b128 v[238:241], v152 offset:2048
	ds_read_b128 v[242:245], v152 offset:3072
	global_load_lds_dwordx4 v[250:251], off
	v_lshl_add_u64 v[250:251], v[248:249], 0, s[52:53]
	s_mov_b32 m0, s5
	s_nop 0
	global_load_lds_dwordx4 v[250:251], off
	s_barrier
	s_waitcnt lgkmcnt(0)
	s_waitcnt lgkmcnt(0)
	v_mfma_f32_16x16x32_bf16 v[92:95], v[198:201], v[230:233], v[92:95]
	v_mfma_f32_16x16x32_bf16 v[88:91], v[198:201], v[238:241], v[88:91]
	v_mfma_f32_16x16x32_bf16 v[80:83], v[206:209], v[238:241], v[80:83]
	v_mfma_f32_16x16x32_bf16 v[84:87], v[206:209], v[230:233], v[84:87]
	v_mfma_f32_16x16x32_bf16 v[76:79], v[214:217], v[230:233], v[76:79]
	v_mfma_f32_16x16x32_bf16 v[72:75], v[214:217], v[238:241], v[72:75]
	v_mfma_f32_16x16x32_bf16 v[64:67], v[222:225], v[238:241], v[64:67]
	v_mfma_f32_16x16x32_bf16 v[68:71], v[222:225], v[230:233], v[68:71]
	v_mfma_f32_16x16x32_bf16 v[92:95], v[202:205], v[234:237], v[92:95]
	v_mfma_f32_16x16x32_bf16 v[88:91], v[202:205], v[242:245], v[88:91]
	v_mfma_f32_16x16x32_bf16 v[80:83], v[210:213], v[242:245], v[80:83]
	v_mfma_f32_16x16x32_bf16 v[84:87], v[210:213], v[234:237], v[84:87]
	v_mfma_f32_16x16x32_bf16 v[76:79], v[218:221], v[234:237], v[76:79]
	v_mfma_f32_16x16x32_bf16 v[72:75], v[218:221], v[242:245], v[72:75]
	v_mfma_f32_16x16x32_bf16 v[64:67], v[226:229], v[242:245], v[64:67]
	v_mfma_f32_16x16x32_bf16 v[68:71], v[226:229], v[234:237], v[68:71]
	v_readfirstlane_b32 s5, v155
	v_lshl_add_u64 v[178:179], v[178:179], 0, s[54:55]
	s_mov_b32 m0, s5
	v_readfirstlane_b32 s5, v156
	s_barrier
	ds_read_b128 v[198:201], v151 offset:49152
	ds_read_b128 v[202:205], v151 offset:50176
	ds_read_b128 v[206:209], v150 offset:49152
	ds_read_b128 v[210:213], v150 offset:50176
	ds_read_b128 v[214:217], v149 offset:49152
	ds_read_b128 v[218:221], v149 offset:50176
	ds_read_b128 v[222:225], v148 offset:49152
	ds_read_b128 v[226:229], v148 offset:50176
	global_load_lds_dwordx4 v[178:179], off
	v_lshl_add_u64 v[178:179], v[188:189], 0, s[54:55]
	s_mov_b32 m0, s5
	s_nop 0
	global_load_lds_dwordx4 v[178:179], off
	s_barrier
; #define WAIT_V(n) asm volatile("s_waitcnt vmcnt(" #n ")" ::: "memory")
; #define WAIT_L(n) asm volatile("s_waitcnt lgkmcnt(" #n ")" ::: "memory")
; #define BAR __builtin_amdgcn_s_barrier()
; #define SCHED __builtin_amdgcn_sched_barrier(0)
; #define LDA(dst, b, h)                                                                            \
;   _Pragma("unroll") for (int m = 0; m < 4; ++m) _Pragma("unroll") for (int k = 0; k < 2; ++k)                                         \
;     dst[m][k] = *reinterpret_cast<const bf16x8*>((char*)SA(b, h) + lds_byte(wr * 64 + m * 16 + fr, k * 32 + fq * 8))
; #define LDB(dst, b, h)                                                                            \
;   _Pragma("unroll") for (int n = 0; n < 2; ++n) _Pragma("unroll") for (int k = 0; k < 2; ++k)                                         \
;     dst[n][k] = *reinterpret_cast<const bf16x8*>((char*)SB(b, h) + lds_byte(wc * 32 + n * 16 + fr, k * 32 + fq * 8))
; template <int K, bool SWAP>
; __device__ __forceinline__ void gemm_kloop(const bf16* __restrict__ A, const bf16* __restrict__ Bt,
;                                            f32x4 (&acc)[2][2][4][2], bool pref = false) {
;     ...
;     LDA(At, 1, 1); STAGE(SA(1, 0), A, 0, t + 3);
;     BAR; WAIT_L(0); MMA(1, 0, At, B0); BAR; SCHED;
;     STAGE(SB(1, 1), Bt, HALF, t + 3);
;     WAIT_V(6); BAR; MMA(1, 1, At, B1); BAR;
;   }
;   { LDB(B0, 0, 0); LDA(At, 0, 0); STAGE(SA(1, 1), A, HALF, nt - 1);
;     BAR; WAIT_L(0); MMA(0, 0, At, B0); BAR;
;     LDB(B1, 0, 1); BAR; WAIT_L(0); MMA(0, 1, At, B1); BAR;
;     LDA(At, 0, 1); WAIT_V(4); BAR; WAIT_L(0); MMA(1, 0, At, B0); MMA(1, 1, At, B1); BAR; }
	s_waitcnt lgkmcnt(0)
	s_waitcnt lgkmcnt(0)
	v_mfma_f32_16x16x32_bf16 v[60:63], v[198:201], v[162:165], v[60:63]
	v_mfma_f32_16x16x32_bf16 v[56:59], v[198:201], v[170:173], v[56:59]
	v_mfma_f32_16x16x32_bf16 v[48:51], v[206:209], v[170:173], v[48:51]
	v_mfma_f32_16x16x32_bf16 v[52:55], v[206:209], v[162:165], v[52:55]
	v_mfma_f32_16x16x32_bf16 v[44:47], v[214:217], v[162:165], v[44:47]
	v_mfma_f32_16x16x32_bf16 v[40:43], v[214:217], v[170:173], v[40:43]
	v_mfma_f32_16x16x32_bf16 v[32:35], v[222:225], v[170:173], v[32:35]
	v_mfma_f32_16x16x32_bf16 v[36:39], v[222:225], v[162:165], v[36:39]
	v_mfma_f32_16x16x32_bf16 v[60:63], v[202:205], v[166:169], v[60:63]
	v_mfma_f32_16x16x32_bf16 v[56:59], v[202:205], v[174:177], v[56:59]
	v_mfma_f32_16x16x32_bf16 v[48:51], v[210:213], v[174:177], v[48:51]
	v_mfma_f32_16x16x32_bf16 v[52:55], v[210:213], v[166:169], v[52:55]
	v_mfma_f32_16x16x32_bf16 v[44:47], v[218:221], v[166:169], v[44:47]
	v_mfma_f32_16x16x32_bf16 v[40:43], v[218:221], v[174:177], v[40:43]
	v_mfma_f32_16x16x32_bf16 v[32:35], v[226:229], v[174:177], v[32:35]
	v_mfma_f32_16x16x32_bf16 v[36:39], v[226:229], v[166:169], v[36:39]
	s_barrier
	v_readfirstlane_b32 s5, v157
	v_add_u32_e32 v164, 0x2000, v157
	v_lshl_add_u64 v[162:163], v[246:247], 0, s[56:57]
	s_mov_b32 m0, s5
	v_readfirstlane_b32 s5, v164
	global_load_lds_dwordx4 v[162:163], off
	v_lshl_add_u64 v[162:163], v[248:249], 0, s[56:57]
	s_mov_b32 m0, s5
	s_nop 0
	global_load_lds_dwordx4 v[162:163], off
	s_waitcnt vmcnt(6)
	s_barrier
	v_mfma_f32_16x16x32_bf16 v[28:31], v[198:201], v[230:233], v[28:31]
	v_mfma_f32_16x16x32_bf16 v[24:27], v[198:201], v[238:241], v[24:27]
	v_mfma_f32_16x16x32_bf16 v[16:19], v[206:209], v[238:241], v[16:19]
	v_mfma_f32_16x16x32_bf16 v[20:23], v[206:209], v[230:233], v[20:23]
	v_mfma_f32_16x16x32_bf16 v[12:15], v[214:217], v[230:233], v[12:15]
	v_mfma_f32_16x16x32_bf16 v[8:11], v[214:217], v[238:241], v[8:11]
	v_mfma_f32_16x16x32_bf16 v[0:3], v[222:225], v[238:241], v[0:3]
	v_mfma_f32_16x16x32_bf16 v[4:7], v[222:225], v[230:233], v[4:7]
	v_mfma_f32_16x16x32_bf16 v[28:31], v[202:205], v[234:237], v[28:31]
	v_mfma_f32_16x16x32_bf16 v[24:27], v[202:205], v[242:245], v[24:27]
	v_mfma_f32_16x16x32_bf16 v[16:19], v[210:213], v[242:245], v[16:19]
	v_mfma_f32_16x16x32_bf16 v[20:23], v[210:213], v[234:237], v[20:23]
	v_mfma_f32_16x16x32_bf16 v[12:15], v[218:221], v[234:237], v[12:15]
	v_mfma_f32_16x16x32_bf16 v[8:11], v[218:221], v[242:245], v[8:11]
	v_mfma_f32_16x16x32_bf16 v[0:3], v[226:229], v[242:245], v[0:3]
	v_mfma_f32_16x16x32_bf16 v[4:7], v[226:229], v[234:237], v[4:7]
	s_add_i32 s4, s4, 2
	v_lshl_add_u64 v[136:137], v[136:137], 0, s[44:45]
	v_lshl_add_u64 v[138:139], v[138:139], 0, s[44:45]
	v_lshl_add_u64 v[140:141], v[140:141], 0, s[44:45]
	s_cmp_lt_u32 s4, 12
	v_lshl_add_u64 v[142:143], v[142:143], 0, s[44:45]
	s_barrier
	s_cbranch_scc1 .LBB0_271
	s_add_u32 s0, s0, 0x40780
	s_addc_u32 s1, s1, 0
	v_lshl_add_u64 v[130:131], s[0:1], 0, v[130:131]
	v_readfirstlane_b32 s4, v160
	v_lshl_add_u64 v[128:129], v[128:129], 1, v[130:131]
	s_mov_b32 m0, s4
	ds_read_b128 v[136:139], v159
	ds_read_b128 v[140:143], v159 offset:1024
	ds_read_b128 v[154:157], v159 offset:2048
	ds_read_b128 v[162:165], v159 offset:3072
	ds_read_b128 v[166:169], v151
	ds_read_b128 v[170:173], v151 offset:1024
	ds_read_b128 v[174:177], v150
	ds_read_b128 v[198:201], v150 offset:1024
	ds_read_b128 v[202:205], v149
	ds_read_b128 v[206:209], v149 offset:1024
	ds_read_b128 v[210:213], v148
	ds_read_b128 v[214:217], v148 offset:1024
	global_load_lds_dwordx4 v[128:129], off
	v_lshl_add_u64 v[128:129], s[0:1], 0, v[134:135]
	v_readfirstlane_b32 s0, v161
	v_lshl_add_u64 v[128:129], v[132:133], 1, v[128:129]
	s_mov_b32 m0, s0
	s_nop 0
	global_load_lds_dwordx4 v[128:129], off
	s_barrier
	s_waitcnt lgkmcnt(0)
	s_waitcnt lgkmcnt(0)
	v_mfma_f32_16x16x32_bf16 v[124:127], v[166:169], v[136:139], v[124:127]
	v_mfma_f32_16x16x32_bf16 v[116:119], v[174:177], v[136:139], v[116:119]
	v_mfma_f32_16x16x32_bf16 v[108:111], v[202:205], v[136:139], v[108:111]
	v_mfma_f32_16x16x32_bf16 v[100:103], v[210:213], v[136:139], v[100:103]
	v_mfma_f32_16x16x32_bf16 v[124:127], v[170:173], v[140:143], v[124:127]
	v_mfma_f32_16x16x32_bf16 v[120:123], v[166:169], v[154:157], v[120:123]
	v_mfma_f32_16x16x32_bf16 v[116:119], v[198:201], v[140:143], v[116:119]
	v_mfma_f32_16x16x32_bf16 v[112:115], v[174:177], v[154:157], v[112:115]
	v_mfma_f32_16x16x32_bf16 v[108:111], v[206:209], v[140:143], v[108:111]
	v_mfma_f32_16x16x32_bf16 v[104:107], v[202:205], v[154:157], v[104:107]
	v_mfma_f32_16x16x32_bf16 v[100:103], v[214:217], v[140:143], v[100:103]
	v_mfma_f32_16x16x32_bf16 v[96:99], v[210:213], v[154:157], v[96:99]
	v_mfma_f32_16x16x32_bf16 v[128:131], v[170:173], v[162:165], v[120:123]
	v_mfma_f32_16x16x32_bf16 v[132:135], v[198:201], v[162:165], v[112:115]
	v_mfma_f32_16x16x32_bf16 v[218:221], v[206:209], v[162:165], v[104:107]
	v_mfma_f32_16x16x32_bf16 v[222:225], v[214:217], v[162:165], v[96:99]
	s_barrier
	s_nop 1
	ds_read_b128 v[96:99], v158
	ds_read_b128 v[104:107], v158 offset:1024
	ds_read_b128 v[112:115], v158 offset:2048
	ds_read_b128 v[120:123], v158 offset:3072
	s_barrier
; #define WAIT_V(n) asm volatile("s_waitcnt vmcnt(" #n ")" ::: "memory")
; #define WAIT_L(n) asm volatile("s_waitcnt lgkmcnt(" #n ")" ::: "memory")
; #define BAR __builtin_amdgcn_s_barrier()
; #define LDA(dst, b, h)                                                                            \
;   _Pragma("unroll") for (int m = 0; m < 4; ++m) _Pragma("unroll") for (int k = 0; k < 2; ++k)                                         \
;     dst[m][k] = *reinterpret_cast<const bf16x8*>((char*)SA(b, h) + lds_byte(wr * 64 + m * 16 + fr, k * 32 + fq * 8))
; #define LDB(dst, b, h)                                                                            \
;   _Pragma("unroll") for (int n = 0; n < 2; ++n) _Pragma("unroll") for (int k = 0; k < 2; ++k)                                         \
;     dst[n][k] = *reinterpret_cast<const bf16x8*>((char*)SB(b, h) + lds_byte(wc * 32 + n * 16 + fr, k * 32 + fq * 8))
; template <int K, bool SWAP>
; __device__ __forceinline__ void gemm_kloop(const bf16* __restrict__ A, const bf16* __restrict__ Bt,
;                                            f32x4 (&acc)[2][2][4][2], bool pref = false) {
;     ...
;     LDB(B1, 0, 1); BAR; WAIT_L(0); MMA(0, 1, At, B1); BAR;
;     LDA(At, 0, 1); WAIT_V(4); BAR; WAIT_L(0); MMA(1, 0, At, B0); MMA(1, 1, At, B1); BAR; }
;   { LDB(B0, 1, 0); LDA(At, 1, 0); WAIT_V(2); BAR; WAIT_L(0); MMA(0, 0, At, B0); BAR;
	s_waitcnt lgkmcnt(0)
	s_waitcnt lgkmcnt(0)
	v_mfma_f32_16x16x32_bf16 v[92:95], v[166:169], v[96:99], v[92:95]
	v_mfma_f32_16x16x32_bf16 v[84:87], v[174:177], v[96:99], v[84:87]
	v_mfma_f32_16x16x32_bf16 v[76:79], v[202:205], v[96:99], v[76:79]
	v_mfma_f32_16x16x32_bf16 v[68:71], v[210:213], v[96:99], v[68:71]
	v_mfma_f32_16x16x32_bf16 v[92:95], v[170:173], v[104:107], v[92:95]
	v_mfma_f32_16x16x32_bf16 v[88:91], v[166:169], v[112:115], v[88:91]
	v_mfma_f32_16x16x32_bf16 v[84:87], v[198:201], v[104:107], v[84:87]
	v_mfma_f32_16x16x32_bf16 v[80:83], v[174:177], v[112:115], v[80:83]
	v_mfma_f32_16x16x32_bf16 v[76:79], v[206:209], v[104:107], v[76:79]
	v_mfma_f32_16x16x32_bf16 v[72:75], v[202:205], v[112:115], v[72:75]
	v_mfma_f32_16x16x32_bf16 v[68:71], v[214:217], v[104:107], v[68:71]
	v_mfma_f32_16x16x32_bf16 v[64:67], v[210:213], v[112:115], v[64:67]
	v_mfma_f32_16x16x32_bf16 v[158:161], v[170:173], v[120:123], v[88:91]
	v_mfma_f32_16x16x32_bf16 v[166:169], v[198:201], v[120:123], v[80:83]
	v_mfma_f32_16x16x32_bf16 v[170:173], v[206:209], v[120:123], v[72:75]
	v_mfma_f32_16x16x32_bf16 v[174:177], v[214:217], v[120:123], v[64:67]
	s_barrier
	s_nop 1
	ds_read_b128 v[64:67], v151 offset:16384
	ds_read_b128 v[72:75], v151 offset:17408
	ds_read_b128 v[80:83], v150 offset:16384
	ds_read_b128 v[88:91], v150 offset:17408
	ds_read_b128 v[198:201], v149 offset:16384
	ds_read_b128 v[202:205], v149 offset:17408
	ds_read_b128 v[206:209], v148 offset:16384
	ds_read_b128 v[210:213], v148 offset:17408
	s_waitcnt vmcnt(4)
	s_barrier
	s_waitcnt lgkmcnt(0)
	s_waitcnt lgkmcnt(0)
	v_mfma_f32_16x16x32_bf16 v[60:63], v[64:67], v[136:139], v[60:63]
	v_mfma_f32_16x16x32_bf16 v[52:55], v[80:83], v[136:139], v[52:55]
	v_mfma_f32_16x16x32_bf16 v[44:47], v[198:201], v[136:139], v[44:47]
	v_mfma_f32_16x16x32_bf16 v[36:39], v[206:209], v[136:139], v[36:39]
	v_mfma_f32_16x16x32_bf16 v[60:63], v[72:75], v[140:143], v[60:63]
	v_mfma_f32_16x16x32_bf16 v[56:59], v[64:67], v[154:157], v[56:59]
	v_mfma_f32_16x16x32_bf16 v[52:55], v[88:91], v[140:143], v[52:55]
	v_mfma_f32_16x16x32_bf16 v[48:51], v[80:83], v[154:157], v[48:51]
	v_mfma_f32_16x16x32_bf16 v[44:47], v[202:205], v[140:143], v[44:47]
	v_mfma_f32_16x16x32_bf16 v[40:43], v[198:201], v[154:157], v[40:43]
	v_mfma_f32_16x16x32_bf16 v[36:39], v[210:213], v[140:143], v[36:39]
	v_mfma_f32_16x16x32_bf16 v[32:35], v[206:209], v[154:157], v[32:35]
	v_mfma_f32_16x16x32_bf16 v[214:217], v[72:75], v[162:165], v[56:59]
	v_mfma_f32_16x16x32_bf16 v[226:229], v[88:91], v[162:165], v[48:51]
	v_mfma_f32_16x16x32_bf16 v[230:233], v[202:205], v[162:165], v[40:43]
	v_mfma_f32_16x16x32_bf16 v[136:139], v[210:213], v[162:165], v[32:35]
	v_mfma_f32_16x16x32_bf16 v[28:31], v[64:67], v[96:99], v[28:31]
	v_mfma_f32_16x16x32_bf16 v[20:23], v[80:83], v[96:99], v[20:23]
	v_mfma_f32_16x16x32_bf16 v[12:15], v[198:201], v[96:99], v[12:15]
	v_mfma_f32_16x16x32_bf16 v[4:7], v[206:209], v[96:99], v[4:7]
	v_mfma_f32_16x16x32_bf16 v[28:31], v[72:75], v[104:107], v[28:31]
	v_mfma_f32_16x16x32_bf16 v[24:27], v[64:67], v[112:115], v[24:27]
	v_mfma_f32_16x16x32_bf16 v[20:23], v[88:91], v[104:107], v[20:23]
	v_mfma_f32_16x16x32_bf16 v[16:19], v[80:83], v[112:115], v[16:19]
	v_mfma_f32_16x16x32_bf16 v[12:15], v[202:205], v[104:107], v[12:15]
	v_mfma_f32_16x16x32_bf16 v[8:11], v[198:201], v[112:115], v[8:11]
	v_mfma_f32_16x16x32_bf16 v[4:7], v[210:213], v[104:107], v[4:7]
	v_mfma_f32_16x16x32_bf16 v[0:3], v[206:209], v[112:115], v[0:3]
	v_mfma_f32_16x16x32_bf16 v[140:143], v[72:75], v[120:123], v[24:27]
	v_mfma_f32_16x16x32_bf16 v[154:157], v[88:91], v[120:123], v[16:19]
	v_mfma_f32_16x16x32_bf16 v[162:165], v[202:205], v[120:123], v[8:11]
	v_mfma_f32_16x16x32_bf16 v[198:201], v[210:213], v[120:123], v[0:3]
	s_barrier
	s_nop 1
	ds_read_b128 v[0:3], v153
	ds_read_b128 v[8:11], v153 offset:1024
	ds_read_b128 v[16:19], v153 offset:2048
	ds_read_b128 v[24:27], v153 offset:3072
	ds_read_b128 v[32:35], v151 offset:32768
	ds_read_b128 v[40:43], v151 offset:33792
	ds_read_b128 v[48:51], v150 offset:32768
	ds_read_b128 v[56:59], v150 offset:33792
	ds_read_b128 v[64:67], v149 offset:32768
	ds_read_b128 v[202:205], v149 offset:33792
	ds_read_b128 v[206:209], v148 offset:32768
	ds_read_b128 v[210:213], v148 offset:33792
	s_waitcnt vmcnt(2)
	s_barrier
; #define WAIT_V(n) asm volatile("s_waitcnt vmcnt(" #n ")" ::: "memory")
; #define WAIT_L(n) asm volatile("s_waitcnt lgkmcnt(" #n ")" ::: "memory")
; #define BAR __builtin_amdgcn_s_barrier()
; #define LDA(dst, b, h)                                                                            \
;   _Pragma("unroll") for (int m = 0; m < 4; ++m) _Pragma("unroll") for (int k = 0; k < 2; ++k)                                         \
;     dst[m][k] = *reinterpret_cast<const bf16x8*>((char*)SA(b, h) + lds_byte(wr * 64 + m * 16 + fr, k * 32 + fq * 8))
; #define LDB(dst, b, h)                                                                            \
;   _Pragma("unroll") for (int n = 0; n < 2; ++n) _Pragma("unroll") for (int k = 0; k < 2; ++k)                                         \
;     dst[n][k] = *reinterpret_cast<const bf16x8*>((char*)SB(b, h) + lds_byte(wc * 32 + n * 16 + fr, k * 32 + fq * 8))
; template <int K, bool SWAP>
; __device__ __forceinline__ void gemm_kloop(const bf16* __restrict__ A, const bf16* __restrict__ Bt,
;                                            f32x4 (&acc)[2][2][4][2], bool pref = false) {
;     ...
;   { LDB(B0, 1, 0); LDA(At, 1, 0); WAIT_V(2); BAR; WAIT_L(0); MMA(0, 0, At, B0); BAR;
;     LDB(B1, 1, 1); WAIT_V(0); BAR; WAIT_L(0); MMA(0, 1, At, B1); BAR;
;     LDA(At, 1, 1); BAR; WAIT_L(0); MMA(1, 0, At, B0); MMA(1, 1, At, B1); BAR; }
;   if (wr == 0) BAR;
	s_waitcnt lgkmcnt(0)
	s_waitcnt lgkmcnt(0)
	v_mfma_f32_16x16x32_bf16 v[72:75], v[32:35], v[0:3], v[124:127]
	v_mfma_f32_16x16x32_bf16 v[120:123], v[40:43], v[8:11], v[72:75]
	v_mfma_f32_16x16x32_bf16 v[72:75], v[32:35], v[16:19], v[128:131]
	v_mfma_f32_16x16x32_bf16 v[124:127], v[40:43], v[24:27], v[72:75]
	v_mfma_f32_16x16x32_bf16 v[72:75], v[48:51], v[0:3], v[116:119]
	v_mfma_f32_16x16x32_bf16 v[112:115], v[56:59], v[8:11], v[72:75]
	v_mfma_f32_16x16x32_bf16 v[72:75], v[48:51], v[16:19], v[132:135]
	v_mfma_f32_16x16x32_bf16 v[116:119], v[56:59], v[24:27], v[72:75]
	v_mfma_f32_16x16x32_bf16 v[72:75], v[64:67], v[0:3], v[108:111]
	v_mfma_f32_16x16x32_bf16 v[104:107], v[202:205], v[8:11], v[72:75]
	v_mfma_f32_16x16x32_bf16 v[72:75], v[64:67], v[16:19], v[218:221]
	v_mfma_f32_16x16x32_bf16 v[108:111], v[202:205], v[24:27], v[72:75]
	v_mfma_f32_16x16x32_bf16 v[72:75], v[206:209], v[0:3], v[100:103]
	v_mfma_f32_16x16x32_bf16 v[96:99], v[210:213], v[8:11], v[72:75]
	v_mfma_f32_16x16x32_bf16 v[72:75], v[206:209], v[16:19], v[222:225]
	v_mfma_f32_16x16x32_bf16 v[100:103], v[210:213], v[24:27], v[72:75]
	s_barrier
	ds_read_b128 v[128:131], v152
	ds_read_b128 v[132:135], v152 offset:1024
	ds_read_b128 v[218:221], v152 offset:2048
	ds_read_b128 v[222:225], v152 offset:3072
	s_waitcnt vmcnt(0)
	s_barrier
	s_waitcnt lgkmcnt(0)
	s_waitcnt lgkmcnt(0)
	v_mfma_f32_16x16x32_bf16 v[72:75], v[32:35], v[128:131], v[92:95]
	v_mfma_f32_16x16x32_bf16 v[32:35], v[32:35], v[218:221], v[158:161]
	v_mfma_f32_16x16x32_bf16 v[92:95], v[40:43], v[222:225], v[32:35]
	v_mfma_f32_16x16x32_bf16 v[32:35], v[48:51], v[128:131], v[84:87]
	v_mfma_f32_16x16x32_bf16 v[80:83], v[56:59], v[132:135], v[32:35]
	v_mfma_f32_16x16x32_bf16 v[32:35], v[48:51], v[218:221], v[166:169]
	v_mfma_f32_16x16x32_bf16 v[84:87], v[56:59], v[222:225], v[32:35]
	v_mfma_f32_16x16x32_bf16 v[32:35], v[64:67], v[128:131], v[76:79]
	v_mfma_f32_16x16x32_bf16 v[88:91], v[40:43], v[132:135], v[72:75]
	v_mfma_f32_16x16x32_bf16 v[72:75], v[202:205], v[132:135], v[32:35]
	v_mfma_f32_16x16x32_bf16 v[32:35], v[64:67], v[218:221], v[170:173]
	v_mfma_f32_16x16x32_bf16 v[76:79], v[202:205], v[222:225], v[32:35]
	v_mfma_f32_16x16x32_bf16 v[32:35], v[206:209], v[128:131], v[68:71]
	v_mfma_f32_16x16x32_bf16 v[64:67], v[210:213], v[132:135], v[32:35]
	v_mfma_f32_16x16x32_bf16 v[32:35], v[206:209], v[218:221], v[174:177]
	v_mfma_f32_16x16x32_bf16 v[68:71], v[210:213], v[222:225], v[32:35]
	s_barrier
	ds_read_b128 v[158:161], v151 offset:49152
	ds_read_b128 v[166:169], v151 offset:50176
	ds_read_b128 v[170:173], v150 offset:49152
	ds_read_b128 v[150:153], v150 offset:50176
	ds_read_b128 v[174:177], v149 offset:49152
	ds_read_b128 v[202:205], v149 offset:50176
	ds_read_b128 v[206:209], v148 offset:49152
	ds_read_b128 v[146:149], v148 offset:50176
	s_barrier
	s_waitcnt lgkmcnt(0)
	s_waitcnt lgkmcnt(0)
	v_mfma_f32_16x16x32_bf16 v[32:35], v[158:161], v[0:3], v[60:63]
	v_mfma_f32_16x16x32_bf16 v[56:59], v[166:169], v[8:11], v[32:35]
	v_mfma_f32_16x16x32_bf16 v[32:35], v[158:161], v[16:19], v[214:217]
	v_mfma_f32_16x16x32_bf16 v[60:63], v[166:169], v[24:27], v[32:35]
	v_mfma_f32_16x16x32_bf16 v[32:35], v[170:173], v[0:3], v[52:55]
	v_mfma_f32_16x16x32_bf16 v[48:51], v[150:153], v[8:11], v[32:35]
	v_mfma_f32_16x16x32_bf16 v[32:35], v[170:173], v[16:19], v[226:229]
	v_mfma_f32_16x16x32_bf16 v[52:55], v[150:153], v[24:27], v[32:35]
	v_mfma_f32_16x16x32_bf16 v[32:35], v[174:177], v[0:3], v[44:47]
	v_mfma_f32_16x16x32_bf16 v[40:43], v[202:205], v[8:11], v[32:35]
	v_mfma_f32_16x16x32_bf16 v[32:35], v[174:177], v[16:19], v[230:233]
	v_mfma_f32_16x16x32_bf16 v[0:3], v[206:209], v[0:3], v[36:39]
	v_mfma_f32_16x16x32_bf16 v[44:47], v[202:205], v[24:27], v[32:35]
	v_mfma_f32_16x16x32_bf16 v[32:35], v[146:149], v[8:11], v[0:3]
	v_mfma_f32_16x16x32_bf16 v[0:3], v[206:209], v[16:19], v[136:139]
	v_mfma_f32_16x16x32_bf16 v[36:39], v[146:149], v[24:27], v[0:3]
	v_mfma_f32_16x16x32_bf16 v[0:3], v[158:161], v[128:131], v[28:31]
	v_mfma_f32_16x16x32_bf16 v[24:27], v[166:169], v[132:135], v[0:3]
	v_mfma_f32_16x16x32_bf16 v[0:3], v[158:161], v[218:221], v[140:143]
	v_mfma_f32_16x16x32_bf16 v[28:31], v[166:169], v[222:225], v[0:3]
	v_mfma_f32_16x16x32_bf16 v[0:3], v[170:173], v[128:131], v[20:23]
	v_mfma_f32_16x16x32_bf16 v[16:19], v[150:153], v[132:135], v[0:3]
	v_mfma_f32_16x16x32_bf16 v[0:3], v[170:173], v[218:221], v[154:157]
	v_mfma_f32_16x16x32_bf16 v[20:23], v[150:153], v[222:225], v[0:3]
	v_mfma_f32_16x16x32_bf16 v[0:3], v[174:177], v[128:131], v[12:15]
	v_mfma_f32_16x16x32_bf16 v[8:11], v[202:205], v[132:135], v[0:3]
	v_mfma_f32_16x16x32_bf16 v[0:3], v[174:177], v[218:221], v[162:165]
	v_mfma_f32_16x16x32_bf16 v[12:15], v[202:205], v[222:225], v[0:3]
	v_mfma_f32_16x16x32_bf16 v[0:3], v[206:209], v[128:131], v[4:7]
	v_mfma_f32_16x16x32_bf16 v[4:7], v[206:209], v[218:221], v[198:201]
	v_mfma_f32_16x16x32_bf16 v[0:3], v[146:149], v[132:135], v[0:3]
	v_mfma_f32_16x16x32_bf16 v[4:7], v[146:149], v[222:225], v[4:7]
	s_movk_i32 s0, 0x100
	v_cmp_gt_u32_e32 vcc, s0, v144
	s_barrier
	s_and_saveexec_b64 s[0:1], vcc
	s_cbranch_execz .LBB0_274
	s_barrier

; #define WAIT_V(n) asm volatile("s_waitcnt vmcnt(" #n ")" ::: "memory")
; #define WAIT_L(n) asm volatile("s_waitcnt lgkmcnt(" #n ")" ::: "memory")
; #define BAR __builtin_amdgcn_s_barrier()
; #define SCHED __builtin_amdgcn_sched_barrier(0)
; #define LDA(dst, b, h)                                                                            \
;   _Pragma("unroll") for (int m = 0; m < 4; ++m) _Pragma("unroll") for (int k = 0; k < 2; ++k)                                         \
;     dst[m][k] = *reinterpret_cast<const bf16x8*>((char*)SA(b, h) + lds_byte(wr * 64 + m * 16 + fr, k * 32 + fq * 8))
; #define LDB(dst, b, h)                                                                            \
;   _Pragma("unroll") for (int n = 0; n < 2; ++n) _Pragma("unroll") for (int k = 0; k < 2; ++k)                                         \
;     dst[n][k] = *reinterpret_cast<const bf16x8*>((char*)SB(b, h) + lds_byte(wc * 32 + n * 16 + fr, k * 32 + fq * 8))
; template <int K, bool SWAP>
; __device__ __forceinline__ void gemm_kloop(const bf16* __restrict__ A, const bf16* __restrict__ Bt,
;                                            f32x4 (&acc)[2][2][4][2], bool pref = false) {
;     ...
;     LDB(B0, 0, 0); SCHED; LDA(At, 0, 0); STAGE(SA(1, 1), A, HALF, t + 1);
;     WAIT_L(8); BAR; WAIT_L(0); MMA(0, 0, At, B0); BAR; SCHED;
;     LDB(B1, 0, 1); STAGE(SB(0, 0), Bt, 0, t + 2);
;     BAR; WAIT_L(0); MMA(0, 1, At, B1); BAR;
;     LDA(At, 0, 1); STAGE(SA(0, 0), A, 0, t + 2);
;     BAR; WAIT_L(0); MMA(1, 0, At, B0); BAR; SCHED;
;     STAGE(SB(0, 1), Bt, HALF, t + 2);
;     WAIT_V(6); BAR; MMA(1, 1, At, B1); BAR;
.LBB0_449:
	ds_read_b128 v[162:165], v159
	ds_read_b128 v[166:169], v159 offset:1024
	ds_read_b128 v[170:173], v159 offset:2048
	ds_read_b128 v[174:177], v159 offset:3072
	v_add_u32_e32 v160, 0xc000, v146
	v_lshl_add_u64 v[178:179], s[58:59], 0, v[140:141]
	v_readfirstlane_b32 s7, v160
	v_lshl_add_u64 v[188:189], v[178:179], 0, s[42:43]
	s_mov_b32 m0, s7
	v_add_u32_e32 v161, 0xe000, v146
	ds_read_b128 v[198:201], v151
	ds_read_b128 v[202:205], v151 offset:1024
	ds_read_b128 v[206:209], v150
	ds_read_b128 v[210:213], v150 offset:1024
	ds_read_b128 v[214:217], v149
	ds_read_b128 v[218:221], v149 offset:1024
	ds_read_b128 v[222:225], v148
	ds_read_b128 v[226:229], v148 offset:1024
	global_load_lds_dwordx4 v[188:189], off
	v_lshl_add_u64 v[188:189], s[58:59], 0, v[142:143]
	v_readfirstlane_b32 s7, v161
	v_lshl_add_u64 v[230:231], v[188:189], 0, s[42:43]
	s_mov_b32 m0, s7
	s_nop 0
	global_load_lds_dwordx4 v[230:231], off
	s_waitcnt lgkmcnt(8)
	s_barrier
	s_waitcnt lgkmcnt(0)
	s_waitcnt lgkmcnt(0)
	v_mfma_f32_16x16x32_bf16 v[124:127], v[198:201], v[162:165], v[124:127]
	v_mfma_f32_16x16x32_bf16 v[120:123], v[198:201], v[170:173], v[120:123]
	v_mfma_f32_16x16x32_bf16 v[112:115], v[206:209], v[170:173], v[112:115]
	v_mfma_f32_16x16x32_bf16 v[116:119], v[206:209], v[162:165], v[116:119]
	v_mfma_f32_16x16x32_bf16 v[108:111], v[214:217], v[162:165], v[108:111]
	v_mfma_f32_16x16x32_bf16 v[104:107], v[214:217], v[170:173], v[104:107]
	v_mfma_f32_16x16x32_bf16 v[96:99], v[222:225], v[170:173], v[96:99]
	v_mfma_f32_16x16x32_bf16 v[100:103], v[222:225], v[162:165], v[100:103]
	v_mfma_f32_16x16x32_bf16 v[124:127], v[202:205], v[166:169], v[124:127]
	v_mfma_f32_16x16x32_bf16 v[120:123], v[202:205], v[174:177], v[120:123]
	v_mfma_f32_16x16x32_bf16 v[112:115], v[210:213], v[174:177], v[112:115]
	v_mfma_f32_16x16x32_bf16 v[116:119], v[210:213], v[166:169], v[116:119]
	v_mfma_f32_16x16x32_bf16 v[108:111], v[218:221], v[166:169], v[108:111]
	v_mfma_f32_16x16x32_bf16 v[104:107], v[218:221], v[174:177], v[104:107]
	v_mfma_f32_16x16x32_bf16 v[96:99], v[226:229], v[174:177], v[96:99]
	v_mfma_f32_16x16x32_bf16 v[100:103], v[226:229], v[166:169], v[100:103]
	s_barrier
	v_add_u32_e32 v186, s1, v145
	v_lshl_add_u64 v[246:247], s[58:59], 0, v[136:137]
	v_readfirstlane_b32 s7, v186
	v_lshl_add_u64 v[248:249], v[246:247], 0, s[44:45]
	s_mov_b32 m0, s7
	v_add_u32_e32 v186, 0x2000, v186
	ds_read_b128 v[230:233], v158
	ds_read_b128 v[234:237], v158 offset:1024
	ds_read_b128 v[238:241], v158 offset:2048
	ds_read_b128 v[242:245], v158 offset:3072
	global_load_lds_dwordx4 v[248:249], off
	v_lshl_add_u64 v[248:249], s[58:59], 0, v[138:139]
	v_readfirstlane_b32 s7, v186
	v_lshl_add_u64 v[250:251], v[248:249], 0, s[44:45]
	s_mov_b32 m0, s7
	s_nop 0
	global_load_lds_dwordx4 v[250:251], off
	s_barrier
	s_waitcnt lgkmcnt(0)
	s_waitcnt lgkmcnt(0)
	v_mfma_f32_16x16x32_bf16 v[92:95], v[198:201], v[230:233], v[92:95]
	v_mfma_f32_16x16x32_bf16 v[88:91], v[198:201], v[238:241], v[88:91]
	v_mfma_f32_16x16x32_bf16 v[80:83], v[206:209], v[238:241], v[80:83]
	v_mfma_f32_16x16x32_bf16 v[84:87], v[206:209], v[230:233], v[84:87]
	v_mfma_f32_16x16x32_bf16 v[76:79], v[214:217], v[230:233], v[76:79]
	v_mfma_f32_16x16x32_bf16 v[72:75], v[214:217], v[238:241], v[72:75]
	v_mfma_f32_16x16x32_bf16 v[64:67], v[222:225], v[238:241], v[64:67]
	v_mfma_f32_16x16x32_bf16 v[68:71], v[222:225], v[230:233], v[68:71]
	v_mfma_f32_16x16x32_bf16 v[92:95], v[202:205], v[234:237], v[92:95]
	v_mfma_f32_16x16x32_bf16 v[88:91], v[202:205], v[242:245], v[88:91]
	v_mfma_f32_16x16x32_bf16 v[80:83], v[210:213], v[242:245], v[80:83]
	v_mfma_f32_16x16x32_bf16 v[84:87], v[210:213], v[234:237], v[84:87]
	v_mfma_f32_16x16x32_bf16 v[76:79], v[218:221], v[234:237], v[76:79]
	v_mfma_f32_16x16x32_bf16 v[72:75], v[218:221], v[242:245], v[72:75]
	v_mfma_f32_16x16x32_bf16 v[64:67], v[226:229], v[242:245], v[64:67]
	v_mfma_f32_16x16x32_bf16 v[68:71], v[226:229], v[234:237], v[68:71]
	v_readfirstlane_b32 s7, v146
	v_add_u32_e32 v186, 0x2000, v146
	v_lshl_add_u64 v[250:251], v[178:179], 0, s[46:47]
	s_mov_b32 m0, s7
	v_readfirstlane_b32 s7, v186
	s_barrier
	ds_read_b128 v[198:201], v151 offset:16384
	ds_read_b128 v[202:205], v151 offset:17408
	ds_read_b128 v[206:209], v150 offset:16384
	ds_read_b128 v[210:213], v150 offset:17408
	ds_read_b128 v[214:217], v149 offset:16384
	ds_read_b128 v[218:221], v149 offset:17408
	ds_read_b128 v[222:225], v148 offset:16384
	ds_read_b128 v[226:229], v148 offset:17408
	global_load_lds_dwordx4 v[250:251], off
	v_lshl_add_u64 v[250:251], v[188:189], 0, s[46:47]
	s_mov_b32 m0, s7
	s_nop 0
	global_load_lds_dwordx4 v[250:251], off
	s_barrier
	s_waitcnt lgkmcnt(0)
	s_waitcnt lgkmcnt(0)
	v_mfma_f32_16x16x32_bf16 v[60:63], v[198:201], v[162:165], v[60:63]
	v_mfma_f32_16x16x32_bf16 v[56:59], v[198:201], v[170:173], v[56:59]
	v_mfma_f32_16x16x32_bf16 v[48:51], v[206:209], v[170:173], v[48:51]
	v_mfma_f32_16x16x32_bf16 v[52:55], v[206:209], v[162:165], v[52:55]
	v_mfma_f32_16x16x32_bf16 v[44:47], v[214:217], v[162:165], v[44:47]
	v_mfma_f32_16x16x32_bf16 v[40:43], v[214:217], v[170:173], v[40:43]
	v_mfma_f32_16x16x32_bf16 v[32:35], v[222:225], v[170:173], v[32:35]
	v_mfma_f32_16x16x32_bf16 v[36:39], v[222:225], v[162:165], v[36:39]
	v_mfma_f32_16x16x32_bf16 v[60:63], v[202:205], v[166:169], v[60:63]
	v_mfma_f32_16x16x32_bf16 v[56:59], v[202:205], v[174:177], v[56:59]
	v_mfma_f32_16x16x32_bf16 v[48:51], v[210:213], v[174:177], v[48:51]
	v_mfma_f32_16x16x32_bf16 v[52:55], v[210:213], v[166:169], v[52:55]
	v_mfma_f32_16x16x32_bf16 v[44:47], v[218:221], v[166:169], v[44:47]
	v_mfma_f32_16x16x32_bf16 v[40:43], v[218:221], v[174:177], v[40:43]
	v_mfma_f32_16x16x32_bf16 v[32:35], v[226:229], v[174:177], v[32:35]
	v_mfma_f32_16x16x32_bf16 v[36:39], v[226:229], v[166:169], v[36:39]
	s_barrier
; #define WAIT_V(n) asm volatile("s_waitcnt vmcnt(" #n ")" ::: "memory")
; #define WAIT_L(n) asm volatile("s_waitcnt lgkmcnt(" #n ")" ::: "memory")
; #define BAR __builtin_amdgcn_s_barrier()
; #define SCHED __builtin_amdgcn_sched_barrier(0)
; #define LDA(dst, b, h)                                                                            \
;   _Pragma("unroll") for (int m = 0; m < 4; ++m) _Pragma("unroll") for (int k = 0; k < 2; ++k)                                         \
;     dst[m][k] = *reinterpret_cast<const bf16x8*>((char*)SA(b, h) + lds_byte(wr * 64 + m * 16 + fr, k * 32 + fq * 8))
; #define LDB(dst, b, h)                                                                            \
;   _Pragma("unroll") for (int n = 0; n < 2; ++n) _Pragma("unroll") for (int k = 0; k < 2; ++k)                                         \
;     dst[n][k] = *reinterpret_cast<const bf16x8*>((char*)SB(b, h) + lds_byte(wc * 32 + n * 16 + fr, k * 32 + fq * 8))
; template <int K, bool SWAP>
; __device__ __forceinline__ void gemm_kloop(const bf16* __restrict__ A, const bf16* __restrict__ Bt,
;                                            f32x4 (&acc)[2][2][4][2], bool pref = false) {
;     ...
;     STAGE(SB(0, 1), Bt, HALF, t + 2);
;     WAIT_V(6); BAR; MMA(1, 1, At, B1); BAR;
;     LDB(B0, 1, 0); SCHED; LDA(At, 1, 0); STAGE(SA(0, 1), A, HALF, t + 2);
;     WAIT_L(8); BAR; WAIT_L(0); MMA(0, 0, At, B0); BAR; SCHED;
;     LDB(B1, 1, 1); STAGE(SB(1, 0), Bt, 0, t + 3);
;     BAR; WAIT_L(0); MMA(0, 1, At, B1); BAR;
;     LDA(At, 1, 1); STAGE(SA(1, 0), A, 0, t + 3);
	v_readfirstlane_b32 s7, v147
	v_add_u32_e32 v164, 0x2000, v147
	v_lshl_add_u64 v[162:163], v[246:247], 0, s[48:49]
	s_mov_b32 m0, s7
	v_readfirstlane_b32 s7, v164
	global_load_lds_dwordx4 v[162:163], off
	v_lshl_add_u64 v[162:163], v[248:249], 0, s[48:49]
	s_mov_b32 m0, s7
	s_nop 0
	global_load_lds_dwordx4 v[162:163], off
	s_waitcnt vmcnt(6)
	s_barrier
	v_mfma_f32_16x16x32_bf16 v[28:31], v[198:201], v[230:233], v[28:31]
	v_mfma_f32_16x16x32_bf16 v[24:27], v[198:201], v[238:241], v[24:27]
	v_mfma_f32_16x16x32_bf16 v[16:19], v[206:209], v[238:241], v[16:19]
	v_mfma_f32_16x16x32_bf16 v[20:23], v[206:209], v[230:233], v[20:23]
	v_mfma_f32_16x16x32_bf16 v[12:15], v[214:217], v[230:233], v[12:15]
	v_mfma_f32_16x16x32_bf16 v[8:11], v[214:217], v[238:241], v[8:11]
	v_mfma_f32_16x16x32_bf16 v[0:3], v[222:225], v[238:241], v[0:3]
	v_mfma_f32_16x16x32_bf16 v[4:7], v[222:225], v[230:233], v[4:7]
	v_mfma_f32_16x16x32_bf16 v[28:31], v[202:205], v[234:237], v[28:31]
	v_mfma_f32_16x16x32_bf16 v[24:27], v[202:205], v[242:245], v[24:27]
	v_mfma_f32_16x16x32_bf16 v[16:19], v[210:213], v[242:245], v[16:19]
	v_mfma_f32_16x16x32_bf16 v[20:23], v[210:213], v[234:237], v[20:23]
	v_mfma_f32_16x16x32_bf16 v[12:15], v[218:221], v[234:237], v[12:15]
	v_mfma_f32_16x16x32_bf16 v[8:11], v[218:221], v[242:245], v[8:11]
	v_mfma_f32_16x16x32_bf16 v[0:3], v[226:229], v[242:245], v[0:3]
	v_mfma_f32_16x16x32_bf16 v[4:7], v[226:229], v[234:237], v[4:7]
	s_barrier
	ds_read_b128 v[162:165], v153
	ds_read_b128 v[166:169], v153 offset:1024
	ds_read_b128 v[170:173], v153 offset:2048
	ds_read_b128 v[174:177], v153 offset:3072
	v_add_u32_e32 v186, 0x4000, v146
	v_lshl_add_u64 v[230:231], v[178:179], 0, s[50:51]
	v_readfirstlane_b32 s7, v186
	v_add_u32_e32 v186, 0x6000, v146
	s_mov_b32 m0, s7
	v_readfirstlane_b32 s7, v186
	ds_read_b128 v[198:201], v151 offset:32768
	ds_read_b128 v[202:205], v151 offset:33792
	ds_read_b128 v[206:209], v150 offset:32768
	ds_read_b128 v[210:213], v150 offset:33792
	ds_read_b128 v[214:217], v149 offset:32768
	ds_read_b128 v[218:221], v149 offset:33792
	ds_read_b128 v[222:225], v148 offset:32768
	ds_read_b128 v[226:229], v148 offset:33792
	global_load_lds_dwordx4 v[230:231], off
	v_lshl_add_u64 v[230:231], v[188:189], 0, s[50:51]
	s_mov_b32 m0, s7
	s_nop 0
	global_load_lds_dwordx4 v[230:231], off
	s_waitcnt lgkmcnt(8)
	s_barrier
	s_waitcnt lgkmcnt(0)
	s_waitcnt lgkmcnt(0)
	v_mfma_f32_16x16x32_bf16 v[124:127], v[198:201], v[162:165], v[124:127]
	v_mfma_f32_16x16x32_bf16 v[120:123], v[198:201], v[170:173], v[120:123]
	v_mfma_f32_16x16x32_bf16 v[112:115], v[206:209], v[170:173], v[112:115]
	v_mfma_f32_16x16x32_bf16 v[116:119], v[206:209], v[162:165], v[116:119]
	v_mfma_f32_16x16x32_bf16 v[108:111], v[214:217], v[162:165], v[108:111]
	v_mfma_f32_16x16x32_bf16 v[104:107], v[214:217], v[170:173], v[104:107]
	v_mfma_f32_16x16x32_bf16 v[96:99], v[222:225], v[170:173], v[96:99]
	v_mfma_f32_16x16x32_bf16 v[100:103], v[222:225], v[162:165], v[100:103]
	v_mfma_f32_16x16x32_bf16 v[124:127], v[202:205], v[166:169], v[124:127]
	v_mfma_f32_16x16x32_bf16 v[120:123], v[202:205], v[174:177], v[120:123]
	v_mfma_f32_16x16x32_bf16 v[112:115], v[210:213], v[174:177], v[112:115]
	v_mfma_f32_16x16x32_bf16 v[116:119], v[210:213], v[166:169], v[116:119]
	v_mfma_f32_16x16x32_bf16 v[108:111], v[218:221], v[166:169], v[108:111]
	v_mfma_f32_16x16x32_bf16 v[104:107], v[218:221], v[174:177], v[104:107]
	v_mfma_f32_16x16x32_bf16 v[96:99], v[226:229], v[174:177], v[96:99]
	v_mfma_f32_16x16x32_bf16 v[100:103], v[226:229], v[166:169], v[100:103]
	s_barrier
	v_readfirstlane_b32 s7, v154
	v_add_u32_e32 v186, 0x2000, v154
	v_lshl_add_u64 v[250:251], v[246:247], 0, s[52:53]
	s_mov_b32 m0, s7
	v_readfirstlane_b32 s7, v186
	ds_read_b128 v[230:233], v152
	ds_read_b128 v[234:237], v152 offset:1024
	ds_read_b128 v[238:241], v152 offset:2048
	ds_read_b128 v[242:245], v152 offset:3072
	global_load_lds_dwordx4 v[250:251], off
	v_lshl_add_u64 v[250:251], v[248:249], 0, s[52:53]
	s_mov_b32 m0, s7
	s_nop 0
	global_load_lds_dwordx4 v[250:251], off
	s_barrier
	s_waitcnt lgkmcnt(0)
	s_waitcnt lgkmcnt(0)
	v_mfma_f32_16x16x32_bf16 v[92:95], v[198:201], v[230:233], v[92:95]
	v_mfma_f32_16x16x32_bf16 v[88:91], v[198:201], v[238:241], v[88:91]
	v_mfma_f32_16x16x32_bf16 v[80:83], v[206:209], v[238:241], v[80:83]
	v_mfma_f32_16x16x32_bf16 v[84:87], v[206:209], v[230:233], v[84:87]
	v_mfma_f32_16x16x32_bf16 v[76:79], v[214:217], v[230:233], v[76:79]
	v_mfma_f32_16x16x32_bf16 v[72:75], v[214:217], v[238:241], v[72:75]
	v_mfma_f32_16x16x32_bf16 v[64:67], v[222:225], v[238:241], v[64:67]
	v_mfma_f32_16x16x32_bf16 v[68:71], v[222:225], v[230:233], v[68:71]
	v_mfma_f32_16x16x32_bf16 v[92:95], v[202:205], v[234:237], v[92:95]
	v_mfma_f32_16x16x32_bf16 v[88:91], v[202:205], v[242:245], v[88:91]
	v_mfma_f32_16x16x32_bf16 v[80:83], v[210:213], v[242:245], v[80:83]
	v_mfma_f32_16x16x32_bf16 v[84:87], v[210:213], v[234:237], v[84:87]
	v_mfma_f32_16x16x32_bf16 v[76:79], v[218:221], v[234:237], v[76:79]
	v_mfma_f32_16x16x32_bf16 v[72:75], v[218:221], v[242:245], v[72:75]
	v_mfma_f32_16x16x32_bf16 v[64:67], v[226:229], v[242:245], v[64:67]
	v_mfma_f32_16x16x32_bf16 v[68:71], v[226:229], v[234:237], v[68:71]
	v_readfirstlane_b32 s7, v155
	v_lshl_add_u64 v[178:179], v[178:179], 0, s[54:55]
	s_mov_b32 m0, s7
	v_readfirstlane_b32 s7, v156
	s_barrier
	ds_read_b128 v[198:201], v151 offset:49152
	ds_read_b128 v[202:205], v151 offset:50176
	ds_read_b128 v[206:209], v150 offset:49152
	ds_read_b128 v[210:213], v150 offset:50176
	ds_read_b128 v[214:217], v149 offset:49152
	ds_read_b128 v[218:221], v149 offset:50176
	ds_read_b128 v[222:225], v148 offset:49152
	ds_read_b128 v[226:229], v148 offset:50176
	global_load_lds_dwordx4 v[178:179], off
	v_lshl_add_u64 v[178:179], v[188:189], 0, s[54:55]
	s_mov_b32 m0, s7
	s_nop 0
	global_load_lds_dwordx4 v[178:179], off
	s_barrier
; #define WAIT_V(n) asm volatile("s_waitcnt vmcnt(" #n ")" ::: "memory")
; #define WAIT_L(n) asm volatile("s_waitcnt lgkmcnt(" #n ")" ::: "memory")
; #define BAR __builtin_amdgcn_s_barrier()
; #define SCHED __builtin_amdgcn_sched_barrier(0)
; #define LDA(dst, b, h)                                                                            \
;   _Pragma("unroll") for (int m = 0; m < 4; ++m) _Pragma("unroll") for (int k = 0; k < 2; ++k)                                         \
;     dst[m][k] = *reinterpret_cast<const bf16x8*>((char*)SA(b, h) + lds_byte(wr * 64 + m * 16 + fr, k * 32 + fq * 8))
; #define LDB(dst, b, h)                                                                            \
;   _Pragma("unroll") for (int n = 0; n < 2; ++n) _Pragma("unroll") for (int k = 0; k < 2; ++k)                                         \
;     dst[n][k] = *reinterpret_cast<const bf16x8*>((char*)SB(b, h) + lds_byte(wc * 32 + n * 16 + fr, k * 32 + fq * 8))
; template <int K, bool SWAP>
; __device__ __forceinline__ void gemm_kloop(const bf16* __restrict__ A, const bf16* __restrict__ Bt,
;                                            f32x4 (&acc)[2][2][4][2], bool pref = false) {
;     ...
;     LDA(At, 1, 1); STAGE(SA(1, 0), A, 0, t + 3);
;     BAR; WAIT_L(0); MMA(1, 0, At, B0); BAR; SCHED;
;     STAGE(SB(1, 1), Bt, HALF, t + 3);
;     WAIT_V(6); BAR; MMA(1, 1, At, B1); BAR;
;   }
;   { LDB(B0, 0, 0); LDA(At, 0, 0); STAGE(SA(1, 1), A, HALF, nt - 1);
;     BAR; WAIT_L(0); MMA(0, 0, At, B0); BAR;
;     LDB(B1, 0, 1); BAR; WAIT_L(0); MMA(0, 1, At, B1); BAR;
;     LDA(At, 0, 1); WAIT_V(4); BAR; WAIT_L(0); MMA(1, 0, At, B0); MMA(1, 1, At, B1); BAR; }
	s_waitcnt lgkmcnt(0)
	s_waitcnt lgkmcnt(0)
	v_mfma_f32_16x16x32_bf16 v[60:63], v[198:201], v[162:165], v[60:63]
	v_mfma_f32_16x16x32_bf16 v[56:59], v[198:201], v[170:173], v[56:59]
	v_mfma_f32_16x16x32_bf16 v[48:51], v[206:209], v[170:173], v[48:51]
	v_mfma_f32_16x16x32_bf16 v[52:55], v[206:209], v[162:165], v[52:55]
	v_mfma_f32_16x16x32_bf16 v[44:47], v[214:217], v[162:165], v[44:47]
	v_mfma_f32_16x16x32_bf16 v[40:43], v[214:217], v[170:173], v[40:43]
	v_mfma_f32_16x16x32_bf16 v[32:35], v[222:225], v[170:173], v[32:35]
	v_mfma_f32_16x16x32_bf16 v[36:39], v[222:225], v[162:165], v[36:39]
	v_mfma_f32_16x16x32_bf16 v[60:63], v[202:205], v[166:169], v[60:63]
	v_mfma_f32_16x16x32_bf16 v[56:59], v[202:205], v[174:177], v[56:59]
	v_mfma_f32_16x16x32_bf16 v[48:51], v[210:213], v[174:177], v[48:51]
	v_mfma_f32_16x16x32_bf16 v[52:55], v[210:213], v[166:169], v[52:55]
	v_mfma_f32_16x16x32_bf16 v[44:47], v[218:221], v[166:169], v[44:47]
	v_mfma_f32_16x16x32_bf16 v[40:43], v[218:221], v[174:177], v[40:43]
	v_mfma_f32_16x16x32_bf16 v[32:35], v[226:229], v[174:177], v[32:35]
	v_mfma_f32_16x16x32_bf16 v[36:39], v[226:229], v[166:169], v[36:39]
	s_barrier
	v_readfirstlane_b32 s7, v157
	v_add_u32_e32 v164, 0x2000, v157
	v_lshl_add_u64 v[162:163], v[246:247], 0, s[56:57]
	s_mov_b32 m0, s7
	v_readfirstlane_b32 s7, v164
	global_load_lds_dwordx4 v[162:163], off
	v_lshl_add_u64 v[162:163], v[248:249], 0, s[56:57]
	s_mov_b32 m0, s7
	s_nop 0
	global_load_lds_dwordx4 v[162:163], off
	s_waitcnt vmcnt(6)
	s_barrier
	v_mfma_f32_16x16x32_bf16 v[28:31], v[198:201], v[230:233], v[28:31]
	v_mfma_f32_16x16x32_bf16 v[24:27], v[198:201], v[238:241], v[24:27]
	v_mfma_f32_16x16x32_bf16 v[16:19], v[206:209], v[238:241], v[16:19]
	v_mfma_f32_16x16x32_bf16 v[20:23], v[206:209], v[230:233], v[20:23]
	v_mfma_f32_16x16x32_bf16 v[12:15], v[214:217], v[230:233], v[12:15]
	v_mfma_f32_16x16x32_bf16 v[8:11], v[214:217], v[238:241], v[8:11]
	v_mfma_f32_16x16x32_bf16 v[0:3], v[222:225], v[238:241], v[0:3]
	v_mfma_f32_16x16x32_bf16 v[4:7], v[222:225], v[230:233], v[4:7]
	v_mfma_f32_16x16x32_bf16 v[28:31], v[202:205], v[234:237], v[28:31]
	v_mfma_f32_16x16x32_bf16 v[24:27], v[202:205], v[242:245], v[24:27]
	v_mfma_f32_16x16x32_bf16 v[16:19], v[210:213], v[242:245], v[16:19]
	v_mfma_f32_16x16x32_bf16 v[20:23], v[210:213], v[234:237], v[20:23]
	v_mfma_f32_16x16x32_bf16 v[12:15], v[218:221], v[234:237], v[12:15]
	v_mfma_f32_16x16x32_bf16 v[8:11], v[218:221], v[242:245], v[8:11]
	v_mfma_f32_16x16x32_bf16 v[0:3], v[226:229], v[242:245], v[0:3]
	v_mfma_f32_16x16x32_bf16 v[4:7], v[226:229], v[234:237], v[4:7]
	s_add_i32 s6, s6, 2
	v_lshl_add_u64 v[136:137], v[136:137], 0, s[44:45]
	v_lshl_add_u64 v[138:139], v[138:139], 0, s[44:45]
	v_lshl_add_u64 v[140:141], v[140:141], 0, s[44:45]
	s_cmp_lt_u32 s6, 12
	v_lshl_add_u64 v[142:143], v[142:143], 0, s[44:45]
	s_barrier
	s_cbranch_scc1 .LBB0_449
	s_add_u32 s4, s4, 0x40780
	s_addc_u32 s5, s5, 0
	v_lshl_add_u64 v[130:131], s[4:5], 0, v[130:131]
	v_readfirstlane_b32 s6, v160
	v_lshl_add_u64 v[128:129], v[128:129], 1, v[130:131]
	s_mov_b32 m0, s6
	ds_read_b128 v[136:139], v159
	ds_read_b128 v[140:143], v159 offset:1024
	ds_read_b128 v[154:157], v159 offset:2048
	ds_read_b128 v[162:165], v159 offset:3072
	ds_read_b128 v[166:169], v151
	ds_read_b128 v[170:173], v151 offset:1024
	ds_read_b128 v[174:177], v150
	ds_read_b128 v[198:201], v150 offset:1024
	ds_read_b128 v[202:205], v149
	ds_read_b128 v[206:209], v149 offset:1024
	ds_read_b128 v[210:213], v148
	ds_read_b128 v[214:217], v148 offset:1024
	global_load_lds_dwordx4 v[128:129], off
	v_lshl_add_u64 v[128:129], s[4:5], 0, v[134:135]
	v_readfirstlane_b32 s4, v161
	v_lshl_add_u64 v[128:129], v[132:133], 1, v[128:129]
	s_mov_b32 m0, s4
	s_nop 0
	global_load_lds_dwordx4 v[128:129], off
	s_barrier
	s_waitcnt lgkmcnt(0)
	s_waitcnt lgkmcnt(0)
	v_mfma_f32_16x16x32_bf16 v[124:127], v[166:169], v[136:139], v[124:127]
	v_mfma_f32_16x16x32_bf16 v[116:119], v[174:177], v[136:139], v[116:119]
	v_mfma_f32_16x16x32_bf16 v[108:111], v[202:205], v[136:139], v[108:111]
	v_mfma_f32_16x16x32_bf16 v[100:103], v[210:213], v[136:139], v[100:103]
	v_mfma_f32_16x16x32_bf16 v[124:127], v[170:173], v[140:143], v[124:127]
	v_mfma_f32_16x16x32_bf16 v[120:123], v[166:169], v[154:157], v[120:123]
	v_mfma_f32_16x16x32_bf16 v[116:119], v[198:201], v[140:143], v[116:119]
	v_mfma_f32_16x16x32_bf16 v[112:115], v[174:177], v[154:157], v[112:115]
	v_mfma_f32_16x16x32_bf16 v[108:111], v[206:209], v[140:143], v[108:111]
	v_mfma_f32_16x16x32_bf16 v[104:107], v[202:205], v[154:157], v[104:107]
	v_mfma_f32_16x16x32_bf16 v[100:103], v[214:217], v[140:143], v[100:103]
	v_mfma_f32_16x16x32_bf16 v[96:99], v[210:213], v[154:157], v[96:99]
	v_mfma_f32_16x16x32_bf16 v[128:131], v[170:173], v[162:165], v[120:123]
	v_mfma_f32_16x16x32_bf16 v[132:135], v[198:201], v[162:165], v[112:115]
	v_mfma_f32_16x16x32_bf16 v[218:221], v[206:209], v[162:165], v[104:107]
	v_mfma_f32_16x16x32_bf16 v[222:225], v[214:217], v[162:165], v[96:99]
	s_barrier
	s_nop 1
	ds_read_b128 v[96:99], v158
	ds_read_b128 v[104:107], v158 offset:1024
	ds_read_b128 v[112:115], v158 offset:2048
	ds_read_b128 v[120:123], v158 offset:3072
	s_barrier
; #define WAIT_V(n) asm volatile("s_waitcnt vmcnt(" #n ")" ::: "memory")
; #define WAIT_L(n) asm volatile("s_waitcnt lgkmcnt(" #n ")" ::: "memory")
; #define BAR __builtin_amdgcn_s_barrier()
; #define LDA(dst, b, h)                                                                            \
;   _Pragma("unroll") for (int m = 0; m < 4; ++m) _Pragma("unroll") for (int k = 0; k < 2; ++k)                                         \
;     dst[m][k] = *reinterpret_cast<const bf16x8*>((char*)SA(b, h) + lds_byte(wr * 64 + m * 16 + fr, k * 32 + fq * 8))
; #define LDB(dst, b, h)                                                                            \
;   _Pragma("unroll") for (int n = 0; n < 2; ++n) _Pragma("unroll") for (int k = 0; k < 2; ++k)                                         \
;     dst[n][k] = *reinterpret_cast<const bf16x8*>((char*)SB(b, h) + lds_byte(wc * 32 + n * 16 + fr, k * 32 + fq * 8))
; template <int K, bool SWAP>
; __device__ __forceinline__ void gemm_kloop(const bf16* __restrict__ A, const bf16* __restrict__ Bt,
;                                            f32x4 (&acc)[2][2][4][2], bool pref = false) {
;     ...
;     LDB(B1, 0, 1); BAR; WAIT_L(0); MMA(0, 1, At, B1); BAR;
;     LDA(At, 0, 1); WAIT_V(4); BAR; WAIT_L(0); MMA(1, 0, At, B0); MMA(1, 1, At, B1); BAR; }
;   { LDB(B0, 1, 0); LDA(At, 1, 0); WAIT_V(2); BAR; WAIT_L(0); MMA(0, 0, At, B0); BAR;
	s_waitcnt lgkmcnt(0)
	s_waitcnt lgkmcnt(0)
	v_mfma_f32_16x16x32_bf16 v[92:95], v[166:169], v[96:99], v[92:95]
	v_mfma_f32_16x16x32_bf16 v[84:87], v[174:177], v[96:99], v[84:87]
	v_mfma_f32_16x16x32_bf16 v[76:79], v[202:205], v[96:99], v[76:79]
	v_mfma_f32_16x16x32_bf16 v[68:71], v[210:213], v[96:99], v[68:71]
	v_mfma_f32_16x16x32_bf16 v[92:95], v[170:173], v[104:107], v[92:95]
	v_mfma_f32_16x16x32_bf16 v[88:91], v[166:169], v[112:115], v[88:91]
	v_mfma_f32_16x16x32_bf16 v[84:87], v[198:201], v[104:107], v[84:87]
	v_mfma_f32_16x16x32_bf16 v[80:83], v[174:177], v[112:115], v[80:83]
	v_mfma_f32_16x16x32_bf16 v[76:79], v[206:209], v[104:107], v[76:79]
	v_mfma_f32_16x16x32_bf16 v[72:75], v[202:205], v[112:115], v[72:75]
	v_mfma_f32_16x16x32_bf16 v[68:71], v[214:217], v[104:107], v[68:71]
	v_mfma_f32_16x16x32_bf16 v[64:67], v[210:213], v[112:115], v[64:67]
	v_mfma_f32_16x16x32_bf16 v[158:161], v[170:173], v[120:123], v[88:91]
	v_mfma_f32_16x16x32_bf16 v[166:169], v[198:201], v[120:123], v[80:83]
	v_mfma_f32_16x16x32_bf16 v[170:173], v[206:209], v[120:123], v[72:75]
	v_mfma_f32_16x16x32_bf16 v[174:177], v[214:217], v[120:123], v[64:67]
	s_barrier
	s_nop 1
	ds_read_b128 v[64:67], v151 offset:16384
	ds_read_b128 v[72:75], v151 offset:17408
	ds_read_b128 v[80:83], v150 offset:16384
	ds_read_b128 v[88:91], v150 offset:17408
	ds_read_b128 v[198:201], v149 offset:16384
	ds_read_b128 v[202:205], v149 offset:17408
	ds_read_b128 v[206:209], v148 offset:16384
	ds_read_b128 v[210:213], v148 offset:17408
	s_waitcnt vmcnt(4)
	s_barrier
	s_waitcnt lgkmcnt(0)
	s_waitcnt lgkmcnt(0)
	v_mfma_f32_16x16x32_bf16 v[60:63], v[64:67], v[136:139], v[60:63]
	v_mfma_f32_16x16x32_bf16 v[52:55], v[80:83], v[136:139], v[52:55]
	v_mfma_f32_16x16x32_bf16 v[44:47], v[198:201], v[136:139], v[44:47]
	v_mfma_f32_16x16x32_bf16 v[36:39], v[206:209], v[136:139], v[36:39]
	v_mfma_f32_16x16x32_bf16 v[60:63], v[72:75], v[140:143], v[60:63]
	v_mfma_f32_16x16x32_bf16 v[56:59], v[64:67], v[154:157], v[56:59]
	v_mfma_f32_16x16x32_bf16 v[52:55], v[88:91], v[140:143], v[52:55]
	v_mfma_f32_16x16x32_bf16 v[48:51], v[80:83], v[154:157], v[48:51]
	v_mfma_f32_16x16x32_bf16 v[44:47], v[202:205], v[140:143], v[44:47]
	v_mfma_f32_16x16x32_bf16 v[40:43], v[198:201], v[154:157], v[40:43]
	v_mfma_f32_16x16x32_bf16 v[36:39], v[210:213], v[140:143], v[36:39]
	v_mfma_f32_16x16x32_bf16 v[32:35], v[206:209], v[154:157], v[32:35]
	v_mfma_f32_16x16x32_bf16 v[214:217], v[72:75], v[162:165], v[56:59]
	v_mfma_f32_16x16x32_bf16 v[226:229], v[88:91], v[162:165], v[48:51]
	v_mfma_f32_16x16x32_bf16 v[230:233], v[202:205], v[162:165], v[40:43]
	v_mfma_f32_16x16x32_bf16 v[136:139], v[210:213], v[162:165], v[32:35]
	v_mfma_f32_16x16x32_bf16 v[28:31], v[64:67], v[96:99], v[28:31]
	v_mfma_f32_16x16x32_bf16 v[20:23], v[80:83], v[96:99], v[20:23]
	v_mfma_f32_16x16x32_bf16 v[12:15], v[198:201], v[96:99], v[12:15]
	v_mfma_f32_16x16x32_bf16 v[4:7], v[206:209], v[96:99], v[4:7]
	v_mfma_f32_16x16x32_bf16 v[28:31], v[72:75], v[104:107], v[28:31]
	v_mfma_f32_16x16x32_bf16 v[24:27], v[64:67], v[112:115], v[24:27]
	v_mfma_f32_16x16x32_bf16 v[20:23], v[88:91], v[104:107], v[20:23]
	v_mfma_f32_16x16x32_bf16 v[16:19], v[80:83], v[112:115], v[16:19]
	v_mfma_f32_16x16x32_bf16 v[12:15], v[202:205], v[104:107], v[12:15]
	v_mfma_f32_16x16x32_bf16 v[8:11], v[198:201], v[112:115], v[8:11]
	v_mfma_f32_16x16x32_bf16 v[4:7], v[210:213], v[104:107], v[4:7]
	v_mfma_f32_16x16x32_bf16 v[0:3], v[206:209], v[112:115], v[0:3]
	v_mfma_f32_16x16x32_bf16 v[140:143], v[72:75], v[120:123], v[24:27]
	v_mfma_f32_16x16x32_bf16 v[154:157], v[88:91], v[120:123], v[16:19]
	v_mfma_f32_16x16x32_bf16 v[162:165], v[202:205], v[120:123], v[8:11]
	v_mfma_f32_16x16x32_bf16 v[198:201], v[210:213], v[120:123], v[0:3]
	s_barrier
	ds_read_b128 v[202:205], v153
	ds_read_b128 v[206:209], v153 offset:1024
	ds_read_b128 v[210:213], v153 offset:2048
	ds_read_b128 v[234:237], v153 offset:3072
	ds_read_b128 v[0:3], v151 offset:32768
	ds_read_b128 v[8:11], v151 offset:33792
	ds_read_b128 v[16:19], v150 offset:32768
	ds_read_b128 v[24:27], v150 offset:33792
	ds_read_b128 v[238:241], v149 offset:32768
	ds_read_b128 v[242:245], v149 offset:33792
	ds_read_b128 v[246:249], v148 offset:32768
	ds_read_b128 v[250:253], v148 offset:33792
	s_waitcnt vmcnt(2)
	s_barrier
; #define WAIT_V(n) asm volatile("s_waitcnt vmcnt(" #n ")" ::: "memory")
; #define WAIT_L(n) asm volatile("s_waitcnt lgkmcnt(" #n ")" ::: "memory")
; #define BAR __builtin_amdgcn_s_barrier()
; #define LDA(dst, b, h)                                                                            \
;   _Pragma("unroll") for (int m = 0; m < 4; ++m) _Pragma("unroll") for (int k = 0; k < 2; ++k)                                         \
;     dst[m][k] = *reinterpret_cast<const bf16x8*>((char*)SA(b, h) + lds_byte(wr * 64 + m * 16 + fr, k * 32 + fq * 8))
; #define LDB(dst, b, h)                                                                            \
;   _Pragma("unroll") for (int n = 0; n < 2; ++n) _Pragma("unroll") for (int k = 0; k < 2; ++k)                                         \
;     dst[n][k] = *reinterpret_cast<const bf16x8*>((char*)SB(b, h) + lds_byte(wc * 32 + n * 16 + fr, k * 32 + fq * 8))
; template <int K, bool SWAP>
; __device__ __forceinline__ void gemm_kloop(const bf16* __restrict__ A, const bf16* __restrict__ Bt,
;                                            f32x4 (&acc)[2][2][4][2], bool pref = false) {
;     ...
;   { LDB(B0, 1, 0); LDA(At, 1, 0); WAIT_V(2); BAR; WAIT_L(0); MMA(0, 0, At, B0); BAR;
;     LDB(B1, 1, 1); WAIT_V(0); BAR; WAIT_L(0); MMA(0, 1, At, B1); BAR;
;     LDA(At, 1, 1); BAR; WAIT_L(0); MMA(1, 0, At, B0); MMA(1, 1, At, B1); BAR; }
;   if (wr == 0) BAR;
	s_waitcnt lgkmcnt(0)
	s_waitcnt lgkmcnt(0)
	v_mfma_f32_16x16x32_bf16 v[32:35], v[0:3], v[202:205], v[124:127]
	v_mfma_f32_16x16x32_bf16 v[120:123], v[8:11], v[206:209], v[32:35]
	v_mfma_f32_16x16x32_bf16 v[32:35], v[0:3], v[210:213], v[128:131]
	v_mfma_f32_16x16x32_bf16 v[112:115], v[8:11], v[234:237], v[32:35]
	v_mfma_f32_16x16x32_bf16 v[32:35], v[16:19], v[202:205], v[116:119]
	v_mfma_f32_16x16x32_bf16 v[104:107], v[24:27], v[206:209], v[32:35]
	v_mfma_f32_16x16x32_bf16 v[32:35], v[16:19], v[210:213], v[132:135]
	v_mfma_f32_16x16x32_bf16 v[96:99], v[24:27], v[234:237], v[32:35]
	v_mfma_f32_16x16x32_bf16 v[32:35], v[238:241], v[202:205], v[108:111]
	v_mfma_f32_16x16x32_bf16 v[88:91], v[242:245], v[206:209], v[32:35]
	v_mfma_f32_16x16x32_bf16 v[32:35], v[238:241], v[210:213], v[218:221]
	v_mfma_f32_16x16x32_bf16 v[80:83], v[242:245], v[234:237], v[32:35]
	v_mfma_f32_16x16x32_bf16 v[32:35], v[246:249], v[202:205], v[100:103]
	v_mfma_f32_16x16x32_bf16 v[72:75], v[250:253], v[206:209], v[32:35]
	v_mfma_f32_16x16x32_bf16 v[32:35], v[246:249], v[210:213], v[222:225]
	v_mfma_f32_16x16x32_bf16 v[64:67], v[250:253], v[234:237], v[32:35]
	s_barrier
	ds_read_b128 v[128:131], v152
	ds_read_b128 v[132:135], v152 offset:1024
	ds_read_b128 v[218:221], v152 offset:2048
	ds_read_b128 v[222:225], v152 offset:3072
	s_waitcnt vmcnt(0)
	s_barrier
	s_waitcnt lgkmcnt(0)
	s_waitcnt lgkmcnt(0)
	v_mfma_f32_16x16x32_bf16 v[32:35], v[0:3], v[128:131], v[92:95]
	v_mfma_f32_16x16x32_bf16 v[0:3], v[0:3], v[218:221], v[158:161]
	v_mfma_f32_16x16x32_bf16 v[48:51], v[8:11], v[222:225], v[0:3]
	v_mfma_f32_16x16x32_bf16 v[0:3], v[16:19], v[128:131], v[84:87]
	v_mfma_f32_16x16x32_bf16 v[40:43], v[24:27], v[132:135], v[0:3]
	v_mfma_f32_16x16x32_bf16 v[0:3], v[16:19], v[218:221], v[166:169]
	v_mfma_f32_16x16x32_bf16 v[56:59], v[8:11], v[132:135], v[32:35]
	v_mfma_f32_16x16x32_bf16 v[32:35], v[24:27], v[222:225], v[0:3]
	v_mfma_f32_16x16x32_bf16 v[0:3], v[238:241], v[128:131], v[76:79]
	v_mfma_f32_16x16x32_bf16 v[24:27], v[242:245], v[132:135], v[0:3]
	v_mfma_f32_16x16x32_bf16 v[0:3], v[238:241], v[218:221], v[170:173]
	v_mfma_f32_16x16x32_bf16 v[16:19], v[242:245], v[222:225], v[0:3]
	v_mfma_f32_16x16x32_bf16 v[0:3], v[246:249], v[128:131], v[68:71]
	v_mfma_f32_16x16x32_bf16 v[8:11], v[250:253], v[132:135], v[0:3]
	v_mfma_f32_16x16x32_bf16 v[0:3], v[246:249], v[218:221], v[174:177]
	v_mfma_f32_16x16x32_bf16 v[0:3], v[250:253], v[222:225], v[0:3]
	s_barrier
	ds_read_b128 v[158:161], v151 offset:49152
	ds_read_b128 v[166:169], v151 offset:50176
	ds_read_b128 v[170:173], v150 offset:49152
	ds_read_b128 v[150:153], v150 offset:50176
	ds_read_b128 v[174:177], v149 offset:49152
	ds_read_b128 v[238:241], v149 offset:50176
	ds_read_b128 v[242:245], v148 offset:49152
	ds_read_b128 v[146:149], v148 offset:50176
	s_barrier
	s_waitcnt lgkmcnt(0)
	s_waitcnt lgkmcnt(0)
	v_mfma_f32_16x16x32_bf16 v[60:63], v[158:161], v[202:205], v[60:63]
	v_mfma_f32_16x16x32_bf16 v[52:55], v[170:173], v[202:205], v[52:55]
	v_mfma_f32_16x16x32_bf16 v[44:47], v[174:177], v[202:205], v[44:47]
	v_mfma_f32_16x16x32_bf16 v[36:39], v[242:245], v[202:205], v[36:39]
	v_mfma_f32_16x16x32_bf16 v[124:127], v[166:169], v[206:209], v[60:63]
	v_mfma_f32_16x16x32_bf16 v[60:63], v[158:161], v[210:213], v[214:217]
	v_mfma_f32_16x16x32_bf16 v[108:111], v[150:153], v[206:209], v[52:55]
	v_mfma_f32_16x16x32_bf16 v[52:55], v[170:173], v[210:213], v[226:229]
	v_mfma_f32_16x16x32_bf16 v[92:95], v[238:241], v[206:209], v[44:47]
	v_mfma_f32_16x16x32_bf16 v[44:47], v[174:177], v[210:213], v[230:233]
	v_mfma_f32_16x16x32_bf16 v[76:79], v[146:149], v[206:209], v[36:39]
	v_mfma_f32_16x16x32_bf16 v[36:39], v[242:245], v[210:213], v[136:139]
	v_mfma_f32_16x16x32_bf16 v[116:119], v[166:169], v[234:237], v[60:63]
	v_mfma_f32_16x16x32_bf16 v[100:103], v[150:153], v[234:237], v[52:55]
	v_mfma_f32_16x16x32_bf16 v[84:87], v[238:241], v[234:237], v[44:47]
	v_mfma_f32_16x16x32_bf16 v[68:71], v[146:149], v[234:237], v[36:39]
	v_mfma_f32_16x16x32_bf16 v[28:31], v[158:161], v[128:131], v[28:31]
	v_mfma_f32_16x16x32_bf16 v[60:63], v[166:169], v[132:135], v[28:31]
	v_mfma_f32_16x16x32_bf16 v[28:31], v[158:161], v[218:221], v[140:143]
	v_mfma_f32_16x16x32_bf16 v[20:23], v[170:173], v[128:131], v[20:23]
	v_mfma_f32_16x16x32_bf16 v[12:15], v[174:177], v[128:131], v[12:15]
	v_mfma_f32_16x16x32_bf16 v[52:55], v[166:169], v[222:225], v[28:31]
	v_mfma_f32_16x16x32_bf16 v[44:47], v[150:153], v[132:135], v[20:23]
	v_mfma_f32_16x16x32_bf16 v[20:23], v[170:173], v[218:221], v[154:157]
	v_mfma_f32_16x16x32_bf16 v[28:31], v[238:241], v[132:135], v[12:15]
	v_mfma_f32_16x16x32_bf16 v[12:15], v[174:177], v[218:221], v[162:165]
	v_mfma_f32_16x16x32_bf16 v[4:7], v[242:245], v[128:131], v[4:7]
	v_mfma_f32_16x16x32_bf16 v[36:39], v[150:153], v[222:225], v[20:23]
	v_mfma_f32_16x16x32_bf16 v[20:23], v[238:241], v[222:225], v[12:15]
	v_mfma_f32_16x16x32_bf16 v[12:15], v[146:149], v[132:135], v[4:7]
	v_mfma_f32_16x16x32_bf16 v[4:7], v[242:245], v[218:221], v[198:201]
	v_mfma_f32_16x16x32_bf16 v[4:7], v[146:149], v[222:225], v[4:7]
	s_movk_i32 s4, 0x100
	v_cmp_gt_u32_e32 vcc, s4, v144
	s_barrier
	s_and_saveexec_b64 s[4:5], vcc
	s_cbranch_execz .LBB0_452
	s_barrier

; #define WAIT_V(n) asm volatile("s_waitcnt vmcnt(" #n ")" ::: "memory")
; #define WAIT_L(n) asm volatile("s_waitcnt lgkmcnt(" #n ")" ::: "memory")
; #define BAR __builtin_amdgcn_s_barrier()
; #define SCHED __builtin_amdgcn_sched_barrier(0)
; #define LDA(dst, b, h)                                                                            \
;   _Pragma("unroll") for (int m = 0; m < 4; ++m) _Pragma("unroll") for (int k = 0; k < 2; ++k)                                         \
;     dst[m][k] = *reinterpret_cast<const bf16x8*>((char*)SA(b, h) + lds_byte(wr * 64 + m * 16 + fr, k * 32 + fq * 8))
; #define LDB(dst, b, h)                                                                            \
;   _Pragma("unroll") for (int n = 0; n < 2; ++n) _Pragma("unroll") for (int k = 0; k < 2; ++k)                                         \
;     dst[n][k] = *reinterpret_cast<const bf16x8*>((char*)SB(b, h) + lds_byte(wc * 32 + n * 16 + fr, k * 32 + fq * 8))
; template <int K, bool SWAP>
; __device__ __forceinline__ void gemm_kloop(const bf16* __restrict__ A, const bf16* __restrict__ Bt,
;                                            f32x4 (&acc)[2][2][4][2], bool pref = false) {
;     ...
;     LDB(B0, 0, 0); SCHED; LDA(At, 0, 0); STAGE(SA(1, 1), A, HALF, t + 1);
;     WAIT_L(8); BAR; WAIT_L(0); MMA(0, 0, At, B0); BAR; SCHED;
;     LDB(B1, 0, 1); STAGE(SB(0, 0), Bt, 0, t + 2);
;     BAR; WAIT_L(0); MMA(0, 1, At, B1); BAR;
;     LDA(At, 0, 1); STAGE(SA(0, 0), A, 0, t + 2);
;     BAR; WAIT_L(0); MMA(1, 0, At, B0); BAR; SCHED;
;     STAGE(SB(0, 1), Bt, HALF, t + 2);
;     WAIT_V(6); BAR; MMA(1, 1, At, B1); BAR;
.LBB0_514:
	ds_read_b128 v[162:165], v159
	ds_read_b128 v[166:169], v159 offset:1024
	ds_read_b128 v[170:173], v159 offset:2048
	ds_read_b128 v[174:177], v159 offset:3072
	v_add_u32_e32 v160, 0xc000, v146
	v_lshl_add_u64 v[178:179], s[58:59], 0, v[140:141]
	v_readfirstlane_b32 s9, v160
	v_lshl_add_u64 v[188:189], v[178:179], 0, s[42:43]
	s_mov_b32 m0, s9
	v_add_u32_e32 v161, 0xe000, v146
	ds_read_b128 v[198:201], v151
	ds_read_b128 v[202:205], v151 offset:1024
	ds_read_b128 v[206:209], v150
	ds_read_b128 v[210:213], v150 offset:1024
	ds_read_b128 v[214:217], v149
	ds_read_b128 v[218:221], v149 offset:1024
	ds_read_b128 v[222:225], v148
	ds_read_b128 v[226:229], v148 offset:1024
	global_load_lds_dwordx4 v[188:189], off
	v_lshl_add_u64 v[188:189], s[58:59], 0, v[142:143]
	v_readfirstlane_b32 s9, v161
	v_lshl_add_u64 v[230:231], v[188:189], 0, s[42:43]
	s_mov_b32 m0, s9
	s_nop 0
	global_load_lds_dwordx4 v[230:231], off
	s_waitcnt lgkmcnt(8)
	s_barrier
	s_waitcnt lgkmcnt(0)
	s_waitcnt lgkmcnt(0)
	v_mfma_f32_16x16x32_bf16 v[124:127], v[162:165], v[198:201], v[124:127]
	v_mfma_f32_16x16x32_bf16 v[120:123], v[170:173], v[198:201], v[120:123]
	v_mfma_f32_16x16x32_bf16 v[112:115], v[170:173], v[206:209], v[112:115]
	v_mfma_f32_16x16x32_bf16 v[116:119], v[162:165], v[206:209], v[116:119]
	v_mfma_f32_16x16x32_bf16 v[108:111], v[162:165], v[214:217], v[108:111]
	v_mfma_f32_16x16x32_bf16 v[104:107], v[170:173], v[214:217], v[104:107]
	v_mfma_f32_16x16x32_bf16 v[96:99], v[170:173], v[222:225], v[96:99]
	v_mfma_f32_16x16x32_bf16 v[100:103], v[162:165], v[222:225], v[100:103]
	v_mfma_f32_16x16x32_bf16 v[124:127], v[166:169], v[202:205], v[124:127]
	v_mfma_f32_16x16x32_bf16 v[120:123], v[174:177], v[202:205], v[120:123]
	v_mfma_f32_16x16x32_bf16 v[112:115], v[174:177], v[210:213], v[112:115]
	v_mfma_f32_16x16x32_bf16 v[116:119], v[166:169], v[210:213], v[116:119]
	v_mfma_f32_16x16x32_bf16 v[108:111], v[166:169], v[218:221], v[108:111]
	v_mfma_f32_16x16x32_bf16 v[104:107], v[174:177], v[218:221], v[104:107]
	v_mfma_f32_16x16x32_bf16 v[96:99], v[174:177], v[226:229], v[96:99]
	v_mfma_f32_16x16x32_bf16 v[100:103], v[166:169], v[226:229], v[100:103]
	s_barrier
	v_add_u32_e32 v186, s7, v145
	v_lshl_add_u64 v[246:247], s[58:59], 0, v[136:137]
	v_readfirstlane_b32 s9, v186
	v_lshl_add_u64 v[248:249], v[246:247], 0, s[44:45]
	s_mov_b32 m0, s9
	v_add_u32_e32 v186, 0x2000, v186
	ds_read_b128 v[230:233], v158
	ds_read_b128 v[234:237], v158 offset:1024
	ds_read_b128 v[238:241], v158 offset:2048
	ds_read_b128 v[242:245], v158 offset:3072
	global_load_lds_dwordx4 v[248:249], off
	v_lshl_add_u64 v[248:249], s[58:59], 0, v[138:139]
	v_readfirstlane_b32 s9, v186
	v_lshl_add_u64 v[250:251], v[248:249], 0, s[44:45]
	s_mov_b32 m0, s9
	s_nop 0
	global_load_lds_dwordx4 v[250:251], off
	s_barrier
	s_waitcnt lgkmcnt(0)
	s_waitcnt lgkmcnt(0)
	v_mfma_f32_16x16x32_bf16 v[92:95], v[230:233], v[198:201], v[92:95]
	v_mfma_f32_16x16x32_bf16 v[88:91], v[238:241], v[198:201], v[88:91]
	v_mfma_f32_16x16x32_bf16 v[72:75], v[238:241], v[206:209], v[72:75]
	v_mfma_f32_16x16x32_bf16 v[84:87], v[230:233], v[206:209], v[84:87]
	v_mfma_f32_16x16x32_bf16 v[60:63], v[230:233], v[214:217], v[60:63]
	v_mfma_f32_16x16x32_bf16 v[56:59], v[238:241], v[214:217], v[56:59]
	v_mfma_f32_16x16x32_bf16 v[48:51], v[238:241], v[222:225], v[48:51]
	v_mfma_f32_16x16x32_bf16 v[52:55], v[230:233], v[222:225], v[52:55]
	v_mfma_f32_16x16x32_bf16 v[92:95], v[234:237], v[202:205], v[92:95]
	v_mfma_f32_16x16x32_bf16 v[88:91], v[242:245], v[202:205], v[88:91]
	v_mfma_f32_16x16x32_bf16 v[72:75], v[242:245], v[210:213], v[72:75]
	v_mfma_f32_16x16x32_bf16 v[84:87], v[234:237], v[210:213], v[84:87]
	v_mfma_f32_16x16x32_bf16 v[60:63], v[234:237], v[218:221], v[60:63]
	v_mfma_f32_16x16x32_bf16 v[56:59], v[242:245], v[218:221], v[56:59]
	v_mfma_f32_16x16x32_bf16 v[48:51], v[242:245], v[226:229], v[48:51]
	v_mfma_f32_16x16x32_bf16 v[52:55], v[234:237], v[226:229], v[52:55]
	v_readfirstlane_b32 s9, v146
	v_add_u32_e32 v186, 0x2000, v146
	v_lshl_add_u64 v[250:251], v[178:179], 0, s[46:47]
	s_mov_b32 m0, s9
	v_readfirstlane_b32 s9, v186
	s_barrier
	ds_read_b128 v[198:201], v151 offset:16384
	ds_read_b128 v[202:205], v151 offset:17408
	ds_read_b128 v[206:209], v150 offset:16384
	ds_read_b128 v[210:213], v150 offset:17408
	ds_read_b128 v[214:217], v149 offset:16384
	ds_read_b128 v[218:221], v149 offset:17408
	ds_read_b128 v[222:225], v148 offset:16384
	ds_read_b128 v[226:229], v148 offset:17408
	global_load_lds_dwordx4 v[250:251], off
	v_lshl_add_u64 v[250:251], v[188:189], 0, s[46:47]
	s_mov_b32 m0, s9
	s_nop 0
	global_load_lds_dwordx4 v[250:251], off
	s_barrier
	s_waitcnt lgkmcnt(0)
	s_waitcnt lgkmcnt(0)
	v_mfma_f32_16x16x32_bf16 v[44:47], v[162:165], v[198:201], v[44:47]
	v_mfma_f32_16x16x32_bf16 v[40:43], v[170:173], v[198:201], v[40:43]
	v_mfma_f32_16x16x32_bf16 v[32:35], v[170:173], v[206:209], v[32:35]
	v_mfma_f32_16x16x32_bf16 v[36:39], v[162:165], v[206:209], v[36:39]
	v_mfma_f32_16x16x32_bf16 v[28:31], v[162:165], v[214:217], v[28:31]
	v_mfma_f32_16x16x32_bf16 v[24:27], v[170:173], v[214:217], v[24:27]
	v_mfma_f32_16x16x32_bf16 v[16:19], v[170:173], v[222:225], v[16:19]
	v_mfma_f32_16x16x32_bf16 v[20:23], v[162:165], v[222:225], v[20:23]
	v_mfma_f32_16x16x32_bf16 v[44:47], v[166:169], v[202:205], v[44:47]
	v_mfma_f32_16x16x32_bf16 v[40:43], v[174:177], v[202:205], v[40:43]
	v_mfma_f32_16x16x32_bf16 v[32:35], v[174:177], v[210:213], v[32:35]
	v_mfma_f32_16x16x32_bf16 v[36:39], v[166:169], v[210:213], v[36:39]
	v_mfma_f32_16x16x32_bf16 v[28:31], v[166:169], v[218:221], v[28:31]
	v_mfma_f32_16x16x32_bf16 v[24:27], v[174:177], v[218:221], v[24:27]
	v_mfma_f32_16x16x32_bf16 v[16:19], v[174:177], v[226:229], v[16:19]
	v_mfma_f32_16x16x32_bf16 v[20:23], v[166:169], v[226:229], v[20:23]
	s_barrier
; #define WAIT_V(n) asm volatile("s_waitcnt vmcnt(" #n ")" ::: "memory")
; #define WAIT_L(n) asm volatile("s_waitcnt lgkmcnt(" #n ")" ::: "memory")
; #define BAR __builtin_amdgcn_s_barrier()
; #define SCHED __builtin_amdgcn_sched_barrier(0)
; #define LDA(dst, b, h)                                                                            \
;   _Pragma("unroll") for (int m = 0; m < 4; ++m) _Pragma("unroll") for (int k = 0; k < 2; ++k)                                         \
;     dst[m][k] = *reinterpret_cast<const bf16x8*>((char*)SA(b, h) + lds_byte(wr * 64 + m * 16 + fr, k * 32 + fq * 8))
; #define LDB(dst, b, h)                                                                            \
;   _Pragma("unroll") for (int n = 0; n < 2; ++n) _Pragma("unroll") for (int k = 0; k < 2; ++k)                                         \
;     dst[n][k] = *reinterpret_cast<const bf16x8*>((char*)SB(b, h) + lds_byte(wc * 32 + n * 16 + fr, k * 32 + fq * 8))
; template <int K, bool SWAP>
; __device__ __forceinline__ void gemm_kloop(const bf16* __restrict__ A, const bf16* __restrict__ Bt,
;                                            f32x4 (&acc)[2][2][4][2], bool pref = false) {
;     ...
;     STAGE(SB(0, 1), Bt, HALF, t + 2);
;     WAIT_V(6); BAR; MMA(1, 1, At, B1); BAR;
;     LDB(B0, 1, 0); SCHED; LDA(At, 1, 0); STAGE(SA(0, 1), A, HALF, t + 2);
;     WAIT_L(8); BAR; WAIT_L(0); MMA(0, 0, At, B0); BAR; SCHED;
;     LDB(B1, 1, 1); STAGE(SB(1, 0), Bt, 0, t + 3);
;     BAR; WAIT_L(0); MMA(0, 1, At, B1); BAR;
;     LDA(At, 1, 1); STAGE(SA(1, 0), A, 0, t + 3);
	v_readfirstlane_b32 s9, v147
	v_add_u32_e32 v164, 0x2000, v147
	v_lshl_add_u64 v[162:163], v[246:247], 0, s[48:49]
	s_mov_b32 m0, s9
	v_readfirstlane_b32 s9, v164
	global_load_lds_dwordx4 v[162:163], off
	v_lshl_add_u64 v[162:163], v[248:249], 0, s[48:49]
	s_mov_b32 m0, s9
	s_nop 0
	global_load_lds_dwordx4 v[162:163], off
	s_waitcnt vmcnt(6)
	s_barrier
	v_mfma_f32_16x16x32_bf16 v[12:15], v[230:233], v[198:201], v[12:15]
	v_mfma_f32_16x16x32_bf16 v[8:11], v[238:241], v[198:201], v[8:11]
	v_mfma_f32_16x16x32_bf16 v[0:3], v[238:241], v[206:209], v[0:3]
	v_mfma_f32_16x16x32_bf16 v[4:7], v[230:233], v[206:209], v[4:7]
	v_mfma_f32_16x16x32_bf16 v[64:67], v[230:233], v[214:217], v[64:67]
	v_mfma_f32_16x16x32_bf16 v[68:71], v[238:241], v[214:217], v[68:71]
	v_mfma_f32_16x16x32_bf16 v[80:83], v[238:241], v[222:225], v[80:83]
	v_mfma_f32_16x16x32_bf16 v[76:79], v[230:233], v[222:225], v[76:79]
	v_mfma_f32_16x16x32_bf16 v[12:15], v[234:237], v[202:205], v[12:15]
	v_mfma_f32_16x16x32_bf16 v[8:11], v[242:245], v[202:205], v[8:11]
	v_mfma_f32_16x16x32_bf16 v[0:3], v[242:245], v[210:213], v[0:3]
	v_mfma_f32_16x16x32_bf16 v[4:7], v[234:237], v[210:213], v[4:7]
	v_mfma_f32_16x16x32_bf16 v[64:67], v[234:237], v[218:221], v[64:67]
	v_mfma_f32_16x16x32_bf16 v[68:71], v[242:245], v[218:221], v[68:71]
	v_mfma_f32_16x16x32_bf16 v[80:83], v[242:245], v[226:229], v[80:83]
	v_mfma_f32_16x16x32_bf16 v[76:79], v[234:237], v[226:229], v[76:79]
	s_barrier
	ds_read_b128 v[162:165], v153
	ds_read_b128 v[166:169], v153 offset:1024
	ds_read_b128 v[170:173], v153 offset:2048
	ds_read_b128 v[174:177], v153 offset:3072
	v_add_u32_e32 v186, 0x4000, v146
	v_lshl_add_u64 v[230:231], v[178:179], 0, s[50:51]
	v_readfirstlane_b32 s9, v186
	v_add_u32_e32 v186, 0x6000, v146
	s_mov_b32 m0, s9
	v_readfirstlane_b32 s9, v186
	ds_read_b128 v[198:201], v151 offset:32768
	ds_read_b128 v[202:205], v151 offset:33792
	ds_read_b128 v[206:209], v150 offset:32768
	ds_read_b128 v[210:213], v150 offset:33792
	ds_read_b128 v[214:217], v149 offset:32768
	ds_read_b128 v[218:221], v149 offset:33792
	ds_read_b128 v[222:225], v148 offset:32768
	ds_read_b128 v[226:229], v148 offset:33792
	global_load_lds_dwordx4 v[230:231], off
	v_lshl_add_u64 v[230:231], v[188:189], 0, s[50:51]
	s_mov_b32 m0, s9
	s_nop 0
	global_load_lds_dwordx4 v[230:231], off
	s_waitcnt lgkmcnt(8)
	s_barrier
	s_waitcnt lgkmcnt(0)
	s_waitcnt lgkmcnt(0)
	v_mfma_f32_16x16x32_bf16 v[124:127], v[162:165], v[198:201], v[124:127]
	v_mfma_f32_16x16x32_bf16 v[120:123], v[170:173], v[198:201], v[120:123]
	v_mfma_f32_16x16x32_bf16 v[112:115], v[170:173], v[206:209], v[112:115]
	v_mfma_f32_16x16x32_bf16 v[116:119], v[162:165], v[206:209], v[116:119]
	v_mfma_f32_16x16x32_bf16 v[108:111], v[162:165], v[214:217], v[108:111]
	v_mfma_f32_16x16x32_bf16 v[104:107], v[170:173], v[214:217], v[104:107]
	v_mfma_f32_16x16x32_bf16 v[96:99], v[170:173], v[222:225], v[96:99]
	v_mfma_f32_16x16x32_bf16 v[100:103], v[162:165], v[222:225], v[100:103]
	v_mfma_f32_16x16x32_bf16 v[124:127], v[166:169], v[202:205], v[124:127]
	v_mfma_f32_16x16x32_bf16 v[120:123], v[174:177], v[202:205], v[120:123]
	v_mfma_f32_16x16x32_bf16 v[112:115], v[174:177], v[210:213], v[112:115]
	v_mfma_f32_16x16x32_bf16 v[116:119], v[166:169], v[210:213], v[116:119]
	v_mfma_f32_16x16x32_bf16 v[108:111], v[166:169], v[218:221], v[108:111]
	v_mfma_f32_16x16x32_bf16 v[104:107], v[174:177], v[218:221], v[104:107]
	v_mfma_f32_16x16x32_bf16 v[96:99], v[174:177], v[226:229], v[96:99]
	v_mfma_f32_16x16x32_bf16 v[100:103], v[166:169], v[226:229], v[100:103]
	s_barrier
	v_readfirstlane_b32 s9, v154
	v_add_u32_e32 v186, 0x2000, v154
	v_lshl_add_u64 v[250:251], v[246:247], 0, s[52:53]
	s_mov_b32 m0, s9
	v_readfirstlane_b32 s9, v186
	ds_read_b128 v[230:233], v152
	ds_read_b128 v[234:237], v152 offset:1024
	ds_read_b128 v[238:241], v152 offset:2048
	ds_read_b128 v[242:245], v152 offset:3072
	global_load_lds_dwordx4 v[250:251], off
	v_lshl_add_u64 v[250:251], v[248:249], 0, s[52:53]
	s_mov_b32 m0, s9
	s_nop 0
	global_load_lds_dwordx4 v[250:251], off
	s_barrier
	s_waitcnt lgkmcnt(0)
	s_waitcnt lgkmcnt(0)
	v_mfma_f32_16x16x32_bf16 v[92:95], v[230:233], v[198:201], v[92:95]
	v_mfma_f32_16x16x32_bf16 v[88:91], v[238:241], v[198:201], v[88:91]
	v_mfma_f32_16x16x32_bf16 v[72:75], v[238:241], v[206:209], v[72:75]
	v_mfma_f32_16x16x32_bf16 v[84:87], v[230:233], v[206:209], v[84:87]
	v_mfma_f32_16x16x32_bf16 v[60:63], v[230:233], v[214:217], v[60:63]
	v_mfma_f32_16x16x32_bf16 v[56:59], v[238:241], v[214:217], v[56:59]
	v_mfma_f32_16x16x32_bf16 v[48:51], v[238:241], v[222:225], v[48:51]
	v_mfma_f32_16x16x32_bf16 v[52:55], v[230:233], v[222:225], v[52:55]
	v_mfma_f32_16x16x32_bf16 v[92:95], v[234:237], v[202:205], v[92:95]
	v_mfma_f32_16x16x32_bf16 v[88:91], v[242:245], v[202:205], v[88:91]
	v_mfma_f32_16x16x32_bf16 v[72:75], v[242:245], v[210:213], v[72:75]
	v_mfma_f32_16x16x32_bf16 v[84:87], v[234:237], v[210:213], v[84:87]
	v_mfma_f32_16x16x32_bf16 v[60:63], v[234:237], v[218:221], v[60:63]
	v_mfma_f32_16x16x32_bf16 v[56:59], v[242:245], v[218:221], v[56:59]
	v_mfma_f32_16x16x32_bf16 v[48:51], v[242:245], v[226:229], v[48:51]
	v_mfma_f32_16x16x32_bf16 v[52:55], v[234:237], v[226:229], v[52:55]
	v_readfirstlane_b32 s9, v155
	v_lshl_add_u64 v[178:179], v[178:179], 0, s[54:55]
	s_mov_b32 m0, s9
	v_readfirstlane_b32 s9, v156
	s_barrier
	ds_read_b128 v[198:201], v151 offset:49152
	ds_read_b128 v[202:205], v151 offset:50176
	ds_read_b128 v[206:209], v150 offset:49152
	ds_read_b128 v[210:213], v150 offset:50176
	ds_read_b128 v[214:217], v149 offset:49152
	ds_read_b128 v[218:221], v149 offset:50176
	ds_read_b128 v[222:225], v148 offset:49152
	ds_read_b128 v[226:229], v148 offset:50176
	global_load_lds_dwordx4 v[178:179], off
	v_lshl_add_u64 v[178:179], v[188:189], 0, s[54:55]
	s_mov_b32 m0, s9
	s_nop 0
	global_load_lds_dwordx4 v[178:179], off
	s_barrier
; #define WAIT_V(n) asm volatile("s_waitcnt vmcnt(" #n ")" ::: "memory")
; #define WAIT_L(n) asm volatile("s_waitcnt lgkmcnt(" #n ")" ::: "memory")
; #define BAR __builtin_amdgcn_s_barrier()
; #define SCHED __builtin_amdgcn_sched_barrier(0)
; #define LDA(dst, b, h)                                                                            \
;   _Pragma("unroll") for (int m = 0; m < 4; ++m) _Pragma("unroll") for (int k = 0; k < 2; ++k)                                         \
;     dst[m][k] = *reinterpret_cast<const bf16x8*>((char*)SA(b, h) + lds_byte(wr * 64 + m * 16 + fr, k * 32 + fq * 8))
; #define LDB(dst, b, h)                                                                            \
;   _Pragma("unroll") for (int n = 0; n < 2; ++n) _Pragma("unroll") for (int k = 0; k < 2; ++k)                                         \
;     dst[n][k] = *reinterpret_cast<const bf16x8*>((char*)SB(b, h) + lds_byte(wc * 32 + n * 16 + fr, k * 32 + fq * 8))
; template <int K, bool SWAP>
; __device__ __forceinline__ void gemm_kloop(const bf16* __restrict__ A, const bf16* __restrict__ Bt,
;                                            f32x4 (&acc)[2][2][4][2], bool pref = false) {
;     ...
;     LDA(At, 1, 1); STAGE(SA(1, 0), A, 0, t + 3);
;     BAR; WAIT_L(0); MMA(1, 0, At, B0); BAR; SCHED;
;     STAGE(SB(1, 1), Bt, HALF, t + 3);
;     WAIT_V(6); BAR; MMA(1, 1, At, B1); BAR;
;   }
;   { LDB(B0, 0, 0); LDA(At, 0, 0); STAGE(SA(1, 1), A, HALF, nt - 1);
;     BAR; WAIT_L(0); MMA(0, 0, At, B0); BAR;
;     LDB(B1, 0, 1); BAR; WAIT_L(0); MMA(0, 1, At, B1); BAR;
;     LDA(At, 0, 1); WAIT_V(4); BAR; WAIT_L(0); MMA(1, 0, At, B0); MMA(1, 1, At, B1); BAR; }
	s_waitcnt lgkmcnt(0)
	s_waitcnt lgkmcnt(0)
	v_mfma_f32_16x16x32_bf16 v[44:47], v[162:165], v[198:201], v[44:47]
	v_mfma_f32_16x16x32_bf16 v[40:43], v[170:173], v[198:201], v[40:43]
	v_mfma_f32_16x16x32_bf16 v[32:35], v[170:173], v[206:209], v[32:35]
	v_mfma_f32_16x16x32_bf16 v[36:39], v[162:165], v[206:209], v[36:39]
	v_mfma_f32_16x16x32_bf16 v[28:31], v[162:165], v[214:217], v[28:31]
	v_mfma_f32_16x16x32_bf16 v[24:27], v[170:173], v[214:217], v[24:27]
	v_mfma_f32_16x16x32_bf16 v[16:19], v[170:173], v[222:225], v[16:19]
	v_mfma_f32_16x16x32_bf16 v[20:23], v[162:165], v[222:225], v[20:23]
	v_mfma_f32_16x16x32_bf16 v[44:47], v[166:169], v[202:205], v[44:47]
	v_mfma_f32_16x16x32_bf16 v[40:43], v[174:177], v[202:205], v[40:43]
	v_mfma_f32_16x16x32_bf16 v[32:35], v[174:177], v[210:213], v[32:35]
	v_mfma_f32_16x16x32_bf16 v[36:39], v[166:169], v[210:213], v[36:39]
	v_mfma_f32_16x16x32_bf16 v[28:31], v[166:169], v[218:221], v[28:31]
	v_mfma_f32_16x16x32_bf16 v[24:27], v[174:177], v[218:221], v[24:27]
	v_mfma_f32_16x16x32_bf16 v[16:19], v[174:177], v[226:229], v[16:19]
	v_mfma_f32_16x16x32_bf16 v[20:23], v[166:169], v[226:229], v[20:23]
	s_barrier
	v_readfirstlane_b32 s9, v157
	v_add_u32_e32 v164, 0x2000, v157
	v_lshl_add_u64 v[162:163], v[246:247], 0, s[56:57]
	s_mov_b32 m0, s9
	v_readfirstlane_b32 s9, v164
	global_load_lds_dwordx4 v[162:163], off
	v_lshl_add_u64 v[162:163], v[248:249], 0, s[56:57]
	s_mov_b32 m0, s9
	s_nop 0
	global_load_lds_dwordx4 v[162:163], off
	s_waitcnt vmcnt(6)
	s_barrier
	v_mfma_f32_16x16x32_bf16 v[12:15], v[230:233], v[198:201], v[12:15]
	v_mfma_f32_16x16x32_bf16 v[8:11], v[238:241], v[198:201], v[8:11]
	v_mfma_f32_16x16x32_bf16 v[0:3], v[238:241], v[206:209], v[0:3]
	v_mfma_f32_16x16x32_bf16 v[4:7], v[230:233], v[206:209], v[4:7]
	v_mfma_f32_16x16x32_bf16 v[64:67], v[230:233], v[214:217], v[64:67]
	v_mfma_f32_16x16x32_bf16 v[68:71], v[238:241], v[214:217], v[68:71]
	v_mfma_f32_16x16x32_bf16 v[80:83], v[238:241], v[222:225], v[80:83]
	v_mfma_f32_16x16x32_bf16 v[76:79], v[230:233], v[222:225], v[76:79]
	v_mfma_f32_16x16x32_bf16 v[12:15], v[234:237], v[202:205], v[12:15]
	v_mfma_f32_16x16x32_bf16 v[8:11], v[242:245], v[202:205], v[8:11]
	v_mfma_f32_16x16x32_bf16 v[0:3], v[242:245], v[210:213], v[0:3]
	v_mfma_f32_16x16x32_bf16 v[4:7], v[234:237], v[210:213], v[4:7]
	v_mfma_f32_16x16x32_bf16 v[64:67], v[234:237], v[218:221], v[64:67]
	v_mfma_f32_16x16x32_bf16 v[68:71], v[242:245], v[218:221], v[68:71]
	v_mfma_f32_16x16x32_bf16 v[80:83], v[242:245], v[226:229], v[80:83]
	v_mfma_f32_16x16x32_bf16 v[76:79], v[234:237], v[226:229], v[76:79]
	s_add_i32 s8, s8, 2
	v_lshl_add_u64 v[136:137], v[136:137], 0, s[44:45]
	v_lshl_add_u64 v[138:139], v[138:139], 0, s[44:45]
	v_lshl_add_u64 v[140:141], v[140:141], 0, s[44:45]
	s_cmp_lt_u32 s8, 12
	v_lshl_add_u64 v[142:143], v[142:143], 0, s[44:45]
	s_barrier
	s_cbranch_scc1 .LBB0_514
	s_add_u32 s4, s4, 0x40780
	s_addc_u32 s5, s5, 0
	v_lshl_add_u64 v[130:131], s[4:5], 0, v[130:131]
	v_readfirstlane_b32 s8, v160
	v_lshl_add_u64 v[128:129], v[128:129], 1, v[130:131]
	s_mov_b32 m0, s8
	ds_read_b128 v[136:139], v159
	ds_read_b128 v[140:143], v159 offset:1024
	ds_read_b128 v[154:157], v159 offset:2048
	ds_read_b128 v[162:165], v159 offset:3072
	ds_read_b128 v[166:169], v151
	ds_read_b128 v[170:173], v151 offset:1024
	ds_read_b128 v[174:177], v150
	ds_read_b128 v[198:201], v150 offset:1024
	ds_read_b128 v[202:205], v149
	ds_read_b128 v[206:209], v149 offset:1024
	ds_read_b128 v[210:213], v148
	ds_read_b128 v[214:217], v148 offset:1024
	global_load_lds_dwordx4 v[128:129], off
	v_lshl_add_u64 v[128:129], s[4:5], 0, v[134:135]
	v_readfirstlane_b32 s4, v161
	v_lshl_add_u64 v[128:129], v[132:133], 1, v[128:129]
	s_mov_b32 m0, s4
	s_nop 0
	global_load_lds_dwordx4 v[128:129], off
	s_barrier
	s_waitcnt lgkmcnt(0)
	s_waitcnt lgkmcnt(0)
	v_mfma_f32_16x16x32_bf16 v[124:127], v[136:139], v[166:169], v[124:127]
	v_mfma_f32_16x16x32_bf16 v[120:123], v[154:157], v[166:169], v[120:123]
	v_mfma_f32_16x16x32_bf16 v[112:115], v[154:157], v[174:177], v[112:115]
	v_mfma_f32_16x16x32_bf16 v[116:119], v[136:139], v[174:177], v[116:119]
	v_mfma_f32_16x16x32_bf16 v[108:111], v[136:139], v[202:205], v[108:111]
	v_mfma_f32_16x16x32_bf16 v[104:107], v[154:157], v[202:205], v[104:107]
	v_mfma_f32_16x16x32_bf16 v[96:99], v[154:157], v[210:213], v[96:99]
	v_mfma_f32_16x16x32_bf16 v[100:103], v[136:139], v[210:213], v[100:103]
	v_mfma_f32_16x16x32_bf16 v[124:127], v[140:143], v[170:173], v[124:127]
	v_mfma_f32_16x16x32_bf16 v[120:123], v[162:165], v[170:173], v[120:123]
	v_mfma_f32_16x16x32_bf16 v[112:115], v[162:165], v[198:201], v[112:115]
	v_mfma_f32_16x16x32_bf16 v[116:119], v[140:143], v[198:201], v[116:119]
	v_mfma_f32_16x16x32_bf16 v[108:111], v[140:143], v[206:209], v[108:111]
	v_mfma_f32_16x16x32_bf16 v[104:107], v[162:165], v[206:209], v[104:107]
	v_mfma_f32_16x16x32_bf16 v[96:99], v[162:165], v[214:217], v[96:99]
	v_mfma_f32_16x16x32_bf16 v[100:103], v[140:143], v[214:217], v[100:103]
	s_barrier
	ds_read_b128 v[128:131], v158
	ds_read_b128 v[132:135], v158 offset:1024
	ds_read_b128 v[218:221], v158 offset:2048
	ds_read_b128 v[158:161], v158 offset:3072
	s_barrier
; #define WAIT_V(n) asm volatile("s_waitcnt vmcnt(" #n ")" ::: "memory")
; #define WAIT_L(n) asm volatile("s_waitcnt lgkmcnt(" #n ")" ::: "memory")
; #define BAR __builtin_amdgcn_s_barrier()
; #define LDA(dst, b, h)                                                                            \
;   _Pragma("unroll") for (int m = 0; m < 4; ++m) _Pragma("unroll") for (int k = 0; k < 2; ++k)                                         \
;     dst[m][k] = *reinterpret_cast<const bf16x8*>((char*)SA(b, h) + lds_byte(wr * 64 + m * 16 + fr, k * 32 + fq * 8))
; #define LDB(dst, b, h)                                                                            \
;   _Pragma("unroll") for (int n = 0; n < 2; ++n) _Pragma("unroll") for (int k = 0; k < 2; ++k)                                         \
;     dst[n][k] = *reinterpret_cast<const bf16x8*>((char*)SB(b, h) + lds_byte(wc * 32 + n * 16 + fr, k * 32 + fq * 8))
; template <int K, bool SWAP>
; __device__ __forceinline__ void gemm_kloop(const bf16* __restrict__ A, const bf16* __restrict__ Bt,
;                                            f32x4 (&acc)[2][2][4][2], bool pref = false) {
;     ...
;     LDB(B1, 0, 1); BAR; WAIT_L(0); MMA(0, 1, At, B1); BAR;
;     LDA(At, 0, 1); WAIT_V(4); BAR; WAIT_L(0); MMA(1, 0, At, B0); MMA(1, 1, At, B1); BAR; }
;   { LDB(B0, 1, 0); LDA(At, 1, 0); WAIT_V(2); BAR; WAIT_L(0); MMA(0, 0, At, B0); BAR;
;     LDB(B1, 1, 1); WAIT_V(0); BAR; WAIT_L(0); MMA(0, 1, At, B1); BAR;
	s_waitcnt lgkmcnt(0)
	s_waitcnt lgkmcnt(0)
	v_mfma_f32_16x16x32_bf16 v[92:95], v[128:131], v[166:169], v[92:95]
	v_mfma_f32_16x16x32_bf16 v[88:91], v[218:221], v[166:169], v[88:91]
	v_mfma_f32_16x16x32_bf16 v[72:75], v[218:221], v[174:177], v[72:75]
	v_mfma_f32_16x16x32_bf16 v[84:87], v[128:131], v[174:177], v[84:87]
	v_mfma_f32_16x16x32_bf16 v[60:63], v[128:131], v[202:205], v[60:63]
	v_mfma_f32_16x16x32_bf16 v[56:59], v[218:221], v[202:205], v[56:59]
	v_mfma_f32_16x16x32_bf16 v[48:51], v[218:221], v[210:213], v[48:51]
	v_mfma_f32_16x16x32_bf16 v[52:55], v[128:131], v[210:213], v[52:55]
	v_mfma_f32_16x16x32_bf16 v[92:95], v[132:135], v[170:173], v[92:95]
	v_mfma_f32_16x16x32_bf16 v[88:91], v[158:161], v[170:173], v[88:91]
	v_mfma_f32_16x16x32_bf16 v[72:75], v[158:161], v[198:201], v[72:75]
	v_mfma_f32_16x16x32_bf16 v[84:87], v[132:135], v[198:201], v[84:87]
	v_mfma_f32_16x16x32_bf16 v[60:63], v[132:135], v[206:209], v[60:63]
	v_mfma_f32_16x16x32_bf16 v[56:59], v[158:161], v[206:209], v[56:59]
	v_mfma_f32_16x16x32_bf16 v[48:51], v[158:161], v[214:217], v[48:51]
	v_mfma_f32_16x16x32_bf16 v[52:55], v[132:135], v[214:217], v[52:55]
	s_barrier
	ds_read_b128 v[166:169], v151 offset:16384
	ds_read_b128 v[170:173], v151 offset:17408
	ds_read_b128 v[174:177], v150 offset:16384
	ds_read_b128 v[198:201], v150 offset:17408
	ds_read_b128 v[202:205], v149 offset:16384
	ds_read_b128 v[206:209], v149 offset:17408
	ds_read_b128 v[210:213], v148 offset:16384
	ds_read_b128 v[214:217], v148 offset:17408
	s_waitcnt vmcnt(4)
	s_barrier
	s_waitcnt lgkmcnt(0)
	s_waitcnt lgkmcnt(0)
	v_mfma_f32_16x16x32_bf16 v[44:47], v[136:139], v[166:169], v[44:47]
	v_mfma_f32_16x16x32_bf16 v[40:43], v[154:157], v[166:169], v[40:43]
	v_mfma_f32_16x16x32_bf16 v[32:35], v[154:157], v[174:177], v[32:35]
	v_mfma_f32_16x16x32_bf16 v[36:39], v[136:139], v[174:177], v[36:39]
	v_mfma_f32_16x16x32_bf16 v[28:31], v[136:139], v[202:205], v[28:31]
	v_mfma_f32_16x16x32_bf16 v[24:27], v[154:157], v[202:205], v[24:27]
	v_mfma_f32_16x16x32_bf16 v[16:19], v[154:157], v[210:213], v[16:19]
	v_mfma_f32_16x16x32_bf16 v[20:23], v[136:139], v[210:213], v[20:23]
	v_mfma_f32_16x16x32_bf16 v[44:47], v[140:143], v[170:173], v[44:47]
	v_mfma_f32_16x16x32_bf16 v[40:43], v[162:165], v[170:173], v[40:43]
	v_mfma_f32_16x16x32_bf16 v[32:35], v[162:165], v[198:201], v[32:35]
	v_mfma_f32_16x16x32_bf16 v[36:39], v[140:143], v[198:201], v[36:39]
	v_mfma_f32_16x16x32_bf16 v[28:31], v[140:143], v[206:209], v[28:31]
	v_mfma_f32_16x16x32_bf16 v[24:27], v[162:165], v[206:209], v[24:27]
	v_mfma_f32_16x16x32_bf16 v[16:19], v[162:165], v[214:217], v[16:19]
	v_mfma_f32_16x16x32_bf16 v[20:23], v[140:143], v[214:217], v[20:23]
	v_mfma_f32_16x16x32_bf16 v[64:67], v[128:131], v[202:205], v[64:67]
	v_mfma_f32_16x16x32_bf16 v[136:139], v[132:135], v[206:209], v[64:67]
	v_mfma_f32_16x16x32_bf16 v[64:67], v[218:221], v[202:205], v[68:71]
	v_mfma_f32_16x16x32_bf16 v[12:15], v[128:131], v[166:169], v[12:15]
	v_mfma_f32_16x16x32_bf16 v[8:11], v[218:221], v[166:169], v[8:11]
	v_mfma_f32_16x16x32_bf16 v[4:7], v[128:131], v[174:177], v[4:7]
	v_mfma_f32_16x16x32_bf16 v[0:3], v[218:221], v[174:177], v[0:3]
	v_mfma_f32_16x16x32_bf16 v[140:143], v[158:161], v[206:209], v[64:67]
	v_mfma_f32_16x16x32_bf16 v[64:67], v[128:131], v[210:213], v[76:79]
	v_mfma_f32_16x16x32_bf16 v[12:15], v[132:135], v[170:173], v[12:15]
	v_mfma_f32_16x16x32_bf16 v[8:11], v[158:161], v[170:173], v[8:11]
	v_mfma_f32_16x16x32_bf16 v[4:7], v[132:135], v[198:201], v[4:7]
	v_mfma_f32_16x16x32_bf16 v[0:3], v[158:161], v[198:201], v[0:3]
	v_mfma_f32_16x16x32_bf16 v[128:131], v[132:135], v[214:217], v[64:67]
	v_mfma_f32_16x16x32_bf16 v[64:67], v[218:221], v[210:213], v[80:83]
	v_mfma_f32_16x16x32_bf16 v[132:135], v[158:161], v[214:217], v[64:67]
	s_barrier
	ds_read_b128 v[154:157], v153
	ds_read_b128 v[158:161], v153 offset:1024
	ds_read_b128 v[162:165], v153 offset:2048
	ds_read_b128 v[166:169], v153 offset:3072
	s_nop 0
	ds_read_b128 v[64:67], v151 offset:32768
	ds_read_b128 v[68:71], v151 offset:33792
	ds_read_b128 v[76:79], v150 offset:32768
	ds_read_b128 v[80:83], v150 offset:33792
	ds_read_b128 v[170:173], v149 offset:32768
	ds_read_b128 v[174:177], v149 offset:33792
	ds_read_b128 v[198:201], v148 offset:32768
	ds_read_b128 v[202:205], v148 offset:33792
	s_waitcnt vmcnt(2)
	s_barrier
; #define WAIT_V(n) asm volatile("s_waitcnt vmcnt(" #n ")" ::: "memory")
; #define WAIT_L(n) asm volatile("s_waitcnt lgkmcnt(" #n ")" ::: "memory")
; #define BAR __builtin_amdgcn_s_barrier()
; #define SCHED __builtin_amdgcn_sched_barrier(0)
; #define LDA(dst, b, h)                                                                            \
;   _Pragma("unroll") for (int m = 0; m < 4; ++m) _Pragma("unroll") for (int k = 0; k < 2; ++k)                                         \
;     dst[m][k] = *reinterpret_cast<const bf16x8*>((char*)SA(b, h) + lds_byte(wr * 64 + m * 16 + fr, k * 32 + fq * 8))
; #define LDB(dst, b, h)                                                                            \
;   _Pragma("unroll") for (int n = 0; n < 2; ++n) _Pragma("unroll") for (int k = 0; k < 2; ++k)                                         \
;     dst[n][k] = *reinterpret_cast<const bf16x8*>((char*)SB(b, h) + lds_byte(wc * 32 + n * 16 + fr, k * 32 + fq * 8))
; template <int K, bool SWAP>
; __device__ __forceinline__ void gemm_kloop(const bf16* __restrict__ A, const bf16* __restrict__ Bt,
;                                            f32x4 (&acc)[2][2][4][2], bool pref = false) {
;     ...
;   { LDB(B0, 0, 0); LDA(At, 0, 0); STAGE(SA(1, 1), A, HALF, nt - 1);
;     BAR; WAIT_L(0); MMA(0, 0, At, B0); BAR;
;     LDB(B1, 0, 1); BAR; WAIT_L(0); MMA(0, 1, At, B1); BAR;
;     LDA(At, 0, 1); WAIT_V(4); BAR; WAIT_L(0); MMA(1, 0, At, B0); MMA(1, 1, At, B1); BAR; }
;   { LDB(B0, 1, 0); LDA(At, 1, 0); WAIT_V(2); BAR; WAIT_L(0); MMA(0, 0, At, B0); BAR;
;     LDB(B1, 1, 1); WAIT_V(0); BAR; WAIT_L(0); MMA(0, 1, At, B1); BAR;
;     LDA(At, 1, 1); BAR; WAIT_L(0); MMA(1, 0, At, B0); MMA(1, 1, At, B1); BAR; }
;   if (wr == 0) BAR;
;   SCHED;
	s_waitcnt lgkmcnt(0)
	s_waitcnt lgkmcnt(0)
	v_mfma_f32_16x16x32_bf16 v[124:127], v[154:157], v[64:67], v[124:127]
	v_mfma_f32_16x16x32_bf16 v[120:123], v[162:165], v[64:67], v[120:123]
	v_mfma_f32_16x16x32_bf16 v[112:115], v[162:165], v[76:79], v[112:115]
	v_mfma_f32_16x16x32_bf16 v[116:119], v[154:157], v[76:79], v[116:119]
	v_mfma_f32_16x16x32_bf16 v[108:111], v[154:157], v[170:173], v[108:111]
	v_mfma_f32_16x16x32_bf16 v[104:107], v[162:165], v[170:173], v[104:107]
	v_mfma_f32_16x16x32_bf16 v[96:99], v[162:165], v[198:201], v[96:99]
	v_mfma_f32_16x16x32_bf16 v[100:103], v[154:157], v[198:201], v[100:103]
	v_mfma_f32_16x16x32_bf16 v[124:127], v[158:161], v[68:71], v[124:127]
	v_mfma_f32_16x16x32_bf16 v[120:123], v[166:169], v[68:71], v[120:123]
	v_mfma_f32_16x16x32_bf16 v[112:115], v[166:169], v[80:83], v[112:115]
	v_mfma_f32_16x16x32_bf16 v[116:119], v[158:161], v[80:83], v[116:119]
	v_mfma_f32_16x16x32_bf16 v[108:111], v[158:161], v[174:177], v[108:111]
	v_mfma_f32_16x16x32_bf16 v[104:107], v[166:169], v[174:177], v[104:107]
	v_mfma_f32_16x16x32_bf16 v[96:99], v[166:169], v[202:205], v[96:99]
	v_mfma_f32_16x16x32_bf16 v[100:103], v[158:161], v[202:205], v[100:103]
	s_barrier
	ds_read_b128 v[206:209], v152
	ds_read_b128 v[210:213], v152 offset:1024
	ds_read_b128 v[214:217], v152 offset:2048
	ds_read_b128 v[218:221], v152 offset:3072
	s_waitcnt vmcnt(0)
	s_barrier
	s_waitcnt lgkmcnt(0)
	s_waitcnt lgkmcnt(0)
	v_mfma_f32_16x16x32_bf16 v[92:95], v[206:209], v[64:67], v[92:95]
	v_mfma_f32_16x16x32_bf16 v[64:67], v[214:217], v[64:67], v[88:91]
	v_mfma_f32_16x16x32_bf16 v[88:91], v[218:221], v[68:71], v[64:67]
	v_mfma_f32_16x16x32_bf16 v[64:67], v[206:209], v[76:79], v[84:87]
	v_mfma_f32_16x16x32_bf16 v[84:87], v[210:213], v[80:83], v[64:67]
	v_mfma_f32_16x16x32_bf16 v[64:67], v[214:217], v[76:79], v[72:75]
	v_mfma_f32_16x16x32_bf16 v[60:63], v[206:209], v[170:173], v[60:63]
	v_mfma_f32_16x16x32_bf16 v[56:59], v[214:217], v[170:173], v[56:59]
	v_mfma_f32_16x16x32_bf16 v[52:55], v[206:209], v[198:201], v[52:55]
	v_mfma_f32_16x16x32_bf16 v[48:51], v[214:217], v[198:201], v[48:51]
	v_mfma_f32_16x16x32_bf16 v[92:95], v[210:213], v[68:71], v[92:95]
	v_mfma_f32_16x16x32_bf16 v[80:83], v[218:221], v[80:83], v[64:67]
	v_mfma_f32_16x16x32_bf16 v[76:79], v[210:213], v[174:177], v[60:63]
	v_mfma_f32_16x16x32_bf16 v[72:75], v[218:221], v[174:177], v[56:59]
	v_mfma_f32_16x16x32_bf16 v[68:71], v[210:213], v[202:205], v[52:55]
	v_mfma_f32_16x16x32_bf16 v[64:67], v[218:221], v[202:205], v[48:51]
	s_barrier
	ds_read_b128 v[170:173], v151 offset:49152
	ds_read_b128 v[174:177], v151 offset:50176
	ds_read_b128 v[198:201], v150 offset:49152
	ds_read_b128 v[150:153], v150 offset:50176
	ds_read_b128 v[202:205], v149 offset:49152
	ds_read_b128 v[222:225], v149 offset:50176
	ds_read_b128 v[226:229], v148 offset:49152
	ds_read_b128 v[146:149], v148 offset:50176
	s_barrier
	s_waitcnt lgkmcnt(0)
	s_waitcnt lgkmcnt(0)
	v_mfma_f32_16x16x32_bf16 v[44:47], v[154:157], v[170:173], v[44:47]
	v_mfma_f32_16x16x32_bf16 v[40:43], v[162:165], v[170:173], v[40:43]
	v_mfma_f32_16x16x32_bf16 v[36:39], v[154:157], v[198:201], v[36:39]
	v_mfma_f32_16x16x32_bf16 v[32:35], v[162:165], v[198:201], v[32:35]
	v_mfma_f32_16x16x32_bf16 v[28:31], v[154:157], v[202:205], v[28:31]
	v_mfma_f32_16x16x32_bf16 v[24:27], v[162:165], v[202:205], v[24:27]
	v_mfma_f32_16x16x32_bf16 v[20:23], v[154:157], v[226:229], v[20:23]
	v_mfma_f32_16x16x32_bf16 v[16:19], v[162:165], v[226:229], v[16:19]
	v_mfma_f32_16x16x32_bf16 v[60:63], v[158:161], v[174:177], v[44:47]
	v_mfma_f32_16x16x32_bf16 v[56:59], v[166:169], v[174:177], v[40:43]
	v_mfma_f32_16x16x32_bf16 v[52:55], v[158:161], v[150:153], v[36:39]
	v_mfma_f32_16x16x32_bf16 v[48:51], v[166:169], v[150:153], v[32:35]
	v_mfma_f32_16x16x32_bf16 v[44:47], v[158:161], v[222:225], v[28:31]
	v_mfma_f32_16x16x32_bf16 v[40:43], v[166:169], v[222:225], v[24:27]
	v_mfma_f32_16x16x32_bf16 v[36:39], v[158:161], v[146:149], v[20:23]
	v_mfma_f32_16x16x32_bf16 v[32:35], v[166:169], v[146:149], v[16:19]
	v_mfma_f32_16x16x32_bf16 v[0:3], v[214:217], v[198:201], v[0:3]
	v_mfma_f32_16x16x32_bf16 v[12:15], v[206:209], v[170:173], v[12:15]
	v_mfma_f32_16x16x32_bf16 v[16:19], v[218:221], v[150:153], v[0:3]
	v_mfma_f32_16x16x32_bf16 v[0:3], v[206:209], v[202:205], v[136:139]
	v_mfma_f32_16x16x32_bf16 v[28:31], v[210:213], v[174:177], v[12:15]
	v_mfma_f32_16x16x32_bf16 v[8:11], v[214:217], v[170:173], v[8:11]
	v_mfma_f32_16x16x32_bf16 v[12:15], v[210:213], v[222:225], v[0:3]
	v_mfma_f32_16x16x32_bf16 v[0:3], v[214:217], v[202:205], v[140:143]
	v_mfma_f32_16x16x32_bf16 v[24:27], v[218:221], v[174:177], v[8:11]
	v_mfma_f32_16x16x32_bf16 v[4:7], v[206:209], v[198:201], v[4:7]
	v_mfma_f32_16x16x32_bf16 v[8:11], v[218:221], v[222:225], v[0:3]
	v_mfma_f32_16x16x32_bf16 v[0:3], v[206:209], v[226:229], v[128:131]
	v_mfma_f32_16x16x32_bf16 v[20:23], v[210:213], v[150:153], v[4:7]
	v_mfma_f32_16x16x32_bf16 v[4:7], v[210:213], v[146:149], v[0:3]
	v_mfma_f32_16x16x32_bf16 v[0:3], v[214:217], v[226:229], v[132:135]
	v_mfma_f32_16x16x32_bf16 v[0:3], v[218:221], v[146:149], v[0:3]
	s_movk_i32 s4, 0x100
	v_cmp_gt_u32_e32 vcc, s4, v144
	s_barrier
	s_and_saveexec_b64 s[4:5], vcc
	s_cbranch_execz .LBB0_517
	s_barrier

; #define WAIT_V(n) asm volatile("s_waitcnt vmcnt(" #n ")" ::: "memory")
; #define WAIT_L(n) asm volatile("s_waitcnt lgkmcnt(" #n ")" ::: "memory")
; #define BAR __builtin_amdgcn_s_barrier()
; #define SCHED __builtin_amdgcn_sched_barrier(0)
; #define LDA(dst, b, h)                                                                            \
;   _Pragma("unroll") for (int m = 0; m < 4; ++m) _Pragma("unroll") for (int k = 0; k < 2; ++k)                                         \
;     dst[m][k] = *reinterpret_cast<const bf16x8*>((char*)SA(b, h) + lds_byte(wr * 64 + m * 16 + fr, k * 32 + fq * 8))
; #define LDB(dst, b, h)                                                                            \
;   _Pragma("unroll") for (int n = 0; n < 2; ++n) _Pragma("unroll") for (int k = 0; k < 2; ++k)                                         \
;     dst[n][k] = *reinterpret_cast<const bf16x8*>((char*)SB(b, h) + lds_byte(wc * 32 + n * 16 + fr, k * 32 + fq * 8))
; template <int K, bool SWAP>
; __device__ __forceinline__ void gemm_kloop(const bf16* __restrict__ A, const bf16* __restrict__ Bt,
;                                            f32x4 (&acc)[2][2][4][2], bool pref = false) {
;     ...
;     LDB(B0, 0, 0); SCHED; LDA(At, 0, 0); STAGE(SA(1, 1), A, HALF, t + 1);
;     WAIT_L(8); BAR; WAIT_L(0); MMA(0, 0, At, B0); BAR; SCHED;
;     LDB(B1, 0, 1); STAGE(SB(0, 0), Bt, 0, t + 2);
;     BAR; WAIT_L(0); MMA(0, 1, At, B1); BAR;
;     LDA(At, 0, 1); STAGE(SA(0, 0), A, 0, t + 2);
;     BAR; WAIT_L(0); MMA(1, 0, At, B0); BAR; SCHED;
;     STAGE(SB(0, 1), Bt, HALF, t + 2);
;     WAIT_V(6); BAR; MMA(1, 1, At, B1); BAR;
.LBB0_527:
	ds_read_b128 v[162:165], v159
	ds_read_b128 v[166:169], v159 offset:1024
	ds_read_b128 v[170:173], v159 offset:2048
	ds_read_b128 v[174:177], v159 offset:3072
	v_add_u32_e32 v160, 0xc000, v146
	v_lshl_add_u64 v[178:179], s[58:59], 0, v[140:141]
	v_readfirstlane_b32 s9, v160
	v_lshl_add_u64 v[188:189], v[178:179], 0, s[42:43]
	s_mov_b32 m0, s9
	v_add_u32_e32 v161, 0xe000, v146
	ds_read_b128 v[198:201], v151
	ds_read_b128 v[202:205], v151 offset:1024
	ds_read_b128 v[206:209], v150
	ds_read_b128 v[210:213], v150 offset:1024
	ds_read_b128 v[214:217], v149
	ds_read_b128 v[218:221], v149 offset:1024
	ds_read_b128 v[222:225], v148
	ds_read_b128 v[226:229], v148 offset:1024
	global_load_lds_dwordx4 v[188:189], off
	v_lshl_add_u64 v[188:189], s[58:59], 0, v[142:143]
	v_readfirstlane_b32 s9, v161
	v_lshl_add_u64 v[230:231], v[188:189], 0, s[42:43]
	s_mov_b32 m0, s9
	s_nop 0
	global_load_lds_dwordx4 v[230:231], off
	s_waitcnt lgkmcnt(8)
	s_barrier
	s_waitcnt lgkmcnt(0)
	s_waitcnt lgkmcnt(0)
	v_mfma_f32_16x16x32_bf16 v[124:127], v[162:165], v[198:201], v[124:127]
	v_mfma_f32_16x16x32_bf16 v[120:123], v[170:173], v[198:201], v[120:123]
	v_mfma_f32_16x16x32_bf16 v[112:115], v[170:173], v[206:209], v[112:115]
	v_mfma_f32_16x16x32_bf16 v[116:119], v[162:165], v[206:209], v[116:119]
	v_mfma_f32_16x16x32_bf16 v[108:111], v[162:165], v[214:217], v[108:111]
	v_mfma_f32_16x16x32_bf16 v[104:107], v[170:173], v[214:217], v[104:107]
	v_mfma_f32_16x16x32_bf16 v[96:99], v[170:173], v[222:225], v[96:99]
	v_mfma_f32_16x16x32_bf16 v[100:103], v[162:165], v[222:225], v[100:103]
	v_mfma_f32_16x16x32_bf16 v[124:127], v[166:169], v[202:205], v[124:127]
	v_mfma_f32_16x16x32_bf16 v[120:123], v[174:177], v[202:205], v[120:123]
	v_mfma_f32_16x16x32_bf16 v[112:115], v[174:177], v[210:213], v[112:115]
	v_mfma_f32_16x16x32_bf16 v[116:119], v[166:169], v[210:213], v[116:119]
	v_mfma_f32_16x16x32_bf16 v[108:111], v[166:169], v[218:221], v[108:111]
	v_mfma_f32_16x16x32_bf16 v[104:107], v[174:177], v[218:221], v[104:107]
	v_mfma_f32_16x16x32_bf16 v[96:99], v[174:177], v[226:229], v[96:99]
	v_mfma_f32_16x16x32_bf16 v[100:103], v[166:169], v[226:229], v[100:103]
	s_barrier
	v_add_u32_e32 v186, s7, v145
	v_lshl_add_u64 v[246:247], s[58:59], 0, v[136:137]
	v_readfirstlane_b32 s9, v186
	v_lshl_add_u64 v[248:249], v[246:247], 0, s[44:45]
	s_mov_b32 m0, s9
	v_add_u32_e32 v186, 0x2000, v186
	ds_read_b128 v[230:233], v158
	ds_read_b128 v[234:237], v158 offset:1024
	ds_read_b128 v[238:241], v158 offset:2048
	ds_read_b128 v[242:245], v158 offset:3072
	global_load_lds_dwordx4 v[248:249], off
	v_lshl_add_u64 v[248:249], s[58:59], 0, v[138:139]
	v_readfirstlane_b32 s9, v186
	v_lshl_add_u64 v[250:251], v[248:249], 0, s[44:45]
	s_mov_b32 m0, s9
	s_nop 0
	global_load_lds_dwordx4 v[250:251], off
	s_barrier
	s_waitcnt lgkmcnt(0)
	s_waitcnt lgkmcnt(0)
	v_mfma_f32_16x16x32_bf16 v[92:95], v[230:233], v[198:201], v[92:95]
	v_mfma_f32_16x16x32_bf16 v[88:91], v[238:241], v[198:201], v[88:91]
	v_mfma_f32_16x16x32_bf16 v[80:83], v[238:241], v[206:209], v[80:83]
	v_mfma_f32_16x16x32_bf16 v[84:87], v[230:233], v[206:209], v[84:87]
	v_mfma_f32_16x16x32_bf16 v[76:79], v[230:233], v[214:217], v[76:79]
	v_mfma_f32_16x16x32_bf16 v[72:75], v[238:241], v[214:217], v[72:75]
	v_mfma_f32_16x16x32_bf16 v[64:67], v[238:241], v[222:225], v[64:67]
	v_mfma_f32_16x16x32_bf16 v[68:71], v[230:233], v[222:225], v[68:71]
	v_mfma_f32_16x16x32_bf16 v[92:95], v[234:237], v[202:205], v[92:95]
	v_mfma_f32_16x16x32_bf16 v[88:91], v[242:245], v[202:205], v[88:91]
	v_mfma_f32_16x16x32_bf16 v[80:83], v[242:245], v[210:213], v[80:83]
	v_mfma_f32_16x16x32_bf16 v[84:87], v[234:237], v[210:213], v[84:87]
	v_mfma_f32_16x16x32_bf16 v[76:79], v[234:237], v[218:221], v[76:79]
	v_mfma_f32_16x16x32_bf16 v[72:75], v[242:245], v[218:221], v[72:75]
	v_mfma_f32_16x16x32_bf16 v[64:67], v[242:245], v[226:229], v[64:67]
	v_mfma_f32_16x16x32_bf16 v[68:71], v[234:237], v[226:229], v[68:71]
	v_readfirstlane_b32 s9, v146
	v_add_u32_e32 v186, 0x2000, v146
	v_lshl_add_u64 v[250:251], v[178:179], 0, s[46:47]
	s_mov_b32 m0, s9
	v_readfirstlane_b32 s9, v186
	s_barrier
	ds_read_b128 v[198:201], v151 offset:16384
	ds_read_b128 v[202:205], v151 offset:17408
	ds_read_b128 v[206:209], v150 offset:16384
	ds_read_b128 v[210:213], v150 offset:17408
	ds_read_b128 v[214:217], v149 offset:16384
	ds_read_b128 v[218:221], v149 offset:17408
	ds_read_b128 v[222:225], v148 offset:16384
	ds_read_b128 v[226:229], v148 offset:17408
	global_load_lds_dwordx4 v[250:251], off
	v_lshl_add_u64 v[250:251], v[188:189], 0, s[46:47]
	s_mov_b32 m0, s9
	s_nop 0
	global_load_lds_dwordx4 v[250:251], off
	s_barrier
	s_waitcnt lgkmcnt(0)
	s_waitcnt lgkmcnt(0)
	v_mfma_f32_16x16x32_bf16 v[60:63], v[162:165], v[198:201], v[60:63]
	v_mfma_f32_16x16x32_bf16 v[56:59], v[170:173], v[198:201], v[56:59]
	v_mfma_f32_16x16x32_bf16 v[48:51], v[170:173], v[206:209], v[48:51]
	v_mfma_f32_16x16x32_bf16 v[52:55], v[162:165], v[206:209], v[52:55]
	v_mfma_f32_16x16x32_bf16 v[44:47], v[162:165], v[214:217], v[44:47]
	v_mfma_f32_16x16x32_bf16 v[40:43], v[170:173], v[214:217], v[40:43]
	v_mfma_f32_16x16x32_bf16 v[32:35], v[170:173], v[222:225], v[32:35]
	v_mfma_f32_16x16x32_bf16 v[36:39], v[162:165], v[222:225], v[36:39]
	v_mfma_f32_16x16x32_bf16 v[60:63], v[166:169], v[202:205], v[60:63]
	v_mfma_f32_16x16x32_bf16 v[56:59], v[174:177], v[202:205], v[56:59]
	v_mfma_f32_16x16x32_bf16 v[48:51], v[174:177], v[210:213], v[48:51]
	v_mfma_f32_16x16x32_bf16 v[52:55], v[166:169], v[210:213], v[52:55]
	v_mfma_f32_16x16x32_bf16 v[44:47], v[166:169], v[218:221], v[44:47]
	v_mfma_f32_16x16x32_bf16 v[40:43], v[174:177], v[218:221], v[40:43]
	v_mfma_f32_16x16x32_bf16 v[32:35], v[174:177], v[226:229], v[32:35]
	v_mfma_f32_16x16x32_bf16 v[36:39], v[166:169], v[226:229], v[36:39]
	s_barrier
; #define WAIT_V(n) asm volatile("s_waitcnt vmcnt(" #n ")" ::: "memory")
; #define WAIT_L(n) asm volatile("s_waitcnt lgkmcnt(" #n ")" ::: "memory")
; #define BAR __builtin_amdgcn_s_barrier()
; #define SCHED __builtin_amdgcn_sched_barrier(0)
; #define LDA(dst, b, h)                                                                            \
;   _Pragma("unroll") for (int m = 0; m < 4; ++m) _Pragma("unroll") for (int k = 0; k < 2; ++k)                                         \
;     dst[m][k] = *reinterpret_cast<const bf16x8*>((char*)SA(b, h) + lds_byte(wr * 64 + m * 16 + fr, k * 32 + fq * 8))
; #define LDB(dst, b, h)                                                                            \
;   _Pragma("unroll") for (int n = 0; n < 2; ++n) _Pragma("unroll") for (int k = 0; k < 2; ++k)                                         \
;     dst[n][k] = *reinterpret_cast<const bf16x8*>((char*)SB(b, h) + lds_byte(wc * 32 + n * 16 + fr, k * 32 + fq * 8))
; template <int K, bool SWAP>
; __device__ __forceinline__ void gemm_kloop(const bf16* __restrict__ A, const bf16* __restrict__ Bt,
;                                            f32x4 (&acc)[2][2][4][2], bool pref = false) {
;     ...
;     WAIT_V(6); BAR; MMA(1, 1, At, B1); BAR;
;     LDB(B0, 1, 0); SCHED; LDA(At, 1, 0); STAGE(SA(0, 1), A, HALF, t + 2);
;     WAIT_L(8); BAR; WAIT_L(0); MMA(0, 0, At, B0); BAR; SCHED;
;     LDB(B1, 1, 1); STAGE(SB(1, 0), Bt, 0, t + 3);
;     BAR; WAIT_L(0); MMA(0, 1, At, B1); BAR;
;     LDA(At, 1, 1); STAGE(SA(1, 0), A, 0, t + 3);
;     BAR; WAIT_L(0); MMA(1, 0, At, B0); BAR; SCHED;
	v_readfirstlane_b32 s9, v147
	v_add_u32_e32 v164, 0x2000, v147
	v_lshl_add_u64 v[162:163], v[246:247], 0, s[48:49]
	s_mov_b32 m0, s9
	v_readfirstlane_b32 s9, v164
	global_load_lds_dwordx4 v[162:163], off
	v_lshl_add_u64 v[162:163], v[248:249], 0, s[48:49]
	s_mov_b32 m0, s9
	s_nop 0
	global_load_lds_dwordx4 v[162:163], off
	s_waitcnt vmcnt(6)
	s_barrier
	v_mfma_f32_16x16x32_bf16 v[28:31], v[230:233], v[198:201], v[28:31]
	v_mfma_f32_16x16x32_bf16 v[24:27], v[238:241], v[198:201], v[24:27]
	v_mfma_f32_16x16x32_bf16 v[16:19], v[238:241], v[206:209], v[16:19]
	v_mfma_f32_16x16x32_bf16 v[20:23], v[230:233], v[206:209], v[20:23]
	v_mfma_f32_16x16x32_bf16 v[12:15], v[230:233], v[214:217], v[12:15]
	v_mfma_f32_16x16x32_bf16 v[8:11], v[238:241], v[214:217], v[8:11]
	v_mfma_f32_16x16x32_bf16 v[0:3], v[238:241], v[222:225], v[0:3]
	v_mfma_f32_16x16x32_bf16 v[4:7], v[230:233], v[222:225], v[4:7]
	v_mfma_f32_16x16x32_bf16 v[28:31], v[234:237], v[202:205], v[28:31]
	v_mfma_f32_16x16x32_bf16 v[24:27], v[242:245], v[202:205], v[24:27]
	v_mfma_f32_16x16x32_bf16 v[16:19], v[242:245], v[210:213], v[16:19]
	v_mfma_f32_16x16x32_bf16 v[20:23], v[234:237], v[210:213], v[20:23]
	v_mfma_f32_16x16x32_bf16 v[12:15], v[234:237], v[218:221], v[12:15]
	v_mfma_f32_16x16x32_bf16 v[8:11], v[242:245], v[218:221], v[8:11]
	v_mfma_f32_16x16x32_bf16 v[0:3], v[242:245], v[226:229], v[0:3]
	v_mfma_f32_16x16x32_bf16 v[4:7], v[234:237], v[226:229], v[4:7]
	s_barrier
	ds_read_b128 v[162:165], v153
	ds_read_b128 v[166:169], v153 offset:1024
	ds_read_b128 v[170:173], v153 offset:2048
	ds_read_b128 v[174:177], v153 offset:3072
	v_add_u32_e32 v186, 0x4000, v146
	v_lshl_add_u64 v[230:231], v[178:179], 0, s[50:51]
	v_readfirstlane_b32 s9, v186
	v_add_u32_e32 v186, 0x6000, v146
	s_mov_b32 m0, s9
	v_readfirstlane_b32 s9, v186
	ds_read_b128 v[198:201], v151 offset:32768
	ds_read_b128 v[202:205], v151 offset:33792
	ds_read_b128 v[206:209], v150 offset:32768
	ds_read_b128 v[210:213], v150 offset:33792
	ds_read_b128 v[214:217], v149 offset:32768
	ds_read_b128 v[218:221], v149 offset:33792
	ds_read_b128 v[222:225], v148 offset:32768
	ds_read_b128 v[226:229], v148 offset:33792
	global_load_lds_dwordx4 v[230:231], off
	v_lshl_add_u64 v[230:231], v[188:189], 0, s[50:51]
	s_mov_b32 m0, s9
	s_nop 0
	global_load_lds_dwordx4 v[230:231], off
	s_waitcnt lgkmcnt(8)
	s_barrier
	s_waitcnt lgkmcnt(0)
	s_waitcnt lgkmcnt(0)
	v_mfma_f32_16x16x32_bf16 v[124:127], v[162:165], v[198:201], v[124:127]
	v_mfma_f32_16x16x32_bf16 v[120:123], v[170:173], v[198:201], v[120:123]
	v_mfma_f32_16x16x32_bf16 v[112:115], v[170:173], v[206:209], v[112:115]
	v_mfma_f32_16x16x32_bf16 v[116:119], v[162:165], v[206:209], v[116:119]
	v_mfma_f32_16x16x32_bf16 v[108:111], v[162:165], v[214:217], v[108:111]
	v_mfma_f32_16x16x32_bf16 v[104:107], v[170:173], v[214:217], v[104:107]
	v_mfma_f32_16x16x32_bf16 v[96:99], v[170:173], v[222:225], v[96:99]
	v_mfma_f32_16x16x32_bf16 v[100:103], v[162:165], v[222:225], v[100:103]
	v_mfma_f32_16x16x32_bf16 v[124:127], v[166:169], v[202:205], v[124:127]
	v_mfma_f32_16x16x32_bf16 v[120:123], v[174:177], v[202:205], v[120:123]
	v_mfma_f32_16x16x32_bf16 v[112:115], v[174:177], v[210:213], v[112:115]
	v_mfma_f32_16x16x32_bf16 v[116:119], v[166:169], v[210:213], v[116:119]
	v_mfma_f32_16x16x32_bf16 v[108:111], v[166:169], v[218:221], v[108:111]
	v_mfma_f32_16x16x32_bf16 v[104:107], v[174:177], v[218:221], v[104:107]
	v_mfma_f32_16x16x32_bf16 v[96:99], v[174:177], v[226:229], v[96:99]
	v_mfma_f32_16x16x32_bf16 v[100:103], v[166:169], v[226:229], v[100:103]
	s_barrier
	v_readfirstlane_b32 s9, v154
	v_add_u32_e32 v186, 0x2000, v154
	v_lshl_add_u64 v[250:251], v[246:247], 0, s[52:53]
	s_mov_b32 m0, s9
	v_readfirstlane_b32 s9, v186
	ds_read_b128 v[230:233], v152
	ds_read_b128 v[234:237], v152 offset:1024
	ds_read_b128 v[238:241], v152 offset:2048
	ds_read_b128 v[242:245], v152 offset:3072
	global_load_lds_dwordx4 v[250:251], off
	v_lshl_add_u64 v[250:251], v[248:249], 0, s[52:53]
	s_mov_b32 m0, s9
	s_nop 0
	global_load_lds_dwordx4 v[250:251], off
	s_barrier
	s_waitcnt lgkmcnt(0)
	s_waitcnt lgkmcnt(0)
	v_mfma_f32_16x16x32_bf16 v[92:95], v[230:233], v[198:201], v[92:95]
	v_mfma_f32_16x16x32_bf16 v[88:91], v[238:241], v[198:201], v[88:91]
	v_mfma_f32_16x16x32_bf16 v[80:83], v[238:241], v[206:209], v[80:83]
	v_mfma_f32_16x16x32_bf16 v[84:87], v[230:233], v[206:209], v[84:87]
	v_mfma_f32_16x16x32_bf16 v[76:79], v[230:233], v[214:217], v[76:79]
	v_mfma_f32_16x16x32_bf16 v[72:75], v[238:241], v[214:217], v[72:75]
	v_mfma_f32_16x16x32_bf16 v[64:67], v[238:241], v[222:225], v[64:67]
	v_mfma_f32_16x16x32_bf16 v[68:71], v[230:233], v[222:225], v[68:71]
	v_mfma_f32_16x16x32_bf16 v[92:95], v[234:237], v[202:205], v[92:95]
	v_mfma_f32_16x16x32_bf16 v[88:91], v[242:245], v[202:205], v[88:91]
	v_mfma_f32_16x16x32_bf16 v[80:83], v[242:245], v[210:213], v[80:83]
	v_mfma_f32_16x16x32_bf16 v[84:87], v[234:237], v[210:213], v[84:87]
	v_mfma_f32_16x16x32_bf16 v[76:79], v[234:237], v[218:221], v[76:79]
	v_mfma_f32_16x16x32_bf16 v[72:75], v[242:245], v[218:221], v[72:75]
	v_mfma_f32_16x16x32_bf16 v[64:67], v[242:245], v[226:229], v[64:67]
	v_mfma_f32_16x16x32_bf16 v[68:71], v[234:237], v[226:229], v[68:71]
	v_readfirstlane_b32 s9, v155
	v_lshl_add_u64 v[178:179], v[178:179], 0, s[54:55]
	s_mov_b32 m0, s9
	v_readfirstlane_b32 s9, v156
	s_barrier
	ds_read_b128 v[198:201], v151 offset:49152
	ds_read_b128 v[202:205], v151 offset:50176
	ds_read_b128 v[206:209], v150 offset:49152
	ds_read_b128 v[210:213], v150 offset:50176
	ds_read_b128 v[214:217], v149 offset:49152
	ds_read_b128 v[218:221], v149 offset:50176
	ds_read_b128 v[222:225], v148 offset:49152
	ds_read_b128 v[226:229], v148 offset:50176
	global_load_lds_dwordx4 v[178:179], off
	v_lshl_add_u64 v[178:179], v[188:189], 0, s[54:55]
	s_mov_b32 m0, s9
	s_nop 0
	global_load_lds_dwordx4 v[178:179], off
	s_barrier
; #define WAIT_V(n) asm volatile("s_waitcnt vmcnt(" #n ")" ::: "memory")
; #define WAIT_L(n) asm volatile("s_waitcnt lgkmcnt(" #n ")" ::: "memory")
; #define BAR __builtin_amdgcn_s_barrier()
; #define SCHED __builtin_amdgcn_sched_barrier(0)
; #define LDA(dst, b, h)                                                                            \
;   _Pragma("unroll") for (int m = 0; m < 4; ++m) _Pragma("unroll") for (int k = 0; k < 2; ++k)                                         \
;     dst[m][k] = *reinterpret_cast<const bf16x8*>((char*)SA(b, h) + lds_byte(wr * 64 + m * 16 + fr, k * 32 + fq * 8))
; #define LDB(dst, b, h)                                                                            \
;   _Pragma("unroll") for (int n = 0; n < 2; ++n) _Pragma("unroll") for (int k = 0; k < 2; ++k)                                         \
;     dst[n][k] = *reinterpret_cast<const bf16x8*>((char*)SB(b, h) + lds_byte(wc * 32 + n * 16 + fr, k * 32 + fq * 8))
; template <int K, bool SWAP>
; __device__ __forceinline__ void gemm_kloop(const bf16* __restrict__ A, const bf16* __restrict__ Bt,
;                                            f32x4 (&acc)[2][2][4][2], bool pref = false) {
;     ...
;     BAR; WAIT_L(0); MMA(1, 0, At, B0); BAR; SCHED;
;     STAGE(SB(1, 1), Bt, HALF, t + 3);
;     WAIT_V(6); BAR; MMA(1, 1, At, B1); BAR;
;   }
;   { LDB(B0, 0, 0); LDA(At, 0, 0); STAGE(SA(1, 1), A, HALF, nt - 1);
;     BAR; WAIT_L(0); MMA(0, 0, At, B0); BAR;
;     LDB(B1, 0, 1); BAR; WAIT_L(0); MMA(0, 1, At, B1); BAR;
;     LDA(At, 0, 1); WAIT_V(4); BAR; WAIT_L(0); MMA(1, 0, At, B0); MMA(1, 1, At, B1); BAR; }
	s_waitcnt lgkmcnt(0)
	s_waitcnt lgkmcnt(0)
	v_mfma_f32_16x16x32_bf16 v[60:63], v[162:165], v[198:201], v[60:63]
	v_mfma_f32_16x16x32_bf16 v[56:59], v[170:173], v[198:201], v[56:59]
	v_mfma_f32_16x16x32_bf16 v[48:51], v[170:173], v[206:209], v[48:51]
	v_mfma_f32_16x16x32_bf16 v[52:55], v[162:165], v[206:209], v[52:55]
	v_mfma_f32_16x16x32_bf16 v[44:47], v[162:165], v[214:217], v[44:47]
	v_mfma_f32_16x16x32_bf16 v[40:43], v[170:173], v[214:217], v[40:43]
	v_mfma_f32_16x16x32_bf16 v[32:35], v[170:173], v[222:225], v[32:35]
	v_mfma_f32_16x16x32_bf16 v[36:39], v[162:165], v[222:225], v[36:39]
	v_mfma_f32_16x16x32_bf16 v[60:63], v[166:169], v[202:205], v[60:63]
	v_mfma_f32_16x16x32_bf16 v[56:59], v[174:177], v[202:205], v[56:59]
	v_mfma_f32_16x16x32_bf16 v[48:51], v[174:177], v[210:213], v[48:51]
	v_mfma_f32_16x16x32_bf16 v[52:55], v[166:169], v[210:213], v[52:55]
	v_mfma_f32_16x16x32_bf16 v[44:47], v[166:169], v[218:221], v[44:47]
	v_mfma_f32_16x16x32_bf16 v[40:43], v[174:177], v[218:221], v[40:43]
	v_mfma_f32_16x16x32_bf16 v[32:35], v[174:177], v[226:229], v[32:35]
	v_mfma_f32_16x16x32_bf16 v[36:39], v[166:169], v[226:229], v[36:39]
	s_barrier
	v_readfirstlane_b32 s9, v157
	v_add_u32_e32 v164, 0x2000, v157
	v_lshl_add_u64 v[162:163], v[246:247], 0, s[56:57]
	s_mov_b32 m0, s9
	v_readfirstlane_b32 s9, v164
	global_load_lds_dwordx4 v[162:163], off
	v_lshl_add_u64 v[162:163], v[248:249], 0, s[56:57]
	s_mov_b32 m0, s9
	s_nop 0
	global_load_lds_dwordx4 v[162:163], off
	s_waitcnt vmcnt(6)
	s_barrier
	v_mfma_f32_16x16x32_bf16 v[28:31], v[230:233], v[198:201], v[28:31]
	v_mfma_f32_16x16x32_bf16 v[24:27], v[238:241], v[198:201], v[24:27]
	v_mfma_f32_16x16x32_bf16 v[16:19], v[238:241], v[206:209], v[16:19]
	v_mfma_f32_16x16x32_bf16 v[20:23], v[230:233], v[206:209], v[20:23]
	v_mfma_f32_16x16x32_bf16 v[12:15], v[230:233], v[214:217], v[12:15]
	v_mfma_f32_16x16x32_bf16 v[8:11], v[238:241], v[214:217], v[8:11]
	v_mfma_f32_16x16x32_bf16 v[0:3], v[238:241], v[222:225], v[0:3]
	v_mfma_f32_16x16x32_bf16 v[4:7], v[230:233], v[222:225], v[4:7]
	v_mfma_f32_16x16x32_bf16 v[28:31], v[234:237], v[202:205], v[28:31]
	v_mfma_f32_16x16x32_bf16 v[24:27], v[242:245], v[202:205], v[24:27]
	v_mfma_f32_16x16x32_bf16 v[16:19], v[242:245], v[210:213], v[16:19]
	v_mfma_f32_16x16x32_bf16 v[20:23], v[234:237], v[210:213], v[20:23]
	v_mfma_f32_16x16x32_bf16 v[12:15], v[234:237], v[218:221], v[12:15]
	v_mfma_f32_16x16x32_bf16 v[8:11], v[242:245], v[218:221], v[8:11]
	v_mfma_f32_16x16x32_bf16 v[0:3], v[242:245], v[226:229], v[0:3]
	v_mfma_f32_16x16x32_bf16 v[4:7], v[234:237], v[226:229], v[4:7]
	s_add_i32 s8, s8, 2
	v_lshl_add_u64 v[136:137], v[136:137], 0, s[44:45]
	v_lshl_add_u64 v[138:139], v[138:139], 0, s[44:45]
	v_lshl_add_u64 v[140:141], v[140:141], 0, s[44:45]
	s_cmp_lt_u32 s8, 12
	v_lshl_add_u64 v[142:143], v[142:143], 0, s[44:45]
	s_barrier
	s_cbranch_scc1 .LBB0_527
	s_add_u32 s0, s0, 0x40780
	s_addc_u32 s1, s1, 0
	v_lshl_add_u64 v[130:131], s[0:1], 0, v[130:131]
	v_readfirstlane_b32 s8, v160
	v_lshl_add_u64 v[128:129], v[128:129], 1, v[130:131]
	s_mov_b32 m0, s8
	ds_read_b128 v[136:139], v159
	ds_read_b128 v[140:143], v159 offset:1024
	ds_read_b128 v[154:157], v159 offset:2048
	ds_read_b128 v[162:165], v159 offset:3072
	ds_read_b128 v[166:169], v151
	ds_read_b128 v[170:173], v151 offset:1024
	ds_read_b128 v[174:177], v150
	ds_read_b128 v[198:201], v150 offset:1024
	ds_read_b128 v[202:205], v149
	ds_read_b128 v[206:209], v149 offset:1024
	ds_read_b128 v[210:213], v148
	ds_read_b128 v[214:217], v148 offset:1024
	global_load_lds_dwordx4 v[128:129], off
	v_lshl_add_u64 v[128:129], s[0:1], 0, v[134:135]
	v_readfirstlane_b32 s0, v161
	v_lshl_add_u64 v[128:129], v[132:133], 1, v[128:129]
	s_mov_b32 m0, s0
	s_nop 0
	global_load_lds_dwordx4 v[128:129], off
	s_barrier
	s_waitcnt lgkmcnt(0)
	s_waitcnt lgkmcnt(0)
	v_mfma_f32_16x16x32_bf16 v[124:127], v[136:139], v[166:169], v[124:127]
	v_mfma_f32_16x16x32_bf16 v[120:123], v[154:157], v[166:169], v[120:123]
	v_mfma_f32_16x16x32_bf16 v[112:115], v[154:157], v[174:177], v[112:115]
	v_mfma_f32_16x16x32_bf16 v[116:119], v[136:139], v[174:177], v[116:119]
	v_mfma_f32_16x16x32_bf16 v[108:111], v[136:139], v[202:205], v[108:111]
	v_mfma_f32_16x16x32_bf16 v[104:107], v[154:157], v[202:205], v[104:107]
	v_mfma_f32_16x16x32_bf16 v[96:99], v[154:157], v[210:213], v[96:99]
	v_mfma_f32_16x16x32_bf16 v[100:103], v[136:139], v[210:213], v[100:103]
	v_mfma_f32_16x16x32_bf16 v[124:127], v[140:143], v[170:173], v[124:127]
	v_mfma_f32_16x16x32_bf16 v[120:123], v[162:165], v[170:173], v[120:123]
	v_mfma_f32_16x16x32_bf16 v[112:115], v[162:165], v[198:201], v[112:115]
	v_mfma_f32_16x16x32_bf16 v[116:119], v[140:143], v[198:201], v[116:119]
	v_mfma_f32_16x16x32_bf16 v[108:111], v[140:143], v[206:209], v[108:111]
	v_mfma_f32_16x16x32_bf16 v[104:107], v[162:165], v[206:209], v[104:107]
	v_mfma_f32_16x16x32_bf16 v[96:99], v[162:165], v[214:217], v[96:99]
	v_mfma_f32_16x16x32_bf16 v[100:103], v[140:143], v[214:217], v[100:103]
	s_barrier
	ds_read_b128 v[128:131], v158
	ds_read_b128 v[132:135], v158 offset:1024
	ds_read_b128 v[218:221], v158 offset:2048
	ds_read_b128 v[158:161], v158 offset:3072
	s_barrier
; #define WAIT_V(n) asm volatile("s_waitcnt vmcnt(" #n ")" ::: "memory")
; #define WAIT_L(n) asm volatile("s_waitcnt lgkmcnt(" #n ")" ::: "memory")
; #define BAR __builtin_amdgcn_s_barrier()
; #define LDA(dst, b, h)                                                                            \
;   _Pragma("unroll") for (int m = 0; m < 4; ++m) _Pragma("unroll") for (int k = 0; k < 2; ++k)                                         \
;     dst[m][k] = *reinterpret_cast<const bf16x8*>((char*)SA(b, h) + lds_byte(wr * 64 + m * 16 + fr, k * 32 + fq * 8))
; #define LDB(dst, b, h)                                                                            \
;   _Pragma("unroll") for (int n = 0; n < 2; ++n) _Pragma("unroll") for (int k = 0; k < 2; ++k)                                         \
;     dst[n][k] = *reinterpret_cast<const bf16x8*>((char*)SB(b, h) + lds_byte(wc * 32 + n * 16 + fr, k * 32 + fq * 8))
; template <int K, bool SWAP>
; __device__ __forceinline__ void gemm_kloop(const bf16* __restrict__ A, const bf16* __restrict__ Bt,
;                                            f32x4 (&acc)[2][2][4][2], bool pref = false) {
;     ...
;     LDB(B1, 0, 1); BAR; WAIT_L(0); MMA(0, 1, At, B1); BAR;
;     LDA(At, 0, 1); WAIT_V(4); BAR; WAIT_L(0); MMA(1, 0, At, B0); MMA(1, 1, At, B1); BAR; }
;   { LDB(B0, 1, 0); LDA(At, 1, 0); WAIT_V(2); BAR; WAIT_L(0); MMA(0, 0, At, B0); BAR;
;     LDB(B1, 1, 1); WAIT_V(0); BAR; WAIT_L(0); MMA(0, 1, At, B1); BAR;
	s_waitcnt lgkmcnt(0)
	s_waitcnt lgkmcnt(0)
	v_mfma_f32_16x16x32_bf16 v[92:95], v[128:131], v[166:169], v[92:95]
	v_mfma_f32_16x16x32_bf16 v[88:91], v[218:221], v[166:169], v[88:91]
	v_mfma_f32_16x16x32_bf16 v[80:83], v[218:221], v[174:177], v[80:83]
	v_mfma_f32_16x16x32_bf16 v[76:79], v[128:131], v[202:205], v[76:79]
	v_mfma_f32_16x16x32_bf16 v[92:95], v[132:135], v[170:173], v[92:95]
	v_mfma_f32_16x16x32_bf16 v[88:91], v[158:161], v[170:173], v[88:91]
	v_mfma_f32_16x16x32_bf16 v[84:87], v[128:131], v[174:177], v[84:87]
	v_mfma_f32_16x16x32_bf16 v[80:83], v[158:161], v[198:201], v[80:83]
	v_mfma_f32_16x16x32_bf16 v[76:79], v[132:135], v[206:209], v[76:79]
	v_mfma_f32_16x16x32_bf16 v[72:75], v[218:221], v[202:205], v[72:75]
	v_mfma_f32_16x16x32_bf16 v[68:71], v[128:131], v[210:213], v[68:71]
	v_mfma_f32_16x16x32_bf16 v[64:67], v[218:221], v[210:213], v[64:67]
	v_mfma_f32_16x16x32_bf16 v[166:169], v[132:135], v[198:201], v[84:87]
	v_mfma_f32_16x16x32_bf16 v[170:173], v[158:161], v[206:209], v[72:75]
	v_mfma_f32_16x16x32_bf16 v[174:177], v[132:135], v[214:217], v[68:71]
	v_mfma_f32_16x16x32_bf16 v[198:201], v[158:161], v[214:217], v[64:67]
	s_barrier
	s_nop 1
	ds_read_b128 v[64:67], v151 offset:16384
	ds_read_b128 v[68:71], v151 offset:17408
	ds_read_b128 v[72:75], v150 offset:16384
	ds_read_b128 v[84:87], v150 offset:17408
	ds_read_b128 v[202:205], v149 offset:16384
	ds_read_b128 v[206:209], v149 offset:17408
	ds_read_b128 v[210:213], v148 offset:16384
	ds_read_b128 v[214:217], v148 offset:17408
	s_waitcnt vmcnt(4)
	s_barrier
	s_waitcnt lgkmcnt(0)
	s_waitcnt lgkmcnt(0)
	v_mfma_f32_16x16x32_bf16 v[60:63], v[136:139], v[64:67], v[60:63]
	v_mfma_f32_16x16x32_bf16 v[52:55], v[136:139], v[72:75], v[52:55]
	v_mfma_f32_16x16x32_bf16 v[40:43], v[154:157], v[202:205], v[40:43]
	v_mfma_f32_16x16x32_bf16 v[60:63], v[140:143], v[68:71], v[60:63]
	v_mfma_f32_16x16x32_bf16 v[56:59], v[154:157], v[64:67], v[56:59]
	v_mfma_f32_16x16x32_bf16 v[52:55], v[140:143], v[84:87], v[52:55]
	v_mfma_f32_16x16x32_bf16 v[48:51], v[154:157], v[72:75], v[48:51]
	v_mfma_f32_16x16x32_bf16 v[44:47], v[136:139], v[202:205], v[44:47]
	v_mfma_f32_16x16x32_bf16 v[40:43], v[162:165], v[206:209], v[40:43]
	v_mfma_f32_16x16x32_bf16 v[36:39], v[136:139], v[210:213], v[36:39]
	v_mfma_f32_16x16x32_bf16 v[32:35], v[154:157], v[210:213], v[32:35]
	v_mfma_f32_16x16x32_bf16 v[222:225], v[162:165], v[68:71], v[56:59]
	v_mfma_f32_16x16x32_bf16 v[226:229], v[162:165], v[84:87], v[48:51]
	v_mfma_f32_16x16x32_bf16 v[230:233], v[140:143], v[206:209], v[44:47]
	v_mfma_f32_16x16x32_bf16 v[136:139], v[140:143], v[214:217], v[36:39]
	v_mfma_f32_16x16x32_bf16 v[140:143], v[162:165], v[214:217], v[32:35]
	v_mfma_f32_16x16x32_bf16 v[20:23], v[128:131], v[72:75], v[20:23]
	v_mfma_f32_16x16x32_bf16 v[0:3], v[218:221], v[210:213], v[0:3]
	v_mfma_f32_16x16x32_bf16 v[28:31], v[128:131], v[64:67], v[28:31]
	v_mfma_f32_16x16x32_bf16 v[24:27], v[218:221], v[64:67], v[24:27]
	v_mfma_f32_16x16x32_bf16 v[20:23], v[132:135], v[84:87], v[20:23]
	v_mfma_f32_16x16x32_bf16 v[16:19], v[218:221], v[72:75], v[16:19]
	v_mfma_f32_16x16x32_bf16 v[12:15], v[128:131], v[202:205], v[12:15]
	v_mfma_f32_16x16x32_bf16 v[8:11], v[218:221], v[202:205], v[8:11]
	v_mfma_f32_16x16x32_bf16 v[4:7], v[128:131], v[210:213], v[4:7]
	v_mfma_f32_16x16x32_bf16 v[0:3], v[158:161], v[214:217], v[0:3]
	v_mfma_f32_16x16x32_bf16 v[154:157], v[132:135], v[68:71], v[28:31]
	v_mfma_f32_16x16x32_bf16 v[162:165], v[158:161], v[68:71], v[24:27]
	v_mfma_f32_16x16x32_bf16 v[234:237], v[158:161], v[84:87], v[16:19]
	v_mfma_f32_16x16x32_bf16 v[238:241], v[132:135], v[206:209], v[12:15]
	v_mfma_f32_16x16x32_bf16 v[202:205], v[158:161], v[206:209], v[8:11]
	v_mfma_f32_16x16x32_bf16 v[128:131], v[132:135], v[214:217], v[4:7]
	s_barrier
	s_nop 0
	ds_read_b128 v[4:7], v153
	ds_read_b128 v[8:11], v153 offset:1024
	ds_read_b128 v[12:15], v153 offset:2048
	ds_read_b128 v[16:19], v153 offset:3072
	ds_read_b128 v[24:27], v151 offset:32768
	ds_read_b128 v[28:31], v151 offset:33792
	ds_read_b128 v[32:35], v150 offset:32768
	ds_read_b128 v[36:39], v150 offset:33792
	ds_read_b128 v[44:47], v149 offset:32768
	ds_read_b128 v[132:135], v149 offset:33792
	ds_read_b128 v[158:161], v148 offset:32768
	ds_read_b128 v[206:209], v148 offset:33792
	s_waitcnt vmcnt(2)
	s_barrier
; #define WAIT_V(n) asm volatile("s_waitcnt vmcnt(" #n ")" ::: "memory")
; #define WAIT_L(n) asm volatile("s_waitcnt lgkmcnt(" #n ")" ::: "memory")
; #define BAR __builtin_amdgcn_s_barrier()
; #define SCHED __builtin_amdgcn_sched_barrier(0)
; #define LDA(dst, b, h)                                                                            \
;   _Pragma("unroll") for (int m = 0; m < 4; ++m) _Pragma("unroll") for (int k = 0; k < 2; ++k)                                         \
;     dst[m][k] = *reinterpret_cast<const bf16x8*>((char*)SA(b, h) + lds_byte(wr * 64 + m * 16 + fr, k * 32 + fq * 8))
; #define LDB(dst, b, h)                                                                            \
;   _Pragma("unroll") for (int n = 0; n < 2; ++n) _Pragma("unroll") for (int k = 0; k < 2; ++k)                                         \
;     dst[n][k] = *reinterpret_cast<const bf16x8*>((char*)SB(b, h) + lds_byte(wc * 32 + n * 16 + fr, k * 32 + fq * 8))
; template <int K, bool SWAP>
; __device__ __forceinline__ void gemm_kloop(const bf16* __restrict__ A, const bf16* __restrict__ Bt,
;                                            f32x4 (&acc)[2][2][4][2], bool pref = false) {
;     ...
;   { LDB(B0, 1, 0); LDA(At, 1, 0); WAIT_V(2); BAR; WAIT_L(0); MMA(0, 0, At, B0); BAR;
;     LDB(B1, 1, 1); WAIT_V(0); BAR; WAIT_L(0); MMA(0, 1, At, B1); BAR;
;     LDA(At, 1, 1); BAR; WAIT_L(0); MMA(1, 0, At, B0); MMA(1, 1, At, B1); BAR; }
;   if (wr == 0) BAR;
;   SCHED;
	s_waitcnt lgkmcnt(0)
	s_waitcnt lgkmcnt(0)
	v_mfma_f32_16x16x32_bf16 v[48:51], v[4:7], v[24:27], v[124:127]
	v_mfma_f32_16x16x32_bf16 v[124:127], v[8:11], v[28:31], v[48:51]
	v_mfma_f32_16x16x32_bf16 v[48:51], v[12:15], v[24:27], v[120:123]
	v_mfma_f32_16x16x32_bf16 v[84:87], v[16:19], v[28:31], v[48:51]
	v_mfma_f32_16x16x32_bf16 v[48:51], v[4:7], v[32:35], v[116:119]
	v_mfma_f32_16x16x32_bf16 v[120:123], v[8:11], v[36:39], v[48:51]
	v_mfma_f32_16x16x32_bf16 v[48:51], v[12:15], v[32:35], v[112:115]
	v_mfma_f32_16x16x32_bf16 v[72:75], v[16:19], v[36:39], v[48:51]
	v_mfma_f32_16x16x32_bf16 v[48:51], v[4:7], v[44:47], v[108:111]
	v_mfma_f32_16x16x32_bf16 v[112:115], v[8:11], v[132:135], v[48:51]
	v_mfma_f32_16x16x32_bf16 v[48:51], v[12:15], v[44:47], v[104:107]
	v_mfma_f32_16x16x32_bf16 v[68:71], v[16:19], v[132:135], v[48:51]
	v_mfma_f32_16x16x32_bf16 v[48:51], v[4:7], v[158:161], v[100:103]
	v_mfma_f32_16x16x32_bf16 v[104:107], v[8:11], v[206:209], v[48:51]
	v_mfma_f32_16x16x32_bf16 v[48:51], v[12:15], v[158:161], v[96:99]
	v_mfma_f32_16x16x32_bf16 v[64:67], v[16:19], v[206:209], v[48:51]
	s_barrier
	ds_read_b128 v[210:213], v152
	ds_read_b128 v[214:217], v152 offset:1024
	ds_read_b128 v[218:221], v152 offset:2048
	ds_read_b128 v[242:245], v152 offset:3072
	s_waitcnt vmcnt(0)
	s_barrier
	s_waitcnt lgkmcnt(0)
	s_waitcnt lgkmcnt(0)
	v_mfma_f32_16x16x32_bf16 v[48:51], v[210:213], v[24:27], v[92:95]
	v_mfma_f32_16x16x32_bf16 v[24:27], v[218:221], v[24:27], v[88:91]
	v_mfma_f32_16x16x32_bf16 v[56:59], v[242:245], v[28:31], v[24:27]
	v_mfma_f32_16x16x32_bf16 v[24:27], v[210:213], v[32:35], v[166:169]
	v_mfma_f32_16x16x32_bf16 v[108:111], v[214:217], v[36:39], v[24:27]
	v_mfma_f32_16x16x32_bf16 v[24:27], v[218:221], v[32:35], v[80:83]
	v_mfma_f32_16x16x32_bf16 v[116:119], v[214:217], v[28:31], v[48:51]
	v_mfma_f32_16x16x32_bf16 v[48:51], v[242:245], v[36:39], v[24:27]
	v_mfma_f32_16x16x32_bf16 v[24:27], v[210:213], v[44:47], v[76:79]
	v_mfma_f32_16x16x32_bf16 v[100:103], v[214:217], v[132:135], v[24:27]
	v_mfma_f32_16x16x32_bf16 v[24:27], v[218:221], v[44:47], v[170:173]
	v_mfma_f32_16x16x32_bf16 v[44:47], v[242:245], v[132:135], v[24:27]
	v_mfma_f32_16x16x32_bf16 v[24:27], v[210:213], v[158:161], v[174:177]
	v_mfma_f32_16x16x32_bf16 v[96:99], v[214:217], v[206:209], v[24:27]
	v_mfma_f32_16x16x32_bf16 v[24:27], v[218:221], v[158:161], v[198:201]
	v_mfma_f32_16x16x32_bf16 v[36:39], v[242:245], v[206:209], v[24:27]
	s_barrier
	ds_read_b128 v[132:135], v151 offset:49152
	ds_read_b128 v[158:161], v151 offset:50176
	ds_read_b128 v[166:169], v150 offset:49152
	ds_read_b128 v[150:153], v150 offset:50176
	ds_read_b128 v[170:173], v149 offset:49152
	ds_read_b128 v[174:177], v149 offset:50176
	ds_read_b128 v[198:201], v148 offset:49152
	ds_read_b128 v[146:149], v148 offset:50176
	s_barrier
	s_waitcnt lgkmcnt(0)
	s_waitcnt lgkmcnt(0)
	v_mfma_f32_16x16x32_bf16 v[24:27], v[4:7], v[132:135], v[60:63]
	v_mfma_f32_16x16x32_bf16 v[92:95], v[8:11], v[158:161], v[24:27]
	v_mfma_f32_16x16x32_bf16 v[24:27], v[12:15], v[132:135], v[222:225]
	v_mfma_f32_16x16x32_bf16 v[32:35], v[16:19], v[158:161], v[24:27]
	v_mfma_f32_16x16x32_bf16 v[24:27], v[4:7], v[166:169], v[52:55]
	v_mfma_f32_16x16x32_bf16 v[88:91], v[8:11], v[150:153], v[24:27]
	v_mfma_f32_16x16x32_bf16 v[24:27], v[12:15], v[166:169], v[226:229]
	v_mfma_f32_16x16x32_bf16 v[28:31], v[16:19], v[150:153], v[24:27]
	v_mfma_f32_16x16x32_bf16 v[24:27], v[4:7], v[170:173], v[230:233]
	v_mfma_f32_16x16x32_bf16 v[4:7], v[4:7], v[198:201], v[136:139]
	v_mfma_f32_16x16x32_bf16 v[76:79], v[8:11], v[174:177], v[24:27]
	v_mfma_f32_16x16x32_bf16 v[24:27], v[12:15], v[170:173], v[40:43]
	v_mfma_f32_16x16x32_bf16 v[52:55], v[8:11], v[146:149], v[4:7]
	v_mfma_f32_16x16x32_bf16 v[4:7], v[12:15], v[198:201], v[140:143]
	v_mfma_f32_16x16x32_bf16 v[24:27], v[16:19], v[174:177], v[24:27]
	v_mfma_f32_16x16x32_bf16 v[16:19], v[16:19], v[146:149], v[4:7]
	v_mfma_f32_16x16x32_bf16 v[4:7], v[210:213], v[132:135], v[154:157]
	v_mfma_f32_16x16x32_bf16 v[80:83], v[214:217], v[158:161], v[4:7]
	v_mfma_f32_16x16x32_bf16 v[4:7], v[218:221], v[132:135], v[162:165]
	v_mfma_f32_16x16x32_bf16 v[12:15], v[242:245], v[158:161], v[4:7]
	v_mfma_f32_16x16x32_bf16 v[4:7], v[210:213], v[166:169], v[20:23]
	v_mfma_f32_16x16x32_bf16 v[60:63], v[214:217], v[150:153], v[4:7]
	v_mfma_f32_16x16x32_bf16 v[4:7], v[218:221], v[166:169], v[234:237]
	v_mfma_f32_16x16x32_bf16 v[8:11], v[242:245], v[150:153], v[4:7]
	v_mfma_f32_16x16x32_bf16 v[4:7], v[210:213], v[170:173], v[238:241]
	v_mfma_f32_16x16x32_bf16 v[40:43], v[214:217], v[174:177], v[4:7]
	v_mfma_f32_16x16x32_bf16 v[4:7], v[218:221], v[170:173], v[202:205]
	v_mfma_f32_16x16x32_bf16 v[20:23], v[210:213], v[198:201], v[128:131]
	v_mfma_f32_16x16x32_bf16 v[0:3], v[218:221], v[198:201], v[0:3]
	v_mfma_f32_16x16x32_bf16 v[4:7], v[242:245], v[174:177], v[4:7]
	v_mfma_f32_16x16x32_bf16 v[20:23], v[214:217], v[146:149], v[20:23]
	v_mfma_f32_16x16x32_bf16 v[0:3], v[242:245], v[146:149], v[0:3]
	s_movk_i32 s0, 0x100
	v_cmp_gt_u32_e32 vcc, s0, v144
	s_barrier
	s_and_saveexec_b64 s[0:1], vcc
	s_cbranch_execz .LBB0_530
	s_barrier

; #define WAIT_V(n) asm volatile("s_waitcnt vmcnt(" #n ")" ::: "memory")
; #define WAIT_L(n) asm volatile("s_waitcnt lgkmcnt(" #n ")" ::: "memory")
; #define BAR __builtin_amdgcn_s_barrier()
; #define SCHED __builtin_amdgcn_sched_barrier(0)
; #define LDA(dst, b, h)                                                                            \
;   _Pragma("unroll") for (int m = 0; m < 4; ++m) _Pragma("unroll") for (int k = 0; k < 2; ++k)                                         \
;     dst[m][k] = *reinterpret_cast<const bf16x8*>((char*)SA(b, h) + lds_byte(wr * 64 + m * 16 + fr, k * 32 + fq * 8))
; #define LDB(dst, b, h)                                                                            \
;   _Pragma("unroll") for (int n = 0; n < 2; ++n) _Pragma("unroll") for (int k = 0; k < 2; ++k)                                         \
;     dst[n][k] = *reinterpret_cast<const bf16x8*>((char*)SB(b, h) + lds_byte(wc * 32 + n * 16 + fr, k * 32 + fq * 8))
; template <int K, bool SWAP>
; __device__ __forceinline__ void gemm_kloop(const bf16* __restrict__ A, const bf16* __restrict__ Bt,
;                                            f32x4 (&acc)[2][2][4][2], bool pref = false) {
;     ...
;     LDB(B0, 0, 0); SCHED; LDA(At, 0, 0); STAGE(SA(1, 1), A, HALF, t + 1);
;     WAIT_L(8); BAR; WAIT_L(0); MMA(0, 0, At, B0); BAR; SCHED;
;     LDB(B1, 0, 1); STAGE(SB(0, 0), Bt, 0, t + 2);
;     BAR; WAIT_L(0); MMA(0, 1, At, B1); BAR;
;     LDA(At, 0, 1); STAGE(SA(0, 0), A, 0, t + 2);
;     BAR; WAIT_L(0); MMA(1, 0, At, B0); BAR; SCHED;
;     STAGE(SB(0, 1), Bt, HALF, t + 2);
;     WAIT_V(6); BAR; MMA(1, 1, At, B1); BAR;
.LBB0_542:
	ds_read_b128 v[162:165], v159
	ds_read_b128 v[166:169], v159 offset:1024
	ds_read_b128 v[170:173], v159 offset:2048
	ds_read_b128 v[174:177], v159 offset:3072
	v_add_u32_e32 v160, 0xc000, v146
	v_lshl_add_u64 v[178:179], s[58:59], 0, v[140:141]
	v_readfirstlane_b32 s5, v160
	v_lshl_add_u64 v[188:189], v[178:179], 0, s[42:43]
	s_mov_b32 m0, s5
	v_add_u32_e32 v161, 0xe000, v146
	ds_read_b128 v[198:201], v151
	ds_read_b128 v[202:205], v151 offset:1024
	ds_read_b128 v[206:209], v150
	ds_read_b128 v[210:213], v150 offset:1024
	ds_read_b128 v[214:217], v149
	ds_read_b128 v[218:221], v149 offset:1024
	ds_read_b128 v[222:225], v148
	ds_read_b128 v[226:229], v148 offset:1024
	global_load_lds_dwordx4 v[188:189], off
	v_lshl_add_u64 v[188:189], s[58:59], 0, v[142:143]
	v_readfirstlane_b32 s5, v161
	v_lshl_add_u64 v[230:231], v[188:189], 0, s[42:43]
	s_mov_b32 m0, s5
	s_nop 0
	global_load_lds_dwordx4 v[230:231], off
	s_waitcnt lgkmcnt(8)
	s_barrier
	s_waitcnt lgkmcnt(0)
	s_waitcnt lgkmcnt(0)
	v_mfma_f32_16x16x32_bf16 v[124:127], v[162:165], v[198:201], v[124:127]
	v_mfma_f32_16x16x32_bf16 v[120:123], v[170:173], v[198:201], v[120:123]
	v_mfma_f32_16x16x32_bf16 v[112:115], v[170:173], v[206:209], v[112:115]
	v_mfma_f32_16x16x32_bf16 v[116:119], v[162:165], v[206:209], v[116:119]
	v_mfma_f32_16x16x32_bf16 v[108:111], v[162:165], v[214:217], v[108:111]
	v_mfma_f32_16x16x32_bf16 v[104:107], v[170:173], v[214:217], v[104:107]
	v_mfma_f32_16x16x32_bf16 v[96:99], v[170:173], v[222:225], v[96:99]
	v_mfma_f32_16x16x32_bf16 v[100:103], v[162:165], v[222:225], v[100:103]
	v_mfma_f32_16x16x32_bf16 v[124:127], v[166:169], v[202:205], v[124:127]
	v_mfma_f32_16x16x32_bf16 v[120:123], v[174:177], v[202:205], v[120:123]
	v_mfma_f32_16x16x32_bf16 v[112:115], v[174:177], v[210:213], v[112:115]
	v_mfma_f32_16x16x32_bf16 v[116:119], v[166:169], v[210:213], v[116:119]
	v_mfma_f32_16x16x32_bf16 v[108:111], v[166:169], v[218:221], v[108:111]
	v_mfma_f32_16x16x32_bf16 v[104:107], v[174:177], v[218:221], v[104:107]
	v_mfma_f32_16x16x32_bf16 v[96:99], v[174:177], v[226:229], v[96:99]
	v_mfma_f32_16x16x32_bf16 v[100:103], v[166:169], v[226:229], v[100:103]
	s_barrier
	v_add_u32_e32 v186, s8, v145
	v_lshl_add_u64 v[246:247], s[58:59], 0, v[136:137]
	v_readfirstlane_b32 s5, v186
	v_lshl_add_u64 v[248:249], v[246:247], 0, s[44:45]
	s_mov_b32 m0, s5
	v_add_u32_e32 v186, 0x2000, v186
	ds_read_b128 v[230:233], v158
	ds_read_b128 v[234:237], v158 offset:1024
	ds_read_b128 v[238:241], v158 offset:2048
	ds_read_b128 v[242:245], v158 offset:3072
	global_load_lds_dwordx4 v[248:249], off
	v_lshl_add_u64 v[248:249], s[58:59], 0, v[138:139]
	v_readfirstlane_b32 s5, v186
	v_lshl_add_u64 v[250:251], v[248:249], 0, s[44:45]
	s_mov_b32 m0, s5
	s_nop 0
	global_load_lds_dwordx4 v[250:251], off
	s_barrier
	s_waitcnt lgkmcnt(0)
	s_waitcnt lgkmcnt(0)
	v_mfma_f32_16x16x32_bf16 v[92:95], v[230:233], v[198:201], v[92:95]
	v_mfma_f32_16x16x32_bf16 v[88:91], v[238:241], v[198:201], v[88:91]
	v_mfma_f32_16x16x32_bf16 v[80:83], v[238:241], v[206:209], v[80:83]
	v_mfma_f32_16x16x32_bf16 v[84:87], v[230:233], v[206:209], v[84:87]
	v_mfma_f32_16x16x32_bf16 v[76:79], v[230:233], v[214:217], v[76:79]
	v_mfma_f32_16x16x32_bf16 v[72:75], v[238:241], v[214:217], v[72:75]
	v_mfma_f32_16x16x32_bf16 v[64:67], v[238:241], v[222:225], v[64:67]
	v_mfma_f32_16x16x32_bf16 v[68:71], v[230:233], v[222:225], v[68:71]
	v_mfma_f32_16x16x32_bf16 v[92:95], v[234:237], v[202:205], v[92:95]
	v_mfma_f32_16x16x32_bf16 v[88:91], v[242:245], v[202:205], v[88:91]
	v_mfma_f32_16x16x32_bf16 v[80:83], v[242:245], v[210:213], v[80:83]
	v_mfma_f32_16x16x32_bf16 v[84:87], v[234:237], v[210:213], v[84:87]
	v_mfma_f32_16x16x32_bf16 v[76:79], v[234:237], v[218:221], v[76:79]
	v_mfma_f32_16x16x32_bf16 v[72:75], v[242:245], v[218:221], v[72:75]
	v_mfma_f32_16x16x32_bf16 v[64:67], v[242:245], v[226:229], v[64:67]
	v_mfma_f32_16x16x32_bf16 v[68:71], v[234:237], v[226:229], v[68:71]
	v_readfirstlane_b32 s5, v146
	v_add_u32_e32 v186, 0x2000, v146
	v_lshl_add_u64 v[250:251], v[178:179], 0, s[46:47]
	s_mov_b32 m0, s5
	v_readfirstlane_b32 s5, v186
	s_barrier
	ds_read_b128 v[198:201], v151 offset:16384
	ds_read_b128 v[202:205], v151 offset:17408
	ds_read_b128 v[206:209], v150 offset:16384
	ds_read_b128 v[210:213], v150 offset:17408
	ds_read_b128 v[214:217], v149 offset:16384
	ds_read_b128 v[218:221], v149 offset:17408
	ds_read_b128 v[222:225], v148 offset:16384
	ds_read_b128 v[226:229], v148 offset:17408
	global_load_lds_dwordx4 v[250:251], off
	v_lshl_add_u64 v[250:251], v[188:189], 0, s[46:47]
	s_mov_b32 m0, s5
	s_nop 0
	global_load_lds_dwordx4 v[250:251], off
	s_barrier
	s_waitcnt lgkmcnt(0)
	s_waitcnt lgkmcnt(0)
	v_mfma_f32_16x16x32_bf16 v[60:63], v[162:165], v[198:201], v[60:63]
	v_mfma_f32_16x16x32_bf16 v[56:59], v[170:173], v[198:201], v[56:59]
	v_mfma_f32_16x16x32_bf16 v[48:51], v[170:173], v[206:209], v[48:51]
	v_mfma_f32_16x16x32_bf16 v[52:55], v[162:165], v[206:209], v[52:55]
	v_mfma_f32_16x16x32_bf16 v[44:47], v[162:165], v[214:217], v[44:47]
	v_mfma_f32_16x16x32_bf16 v[40:43], v[170:173], v[214:217], v[40:43]
	v_mfma_f32_16x16x32_bf16 v[32:35], v[170:173], v[222:225], v[32:35]
	v_mfma_f32_16x16x32_bf16 v[36:39], v[162:165], v[222:225], v[36:39]
	v_mfma_f32_16x16x32_bf16 v[60:63], v[166:169], v[202:205], v[60:63]
	v_mfma_f32_16x16x32_bf16 v[56:59], v[174:177], v[202:205], v[56:59]
	v_mfma_f32_16x16x32_bf16 v[48:51], v[174:177], v[210:213], v[48:51]
	v_mfma_f32_16x16x32_bf16 v[52:55], v[166:169], v[210:213], v[52:55]
	v_mfma_f32_16x16x32_bf16 v[44:47], v[166:169], v[218:221], v[44:47]
	v_mfma_f32_16x16x32_bf16 v[40:43], v[174:177], v[218:221], v[40:43]
	v_mfma_f32_16x16x32_bf16 v[32:35], v[174:177], v[226:229], v[32:35]
	v_mfma_f32_16x16x32_bf16 v[36:39], v[166:169], v[226:229], v[36:39]
	s_barrier
; #define WAIT_V(n) asm volatile("s_waitcnt vmcnt(" #n ")" ::: "memory")
; #define WAIT_L(n) asm volatile("s_waitcnt lgkmcnt(" #n ")" ::: "memory")
; #define BAR __builtin_amdgcn_s_barrier()
; #define SCHED __builtin_amdgcn_sched_barrier(0)
; #define LDA(dst, b, h)                                                                            \
;   _Pragma("unroll") for (int m = 0; m < 4; ++m) _Pragma("unroll") for (int k = 0; k < 2; ++k)                                         \
;     dst[m][k] = *reinterpret_cast<const bf16x8*>((char*)SA(b, h) + lds_byte(wr * 64 + m * 16 + fr, k * 32 + fq * 8))
; #define LDB(dst, b, h)                                                                            \
;   _Pragma("unroll") for (int n = 0; n < 2; ++n) _Pragma("unroll") for (int k = 0; k < 2; ++k)                                         \
;     dst[n][k] = *reinterpret_cast<const bf16x8*>((char*)SB(b, h) + lds_byte(wc * 32 + n * 16 + fr, k * 32 + fq * 8))
; template <int K, bool SWAP>
; __device__ __forceinline__ void gemm_kloop(const bf16* __restrict__ A, const bf16* __restrict__ Bt,
;                                            f32x4 (&acc)[2][2][4][2], bool pref = false) {
;     ...
;     WAIT_V(6); BAR; MMA(1, 1, At, B1); BAR;
;     LDB(B0, 1, 0); SCHED; LDA(At, 1, 0); STAGE(SA(0, 1), A, HALF, t + 2);
;     WAIT_L(8); BAR; WAIT_L(0); MMA(0, 0, At, B0); BAR; SCHED;
;     LDB(B1, 1, 1); STAGE(SB(1, 0), Bt, 0, t + 3);
;     BAR; WAIT_L(0); MMA(0, 1, At, B1); BAR;
;     LDA(At, 1, 1); STAGE(SA(1, 0), A, 0, t + 3);
;     BAR; WAIT_L(0); MMA(1, 0, At, B0); BAR; SCHED;
	v_readfirstlane_b32 s5, v147
	v_add_u32_e32 v164, 0x2000, v147
	v_lshl_add_u64 v[162:163], v[246:247], 0, s[48:49]
	s_mov_b32 m0, s5
	v_readfirstlane_b32 s5, v164
	global_load_lds_dwordx4 v[162:163], off
	v_lshl_add_u64 v[162:163], v[248:249], 0, s[48:49]
	s_mov_b32 m0, s5
	s_nop 0
	global_load_lds_dwordx4 v[162:163], off
	s_waitcnt vmcnt(6)
	s_barrier
	v_mfma_f32_16x16x32_bf16 v[28:31], v[230:233], v[198:201], v[28:31]
	v_mfma_f32_16x16x32_bf16 v[24:27], v[238:241], v[198:201], v[24:27]
	v_mfma_f32_16x16x32_bf16 v[16:19], v[238:241], v[206:209], v[16:19]
	v_mfma_f32_16x16x32_bf16 v[20:23], v[230:233], v[206:209], v[20:23]
	v_mfma_f32_16x16x32_bf16 v[12:15], v[230:233], v[214:217], v[12:15]
	v_mfma_f32_16x16x32_bf16 v[8:11], v[238:241], v[214:217], v[8:11]
	v_mfma_f32_16x16x32_bf16 v[0:3], v[238:241], v[222:225], v[0:3]
	v_mfma_f32_16x16x32_bf16 v[4:7], v[230:233], v[222:225], v[4:7]
	v_mfma_f32_16x16x32_bf16 v[28:31], v[234:237], v[202:205], v[28:31]
	v_mfma_f32_16x16x32_bf16 v[24:27], v[242:245], v[202:205], v[24:27]
	v_mfma_f32_16x16x32_bf16 v[16:19], v[242:245], v[210:213], v[16:19]
	v_mfma_f32_16x16x32_bf16 v[20:23], v[234:237], v[210:213], v[20:23]
	v_mfma_f32_16x16x32_bf16 v[12:15], v[234:237], v[218:221], v[12:15]
	v_mfma_f32_16x16x32_bf16 v[8:11], v[242:245], v[218:221], v[8:11]
	v_mfma_f32_16x16x32_bf16 v[0:3], v[242:245], v[226:229], v[0:3]
	v_mfma_f32_16x16x32_bf16 v[4:7], v[234:237], v[226:229], v[4:7]
	s_barrier
	ds_read_b128 v[162:165], v153
	ds_read_b128 v[166:169], v153 offset:1024
	ds_read_b128 v[170:173], v153 offset:2048
	ds_read_b128 v[174:177], v153 offset:3072
	v_add_u32_e32 v186, 0x4000, v146
	v_lshl_add_u64 v[230:231], v[178:179], 0, s[50:51]
	v_readfirstlane_b32 s5, v186
	v_add_u32_e32 v186, 0x6000, v146
	s_mov_b32 m0, s5
	v_readfirstlane_b32 s5, v186
	ds_read_b128 v[198:201], v151 offset:32768
	ds_read_b128 v[202:205], v151 offset:33792
	ds_read_b128 v[206:209], v150 offset:32768
	ds_read_b128 v[210:213], v150 offset:33792
	ds_read_b128 v[214:217], v149 offset:32768
	ds_read_b128 v[218:221], v149 offset:33792
	ds_read_b128 v[222:225], v148 offset:32768
	ds_read_b128 v[226:229], v148 offset:33792
	global_load_lds_dwordx4 v[230:231], off
	v_lshl_add_u64 v[230:231], v[188:189], 0, s[50:51]
	s_mov_b32 m0, s5
	s_nop 0
	global_load_lds_dwordx4 v[230:231], off
	s_waitcnt lgkmcnt(8)
	s_barrier
	s_waitcnt lgkmcnt(0)
	s_waitcnt lgkmcnt(0)
	v_mfma_f32_16x16x32_bf16 v[124:127], v[162:165], v[198:201], v[124:127]
	v_mfma_f32_16x16x32_bf16 v[120:123], v[170:173], v[198:201], v[120:123]
	v_mfma_f32_16x16x32_bf16 v[112:115], v[170:173], v[206:209], v[112:115]
	v_mfma_f32_16x16x32_bf16 v[116:119], v[162:165], v[206:209], v[116:119]
	v_mfma_f32_16x16x32_bf16 v[108:111], v[162:165], v[214:217], v[108:111]
	v_mfma_f32_16x16x32_bf16 v[104:107], v[170:173], v[214:217], v[104:107]
	v_mfma_f32_16x16x32_bf16 v[96:99], v[170:173], v[222:225], v[96:99]
	v_mfma_f32_16x16x32_bf16 v[100:103], v[162:165], v[222:225], v[100:103]
	v_mfma_f32_16x16x32_bf16 v[124:127], v[166:169], v[202:205], v[124:127]
	v_mfma_f32_16x16x32_bf16 v[120:123], v[174:177], v[202:205], v[120:123]
	v_mfma_f32_16x16x32_bf16 v[112:115], v[174:177], v[210:213], v[112:115]
	v_mfma_f32_16x16x32_bf16 v[116:119], v[166:169], v[210:213], v[116:119]
	v_mfma_f32_16x16x32_bf16 v[108:111], v[166:169], v[218:221], v[108:111]
	v_mfma_f32_16x16x32_bf16 v[104:107], v[174:177], v[218:221], v[104:107]
	v_mfma_f32_16x16x32_bf16 v[96:99], v[174:177], v[226:229], v[96:99]
	v_mfma_f32_16x16x32_bf16 v[100:103], v[166:169], v[226:229], v[100:103]
	s_barrier
	v_readfirstlane_b32 s5, v154
	v_add_u32_e32 v186, 0x2000, v154
	v_lshl_add_u64 v[250:251], v[246:247], 0, s[52:53]
	s_mov_b32 m0, s5
	v_readfirstlane_b32 s5, v186
	ds_read_b128 v[230:233], v152
	ds_read_b128 v[234:237], v152 offset:1024
	ds_read_b128 v[238:241], v152 offset:2048
	ds_read_b128 v[242:245], v152 offset:3072
	global_load_lds_dwordx4 v[250:251], off
	v_lshl_add_u64 v[250:251], v[248:249], 0, s[52:53]
	s_mov_b32 m0, s5
	s_nop 0
	global_load_lds_dwordx4 v[250:251], off
	s_barrier
	s_waitcnt lgkmcnt(0)
	s_waitcnt lgkmcnt(0)
	v_mfma_f32_16x16x32_bf16 v[92:95], v[230:233], v[198:201], v[92:95]
	v_mfma_f32_16x16x32_bf16 v[88:91], v[238:241], v[198:201], v[88:91]
	v_mfma_f32_16x16x32_bf16 v[80:83], v[238:241], v[206:209], v[80:83]
	v_mfma_f32_16x16x32_bf16 v[84:87], v[230:233], v[206:209], v[84:87]
	v_mfma_f32_16x16x32_bf16 v[76:79], v[230:233], v[214:217], v[76:79]
	v_mfma_f32_16x16x32_bf16 v[72:75], v[238:241], v[214:217], v[72:75]
	v_mfma_f32_16x16x32_bf16 v[64:67], v[238:241], v[222:225], v[64:67]
	v_mfma_f32_16x16x32_bf16 v[68:71], v[230:233], v[222:225], v[68:71]
	v_mfma_f32_16x16x32_bf16 v[92:95], v[234:237], v[202:205], v[92:95]
	v_mfma_f32_16x16x32_bf16 v[88:91], v[242:245], v[202:205], v[88:91]
	v_mfma_f32_16x16x32_bf16 v[80:83], v[242:245], v[210:213], v[80:83]
	v_mfma_f32_16x16x32_bf16 v[84:87], v[234:237], v[210:213], v[84:87]
	v_mfma_f32_16x16x32_bf16 v[76:79], v[234:237], v[218:221], v[76:79]
	v_mfma_f32_16x16x32_bf16 v[72:75], v[242:245], v[218:221], v[72:75]
	v_mfma_f32_16x16x32_bf16 v[64:67], v[242:245], v[226:229], v[64:67]
	v_mfma_f32_16x16x32_bf16 v[68:71], v[234:237], v[226:229], v[68:71]
	v_readfirstlane_b32 s5, v155
	v_lshl_add_u64 v[178:179], v[178:179], 0, s[54:55]
	s_mov_b32 m0, s5
	v_readfirstlane_b32 s5, v156
	s_barrier
	ds_read_b128 v[198:201], v151 offset:49152
	ds_read_b128 v[202:205], v151 offset:50176
	ds_read_b128 v[206:209], v150 offset:49152
	ds_read_b128 v[210:213], v150 offset:50176
	ds_read_b128 v[214:217], v149 offset:49152
	ds_read_b128 v[218:221], v149 offset:50176
	ds_read_b128 v[222:225], v148 offset:49152
	ds_read_b128 v[226:229], v148 offset:50176
	global_load_lds_dwordx4 v[178:179], off
	v_lshl_add_u64 v[178:179], v[188:189], 0, s[54:55]
	s_mov_b32 m0, s5
	s_nop 0
	global_load_lds_dwordx4 v[178:179], off
	s_barrier
; #define WAIT_V(n) asm volatile("s_waitcnt vmcnt(" #n ")" ::: "memory")
; #define WAIT_L(n) asm volatile("s_waitcnt lgkmcnt(" #n ")" ::: "memory")
; #define BAR __builtin_amdgcn_s_barrier()
; #define SCHED __builtin_amdgcn_sched_barrier(0)
; #define LDA(dst, b, h)                                                                            \
;   _Pragma("unroll") for (int m = 0; m < 4; ++m) _Pragma("unroll") for (int k = 0; k < 2; ++k)                                         \
;     dst[m][k] = *reinterpret_cast<const bf16x8*>((char*)SA(b, h) + lds_byte(wr * 64 + m * 16 + fr, k * 32 + fq * 8))
; #define LDB(dst, b, h)                                                                            \
;   _Pragma("unroll") for (int n = 0; n < 2; ++n) _Pragma("unroll") for (int k = 0; k < 2; ++k)                                         \
;     dst[n][k] = *reinterpret_cast<const bf16x8*>((char*)SB(b, h) + lds_byte(wc * 32 + n * 16 + fr, k * 32 + fq * 8))
; template <int K, bool SWAP>
; __device__ __forceinline__ void gemm_kloop(const bf16* __restrict__ A, const bf16* __restrict__ Bt,
;                                            f32x4 (&acc)[2][2][4][2], bool pref = false) {
;     ...
;     BAR; WAIT_L(0); MMA(1, 0, At, B0); BAR; SCHED;
;     STAGE(SB(1, 1), Bt, HALF, t + 3);
;     WAIT_V(6); BAR; MMA(1, 1, At, B1); BAR;
;   }
;   { LDB(B0, 0, 0); LDA(At, 0, 0); STAGE(SA(1, 1), A, HALF, nt - 1);
;     BAR; WAIT_L(0); MMA(0, 0, At, B0); BAR;
;     LDB(B1, 0, 1); BAR; WAIT_L(0); MMA(0, 1, At, B1); BAR;
;     LDA(At, 0, 1); WAIT_V(4); BAR; WAIT_L(0); MMA(1, 0, At, B0); MMA(1, 1, At, B1); BAR; }
	s_waitcnt lgkmcnt(0)
	s_waitcnt lgkmcnt(0)
	v_mfma_f32_16x16x32_bf16 v[60:63], v[162:165], v[198:201], v[60:63]
	v_mfma_f32_16x16x32_bf16 v[56:59], v[170:173], v[198:201], v[56:59]
	v_mfma_f32_16x16x32_bf16 v[48:51], v[170:173], v[206:209], v[48:51]
	v_mfma_f32_16x16x32_bf16 v[52:55], v[162:165], v[206:209], v[52:55]
	v_mfma_f32_16x16x32_bf16 v[44:47], v[162:165], v[214:217], v[44:47]
	v_mfma_f32_16x16x32_bf16 v[40:43], v[170:173], v[214:217], v[40:43]
	v_mfma_f32_16x16x32_bf16 v[32:35], v[170:173], v[222:225], v[32:35]
	v_mfma_f32_16x16x32_bf16 v[36:39], v[162:165], v[222:225], v[36:39]
	v_mfma_f32_16x16x32_bf16 v[60:63], v[166:169], v[202:205], v[60:63]
	v_mfma_f32_16x16x32_bf16 v[56:59], v[174:177], v[202:205], v[56:59]
	v_mfma_f32_16x16x32_bf16 v[48:51], v[174:177], v[210:213], v[48:51]
	v_mfma_f32_16x16x32_bf16 v[52:55], v[166:169], v[210:213], v[52:55]
	v_mfma_f32_16x16x32_bf16 v[44:47], v[166:169], v[218:221], v[44:47]
	v_mfma_f32_16x16x32_bf16 v[40:43], v[174:177], v[218:221], v[40:43]
	v_mfma_f32_16x16x32_bf16 v[32:35], v[174:177], v[226:229], v[32:35]
	v_mfma_f32_16x16x32_bf16 v[36:39], v[166:169], v[226:229], v[36:39]
	s_barrier
	v_readfirstlane_b32 s5, v157
	v_add_u32_e32 v164, 0x2000, v157
	v_lshl_add_u64 v[162:163], v[246:247], 0, s[56:57]
	s_mov_b32 m0, s5
	v_readfirstlane_b32 s5, v164
	global_load_lds_dwordx4 v[162:163], off
	v_lshl_add_u64 v[162:163], v[248:249], 0, s[56:57]
	s_mov_b32 m0, s5
	s_nop 0
	global_load_lds_dwordx4 v[162:163], off
	s_waitcnt vmcnt(6)
	s_barrier
	v_mfma_f32_16x16x32_bf16 v[28:31], v[230:233], v[198:201], v[28:31]
	v_mfma_f32_16x16x32_bf16 v[24:27], v[238:241], v[198:201], v[24:27]
	v_mfma_f32_16x16x32_bf16 v[16:19], v[238:241], v[206:209], v[16:19]
	v_mfma_f32_16x16x32_bf16 v[20:23], v[230:233], v[206:209], v[20:23]
	v_mfma_f32_16x16x32_bf16 v[12:15], v[230:233], v[214:217], v[12:15]
	v_mfma_f32_16x16x32_bf16 v[8:11], v[238:241], v[214:217], v[8:11]
	v_mfma_f32_16x16x32_bf16 v[0:3], v[238:241], v[222:225], v[0:3]
	v_mfma_f32_16x16x32_bf16 v[4:7], v[230:233], v[222:225], v[4:7]
	v_mfma_f32_16x16x32_bf16 v[28:31], v[234:237], v[202:205], v[28:31]
	v_mfma_f32_16x16x32_bf16 v[24:27], v[242:245], v[202:205], v[24:27]
	v_mfma_f32_16x16x32_bf16 v[16:19], v[242:245], v[210:213], v[16:19]
	v_mfma_f32_16x16x32_bf16 v[20:23], v[234:237], v[210:213], v[20:23]
	v_mfma_f32_16x16x32_bf16 v[12:15], v[234:237], v[218:221], v[12:15]
	v_mfma_f32_16x16x32_bf16 v[8:11], v[242:245], v[218:221], v[8:11]
	v_mfma_f32_16x16x32_bf16 v[0:3], v[242:245], v[226:229], v[0:3]
	v_mfma_f32_16x16x32_bf16 v[4:7], v[234:237], v[226:229], v[4:7]
	s_add_i32 s4, s4, 2
	v_lshl_add_u64 v[136:137], v[136:137], 0, s[44:45]
	v_lshl_add_u64 v[138:139], v[138:139], 0, s[44:45]
	v_lshl_add_u64 v[140:141], v[140:141], 0, s[44:45]
	s_cmp_lt_u32 s4, 12
	v_lshl_add_u64 v[142:143], v[142:143], 0, s[44:45]
	s_barrier
	s_cbranch_scc1 .LBB0_542
	s_add_u32 s0, s0, 0x40780
	s_addc_u32 s1, s1, 0
	v_lshl_add_u64 v[130:131], s[0:1], 0, v[130:131]
	v_readfirstlane_b32 s4, v160
	v_lshl_add_u64 v[128:129], v[128:129], 1, v[130:131]
	s_mov_b32 m0, s4
	ds_read_b128 v[136:139], v159
	ds_read_b128 v[140:143], v159 offset:1024
	ds_read_b128 v[154:157], v159 offset:2048
	ds_read_b128 v[162:165], v159 offset:3072
	ds_read_b128 v[166:169], v151
	ds_read_b128 v[170:173], v151 offset:1024
	ds_read_b128 v[174:177], v150
	ds_read_b128 v[198:201], v150 offset:1024
	ds_read_b128 v[202:205], v149
	ds_read_b128 v[206:209], v149 offset:1024
	ds_read_b128 v[210:213], v148
	ds_read_b128 v[214:217], v148 offset:1024
	global_load_lds_dwordx4 v[128:129], off
	v_lshl_add_u64 v[128:129], s[0:1], 0, v[134:135]
	v_readfirstlane_b32 s0, v161
	v_lshl_add_u64 v[128:129], v[132:133], 1, v[128:129]
	s_mov_b32 m0, s0
	s_nop 0
	global_load_lds_dwordx4 v[128:129], off
	s_barrier
	s_waitcnt lgkmcnt(0)
	s_waitcnt lgkmcnt(0)
	v_mfma_f32_16x16x32_bf16 v[124:127], v[136:139], v[166:169], v[124:127]
	v_mfma_f32_16x16x32_bf16 v[120:123], v[154:157], v[166:169], v[120:123]
	v_mfma_f32_16x16x32_bf16 v[112:115], v[154:157], v[174:177], v[112:115]
	v_mfma_f32_16x16x32_bf16 v[116:119], v[136:139], v[174:177], v[116:119]
	v_mfma_f32_16x16x32_bf16 v[108:111], v[136:139], v[202:205], v[108:111]
	v_mfma_f32_16x16x32_bf16 v[104:107], v[154:157], v[202:205], v[104:107]
	v_mfma_f32_16x16x32_bf16 v[96:99], v[154:157], v[210:213], v[96:99]
	v_mfma_f32_16x16x32_bf16 v[100:103], v[136:139], v[210:213], v[100:103]
	v_mfma_f32_16x16x32_bf16 v[124:127], v[140:143], v[170:173], v[124:127]
	v_mfma_f32_16x16x32_bf16 v[120:123], v[162:165], v[170:173], v[120:123]
	v_mfma_f32_16x16x32_bf16 v[112:115], v[162:165], v[198:201], v[112:115]
	v_mfma_f32_16x16x32_bf16 v[116:119], v[140:143], v[198:201], v[116:119]
	v_mfma_f32_16x16x32_bf16 v[108:111], v[140:143], v[206:209], v[108:111]
	v_mfma_f32_16x16x32_bf16 v[104:107], v[162:165], v[206:209], v[104:107]
	v_mfma_f32_16x16x32_bf16 v[96:99], v[162:165], v[214:217], v[96:99]
	v_mfma_f32_16x16x32_bf16 v[100:103], v[140:143], v[214:217], v[100:103]
	s_barrier
	ds_read_b128 v[128:131], v158
	ds_read_b128 v[132:135], v158 offset:1024
	ds_read_b128 v[218:221], v158 offset:2048
	ds_read_b128 v[158:161], v158 offset:3072
	s_barrier
; #define WAIT_V(n) asm volatile("s_waitcnt vmcnt(" #n ")" ::: "memory")
; #define WAIT_L(n) asm volatile("s_waitcnt lgkmcnt(" #n ")" ::: "memory")
; #define BAR __builtin_amdgcn_s_barrier()
; #define LDA(dst, b, h)                                                                            \
;   _Pragma("unroll") for (int m = 0; m < 4; ++m) _Pragma("unroll") for (int k = 0; k < 2; ++k)                                         \
;     dst[m][k] = *reinterpret_cast<const bf16x8*>((char*)SA(b, h) + lds_byte(wr * 64 + m * 16 + fr, k * 32 + fq * 8))
; #define LDB(dst, b, h)                                                                            \
;   _Pragma("unroll") for (int n = 0; n < 2; ++n) _Pragma("unroll") for (int k = 0; k < 2; ++k)                                         \
;     dst[n][k] = *reinterpret_cast<const bf16x8*>((char*)SB(b, h) + lds_byte(wc * 32 + n * 16 + fr, k * 32 + fq * 8))
; template <int K, bool SWAP>
; __device__ __forceinline__ void gemm_kloop(const bf16* __restrict__ A, const bf16* __restrict__ Bt,
;                                            f32x4 (&acc)[2][2][4][2], bool pref = false) {
;     ...
;     LDB(B1, 0, 1); BAR; WAIT_L(0); MMA(0, 1, At, B1); BAR;
;     LDA(At, 0, 1); WAIT_V(4); BAR; WAIT_L(0); MMA(1, 0, At, B0); MMA(1, 1, At, B1); BAR; }
;   { LDB(B0, 1, 0); LDA(At, 1, 0); WAIT_V(2); BAR; WAIT_L(0); MMA(0, 0, At, B0); BAR;
;     LDB(B1, 1, 1); WAIT_V(0); BAR; WAIT_L(0); MMA(0, 1, At, B1); BAR;
	s_waitcnt lgkmcnt(0)
	s_waitcnt lgkmcnt(0)
	v_mfma_f32_16x16x32_bf16 v[92:95], v[128:131], v[166:169], v[92:95]
	v_mfma_f32_16x16x32_bf16 v[88:91], v[218:221], v[166:169], v[88:91]
	v_mfma_f32_16x16x32_bf16 v[76:79], v[128:131], v[202:205], v[76:79]
	v_mfma_f32_16x16x32_bf16 v[72:75], v[218:221], v[202:205], v[72:75]
	v_mfma_f32_16x16x32_bf16 v[68:71], v[128:131], v[210:213], v[68:71]
	v_mfma_f32_16x16x32_bf16 v[64:67], v[218:221], v[210:213], v[64:67]
	v_mfma_f32_16x16x32_bf16 v[92:95], v[132:135], v[170:173], v[92:95]
	v_mfma_f32_16x16x32_bf16 v[88:91], v[158:161], v[170:173], v[88:91]
	v_mfma_f32_16x16x32_bf16 v[84:87], v[128:131], v[174:177], v[84:87]
	v_mfma_f32_16x16x32_bf16 v[80:83], v[218:221], v[174:177], v[80:83]
	v_mfma_f32_16x16x32_bf16 v[76:79], v[132:135], v[206:209], v[76:79]
	v_mfma_f32_16x16x32_bf16 v[72:75], v[158:161], v[206:209], v[72:75]
	v_mfma_f32_16x16x32_bf16 v[68:71], v[132:135], v[214:217], v[68:71]
	v_mfma_f32_16x16x32_bf16 v[64:67], v[158:161], v[214:217], v[64:67]
	v_mfma_f32_16x16x32_bf16 v[84:87], v[132:135], v[198:201], v[84:87]
	v_mfma_f32_16x16x32_bf16 v[80:83], v[158:161], v[198:201], v[80:83]
	s_barrier
	ds_read_b128 v[166:169], v151 offset:16384
	ds_read_b128 v[170:173], v151 offset:17408
	ds_read_b128 v[174:177], v150 offset:16384
	ds_read_b128 v[198:201], v150 offset:17408
	ds_read_b128 v[202:205], v149 offset:16384
	ds_read_b128 v[206:209], v149 offset:17408
	ds_read_b128 v[210:213], v148 offset:16384
	ds_read_b128 v[214:217], v148 offset:17408
	s_waitcnt vmcnt(4)
	s_barrier
	s_waitcnt lgkmcnt(0)
	s_waitcnt lgkmcnt(0)
	v_mfma_f32_16x16x32_bf16 v[60:63], v[136:139], v[166:169], v[60:63]
	v_mfma_f32_16x16x32_bf16 v[56:59], v[154:157], v[166:169], v[56:59]
	v_mfma_f32_16x16x32_bf16 v[52:55], v[136:139], v[174:177], v[52:55]
	v_mfma_f32_16x16x32_bf16 v[48:51], v[154:157], v[174:177], v[48:51]
	v_mfma_f32_16x16x32_bf16 v[44:47], v[136:139], v[202:205], v[44:47]
	v_mfma_f32_16x16x32_bf16 v[36:39], v[136:139], v[210:213], v[36:39]
	v_mfma_f32_16x16x32_bf16 v[60:63], v[140:143], v[170:173], v[60:63]
	v_mfma_f32_16x16x32_bf16 v[56:59], v[162:165], v[170:173], v[56:59]
	v_mfma_f32_16x16x32_bf16 v[52:55], v[140:143], v[198:201], v[52:55]
	v_mfma_f32_16x16x32_bf16 v[48:51], v[162:165], v[198:201], v[48:51]
	v_mfma_f32_16x16x32_bf16 v[44:47], v[140:143], v[206:209], v[44:47]
	v_mfma_f32_16x16x32_bf16 v[40:43], v[154:157], v[202:205], v[40:43]
	v_mfma_f32_16x16x32_bf16 v[36:39], v[140:143], v[214:217], v[36:39]
	v_mfma_f32_16x16x32_bf16 v[32:35], v[154:157], v[210:213], v[32:35]
	v_mfma_f32_16x16x32_bf16 v[40:43], v[162:165], v[206:209], v[40:43]
	v_mfma_f32_16x16x32_bf16 v[32:35], v[162:165], v[214:217], v[32:35]
	v_mfma_f32_16x16x32_bf16 v[28:31], v[128:131], v[166:169], v[28:31]
	v_mfma_f32_16x16x32_bf16 v[24:27], v[218:221], v[166:169], v[24:27]
	v_mfma_f32_16x16x32_bf16 v[16:19], v[218:221], v[174:177], v[16:19]
	v_mfma_f32_16x16x32_bf16 v[20:23], v[128:131], v[174:177], v[20:23]
	v_mfma_f32_16x16x32_bf16 v[12:15], v[128:131], v[202:205], v[12:15]
	v_mfma_f32_16x16x32_bf16 v[8:11], v[218:221], v[202:205], v[8:11]
	v_mfma_f32_16x16x32_bf16 v[0:3], v[218:221], v[210:213], v[0:3]
	v_mfma_f32_16x16x32_bf16 v[4:7], v[128:131], v[210:213], v[4:7]
	v_mfma_f32_16x16x32_bf16 v[28:31], v[132:135], v[170:173], v[28:31]
	v_mfma_f32_16x16x32_bf16 v[24:27], v[158:161], v[170:173], v[24:27]
	v_mfma_f32_16x16x32_bf16 v[16:19], v[158:161], v[198:201], v[16:19]
	v_mfma_f32_16x16x32_bf16 v[20:23], v[132:135], v[198:201], v[20:23]
	v_mfma_f32_16x16x32_bf16 v[12:15], v[132:135], v[206:209], v[12:15]
	v_mfma_f32_16x16x32_bf16 v[8:11], v[158:161], v[206:209], v[8:11]
	v_mfma_f32_16x16x32_bf16 v[0:3], v[158:161], v[214:217], v[0:3]
	v_mfma_f32_16x16x32_bf16 v[4:7], v[132:135], v[214:217], v[4:7]
	s_barrier
	ds_read_b128 v[154:157], v153
	ds_read_b128 v[158:161], v153 offset:1024
	ds_read_b128 v[162:165], v153 offset:2048
	ds_read_b128 v[166:169], v153 offset:3072
	ds_read_b128 v[170:173], v151 offset:32768
	ds_read_b128 v[174:177], v151 offset:33792
	ds_read_b128 v[198:201], v150 offset:32768
	ds_read_b128 v[202:205], v150 offset:33792
	ds_read_b128 v[206:209], v149 offset:32768
	ds_read_b128 v[210:213], v149 offset:33792
	ds_read_b128 v[214:217], v148 offset:32768
	ds_read_b128 v[218:221], v148 offset:33792
	s_waitcnt vmcnt(2)
	s_barrier
; #define WAIT_V(n) asm volatile("s_waitcnt vmcnt(" #n ")" ::: "memory")
; #define WAIT_L(n) asm volatile("s_waitcnt lgkmcnt(" #n ")" ::: "memory")
; #define BAR __builtin_amdgcn_s_barrier()
; #define SCHED __builtin_amdgcn_sched_barrier(0)
; #define LDA(dst, b, h)                                                                            \
;   _Pragma("unroll") for (int m = 0; m < 4; ++m) _Pragma("unroll") for (int k = 0; k < 2; ++k)                                         \
;     dst[m][k] = *reinterpret_cast<const bf16x8*>((char*)SA(b, h) + lds_byte(wr * 64 + m * 16 + fr, k * 32 + fq * 8))
; #define LDB(dst, b, h)                                                                            \
;   _Pragma("unroll") for (int n = 0; n < 2; ++n) _Pragma("unroll") for (int k = 0; k < 2; ++k)                                         \
;     dst[n][k] = *reinterpret_cast<const bf16x8*>((char*)SB(b, h) + lds_byte(wc * 32 + n * 16 + fr, k * 32 + fq * 8))
; template <int K, bool SWAP>
; __device__ __forceinline__ void gemm_kloop(const bf16* __restrict__ A, const bf16* __restrict__ Bt,
;                                            f32x4 (&acc)[2][2][4][2], bool pref = false) {
;     ...
;   { LDB(B0, 1, 0); LDA(At, 1, 0); WAIT_V(2); BAR; WAIT_L(0); MMA(0, 0, At, B0); BAR;
;     LDB(B1, 1, 1); WAIT_V(0); BAR; WAIT_L(0); MMA(0, 1, At, B1); BAR;
;     LDA(At, 1, 1); BAR; WAIT_L(0); MMA(1, 0, At, B0); MMA(1, 1, At, B1); BAR; }
;   if (wr == 0) BAR;
;   SCHED;
	s_waitcnt lgkmcnt(0)
	s_waitcnt lgkmcnt(0)
	v_mfma_f32_16x16x32_bf16 v[124:127], v[154:157], v[170:173], v[124:127]
	v_mfma_f32_16x16x32_bf16 v[120:123], v[162:165], v[170:173], v[120:123]
	v_mfma_f32_16x16x32_bf16 v[116:119], v[154:157], v[198:201], v[116:119]
	v_mfma_f32_16x16x32_bf16 v[112:115], v[162:165], v[198:201], v[112:115]
	v_mfma_f32_16x16x32_bf16 v[108:111], v[154:157], v[206:209], v[108:111]
	v_mfma_f32_16x16x32_bf16 v[104:107], v[162:165], v[206:209], v[104:107]
	v_mfma_f32_16x16x32_bf16 v[100:103], v[154:157], v[214:217], v[100:103]
	v_mfma_f32_16x16x32_bf16 v[96:99], v[162:165], v[214:217], v[96:99]
	v_mfma_f32_16x16x32_bf16 v[140:143], v[158:161], v[174:177], v[124:127]
	v_mfma_f32_16x16x32_bf16 v[136:139], v[166:169], v[174:177], v[120:123]
	v_mfma_f32_16x16x32_bf16 v[132:135], v[158:161], v[202:205], v[116:119]
	v_mfma_f32_16x16x32_bf16 v[128:131], v[166:169], v[202:205], v[112:115]
	v_mfma_f32_16x16x32_bf16 v[124:127], v[158:161], v[210:213], v[108:111]
	v_mfma_f32_16x16x32_bf16 v[120:123], v[166:169], v[210:213], v[104:107]
	v_mfma_f32_16x16x32_bf16 v[116:119], v[158:161], v[218:221], v[100:103]
	v_mfma_f32_16x16x32_bf16 v[112:115], v[166:169], v[218:221], v[96:99]
	s_barrier
	ds_read_b128 v[222:225], v152
	ds_read_b128 v[226:229], v152 offset:1024
	ds_read_b128 v[230:233], v152 offset:2048
	ds_read_b128 v[234:237], v152 offset:3072
	s_waitcnt vmcnt(0)
	s_barrier
	s_waitcnt lgkmcnt(0)
	s_waitcnt lgkmcnt(0)
	v_mfma_f32_16x16x32_bf16 v[92:95], v[222:225], v[170:173], v[92:95]
	v_mfma_f32_16x16x32_bf16 v[88:91], v[230:233], v[170:173], v[88:91]
	v_mfma_f32_16x16x32_bf16 v[84:87], v[222:225], v[198:201], v[84:87]
	v_mfma_f32_16x16x32_bf16 v[80:83], v[230:233], v[198:201], v[80:83]
	v_mfma_f32_16x16x32_bf16 v[76:79], v[222:225], v[206:209], v[76:79]
	v_mfma_f32_16x16x32_bf16 v[72:75], v[230:233], v[206:209], v[72:75]
	v_mfma_f32_16x16x32_bf16 v[68:71], v[222:225], v[214:217], v[68:71]
	v_mfma_f32_16x16x32_bf16 v[64:67], v[230:233], v[214:217], v[64:67]
	v_mfma_f32_16x16x32_bf16 v[108:111], v[226:229], v[174:177], v[92:95]
	v_mfma_f32_16x16x32_bf16 v[104:107], v[234:237], v[174:177], v[88:91]
	v_mfma_f32_16x16x32_bf16 v[100:103], v[226:229], v[202:205], v[84:87]
	v_mfma_f32_16x16x32_bf16 v[96:99], v[234:237], v[202:205], v[80:83]
	v_mfma_f32_16x16x32_bf16 v[92:95], v[226:229], v[210:213], v[76:79]
	v_mfma_f32_16x16x32_bf16 v[88:91], v[234:237], v[210:213], v[72:75]
	v_mfma_f32_16x16x32_bf16 v[76:79], v[226:229], v[218:221], v[68:71]
	v_mfma_f32_16x16x32_bf16 v[72:75], v[234:237], v[218:221], v[64:67]
	s_barrier
	ds_read_b128 v[80:83], v151 offset:49152
	ds_read_b128 v[84:87], v151 offset:50176
	ds_read_b128 v[170:173], v150 offset:49152
	ds_read_b128 v[150:153], v150 offset:50176
	ds_read_b128 v[174:177], v149 offset:49152
	ds_read_b128 v[198:201], v149 offset:50176
	ds_read_b128 v[202:205], v148 offset:49152
	ds_read_b128 v[146:149], v148 offset:50176
	s_barrier
	s_waitcnt lgkmcnt(0)
	s_waitcnt lgkmcnt(0)
	v_mfma_f32_16x16x32_bf16 v[60:63], v[154:157], v[80:83], v[60:63]
	v_mfma_f32_16x16x32_bf16 v[56:59], v[162:165], v[80:83], v[56:59]
	v_mfma_f32_16x16x32_bf16 v[52:55], v[154:157], v[170:173], v[52:55]
	v_mfma_f32_16x16x32_bf16 v[48:51], v[162:165], v[170:173], v[48:51]
	v_mfma_f32_16x16x32_bf16 v[44:47], v[154:157], v[174:177], v[44:47]
	v_mfma_f32_16x16x32_bf16 v[40:43], v[162:165], v[174:177], v[40:43]
	v_mfma_f32_16x16x32_bf16 v[36:39], v[154:157], v[202:205], v[36:39]
	v_mfma_f32_16x16x32_bf16 v[32:35], v[162:165], v[202:205], v[32:35]
	v_mfma_f32_16x16x32_bf16 v[68:71], v[158:161], v[84:87], v[60:63]
	v_mfma_f32_16x16x32_bf16 v[64:67], v[166:169], v[84:87], v[56:59]
	v_mfma_f32_16x16x32_bf16 v[60:63], v[158:161], v[150:153], v[52:55]
	v_mfma_f32_16x16x32_bf16 v[56:59], v[166:169], v[150:153], v[48:51]
	v_mfma_f32_16x16x32_bf16 v[52:55], v[158:161], v[198:201], v[44:47]
	v_mfma_f32_16x16x32_bf16 v[48:51], v[166:169], v[198:201], v[40:43]
	v_mfma_f32_16x16x32_bf16 v[44:47], v[158:161], v[146:149], v[36:39]
	v_mfma_f32_16x16x32_bf16 v[36:39], v[166:169], v[146:149], v[32:35]
	v_mfma_f32_16x16x32_bf16 v[28:31], v[222:225], v[80:83], v[28:31]
	v_mfma_f32_16x16x32_bf16 v[24:27], v[230:233], v[80:83], v[24:27]
	v_mfma_f32_16x16x32_bf16 v[16:19], v[230:233], v[170:173], v[16:19]
	v_mfma_f32_16x16x32_bf16 v[20:23], v[222:225], v[170:173], v[20:23]
	v_mfma_f32_16x16x32_bf16 v[12:15], v[222:225], v[174:177], v[12:15]
	v_mfma_f32_16x16x32_bf16 v[8:11], v[230:233], v[174:177], v[8:11]
	v_mfma_f32_16x16x32_bf16 v[0:3], v[230:233], v[202:205], v[0:3]
	v_mfma_f32_16x16x32_bf16 v[4:7], v[222:225], v[202:205], v[4:7]
	v_mfma_f32_16x16x32_bf16 v[28:31], v[226:229], v[84:87], v[28:31]
	v_mfma_f32_16x16x32_bf16 v[24:27], v[234:237], v[84:87], v[24:27]
	v_mfma_f32_16x16x32_bf16 v[16:19], v[234:237], v[150:153], v[16:19]
	v_mfma_f32_16x16x32_bf16 v[20:23], v[226:229], v[150:153], v[20:23]
	v_mfma_f32_16x16x32_bf16 v[12:15], v[226:229], v[198:201], v[12:15]
	v_mfma_f32_16x16x32_bf16 v[8:11], v[234:237], v[198:201], v[8:11]
	v_mfma_f32_16x16x32_bf16 v[0:3], v[234:237], v[146:149], v[0:3]
	v_mfma_f32_16x16x32_bf16 v[4:7], v[226:229], v[146:149], v[4:7]
	s_movk_i32 s0, 0x100
	v_cmp_gt_u32_e32 vcc, s0, v144
	s_barrier
	s_and_saveexec_b64 s[0:1], vcc
	s_cbranch_execz .LBB0_545
	s_barrier

; #define WAIT_V(n) asm volatile("s_waitcnt vmcnt(" #n ")" ::: "memory")
; #define WAIT_L(n) asm volatile("s_waitcnt lgkmcnt(" #n ")" ::: "memory")
; #define BAR __builtin_amdgcn_s_barrier()
; #define SCHED __builtin_amdgcn_sched_barrier(0)
; #define LDA(dst, b, h)                                                                            \
;   _Pragma("unroll") for (int m = 0; m < 4; ++m) _Pragma("unroll") for (int k = 0; k < 2; ++k)                                         \
;     dst[m][k] = *reinterpret_cast<const bf16x8*>((char*)SA(b, h) + lds_byte(wr * 64 + m * 16 + fr, k * 32 + fq * 8))
; #define LDB(dst, b, h)                                                                            \
;   _Pragma("unroll") for (int n = 0; n < 2; ++n) _Pragma("unroll") for (int k = 0; k < 2; ++k)                                         \
;     dst[n][k] = *reinterpret_cast<const bf16x8*>((char*)SB(b, h) + lds_byte(wc * 32 + n * 16 + fr, k * 32 + fq * 8))
; template <int K, bool SWAP>
; __device__ __forceinline__ void gemm_kloop(const bf16* __restrict__ A, const bf16* __restrict__ Bt,
;                                            f32x4 (&acc)[2][2][4][2], bool pref = false) {
;     ...
;     LDB(B0, 0, 0); SCHED; LDA(At, 0, 0); STAGE(SA(1, 1), A, HALF, t + 1);
;     WAIT_L(8); BAR; WAIT_L(0); MMA(0, 0, At, B0); BAR; SCHED;
;     LDB(B1, 0, 1); STAGE(SB(0, 0), Bt, 0, t + 2);
;     BAR; WAIT_L(0); MMA(0, 1, At, B1); BAR;
;     LDA(At, 0, 1); STAGE(SA(0, 0), A, 0, t + 2);
;     BAR; WAIT_L(0); MMA(1, 0, At, B0); BAR; SCHED;
;     STAGE(SB(0, 1), Bt, HALF, t + 2);
;     WAIT_V(6); BAR; MMA(1, 1, At, B1); BAR;
.LBB0_590:
	ds_read_b128 v[162:165], v159
	ds_read_b128 v[166:169], v159 offset:1024
	ds_read_b128 v[170:173], v159 offset:2048
	ds_read_b128 v[174:177], v159 offset:3072
	v_add_u32_e32 v160, 0xc000, v146
	v_lshl_add_u64 v[178:179], s[6:7], 0, v[140:141]
	v_readfirstlane_b32 s14, v160
	v_lshl_add_u64 v[188:189], v[178:179], 0, s[22:23]
	s_mov_b32 m0, s14
	v_add_u32_e32 v161, 0xe000, v146
	ds_read_b128 v[198:201], v151
	ds_read_b128 v[202:205], v151 offset:1024
	ds_read_b128 v[206:209], v150
	ds_read_b128 v[210:213], v150 offset:1024
	ds_read_b128 v[214:217], v149
	ds_read_b128 v[218:221], v149 offset:1024
	ds_read_b128 v[222:225], v148
	ds_read_b128 v[226:229], v148 offset:1024
	global_load_lds_dwordx4 v[188:189], off
	v_lshl_add_u64 v[188:189], s[6:7], 0, v[142:143]
	v_readfirstlane_b32 s14, v161
	v_lshl_add_u64 v[230:231], v[188:189], 0, s[22:23]
	s_mov_b32 m0, s14
	s_nop 0
	global_load_lds_dwordx4 v[230:231], off
	s_waitcnt lgkmcnt(8)
	s_barrier
	s_waitcnt lgkmcnt(0)
	s_waitcnt lgkmcnt(0)
	v_mfma_f32_16x16x32_bf16 v[124:127], v[162:165], v[198:201], v[124:127]
	v_mfma_f32_16x16x32_bf16 v[120:123], v[170:173], v[198:201], v[120:123]
	v_mfma_f32_16x16x32_bf16 v[112:115], v[170:173], v[206:209], v[112:115]
	v_mfma_f32_16x16x32_bf16 v[116:119], v[162:165], v[206:209], v[116:119]
	v_mfma_f32_16x16x32_bf16 v[108:111], v[162:165], v[214:217], v[108:111]
	v_mfma_f32_16x16x32_bf16 v[104:107], v[170:173], v[214:217], v[104:107]
	v_mfma_f32_16x16x32_bf16 v[96:99], v[170:173], v[222:225], v[96:99]
	v_mfma_f32_16x16x32_bf16 v[100:103], v[162:165], v[222:225], v[100:103]
	v_mfma_f32_16x16x32_bf16 v[124:127], v[166:169], v[202:205], v[124:127]
	v_mfma_f32_16x16x32_bf16 v[120:123], v[174:177], v[202:205], v[120:123]
	v_mfma_f32_16x16x32_bf16 v[112:115], v[174:177], v[210:213], v[112:115]
	v_mfma_f32_16x16x32_bf16 v[116:119], v[166:169], v[210:213], v[116:119]
	v_mfma_f32_16x16x32_bf16 v[108:111], v[166:169], v[218:221], v[108:111]
	v_mfma_f32_16x16x32_bf16 v[104:107], v[174:177], v[218:221], v[104:107]
	v_mfma_f32_16x16x32_bf16 v[96:99], v[174:177], v[226:229], v[96:99]
	v_mfma_f32_16x16x32_bf16 v[100:103], v[166:169], v[226:229], v[100:103]
	s_barrier
	v_add_u32_e32 v186, s1, v145
	v_lshl_add_u64 v[246:247], s[6:7], 0, v[136:137]
	v_readfirstlane_b32 s14, v186
	v_lshl_add_u64 v[248:249], v[246:247], 0, s[40:41]
	s_mov_b32 m0, s14
	v_add_u32_e32 v186, 0x2000, v186
	ds_read_b128 v[230:233], v156
	ds_read_b128 v[234:237], v156 offset:1024
	ds_read_b128 v[238:241], v156 offset:2048
	ds_read_b128 v[242:245], v156 offset:3072
	global_load_lds_dwordx4 v[248:249], off
	v_lshl_add_u64 v[248:249], s[6:7], 0, v[138:139]
	v_readfirstlane_b32 s14, v186
	v_lshl_add_u64 v[250:251], v[248:249], 0, s[40:41]
	s_mov_b32 m0, s14
	s_nop 0
	global_load_lds_dwordx4 v[250:251], off
	s_barrier
	s_waitcnt lgkmcnt(0)
	s_waitcnt lgkmcnt(0)
	v_mfma_f32_16x16x32_bf16 v[92:95], v[230:233], v[198:201], v[92:95]
	v_mfma_f32_16x16x32_bf16 v[88:91], v[238:241], v[198:201], v[88:91]
	v_mfma_f32_16x16x32_bf16 v[80:83], v[238:241], v[206:209], v[80:83]
	v_mfma_f32_16x16x32_bf16 v[84:87], v[230:233], v[206:209], v[84:87]
	v_mfma_f32_16x16x32_bf16 v[76:79], v[230:233], v[214:217], v[76:79]
	v_mfma_f32_16x16x32_bf16 v[72:75], v[238:241], v[214:217], v[72:75]
	v_mfma_f32_16x16x32_bf16 v[64:67], v[238:241], v[222:225], v[64:67]
	v_mfma_f32_16x16x32_bf16 v[68:71], v[230:233], v[222:225], v[68:71]
	v_mfma_f32_16x16x32_bf16 v[92:95], v[234:237], v[202:205], v[92:95]
	v_mfma_f32_16x16x32_bf16 v[88:91], v[242:245], v[202:205], v[88:91]
	v_mfma_f32_16x16x32_bf16 v[80:83], v[242:245], v[210:213], v[80:83]
	v_mfma_f32_16x16x32_bf16 v[84:87], v[234:237], v[210:213], v[84:87]
	v_mfma_f32_16x16x32_bf16 v[76:79], v[234:237], v[218:221], v[76:79]
	v_mfma_f32_16x16x32_bf16 v[72:75], v[242:245], v[218:221], v[72:75]
	v_mfma_f32_16x16x32_bf16 v[64:67], v[242:245], v[226:229], v[64:67]
	v_mfma_f32_16x16x32_bf16 v[68:71], v[234:237], v[226:229], v[68:71]
	v_readfirstlane_b32 s14, v146
	v_add_u32_e32 v186, 0x2000, v146
	v_lshl_add_u64 v[250:251], v[178:179], 0, s[58:59]
	s_mov_b32 m0, s14
	v_readfirstlane_b32 s14, v186
	s_barrier
	ds_read_b128 v[198:201], v151 offset:16384
	ds_read_b128 v[202:205], v151 offset:17408
	ds_read_b128 v[206:209], v150 offset:16384
	ds_read_b128 v[210:213], v150 offset:17408
	ds_read_b128 v[214:217], v149 offset:16384
	ds_read_b128 v[218:221], v149 offset:17408
	ds_read_b128 v[222:225], v148 offset:16384
	ds_read_b128 v[226:229], v148 offset:17408
	global_load_lds_dwordx4 v[250:251], off
	v_lshl_add_u64 v[250:251], v[188:189], 0, s[58:59]
	s_mov_b32 m0, s14
	s_nop 0
	global_load_lds_dwordx4 v[250:251], off
	s_barrier
	s_waitcnt lgkmcnt(0)
	s_waitcnt lgkmcnt(0)
	v_mfma_f32_16x16x32_bf16 v[60:63], v[162:165], v[198:201], v[60:63]
	v_mfma_f32_16x16x32_bf16 v[56:59], v[170:173], v[198:201], v[56:59]
	v_mfma_f32_16x16x32_bf16 v[48:51], v[170:173], v[206:209], v[48:51]
	v_mfma_f32_16x16x32_bf16 v[52:55], v[162:165], v[206:209], v[52:55]
	v_mfma_f32_16x16x32_bf16 v[44:47], v[162:165], v[214:217], v[44:47]
	v_mfma_f32_16x16x32_bf16 v[40:43], v[170:173], v[214:217], v[40:43]
	v_mfma_f32_16x16x32_bf16 v[32:35], v[170:173], v[222:225], v[32:35]
	v_mfma_f32_16x16x32_bf16 v[36:39], v[162:165], v[222:225], v[36:39]
	v_mfma_f32_16x16x32_bf16 v[60:63], v[166:169], v[202:205], v[60:63]
	v_mfma_f32_16x16x32_bf16 v[56:59], v[174:177], v[202:205], v[56:59]
	v_mfma_f32_16x16x32_bf16 v[48:51], v[174:177], v[210:213], v[48:51]
	v_mfma_f32_16x16x32_bf16 v[52:55], v[166:169], v[210:213], v[52:55]
	v_mfma_f32_16x16x32_bf16 v[44:47], v[166:169], v[218:221], v[44:47]
	v_mfma_f32_16x16x32_bf16 v[40:43], v[174:177], v[218:221], v[40:43]
	v_mfma_f32_16x16x32_bf16 v[32:35], v[174:177], v[226:229], v[32:35]
	v_mfma_f32_16x16x32_bf16 v[36:39], v[166:169], v[226:229], v[36:39]
	s_barrier
; #define WAIT_V(n) asm volatile("s_waitcnt vmcnt(" #n ")" ::: "memory")
; #define WAIT_L(n) asm volatile("s_waitcnt lgkmcnt(" #n ")" ::: "memory")
; #define BAR __builtin_amdgcn_s_barrier()
; #define SCHED __builtin_amdgcn_sched_barrier(0)
; #define LDA(dst, b, h)                                                                            \
;   _Pragma("unroll") for (int m = 0; m < 4; ++m) _Pragma("unroll") for (int k = 0; k < 2; ++k)                                         \
;     dst[m][k] = *reinterpret_cast<const bf16x8*>((char*)SA(b, h) + lds_byte(wr * 64 + m * 16 + fr, k * 32 + fq * 8))
; #define LDB(dst, b, h)                                                                            \
;   _Pragma("unroll") for (int n = 0; n < 2; ++n) _Pragma("unroll") for (int k = 0; k < 2; ++k)                                         \
;     dst[n][k] = *reinterpret_cast<const bf16x8*>((char*)SB(b, h) + lds_byte(wc * 32 + n * 16 + fr, k * 32 + fq * 8))
; template <int K, bool SWAP>
; __device__ __forceinline__ void gemm_kloop(const bf16* __restrict__ A, const bf16* __restrict__ Bt,
;                                            f32x4 (&acc)[2][2][4][2], bool pref = false) {
;     ...
;     WAIT_V(6); BAR; MMA(1, 1, At, B1); BAR;
;     LDB(B0, 1, 0); SCHED; LDA(At, 1, 0); STAGE(SA(0, 1), A, HALF, t + 2);
;     WAIT_L(8); BAR; WAIT_L(0); MMA(0, 0, At, B0); BAR; SCHED;
;     LDB(B1, 1, 1); STAGE(SB(1, 0), Bt, 0, t + 3);
;     BAR; WAIT_L(0); MMA(0, 1, At, B1); BAR;
;     LDA(At, 1, 1); STAGE(SA(1, 0), A, 0, t + 3);
;     BAR; WAIT_L(0); MMA(1, 0, At, B0); BAR; SCHED;
	v_readfirstlane_b32 s14, v147
	v_add_u32_e32 v164, 0x2000, v147
	v_lshl_add_u64 v[162:163], v[246:247], 0, s[60:61]
	s_mov_b32 m0, s14
	v_readfirstlane_b32 s14, v164
	global_load_lds_dwordx4 v[162:163], off
	v_lshl_add_u64 v[162:163], v[248:249], 0, s[60:61]
	s_mov_b32 m0, s14
	s_nop 0
	global_load_lds_dwordx4 v[162:163], off
	s_waitcnt vmcnt(6)
	s_barrier
	v_mfma_f32_16x16x32_bf16 v[28:31], v[230:233], v[198:201], v[28:31]
	v_mfma_f32_16x16x32_bf16 v[24:27], v[238:241], v[198:201], v[24:27]
	v_mfma_f32_16x16x32_bf16 v[16:19], v[238:241], v[206:209], v[16:19]
	v_mfma_f32_16x16x32_bf16 v[20:23], v[230:233], v[206:209], v[20:23]
	v_mfma_f32_16x16x32_bf16 v[12:15], v[230:233], v[214:217], v[12:15]
	v_mfma_f32_16x16x32_bf16 v[8:11], v[238:241], v[214:217], v[8:11]
	v_mfma_f32_16x16x32_bf16 v[0:3], v[238:241], v[222:225], v[0:3]
	v_mfma_f32_16x16x32_bf16 v[4:7], v[230:233], v[222:225], v[4:7]
	v_mfma_f32_16x16x32_bf16 v[28:31], v[234:237], v[202:205], v[28:31]
	v_mfma_f32_16x16x32_bf16 v[24:27], v[242:245], v[202:205], v[24:27]
	v_mfma_f32_16x16x32_bf16 v[16:19], v[242:245], v[210:213], v[16:19]
	v_mfma_f32_16x16x32_bf16 v[20:23], v[234:237], v[210:213], v[20:23]
	v_mfma_f32_16x16x32_bf16 v[12:15], v[234:237], v[218:221], v[12:15]
	v_mfma_f32_16x16x32_bf16 v[8:11], v[242:245], v[218:221], v[8:11]
	v_mfma_f32_16x16x32_bf16 v[0:3], v[242:245], v[226:229], v[0:3]
	v_mfma_f32_16x16x32_bf16 v[4:7], v[234:237], v[226:229], v[4:7]
	s_barrier
	ds_read_b128 v[162:165], v153
	ds_read_b128 v[166:169], v153 offset:1024
	ds_read_b128 v[170:173], v153 offset:2048
	ds_read_b128 v[174:177], v153 offset:3072
	v_add_u32_e32 v186, 0x4000, v146
	v_lshl_add_u64 v[230:231], v[178:179], 0, s[72:73]
	v_readfirstlane_b32 s14, v186
	v_add_u32_e32 v186, 0x6000, v146
	s_mov_b32 m0, s14
	v_readfirstlane_b32 s14, v186
	ds_read_b128 v[198:201], v151 offset:32768
	ds_read_b128 v[202:205], v151 offset:33792
	ds_read_b128 v[206:209], v150 offset:32768
	ds_read_b128 v[210:213], v150 offset:33792
	ds_read_b128 v[214:217], v149 offset:32768
	ds_read_b128 v[218:221], v149 offset:33792
	ds_read_b128 v[222:225], v148 offset:32768
	ds_read_b128 v[226:229], v148 offset:33792
	global_load_lds_dwordx4 v[230:231], off
	v_lshl_add_u64 v[230:231], v[188:189], 0, s[72:73]
	s_mov_b32 m0, s14
	s_nop 0
	global_load_lds_dwordx4 v[230:231], off
	s_waitcnt lgkmcnt(8)
	s_barrier
	s_waitcnt lgkmcnt(0)
	s_waitcnt lgkmcnt(0)
	v_mfma_f32_16x16x32_bf16 v[124:127], v[162:165], v[198:201], v[124:127]
	v_mfma_f32_16x16x32_bf16 v[120:123], v[170:173], v[198:201], v[120:123]
	v_mfma_f32_16x16x32_bf16 v[112:115], v[170:173], v[206:209], v[112:115]
	v_mfma_f32_16x16x32_bf16 v[116:119], v[162:165], v[206:209], v[116:119]
	v_mfma_f32_16x16x32_bf16 v[108:111], v[162:165], v[214:217], v[108:111]
	v_mfma_f32_16x16x32_bf16 v[104:107], v[170:173], v[214:217], v[104:107]
	v_mfma_f32_16x16x32_bf16 v[96:99], v[170:173], v[222:225], v[96:99]
	v_mfma_f32_16x16x32_bf16 v[100:103], v[162:165], v[222:225], v[100:103]
	v_mfma_f32_16x16x32_bf16 v[124:127], v[166:169], v[202:205], v[124:127]
	v_mfma_f32_16x16x32_bf16 v[120:123], v[174:177], v[202:205], v[120:123]
	v_mfma_f32_16x16x32_bf16 v[112:115], v[174:177], v[210:213], v[112:115]
	v_mfma_f32_16x16x32_bf16 v[116:119], v[166:169], v[210:213], v[116:119]
	v_mfma_f32_16x16x32_bf16 v[108:111], v[166:169], v[218:221], v[108:111]
	v_mfma_f32_16x16x32_bf16 v[104:107], v[174:177], v[218:221], v[104:107]
	v_mfma_f32_16x16x32_bf16 v[96:99], v[174:177], v[226:229], v[96:99]
	v_mfma_f32_16x16x32_bf16 v[100:103], v[166:169], v[226:229], v[100:103]
	s_barrier
	v_readfirstlane_b32 s14, v154
	v_add_u32_e32 v186, 0x2000, v154
	v_lshl_add_u64 v[250:251], v[246:247], 0, vcc
	s_mov_b32 m0, s14
	v_readfirstlane_b32 s14, v186
	ds_read_b128 v[230:233], v152
	ds_read_b128 v[234:237], v152 offset:1024
	ds_read_b128 v[238:241], v152 offset:2048
	ds_read_b128 v[242:245], v152 offset:3072
	global_load_lds_dwordx4 v[250:251], off
	v_lshl_add_u64 v[250:251], v[248:249], 0, vcc
	s_mov_b32 m0, s14
	s_nop 0
	global_load_lds_dwordx4 v[250:251], off
	s_barrier
	s_waitcnt lgkmcnt(0)
	s_waitcnt lgkmcnt(0)
	v_mfma_f32_16x16x32_bf16 v[92:95], v[230:233], v[198:201], v[92:95]
	v_mfma_f32_16x16x32_bf16 v[88:91], v[238:241], v[198:201], v[88:91]
	v_mfma_f32_16x16x32_bf16 v[80:83], v[238:241], v[206:209], v[80:83]
	v_mfma_f32_16x16x32_bf16 v[84:87], v[230:233], v[206:209], v[84:87]
	v_mfma_f32_16x16x32_bf16 v[76:79], v[230:233], v[214:217], v[76:79]
	v_mfma_f32_16x16x32_bf16 v[72:75], v[238:241], v[214:217], v[72:75]
	v_mfma_f32_16x16x32_bf16 v[64:67], v[238:241], v[222:225], v[64:67]
	v_mfma_f32_16x16x32_bf16 v[68:71], v[230:233], v[222:225], v[68:71]
	v_mfma_f32_16x16x32_bf16 v[92:95], v[234:237], v[202:205], v[92:95]
	v_mfma_f32_16x16x32_bf16 v[88:91], v[242:245], v[202:205], v[88:91]
	v_mfma_f32_16x16x32_bf16 v[80:83], v[242:245], v[210:213], v[80:83]
	v_mfma_f32_16x16x32_bf16 v[84:87], v[234:237], v[210:213], v[84:87]
	v_mfma_f32_16x16x32_bf16 v[76:79], v[234:237], v[218:221], v[76:79]
	v_mfma_f32_16x16x32_bf16 v[72:75], v[242:245], v[218:221], v[72:75]
	v_mfma_f32_16x16x32_bf16 v[64:67], v[242:245], v[226:229], v[64:67]
	v_mfma_f32_16x16x32_bf16 v[68:71], v[234:237], v[226:229], v[68:71]
	v_readfirstlane_b32 s14, v155
	v_lshl_add_u64 v[178:179], v[178:179], 0, s[64:65]
	s_mov_b32 m0, s14
	v_readfirstlane_b32 s14, v157
	s_barrier
	ds_read_b128 v[198:201], v151 offset:49152
	ds_read_b128 v[202:205], v151 offset:50176
	ds_read_b128 v[206:209], v150 offset:49152
	ds_read_b128 v[210:213], v150 offset:50176
	ds_read_b128 v[214:217], v149 offset:49152
	ds_read_b128 v[218:221], v149 offset:50176
	ds_read_b128 v[222:225], v148 offset:49152
	ds_read_b128 v[226:229], v148 offset:50176
	global_load_lds_dwordx4 v[178:179], off
	v_lshl_add_u64 v[178:179], v[188:189], 0, s[64:65]
	s_mov_b32 m0, s14
	s_nop 0
	global_load_lds_dwordx4 v[178:179], off
	s_barrier
; #define WAIT_V(n) asm volatile("s_waitcnt vmcnt(" #n ")" ::: "memory")
; #define WAIT_L(n) asm volatile("s_waitcnt lgkmcnt(" #n ")" ::: "memory")
; #define BAR __builtin_amdgcn_s_barrier()
; #define SCHED __builtin_amdgcn_sched_barrier(0)
; #define LDA(dst, b, h)                                                                            \
;   _Pragma("unroll") for (int m = 0; m < 4; ++m) _Pragma("unroll") for (int k = 0; k < 2; ++k)                                         \
;     dst[m][k] = *reinterpret_cast<const bf16x8*>((char*)SA(b, h) + lds_byte(wr * 64 + m * 16 + fr, k * 32 + fq * 8))
; #define LDB(dst, b, h)                                                                            \
;   _Pragma("unroll") for (int n = 0; n < 2; ++n) _Pragma("unroll") for (int k = 0; k < 2; ++k)                                         \
;     dst[n][k] = *reinterpret_cast<const bf16x8*>((char*)SB(b, h) + lds_byte(wc * 32 + n * 16 + fr, k * 32 + fq * 8))
; template <int K, bool SWAP>
; __device__ __forceinline__ void gemm_kloop(const bf16* __restrict__ A, const bf16* __restrict__ Bt,
;                                            f32x4 (&acc)[2][2][4][2], bool pref = false) {
;     ...
;     BAR; WAIT_L(0); MMA(1, 0, At, B0); BAR; SCHED;
;     STAGE(SB(1, 1), Bt, HALF, t + 3);
;     WAIT_V(6); BAR; MMA(1, 1, At, B1); BAR;
;   }
;   { LDB(B0, 0, 0); LDA(At, 0, 0); STAGE(SA(1, 1), A, HALF, nt - 1);
;     BAR; WAIT_L(0); MMA(0, 0, At, B0); BAR;
;     LDB(B1, 0, 1); BAR; WAIT_L(0); MMA(0, 1, At, B1); BAR;
;     LDA(At, 0, 1); WAIT_V(4); BAR; WAIT_L(0); MMA(1, 0, At, B0); MMA(1, 1, At, B1); BAR; }
	s_waitcnt lgkmcnt(0)
	s_waitcnt lgkmcnt(0)
	v_mfma_f32_16x16x32_bf16 v[60:63], v[162:165], v[198:201], v[60:63]
	v_mfma_f32_16x16x32_bf16 v[56:59], v[170:173], v[198:201], v[56:59]
	v_mfma_f32_16x16x32_bf16 v[48:51], v[170:173], v[206:209], v[48:51]
	v_mfma_f32_16x16x32_bf16 v[52:55], v[162:165], v[206:209], v[52:55]
	v_mfma_f32_16x16x32_bf16 v[44:47], v[162:165], v[214:217], v[44:47]
	v_mfma_f32_16x16x32_bf16 v[40:43], v[170:173], v[214:217], v[40:43]
	v_mfma_f32_16x16x32_bf16 v[32:35], v[170:173], v[222:225], v[32:35]
	v_mfma_f32_16x16x32_bf16 v[36:39], v[162:165], v[222:225], v[36:39]
	v_mfma_f32_16x16x32_bf16 v[60:63], v[166:169], v[202:205], v[60:63]
	v_mfma_f32_16x16x32_bf16 v[56:59], v[174:177], v[202:205], v[56:59]
	v_mfma_f32_16x16x32_bf16 v[48:51], v[174:177], v[210:213], v[48:51]
	v_mfma_f32_16x16x32_bf16 v[52:55], v[166:169], v[210:213], v[52:55]
	v_mfma_f32_16x16x32_bf16 v[44:47], v[166:169], v[218:221], v[44:47]
	v_mfma_f32_16x16x32_bf16 v[40:43], v[174:177], v[218:221], v[40:43]
	v_mfma_f32_16x16x32_bf16 v[32:35], v[174:177], v[226:229], v[32:35]
	v_mfma_f32_16x16x32_bf16 v[36:39], v[166:169], v[226:229], v[36:39]
	s_barrier
	v_readfirstlane_b32 s14, v158
	v_add_u32_e32 v164, 0x2000, v158
	v_lshl_add_u64 v[162:163], v[246:247], 0, s[70:71]
	s_mov_b32 m0, s14
	v_readfirstlane_b32 s14, v164
	global_load_lds_dwordx4 v[162:163], off
	v_lshl_add_u64 v[162:163], v[248:249], 0, s[70:71]
	s_mov_b32 m0, s14
	s_nop 0
	global_load_lds_dwordx4 v[162:163], off
	s_waitcnt vmcnt(6)
	s_barrier
	v_mfma_f32_16x16x32_bf16 v[28:31], v[230:233], v[198:201], v[28:31]
	v_mfma_f32_16x16x32_bf16 v[24:27], v[238:241], v[198:201], v[24:27]
	v_mfma_f32_16x16x32_bf16 v[16:19], v[238:241], v[206:209], v[16:19]
	v_mfma_f32_16x16x32_bf16 v[20:23], v[230:233], v[206:209], v[20:23]
	v_mfma_f32_16x16x32_bf16 v[12:15], v[230:233], v[214:217], v[12:15]
	v_mfma_f32_16x16x32_bf16 v[8:11], v[238:241], v[214:217], v[8:11]
	v_mfma_f32_16x16x32_bf16 v[0:3], v[238:241], v[222:225], v[0:3]
	v_mfma_f32_16x16x32_bf16 v[4:7], v[230:233], v[222:225], v[4:7]
	v_mfma_f32_16x16x32_bf16 v[28:31], v[234:237], v[202:205], v[28:31]
	v_mfma_f32_16x16x32_bf16 v[24:27], v[242:245], v[202:205], v[24:27]
	v_mfma_f32_16x16x32_bf16 v[16:19], v[242:245], v[210:213], v[16:19]
	v_mfma_f32_16x16x32_bf16 v[20:23], v[234:237], v[210:213], v[20:23]
	v_mfma_f32_16x16x32_bf16 v[12:15], v[234:237], v[218:221], v[12:15]
	v_mfma_f32_16x16x32_bf16 v[8:11], v[242:245], v[218:221], v[8:11]
	v_mfma_f32_16x16x32_bf16 v[0:3], v[242:245], v[226:229], v[0:3]
	v_mfma_f32_16x16x32_bf16 v[4:7], v[234:237], v[226:229], v[4:7]
	s_add_i32 s5, s5, 2
	v_lshl_add_u64 v[136:137], v[136:137], 0, s[44:45]
	v_lshl_add_u64 v[138:139], v[138:139], 0, s[44:45]
	v_lshl_add_u64 v[140:141], v[140:141], 0, s[44:45]
	s_cmp_lt_u32 s5, 60
	v_lshl_add_u64 v[142:143], v[142:143], 0, s[44:45]
	s_barrier
	s_cbranch_scc1 .LBB0_590
	s_add_u32 s12, s12, 0x101f80
	s_addc_u32 s13, s13, 0
	v_lshl_add_u64 v[130:131], s[12:13], 0, v[130:131]
	v_readfirstlane_b32 s5, v160
	v_lshl_add_u64 v[128:129], v[128:129], 1, v[130:131]
	s_mov_b32 m0, s5
	ds_read_b128 v[136:139], v159
	ds_read_b128 v[140:143], v159 offset:1024
	ds_read_b128 v[162:165], v159 offset:2048
	ds_read_b128 v[166:169], v159 offset:3072
	ds_read_b128 v[170:173], v151
	ds_read_b128 v[174:177], v151 offset:1024
	ds_read_b128 v[198:201], v150
	ds_read_b128 v[202:205], v150 offset:1024
	ds_read_b128 v[206:209], v149
	ds_read_b128 v[210:213], v149 offset:1024
	ds_read_b128 v[214:217], v148
	ds_read_b128 v[218:221], v148 offset:1024
	global_load_lds_dwordx4 v[128:129], off
	v_lshl_add_u64 v[128:129], s[12:13], 0, v[134:135]
	v_readfirstlane_b32 s5, v161
	v_lshl_add_u64 v[128:129], v[132:133], 1, v[128:129]
	s_mov_b32 m0, s5
	s_nop 0
	global_load_lds_dwordx4 v[128:129], off
	s_barrier
	s_waitcnt lgkmcnt(0)
	s_waitcnt lgkmcnt(0)
	v_mfma_f32_16x16x32_bf16 v[124:127], v[136:139], v[170:173], v[124:127]
	v_mfma_f32_16x16x32_bf16 v[120:123], v[162:165], v[170:173], v[120:123]
	v_mfma_f32_16x16x32_bf16 v[112:115], v[162:165], v[198:201], v[112:115]
	v_mfma_f32_16x16x32_bf16 v[116:119], v[136:139], v[198:201], v[116:119]
	v_mfma_f32_16x16x32_bf16 v[108:111], v[136:139], v[206:209], v[108:111]
	v_mfma_f32_16x16x32_bf16 v[104:107], v[162:165], v[206:209], v[104:107]
	v_mfma_f32_16x16x32_bf16 v[96:99], v[162:165], v[214:217], v[96:99]
	v_mfma_f32_16x16x32_bf16 v[100:103], v[136:139], v[214:217], v[100:103]
	v_mfma_f32_16x16x32_bf16 v[124:127], v[140:143], v[174:177], v[124:127]
	v_mfma_f32_16x16x32_bf16 v[120:123], v[166:169], v[174:177], v[120:123]
	v_mfma_f32_16x16x32_bf16 v[112:115], v[166:169], v[202:205], v[112:115]
	v_mfma_f32_16x16x32_bf16 v[116:119], v[140:143], v[202:205], v[116:119]
	v_mfma_f32_16x16x32_bf16 v[108:111], v[140:143], v[210:213], v[108:111]
	v_mfma_f32_16x16x32_bf16 v[104:107], v[166:169], v[210:213], v[104:107]
	v_mfma_f32_16x16x32_bf16 v[96:99], v[166:169], v[218:221], v[96:99]
	v_mfma_f32_16x16x32_bf16 v[100:103], v[140:143], v[218:221], v[100:103]
	s_barrier
	ds_read_b128 v[128:131], v156
	ds_read_b128 v[132:135], v156 offset:1024
	ds_read_b128 v[158:161], v156 offset:2048
	ds_read_b128 v[154:157], v156 offset:3072
	s_barrier
; #define WAIT_V(n) asm volatile("s_waitcnt vmcnt(" #n ")" ::: "memory")
; #define WAIT_L(n) asm volatile("s_waitcnt lgkmcnt(" #n ")" ::: "memory")
; #define BAR __builtin_amdgcn_s_barrier()
; #define LDA(dst, b, h)                                                                            \
;   _Pragma("unroll") for (int m = 0; m < 4; ++m) _Pragma("unroll") for (int k = 0; k < 2; ++k)                                         \
;     dst[m][k] = *reinterpret_cast<const bf16x8*>((char*)SA(b, h) + lds_byte(wr * 64 + m * 16 + fr, k * 32 + fq * 8))
; #define LDB(dst, b, h)                                                                            \
;   _Pragma("unroll") for (int n = 0; n < 2; ++n) _Pragma("unroll") for (int k = 0; k < 2; ++k)                                         \
;     dst[n][k] = *reinterpret_cast<const bf16x8*>((char*)SB(b, h) + lds_byte(wc * 32 + n * 16 + fr, k * 32 + fq * 8))
; template <int K, bool SWAP>
; __device__ __forceinline__ void gemm_kloop(const bf16* __restrict__ A, const bf16* __restrict__ Bt,
;                                            f32x4 (&acc)[2][2][4][2], bool pref = false) {
;     ...
;     LDB(B1, 0, 1); BAR; WAIT_L(0); MMA(0, 1, At, B1); BAR;
;     LDA(At, 0, 1); WAIT_V(4); BAR; WAIT_L(0); MMA(1, 0, At, B0); MMA(1, 1, At, B1); BAR; }
;   { LDB(B0, 1, 0); LDA(At, 1, 0); WAIT_V(2); BAR; WAIT_L(0); MMA(0, 0, At, B0); BAR;
;     LDB(B1, 1, 1); WAIT_V(0); BAR; WAIT_L(0); MMA(0, 1, At, B1); BAR;
	s_waitcnt lgkmcnt(0)
	s_waitcnt lgkmcnt(0)
	v_mfma_f32_16x16x32_bf16 v[92:95], v[128:131], v[170:173], v[92:95]
	v_mfma_f32_16x16x32_bf16 v[88:91], v[158:161], v[170:173], v[88:91]
	v_mfma_f32_16x16x32_bf16 v[80:83], v[158:161], v[198:201], v[80:83]
	v_mfma_f32_16x16x32_bf16 v[84:87], v[128:131], v[198:201], v[84:87]
	v_mfma_f32_16x16x32_bf16 v[76:79], v[128:131], v[206:209], v[76:79]
	v_mfma_f32_16x16x32_bf16 v[72:75], v[158:161], v[206:209], v[72:75]
	v_mfma_f32_16x16x32_bf16 v[64:67], v[158:161], v[214:217], v[64:67]
	v_mfma_f32_16x16x32_bf16 v[68:71], v[128:131], v[214:217], v[68:71]
	v_mfma_f32_16x16x32_bf16 v[92:95], v[132:135], v[174:177], v[92:95]
	v_mfma_f32_16x16x32_bf16 v[88:91], v[154:157], v[174:177], v[88:91]
	v_mfma_f32_16x16x32_bf16 v[80:83], v[154:157], v[202:205], v[80:83]
	v_mfma_f32_16x16x32_bf16 v[84:87], v[132:135], v[202:205], v[84:87]
	v_mfma_f32_16x16x32_bf16 v[76:79], v[132:135], v[210:213], v[76:79]
	v_mfma_f32_16x16x32_bf16 v[72:75], v[154:157], v[210:213], v[72:75]
	v_mfma_f32_16x16x32_bf16 v[64:67], v[154:157], v[218:221], v[64:67]
	v_mfma_f32_16x16x32_bf16 v[68:71], v[132:135], v[218:221], v[68:71]
	s_barrier
	ds_read_b128 v[170:173], v151 offset:16384
	ds_read_b128 v[174:177], v151 offset:17408
	ds_read_b128 v[198:201], v150 offset:16384
	ds_read_b128 v[202:205], v150 offset:17408
	ds_read_b128 v[206:209], v149 offset:16384
	ds_read_b128 v[210:213], v149 offset:17408
	ds_read_b128 v[214:217], v148 offset:16384
	ds_read_b128 v[218:221], v148 offset:17408
	s_waitcnt vmcnt(4)
	s_barrier
	s_waitcnt lgkmcnt(0)
	s_waitcnt lgkmcnt(0)
	v_mfma_f32_16x16x32_bf16 v[60:63], v[136:139], v[170:173], v[60:63]
	v_mfma_f32_16x16x32_bf16 v[56:59], v[162:165], v[170:173], v[56:59]
	v_mfma_f32_16x16x32_bf16 v[48:51], v[162:165], v[198:201], v[48:51]
	v_mfma_f32_16x16x32_bf16 v[52:55], v[136:139], v[198:201], v[52:55]
	v_mfma_f32_16x16x32_bf16 v[44:47], v[136:139], v[206:209], v[44:47]
	v_mfma_f32_16x16x32_bf16 v[40:43], v[162:165], v[206:209], v[40:43]
	v_mfma_f32_16x16x32_bf16 v[32:35], v[162:165], v[214:217], v[32:35]
	v_mfma_f32_16x16x32_bf16 v[36:39], v[136:139], v[214:217], v[36:39]
	v_mfma_f32_16x16x32_bf16 v[60:63], v[140:143], v[174:177], v[60:63]
	v_mfma_f32_16x16x32_bf16 v[56:59], v[166:169], v[174:177], v[56:59]
	v_mfma_f32_16x16x32_bf16 v[48:51], v[166:169], v[202:205], v[48:51]
	v_mfma_f32_16x16x32_bf16 v[52:55], v[140:143], v[202:205], v[52:55]
	v_mfma_f32_16x16x32_bf16 v[44:47], v[140:143], v[210:213], v[44:47]
	v_mfma_f32_16x16x32_bf16 v[40:43], v[166:169], v[210:213], v[40:43]
	v_mfma_f32_16x16x32_bf16 v[32:35], v[166:169], v[218:221], v[32:35]
	v_mfma_f32_16x16x32_bf16 v[36:39], v[140:143], v[218:221], v[36:39]
	v_mfma_f32_16x16x32_bf16 v[28:31], v[128:131], v[170:173], v[28:31]
	v_mfma_f32_16x16x32_bf16 v[24:27], v[158:161], v[170:173], v[24:27]
	v_mfma_f32_16x16x32_bf16 v[16:19], v[158:161], v[198:201], v[16:19]
	v_mfma_f32_16x16x32_bf16 v[20:23], v[128:131], v[198:201], v[20:23]
	v_mfma_f32_16x16x32_bf16 v[12:15], v[128:131], v[206:209], v[12:15]
	v_mfma_f32_16x16x32_bf16 v[8:11], v[158:161], v[206:209], v[8:11]
	v_mfma_f32_16x16x32_bf16 v[0:3], v[158:161], v[214:217], v[0:3]
	v_mfma_f32_16x16x32_bf16 v[4:7], v[128:131], v[214:217], v[4:7]
	v_mfma_f32_16x16x32_bf16 v[28:31], v[132:135], v[174:177], v[28:31]
	v_mfma_f32_16x16x32_bf16 v[24:27], v[154:157], v[174:177], v[24:27]
	v_mfma_f32_16x16x32_bf16 v[16:19], v[154:157], v[202:205], v[16:19]
	v_mfma_f32_16x16x32_bf16 v[20:23], v[132:135], v[202:205], v[20:23]
	v_mfma_f32_16x16x32_bf16 v[12:15], v[132:135], v[210:213], v[12:15]
	v_mfma_f32_16x16x32_bf16 v[8:11], v[154:157], v[210:213], v[8:11]
	v_mfma_f32_16x16x32_bf16 v[0:3], v[154:157], v[218:221], v[0:3]
	v_mfma_f32_16x16x32_bf16 v[4:7], v[132:135], v[218:221], v[4:7]
	s_barrier
	ds_read_b128 v[128:131], v153
	ds_read_b128 v[132:135], v153 offset:1024
	ds_read_b128 v[136:139], v153 offset:2048
	ds_read_b128 v[140:143], v153 offset:3072
	ds_read_b128 v[154:157], v151 offset:32768
	ds_read_b128 v[158:161], v151 offset:33792
	ds_read_b128 v[162:165], v150 offset:32768
	ds_read_b128 v[166:169], v150 offset:33792
	ds_read_b128 v[170:173], v149 offset:32768
	ds_read_b128 v[174:177], v149 offset:33792
	ds_read_b128 v[198:201], v148 offset:32768
	ds_read_b128 v[202:205], v148 offset:33792
	s_waitcnt vmcnt(2)
	s_barrier
; #define WAIT_V(n) asm volatile("s_waitcnt vmcnt(" #n ")" ::: "memory")
; #define WAIT_L(n) asm volatile("s_waitcnt lgkmcnt(" #n ")" ::: "memory")
; #define BAR __builtin_amdgcn_s_barrier()
; #define SCHED __builtin_amdgcn_sched_barrier(0)
; #define LDA(dst, b, h)                                                                            \
;   _Pragma("unroll") for (int m = 0; m < 4; ++m) _Pragma("unroll") for (int k = 0; k < 2; ++k)                                         \
;     dst[m][k] = *reinterpret_cast<const bf16x8*>((char*)SA(b, h) + lds_byte(wr * 64 + m * 16 + fr, k * 32 + fq * 8))
; #define LDB(dst, b, h)                                                                            \
;   _Pragma("unroll") for (int n = 0; n < 2; ++n) _Pragma("unroll") for (int k = 0; k < 2; ++k)                                         \
;     dst[n][k] = *reinterpret_cast<const bf16x8*>((char*)SB(b, h) + lds_byte(wc * 32 + n * 16 + fr, k * 32 + fq * 8))
; template <int K, bool SWAP>
; __device__ __forceinline__ void gemm_kloop(const bf16* __restrict__ A, const bf16* __restrict__ Bt,
;                                            f32x4 (&acc)[2][2][4][2], bool pref = false) {
;     ...
;   { LDB(B0, 1, 0); LDA(At, 1, 0); WAIT_V(2); BAR; WAIT_L(0); MMA(0, 0, At, B0); BAR;
;     LDB(B1, 1, 1); WAIT_V(0); BAR; WAIT_L(0); MMA(0, 1, At, B1); BAR;
;     LDA(At, 1, 1); BAR; WAIT_L(0); MMA(1, 0, At, B0); MMA(1, 1, At, B1); BAR; }
;   if (wr == 0) BAR;
;   SCHED;
	s_waitcnt lgkmcnt(0)
	s_waitcnt lgkmcnt(0)
	v_mfma_f32_16x16x32_bf16 v[124:127], v[128:131], v[154:157], v[124:127]
	v_mfma_f32_16x16x32_bf16 v[120:123], v[136:139], v[154:157], v[120:123]
	v_mfma_f32_16x16x32_bf16 v[112:115], v[136:139], v[162:165], v[112:115]
	v_mfma_f32_16x16x32_bf16 v[116:119], v[128:131], v[162:165], v[116:119]
	v_mfma_f32_16x16x32_bf16 v[108:111], v[128:131], v[170:173], v[108:111]
	v_mfma_f32_16x16x32_bf16 v[104:107], v[136:139], v[170:173], v[104:107]
	v_mfma_f32_16x16x32_bf16 v[96:99], v[136:139], v[198:201], v[96:99]
	v_mfma_f32_16x16x32_bf16 v[100:103], v[128:131], v[198:201], v[100:103]
	v_mfma_f32_16x16x32_bf16 v[124:127], v[132:135], v[158:161], v[124:127]
	v_mfma_f32_16x16x32_bf16 v[120:123], v[140:143], v[158:161], v[120:123]
	v_mfma_f32_16x16x32_bf16 v[112:115], v[140:143], v[166:169], v[112:115]
	v_mfma_f32_16x16x32_bf16 v[116:119], v[132:135], v[166:169], v[116:119]
	v_mfma_f32_16x16x32_bf16 v[108:111], v[132:135], v[174:177], v[108:111]
	v_mfma_f32_16x16x32_bf16 v[104:107], v[140:143], v[174:177], v[104:107]
	v_mfma_f32_16x16x32_bf16 v[96:99], v[140:143], v[202:205], v[96:99]
	v_mfma_f32_16x16x32_bf16 v[100:103], v[132:135], v[202:205], v[100:103]
	s_barrier
	ds_read_b128 v[206:209], v152
	ds_read_b128 v[210:213], v152 offset:1024
	ds_read_b128 v[214:217], v152 offset:2048
	ds_read_b128 v[218:221], v152 offset:3072
	s_waitcnt vmcnt(0)
	s_barrier
	s_waitcnt lgkmcnt(0)
	s_waitcnt lgkmcnt(0)
	v_mfma_f32_16x16x32_bf16 v[92:95], v[206:209], v[154:157], v[92:95]
	v_mfma_f32_16x16x32_bf16 v[88:91], v[214:217], v[154:157], v[88:91]
	v_mfma_f32_16x16x32_bf16 v[80:83], v[214:217], v[162:165], v[80:83]
	v_mfma_f32_16x16x32_bf16 v[84:87], v[206:209], v[162:165], v[84:87]
	v_mfma_f32_16x16x32_bf16 v[76:79], v[206:209], v[170:173], v[76:79]
	v_mfma_f32_16x16x32_bf16 v[72:75], v[214:217], v[170:173], v[72:75]
	v_mfma_f32_16x16x32_bf16 v[64:67], v[214:217], v[198:201], v[64:67]
	v_mfma_f32_16x16x32_bf16 v[68:71], v[206:209], v[198:201], v[68:71]
	v_mfma_f32_16x16x32_bf16 v[92:95], v[210:213], v[158:161], v[92:95]
	v_mfma_f32_16x16x32_bf16 v[88:91], v[218:221], v[158:161], v[88:91]
	v_mfma_f32_16x16x32_bf16 v[80:83], v[218:221], v[166:169], v[80:83]
	v_mfma_f32_16x16x32_bf16 v[84:87], v[210:213], v[166:169], v[84:87]
	v_mfma_f32_16x16x32_bf16 v[76:79], v[210:213], v[174:177], v[76:79]
	v_mfma_f32_16x16x32_bf16 v[72:75], v[218:221], v[174:177], v[72:75]
	v_mfma_f32_16x16x32_bf16 v[64:67], v[218:221], v[202:205], v[64:67]
	v_mfma_f32_16x16x32_bf16 v[68:71], v[210:213], v[202:205], v[68:71]
	s_barrier
	ds_read_b128 v[152:155], v151 offset:49152
	ds_read_b128 v[156:159], v151 offset:50176
	ds_read_b128 v[160:163], v150 offset:49152
	ds_read_b128 v[164:167], v150 offset:50176
	ds_read_b128 v[168:171], v149 offset:49152
	ds_read_b128 v[172:175], v149 offset:50176
	ds_read_b128 v[176:179], v148 offset:49152
	ds_read_b128 v[146:149], v148 offset:50176
	s_barrier
	s_waitcnt lgkmcnt(0)
	s_waitcnt lgkmcnt(0)
	v_mfma_f32_16x16x32_bf16 v[60:63], v[128:131], v[152:155], v[60:63]
	v_mfma_f32_16x16x32_bf16 v[56:59], v[136:139], v[152:155], v[56:59]
	v_mfma_f32_16x16x32_bf16 v[48:51], v[136:139], v[160:163], v[48:51]
	v_mfma_f32_16x16x32_bf16 v[52:55], v[128:131], v[160:163], v[52:55]
	v_mfma_f32_16x16x32_bf16 v[44:47], v[128:131], v[168:171], v[44:47]
	v_mfma_f32_16x16x32_bf16 v[40:43], v[136:139], v[168:171], v[40:43]
	v_mfma_f32_16x16x32_bf16 v[32:35], v[136:139], v[176:179], v[32:35]
	v_mfma_f32_16x16x32_bf16 v[36:39], v[128:131], v[176:179], v[36:39]
	v_mfma_f32_16x16x32_bf16 v[60:63], v[132:135], v[156:159], v[60:63]
	v_mfma_f32_16x16x32_bf16 v[56:59], v[140:143], v[156:159], v[56:59]
	v_mfma_f32_16x16x32_bf16 v[48:51], v[140:143], v[164:167], v[48:51]
	v_mfma_f32_16x16x32_bf16 v[52:55], v[132:135], v[164:167], v[52:55]
	v_mfma_f32_16x16x32_bf16 v[44:47], v[132:135], v[172:175], v[44:47]
	v_mfma_f32_16x16x32_bf16 v[40:43], v[140:143], v[172:175], v[40:43]
	v_mfma_f32_16x16x32_bf16 v[32:35], v[140:143], v[146:149], v[32:35]
	v_mfma_f32_16x16x32_bf16 v[36:39], v[132:135], v[146:149], v[36:39]
	v_mfma_f32_16x16x32_bf16 v[28:31], v[206:209], v[152:155], v[28:31]
	v_mfma_f32_16x16x32_bf16 v[24:27], v[214:217], v[152:155], v[24:27]
	v_mfma_f32_16x16x32_bf16 v[16:19], v[214:217], v[160:163], v[16:19]
	v_mfma_f32_16x16x32_bf16 v[20:23], v[206:209], v[160:163], v[20:23]
	v_mfma_f32_16x16x32_bf16 v[12:15], v[206:209], v[168:171], v[12:15]
	v_mfma_f32_16x16x32_bf16 v[8:11], v[214:217], v[168:171], v[8:11]
	v_mfma_f32_16x16x32_bf16 v[0:3], v[214:217], v[176:179], v[0:3]
	v_mfma_f32_16x16x32_bf16 v[4:7], v[206:209], v[176:179], v[4:7]
	v_mfma_f32_16x16x32_bf16 v[28:31], v[210:213], v[156:159], v[28:31]
	v_mfma_f32_16x16x32_bf16 v[24:27], v[218:221], v[156:159], v[24:27]
	v_mfma_f32_16x16x32_bf16 v[16:19], v[218:221], v[164:167], v[16:19]
	v_mfma_f32_16x16x32_bf16 v[20:23], v[210:213], v[164:167], v[20:23]
	v_mfma_f32_16x16x32_bf16 v[12:15], v[210:213], v[172:175], v[12:15]
	v_mfma_f32_16x16x32_bf16 v[8:11], v[218:221], v[172:175], v[8:11]
	v_mfma_f32_16x16x32_bf16 v[0:3], v[218:221], v[146:149], v[0:3]
	v_mfma_f32_16x16x32_bf16 v[4:7], v[210:213], v[146:149], v[4:7]
	s_movk_i32 s5, 0x100
	v_cmp_gt_u32_e32 vcc, s5, v144
	s_barrier
	s_and_saveexec_b64 s[12:13], vcc
	s_cbranch_execz .LBB0_593
	s_barrier

; #define WAIT_V(n) asm volatile("s_waitcnt vmcnt(" #n ")" ::: "memory")
; #define WAIT_L(n) asm volatile("s_waitcnt lgkmcnt(" #n ")" ::: "memory")
; #define BAR __builtin_amdgcn_s_barrier()
; #define SCHED __builtin_amdgcn_sched_barrier(0)
; #define LDA(dst, b, h)                                                                            \
;   _Pragma("unroll") for (int m = 0; m < 4; ++m) _Pragma("unroll") for (int k = 0; k < 2; ++k)                                         \
;     dst[m][k] = *reinterpret_cast<const bf16x8*>((char*)SA(b, h) + lds_byte(wr * 64 + m * 16 + fr, k * 32 + fq * 8))
; #define LDB(dst, b, h)                                                                            \
;   _Pragma("unroll") for (int n = 0; n < 2; ++n) _Pragma("unroll") for (int k = 0; k < 2; ++k)                                         \
;     dst[n][k] = *reinterpret_cast<const bf16x8*>((char*)SB(b, h) + lds_byte(wc * 32 + n * 16 + fr, k * 32 + fq * 8))
; template <int K, bool SWAP>
; __device__ __forceinline__ void gemm_kloop(const bf16* __restrict__ A, const bf16* __restrict__ Bt,
;                                            f32x4 (&acc)[2][2][4][2], bool pref = false) {
;     ...
;   if (!pref) {
;     STAGE(SB(0, 0), Bt, 0, 0); STAGE(SA(0, 0), A, 0, 0);
;     STAGE(SB(0, 1), Bt, HALF, 0); STAGE(SA(0, 1), A, HALF, 0);
;   }
;   if (wr == 1) BAR;
;   WAIT_V(4); BAR;
;   STAGE(SB(1, 0), Bt, 0, 1); STAGE(SA(1, 0), A, 0, 1); STAGE(SB(1, 1), Bt, HALF, 1);
;   WAIT_V(6); BAR;
;   for (int t = 0; t < nt - 2; t += 2) {
;     LDB(B0, 0, 0); SCHED; LDA(At, 0, 0); STAGE(SA(1, 1), A, HALF, t + 1);
;     WAIT_L(8); BAR; WAIT_L(0); MMA(0, 0, At, B0); BAR; SCHED;
.LBB0_671:
	s_or_b64 exec, exec, s[0:1]
	v_add_u32_e32 v0, v15, v0
	v_and_b32_e32 v0, 0xfffffc00, v0
	v_sub_u32_e32 v0, v15, v0
	v_lshrrev_b32_e32 v2, 4, v0
	v_bitop3_b32 v2, v2, v0, 32 bitop3:0x6c
	v_ashrrev_i32_e32 v3, 31, v2
	v_add_u32_e32 v1, v128, v1
	v_lshrrev_b32_e32 v3, 26, v3
	v_ashrrev_i32_e32 v1, 6, v1
	v_add_u32_e32 v3, v2, v3
	v_lshlrev_b32_e32 v0, 3, v1
	v_ashrrev_i32_e32 v4, 6, v3
	v_and_b32_e32 v3, 0xc0, v3
	v_and_b32_e32 v0, -16, v0
	v_lshlrev_b32_e32 v1, 5, v1
	v_sub_u32_e32 v2, v2, v3
	v_add_u32_e32 v0, v4, v0
	v_and_b32_e32 v1, 32, v1
	v_ashrrev_i16_sdwa v2, v193, sext(v2) dst_sel:DWORD dst_unused:UNUSED_PAD src0_sel:DWORD src1_sel:BYTE_0
	v_add_u32_sdwa v2, v1, sext(v2) dst_sel:DWORD dst_unused:UNUSED_PAD src0_sel:DWORD src1_sel:WORD_0
	v_ashrrev_i32_e32 v1, 31, v0
	v_lshlrev_b64 v[0:1], 9, v[0:1]
	v_ashrrev_i32_e32 v3, 31, v2
	v_readlane_b32 s68, v254, 33
	v_lshl_add_u64 v[4:5], s[58:59], 0, v[0:1]
	v_lshlrev_b64 v[2:3], 1, v[2:3]
	v_add_u32_e32 v6, s68, v15
	v_lshl_add_u64 v[8:9], v[4:5], 0, v[2:3]
	s_mov_b64 s[0:1], 0x80
	v_readfirstlane_b32 s63, v6
	v_lshl_add_u64 v[4:5], v[8:9], 0, s[0:1]
	s_mov_b32 m0, s63
	s_waitcnt vmcnt(4)
	s_barrier
	global_load_lds_dwordx4 v[4:5], off
	v_ashrrev_i32_e32 v4, 31, v13
	v_lshrrev_b32_e32 v4, 22, v4
	v_add_u32_e32 v4, v13, v4
	v_ashrrev_i32_e32 v5, 10, v4
	v_mul_i32_i24_e32 v4, 0x400, v5
	v_sub_u32_e32 v4, v13, v4
	v_lshrrev_b32_e32 v6, 4, v4
	v_bitop3_b32 v6, v6, v4, 32 bitop3:0x6c
	v_ashrrev_i32_e32 v7, 31, v6
	v_lshrrev_b32_e32 v7, 26, v7
	v_add_u32_e32 v7, v6, v7
	v_lshlrev_b32_e32 v4, 3, v5
	v_ashrrev_i32_e32 v10, 6, v7
	v_and_b32_e32 v7, 0xc0, v7
	v_and_b32_e32 v4, -16, v4
	v_lshlrev_b32_e32 v5, 5, v5
	v_sub_u32_e32 v6, v6, v7
	v_add_u32_e32 v4, v10, v4
	v_and_b32_e32 v5, 32, v5
	v_ashrrev_i16_sdwa v6, v193, sext(v6) dst_sel:DWORD dst_unused:UNUSED_PAD src0_sel:DWORD src1_sel:BYTE_0
	v_add_u32_sdwa v6, v5, sext(v6) dst_sel:DWORD dst_unused:UNUSED_PAD src0_sel:DWORD src1_sel:WORD_0
	v_ashrrev_i32_e32 v5, 31, v4
	v_lshlrev_b64 v[4:5], 9, v[4:5]
	v_ashrrev_i32_e32 v7, 31, v6
	v_lshl_add_u64 v[10:11], s[58:59], 0, v[4:5]
	v_lshlrev_b64 v[6:7], 1, v[6:7]
	v_lshl_add_u64 v[10:11], v[10:11], 0, v[6:7]
	v_add_u32_e32 v17, s68, v13
	v_lshl_add_u64 v[18:19], v[10:11], 0, s[0:1]
	v_readfirstlane_b32 s67, v17
	v_readlane_b32 s0, v254, 50
	s_mov_b32 m0, s67
	v_readlane_b32 s1, v254, 51
	v_add_u32_e32 v17, 0x8000, v12
	global_load_lds_dwordx4 v[18:19], off
	v_lshl_add_u64 v[18:19], s[0:1], 0, v[0:1]
	v_readfirstlane_b32 s65, v17
	v_lshl_add_u64 v[18:19], v[18:19], 0, v[2:3]
	s_mov_b32 m0, s65
	v_add_u32_e32 v17, 0xa000, v12
	global_load_lds_dwordx4 v[18:19], off
	v_lshl_add_u64 v[18:19], s[0:1], 0, v[4:5]
	v_readfirstlane_b32 s61, v17
	s_add_u32 s0, s58, 0x10080
	v_readlane_b32 s69, v254, 34
	v_lshl_add_u64 v[18:19], v[18:19], 0, v[6:7]
	s_mov_b32 m0, s61
	s_addc_u32 s1, s59, 0
	v_add_u32_e32 v17, s69, v15
	global_load_lds_dwordx4 v[18:19], off
	v_lshl_add_u64 v[18:19], s[0:1], 0, v[0:1]
	v_readfirstlane_b32 s41, v17
	v_lshl_add_u64 v[18:19], v[18:19], 0, v[2:3]
	s_mov_b32 m0, s41
	v_add_u32_e32 v17, s69, v13
	global_load_lds_dwordx4 v[18:19], off
	v_lshl_add_u64 v[18:19], s[0:1], 0, v[4:5]
	v_readfirstlane_b32 s23, v17
	v_lshl_add_u64 v[18:19], v[18:19], 0, v[6:7]
	s_mov_b32 m0, s23
	v_and_b32_e32 v17, 15, v128
	global_load_lds_dwordx4 v[18:19], off
	v_lshlrev_b32_e32 v18, 2, v128
	v_and_b32_e32 v42, 48, v128
	v_lshlrev_b32_e32 v17, 6, v17
	v_and_b32_e32 v43, 32, v18
	v_bitop3_b32 v126, v17, v43, v42 bitop3:0x36
	v_lshlrev_b32_e32 v17, 6, v128
	s_add_i32 s40, 0, 0x10000
	v_and_b32_e32 v127, 0x3000, v17
	v_add3_u32 v129, s40, v126, v127
	s_waitcnt vmcnt(6)
	s_barrier
	ds_read_b128 v[18:21], v129
	ds_read_b128 v[22:25], v129 offset:1024
	ds_read_b128 v[26:29], v129 offset:2048
	ds_read_b128 v[30:33], v129 offset:3072
	s_add_u32 s0, s58, 0x10180
	s_addc_u32 s1, s59, 0
	v_and_b32_e32 v17, 0x3c0, v17
	v_lshlrev_b32_e32 v16, 13, v16
	v_bitop3_b32 v17, v17, v43, v42 bitop3:0x36
	s_mov_b64 s[70:71], s[72:73]
	v_add_u32_e32 v66, 0xc000, v12
	v_add3_u32 v178, 0, v126, v16
	v_add3_u32 v179, 0, v17, v16
	v_lshl_add_u64 v[16:17], s[70:71], 0, v[0:1]
	v_readfirstlane_b32 s66, v66
	v_lshl_add_u64 v[16:17], v[16:17], 0, v[2:3]
	s_mov_b32 m0, s66
	v_add_u32_e32 v66, 0xe000, v12
	ds_read_b128 v[34:37], v178
	ds_read_b128 v[38:41], v178 offset:1024
	ds_read_b128 v[42:45], v179 offset:2048
	ds_read_b128 v[46:49], v179 offset:3072
	ds_read_b128 v[50:53], v179 offset:4096
	ds_read_b128 v[54:57], v179 offset:5120
	ds_read_b128 v[58:61], v179 offset:6144
	ds_read_b128 v[62:65], v179 offset:7168
	global_load_lds_dwordx4 v[16:17], off
	v_lshl_add_u64 v[16:17], s[70:71], 0, v[4:5]
	v_readfirstlane_b32 s64, v66
	v_lshl_add_u64 v[16:17], v[16:17], 0, v[6:7]
	s_mov_b32 m0, s64
	s_add_u32 s58, s58, 0x10100
	global_load_lds_dwordx4 v[16:17], off
	s_waitcnt lgkmcnt(8)
	s_barrier
	s_waitcnt lgkmcnt(0)
	s_addc_u32 s59, s59, 0
	s_waitcnt lgkmcnt(0)
	v_mfma_f32_16x16x32_bf16 v[66:69], v[18:21], v[34:37], 0
	v_mfma_f32_16x16x32_bf16 v[70:73], v[26:29], v[34:37], 0
	v_mfma_f32_16x16x32_bf16 v[74:77], v[18:21], v[42:45], 0
	v_mfma_f32_16x16x32_bf16 v[78:81], v[26:29], v[42:45], 0
	v_mfma_f32_16x16x32_bf16 v[82:85], v[18:21], v[50:53], 0
	v_mfma_f32_16x16x32_bf16 v[86:89], v[26:29], v[50:53], 0
	v_mfma_f32_16x16x32_bf16 v[90:93], v[18:21], v[58:61], 0
	v_mfma_f32_16x16x32_bf16 v[94:97], v[26:29], v[58:61], 0
	v_mfma_f32_16x16x32_bf16 v[66:69], v[22:25], v[38:41], v[66:69]
	v_mfma_f32_16x16x32_bf16 v[70:73], v[30:33], v[38:41], v[70:73]
	v_mfma_f32_16x16x32_bf16 v[74:77], v[22:25], v[46:49], v[74:77]
	v_mfma_f32_16x16x32_bf16 v[78:81], v[30:33], v[46:49], v[78:81]
	v_mfma_f32_16x16x32_bf16 v[82:85], v[22:25], v[54:57], v[82:85]
	v_mfma_f32_16x16x32_bf16 v[86:89], v[30:33], v[54:57], v[86:89]
	v_mfma_f32_16x16x32_bf16 v[90:93], v[22:25], v[62:65], v[90:93]
	v_mfma_f32_16x16x32_bf16 v[94:97], v[30:33], v[62:65], v[94:97]
	s_barrier
; #define WAIT_V(n) asm volatile("s_waitcnt vmcnt(" #n ")" ::: "memory")
; #define WAIT_L(n) asm volatile("s_waitcnt lgkmcnt(" #n ")" ::: "memory")
; #define BAR __builtin_amdgcn_s_barrier()
; #define SCHED __builtin_amdgcn_sched_barrier(0)
; #define LDA(dst, b, h)                                                                            \
;   _Pragma("unroll") for (int m = 0; m < 4; ++m) _Pragma("unroll") for (int k = 0; k < 2; ++k)                                         \
;     dst[m][k] = *reinterpret_cast<const bf16x8*>((char*)SA(b, h) + lds_byte(wr * 64 + m * 16 + fr, k * 32 + fq * 8))
; #define LDB(dst, b, h)                                                                            \
;   _Pragma("unroll") for (int n = 0; n < 2; ++n) _Pragma("unroll") for (int k = 0; k < 2; ++k)                                         \
;     dst[n][k] = *reinterpret_cast<const bf16x8*>((char*)SB(b, h) + lds_byte(wc * 32 + n * 16 + fr, k * 32 + fq * 8))
; template <int K, bool SWAP>
; __device__ __forceinline__ void gemm_kloop(const bf16* __restrict__ A, const bf16* __restrict__ Bt,
;                                            f32x4 (&acc)[2][2][4][2], bool pref = false) {
;     ...
;     WAIT_L(8); BAR; WAIT_L(0); MMA(0, 0, At, B0); BAR; SCHED;
;     LDB(B1, 0, 1); STAGE(SB(0, 0), Bt, 0, t + 2);
;     BAR; WAIT_L(0); MMA(0, 1, At, B1); BAR;
;     LDA(At, 0, 1); STAGE(SA(0, 0), A, 0, t + 2);
;     BAR; WAIT_L(0); MMA(1, 0, At, B0); BAR; SCHED;
;     STAGE(SB(0, 1), Bt, HALF, t + 2);
;     WAIT_V(6); BAR; MMA(1, 1, At, B1); BAR;
;     LDB(B0, 1, 0); SCHED; LDA(At, 1, 0); STAGE(SA(0, 1), A, HALF, t + 2);
;     WAIT_L(8); BAR; WAIT_L(0); MMA(0, 0, At, B0); BAR; SCHED;
	v_add_u32_e32 v15, s40, v15
	v_add3_u32 v186, s33, v126, v127
	v_readfirstlane_b32 s70, v15
	v_add_u32_e32 v15, s40, v13
	v_lshl_add_u64 v[16:17], v[8:9], 0, s[44:45]
	s_mov_b32 m0, s70
	v_readfirstlane_b32 s70, v15
	ds_read_b128 v[98:101], v186
	ds_read_b128 v[102:105], v186 offset:1024
	ds_read_b128 v[106:109], v186 offset:2048
	ds_read_b128 v[110:113], v186 offset:3072
	global_load_lds_dwordx4 v[16:17], off
	v_lshl_add_u64 v[16:17], v[10:11], 0, s[44:45]
	s_mov_b32 m0, s70
	s_nop 0
	global_load_lds_dwordx4 v[16:17], off
	s_barrier
	s_waitcnt lgkmcnt(0)
	s_waitcnt lgkmcnt(0)
	v_mfma_f32_16x16x32_bf16 v[114:117], v[98:101], v[34:37], 0
	v_mfma_f32_16x16x32_bf16 v[34:37], v[106:109], v[34:37], 0
	v_mfma_f32_16x16x32_bf16 v[114:117], v[102:105], v[38:41], v[114:117]
	v_mfma_f32_16x16x32_bf16 v[34:37], v[110:113], v[38:41], v[34:37]
	v_mfma_f32_16x16x32_bf16 v[38:41], v[98:101], v[42:45], 0
	v_mfma_f32_16x16x32_bf16 v[42:45], v[106:109], v[42:45], 0
	v_mfma_f32_16x16x32_bf16 v[38:41], v[102:105], v[46:49], v[38:41]
	v_mfma_f32_16x16x32_bf16 v[42:45], v[110:113], v[46:49], v[42:45]
	v_mfma_f32_16x16x32_bf16 v[46:49], v[98:101], v[50:53], 0
	v_mfma_f32_16x16x32_bf16 v[50:53], v[106:109], v[50:53], 0
	v_mfma_f32_16x16x32_bf16 v[46:49], v[102:105], v[54:57], v[46:49]
	v_mfma_f32_16x16x32_bf16 v[50:53], v[110:113], v[54:57], v[50:53]
	v_mfma_f32_16x16x32_bf16 v[54:57], v[98:101], v[58:61], 0
	v_mfma_f32_16x16x32_bf16 v[58:61], v[106:109], v[58:61], 0
	v_mfma_f32_16x16x32_bf16 v[54:57], v[102:105], v[62:65], v[54:57]
	v_mfma_f32_16x16x32_bf16 v[58:61], v[110:113], v[62:65], v[58:61]
	v_lshl_add_u64 v[16:17], s[4:5], 0, v[0:1]
	v_readfirstlane_b32 s70, v12
	v_lshl_add_u64 v[16:17], v[16:17], 0, v[2:3]
	s_mov_b32 m0, s70
	v_add_u32_e32 v15, 0x2000, v12
	s_barrier
	ds_read_b128 v[62:65], v178 offset:16384
	ds_read_b128 v[118:121], v178 offset:17408
	ds_read_b128 v[122:125], v179 offset:18432
	ds_read_b128 v[130:133], v179 offset:19456
	ds_read_b128 v[134:137], v179 offset:20480
	ds_read_b128 v[138:141], v179 offset:21504
	ds_read_b128 v[142:145], v179 offset:22528
	ds_read_b128 v[146:149], v179 offset:23552
	global_load_lds_dwordx4 v[16:17], off
	v_lshl_add_u64 v[16:17], s[4:5], 0, v[4:5]
	v_readfirstlane_b32 s70, v15
	v_lshl_add_u64 v[16:17], v[16:17], 0, v[6:7]
	s_mov_b32 m0, s70
	s_nop 0
	global_load_lds_dwordx4 v[16:17], off
	s_barrier
	s_waitcnt lgkmcnt(0)
	s_waitcnt lgkmcnt(0)
	v_mfma_f32_16x16x32_bf16 v[150:153], v[18:21], v[62:65], 0
	v_mfma_f32_16x16x32_bf16 v[158:161], v[18:21], v[122:125], 0
	v_mfma_f32_16x16x32_bf16 v[166:169], v[18:21], v[134:137], 0
	v_mfma_f32_16x16x32_bf16 v[16:19], v[18:21], v[142:145], 0
	v_mfma_f32_16x16x32_bf16 v[150:153], v[22:25], v[118:121], v[150:153]
	v_mfma_f32_16x16x32_bf16 v[158:161], v[22:25], v[130:133], v[158:161]
	v_mfma_f32_16x16x32_bf16 v[166:169], v[22:25], v[138:141], v[166:169]
	v_mfma_f32_16x16x32_bf16 v[16:19], v[22:25], v[146:149], v[16:19]
	v_mfma_f32_16x16x32_bf16 v[20:23], v[26:29], v[142:145], 0
	v_mfma_f32_16x16x32_bf16 v[154:157], v[26:29], v[62:65], 0
	v_mfma_f32_16x16x32_bf16 v[162:165], v[26:29], v[122:125], 0
	v_mfma_f32_16x16x32_bf16 v[170:173], v[26:29], v[134:137], 0
	v_mfma_f32_16x16x32_bf16 v[20:23], v[30:33], v[146:149], v[20:23]
	v_mfma_f32_16x16x32_bf16 v[154:157], v[30:33], v[118:121], v[154:157]
	v_mfma_f32_16x16x32_bf16 v[162:165], v[30:33], v[130:133], v[162:165]
	v_mfma_f32_16x16x32_bf16 v[170:173], v[30:33], v[138:141], v[170:173]
	s_barrier
	v_lshl_add_u64 v[24:25], s[58:59], 0, v[0:1]
	v_readfirstlane_b32 s70, v14
	v_add_u32_e32 v13, s33, v13
	v_lshl_add_u64 v[24:25], v[24:25], 0, v[2:3]
	s_mov_b32 m0, s70
	v_lshl_add_u64 v[14:15], s[58:59], 0, v[4:5]
	v_readfirstlane_b32 s58, v13
	global_load_lds_dwordx4 v[24:25], off
	v_lshl_add_u64 v[14:15], v[14:15], 0, v[6:7]
	s_mov_b32 m0, s58
	s_nop 0
	global_load_lds_dwordx4 v[14:15], off
	s_waitcnt vmcnt(6)
	s_barrier
	v_mfma_f32_16x16x32_bf16 v[24:27], v[98:101], v[62:65], 0
	v_mfma_f32_16x16x32_bf16 v[28:31], v[106:109], v[62:65], 0
	v_mfma_f32_16x16x32_bf16 v[24:27], v[102:105], v[118:121], v[24:27]
	v_mfma_f32_16x16x32_bf16 v[28:31], v[110:113], v[118:121], v[28:31]
	v_mfma_f32_16x16x32_bf16 v[62:65], v[98:101], v[122:125], 0
	v_mfma_f32_16x16x32_bf16 v[118:121], v[106:109], v[122:125], 0
	v_mfma_f32_16x16x32_bf16 v[122:125], v[98:101], v[134:137], 0
	v_mfma_f32_16x16x32_bf16 v[98:101], v[98:101], v[142:145], 0
	v_mfma_f32_16x16x32_bf16 v[62:65], v[102:105], v[130:133], v[62:65]
	v_mfma_f32_16x16x32_bf16 v[122:125], v[102:105], v[138:141], v[122:125]
	v_mfma_f32_16x16x32_bf16 v[98:101], v[102:105], v[146:149], v[98:101]
	v_mfma_f32_16x16x32_bf16 v[102:105], v[106:109], v[142:145], 0
	v_mfma_f32_16x16x32_bf16 v[118:121], v[110:113], v[130:133], v[118:121]
	v_mfma_f32_16x16x32_bf16 v[130:133], v[106:109], v[134:137], 0
	v_mfma_f32_16x16x32_bf16 v[102:105], v[110:113], v[146:149], v[102:105]
	v_mfma_f32_16x16x32_bf16 v[130:133], v[110:113], v[138:141], v[130:133]
	v_add3_u32 v188, s68, v126, v127
	s_barrier
	ds_read_b128 v[106:109], v188
	ds_read_b128 v[110:113], v188 offset:1024
	ds_read_b128 v[134:137], v188 offset:2048
	ds_read_b128 v[138:141], v188 offset:3072
	v_add_u32_e32 v13, 0x4000, v12
	v_lshl_add_u64 v[14:15], s[8:9], 0, v[0:1]
	v_readfirstlane_b32 s58, v13
	v_lshl_add_u64 v[14:15], v[14:15], 0, v[2:3]
	s_mov_b32 m0, s58
	v_add_u32_e32 v12, 0x6000, v12
	ds_read_b128 v[142:145], v178 offset:32768
	ds_read_b128 v[146:149], v178 offset:33792
	ds_read_b128 v[174:177], v179 offset:34816
	ds_read_b128 v[198:201], v179 offset:35840
	ds_read_b128 v[202:205], v179 offset:36864
	ds_read_b128 v[206:209], v179 offset:37888
	ds_read_b128 v[210:213], v179 offset:38912
	ds_read_b128 v[214:217], v179 offset:39936
	global_load_lds_dwordx4 v[14:15], off
	v_lshl_add_u64 v[14:15], s[8:9], 0, v[4:5]
	v_readfirstlane_b32 s58, v12
	v_lshl_add_u64 v[14:15], v[14:15], 0, v[6:7]
	s_mov_b32 m0, s58
	s_nop 0
	global_load_lds_dwordx4 v[14:15], off
	s_waitcnt lgkmcnt(8)
	s_barrier
; #define WAIT_V(n) asm volatile("s_waitcnt vmcnt(" #n ")" ::: "memory")
; #define WAIT_L(n) asm volatile("s_waitcnt lgkmcnt(" #n ")" ::: "memory")
; #define BAR __builtin_amdgcn_s_barrier()
; #define SCHED __builtin_amdgcn_sched_barrier(0)
; #define LDA(dst, b, h)                                                                            \
;   _Pragma("unroll") for (int m = 0; m < 4; ++m) _Pragma("unroll") for (int k = 0; k < 2; ++k)                                         \
;     dst[m][k] = *reinterpret_cast<const bf16x8*>((char*)SA(b, h) + lds_byte(wr * 64 + m * 16 + fr, k * 32 + fq * 8))
; #define LDB(dst, b, h)                                                                            \
;   _Pragma("unroll") for (int n = 0; n < 2; ++n) _Pragma("unroll") for (int k = 0; k < 2; ++k)                                         \
;     dst[n][k] = *reinterpret_cast<const bf16x8*>((char*)SB(b, h) + lds_byte(wc * 32 + n * 16 + fr, k * 32 + fq * 8))
; template <int K, bool SWAP>
; __device__ __forceinline__ void gemm_kloop(const bf16* __restrict__ A, const bf16* __restrict__ Bt,
;                                            f32x4 (&acc)[2][2][4][2], bool pref = false) {
;     ...
;     WAIT_L(8); BAR; WAIT_L(0); MMA(0, 0, At, B0); BAR; SCHED;
;     LDB(B1, 1, 1); STAGE(SB(1, 0), Bt, 0, t + 3);
;     BAR; WAIT_L(0); MMA(0, 1, At, B1); BAR;
;     LDA(At, 1, 1); STAGE(SA(1, 0), A, 0, t + 3);
;     BAR; WAIT_L(0); MMA(1, 0, At, B0); BAR; SCHED;
;     STAGE(SB(1, 1), Bt, HALF, t + 3);
;     WAIT_V(6); BAR; MMA(1, 1, At, B1); BAR;
	s_waitcnt lgkmcnt(0)
	s_waitcnt lgkmcnt(0)
	v_mfma_f32_16x16x32_bf16 v[12:15], v[106:109], v[142:145], v[66:69]
	v_mfma_f32_16x16x32_bf16 v[66:69], v[134:137], v[142:145], v[70:73]
	v_mfma_f32_16x16x32_bf16 v[70:73], v[106:109], v[174:177], v[74:77]
	v_mfma_f32_16x16x32_bf16 v[74:77], v[134:137], v[174:177], v[78:81]
	v_mfma_f32_16x16x32_bf16 v[78:81], v[106:109], v[202:205], v[82:85]
	v_mfma_f32_16x16x32_bf16 v[82:85], v[134:137], v[202:205], v[86:89]
	v_mfma_f32_16x16x32_bf16 v[86:89], v[106:109], v[210:213], v[90:93]
	v_mfma_f32_16x16x32_bf16 v[90:93], v[134:137], v[210:213], v[94:97]
	v_mfma_f32_16x16x32_bf16 v[12:15], v[110:113], v[146:149], v[12:15]
	v_mfma_f32_16x16x32_bf16 v[66:69], v[138:141], v[146:149], v[66:69]
	v_mfma_f32_16x16x32_bf16 v[70:73], v[110:113], v[198:201], v[70:73]
	v_mfma_f32_16x16x32_bf16 v[74:77], v[138:141], v[198:201], v[74:77]
	v_mfma_f32_16x16x32_bf16 v[78:81], v[110:113], v[206:209], v[78:81]
	v_mfma_f32_16x16x32_bf16 v[82:85], v[138:141], v[206:209], v[82:85]
	v_mfma_f32_16x16x32_bf16 v[86:89], v[110:113], v[214:217], v[86:89]
	v_mfma_f32_16x16x32_bf16 v[90:93], v[138:141], v[214:217], v[90:93]
	s_barrier
	s_mov_b32 m0, s63
	v_add3_u32 v189, s69, v126, v127
	v_lshl_add_u64 v[8:9], v[8:9], 0, s[52:53]
	ds_read_b128 v[94:97], v189
	ds_read_b128 v[218:221], v189 offset:1024
	ds_read_b128 v[222:225], v189 offset:2048
	ds_read_b128 v[226:229], v189 offset:3072
	global_load_lds_dwordx4 v[8:9], off
	v_lshl_add_u64 v[8:9], v[10:11], 0, s[52:53]
	s_mov_b32 m0, s67
	s_nop 0
	global_load_lds_dwordx4 v[8:9], off
	s_barrier
	s_waitcnt lgkmcnt(0)
	s_waitcnt lgkmcnt(0)
	v_mfma_f32_16x16x32_bf16 v[8:11], v[94:97], v[142:145], v[114:117]
	v_mfma_f32_16x16x32_bf16 v[32:35], v[222:225], v[142:145], v[34:37]
	v_mfma_f32_16x16x32_bf16 v[36:39], v[94:97], v[174:177], v[38:41]
	v_mfma_f32_16x16x32_bf16 v[40:43], v[222:225], v[174:177], v[42:45]
	v_mfma_f32_16x16x32_bf16 v[44:47], v[94:97], v[202:205], v[46:49]
	v_mfma_f32_16x16x32_bf16 v[48:51], v[222:225], v[202:205], v[50:53]
	v_mfma_f32_16x16x32_bf16 v[52:55], v[94:97], v[210:213], v[54:57]
	v_mfma_f32_16x16x32_bf16 v[56:59], v[222:225], v[210:213], v[58:61]
	v_mfma_f32_16x16x32_bf16 v[8:11], v[218:221], v[146:149], v[8:11]
	v_mfma_f32_16x16x32_bf16 v[32:35], v[226:229], v[146:149], v[32:35]
	v_mfma_f32_16x16x32_bf16 v[36:39], v[218:221], v[198:201], v[36:39]
	v_mfma_f32_16x16x32_bf16 v[40:43], v[226:229], v[198:201], v[40:43]
	v_mfma_f32_16x16x32_bf16 v[44:47], v[218:221], v[206:209], v[44:47]
	v_mfma_f32_16x16x32_bf16 v[48:51], v[226:229], v[206:209], v[48:51]
	v_mfma_f32_16x16x32_bf16 v[52:55], v[218:221], v[214:217], v[52:55]
	v_mfma_f32_16x16x32_bf16 v[56:59], v[226:229], v[214:217], v[56:59]
	v_lshl_add_u64 v[60:61], s[14:15], 0, v[0:1]
	s_mov_b32 m0, s65
	v_lshl_add_u64 v[60:61], v[60:61], 0, v[2:3]
	s_barrier
	ds_read_b128 v[114:117], v178 offset:49152
	ds_read_b128 v[142:145], v178 offset:50176
	ds_read_b128 v[146:149], v179 offset:51200
	ds_read_b128 v[174:177], v179 offset:52224
	ds_read_b128 v[198:201], v179 offset:53248
	ds_read_b128 v[202:205], v179 offset:54272
	ds_read_b128 v[206:209], v179 offset:55296
	ds_read_b128 v[210:213], v179 offset:56320
	global_load_lds_dwordx4 v[60:61], off
	v_lshl_add_u64 v[60:61], s[14:15], 0, v[4:5]
	v_lshl_add_u64 v[60:61], v[60:61], 0, v[6:7]
	s_mov_b32 m0, s61
	s_nop 0
	global_load_lds_dwordx4 v[60:61], off
	s_barrier
	s_waitcnt lgkmcnt(0)
	s_waitcnt lgkmcnt(0)
	v_mfma_f32_16x16x32_bf16 v[16:19], v[106:109], v[206:209], v[16:19]
	v_mfma_f32_16x16x32_bf16 v[20:23], v[134:137], v[206:209], v[20:23]
	v_mfma_f32_16x16x32_bf16 v[154:157], v[134:137], v[114:117], v[154:157]
	v_mfma_f32_16x16x32_bf16 v[150:153], v[106:109], v[114:117], v[150:153]
	v_mfma_f32_16x16x32_bf16 v[158:161], v[106:109], v[146:149], v[158:161]
	v_mfma_f32_16x16x32_bf16 v[162:165], v[134:137], v[146:149], v[162:165]
	v_mfma_f32_16x16x32_bf16 v[170:173], v[134:137], v[198:201], v[170:173]
	v_mfma_f32_16x16x32_bf16 v[166:169], v[106:109], v[198:201], v[166:169]
	v_mfma_f32_16x16x32_bf16 v[16:19], v[110:113], v[210:213], v[16:19]
	v_mfma_f32_16x16x32_bf16 v[20:23], v[138:141], v[210:213], v[20:23]
	v_mfma_f32_16x16x32_bf16 v[154:157], v[138:141], v[142:145], v[154:157]
	v_mfma_f32_16x16x32_bf16 v[150:153], v[110:113], v[142:145], v[150:153]
	v_mfma_f32_16x16x32_bf16 v[158:161], v[110:113], v[174:177], v[158:161]
	v_mfma_f32_16x16x32_bf16 v[162:165], v[138:141], v[174:177], v[162:165]
	v_mfma_f32_16x16x32_bf16 v[170:173], v[138:141], v[202:205], v[170:173]
	v_mfma_f32_16x16x32_bf16 v[166:169], v[110:113], v[202:205], v[166:169]
	s_barrier
	v_lshl_add_u64 v[60:61], s[0:1], 0, v[0:1]
	s_mov_b32 m0, s41
	v_lshl_add_u64 v[60:61], v[60:61], 0, v[2:3]
	global_load_lds_dwordx4 v[60:61], off
	v_lshl_add_u64 v[60:61], s[0:1], 0, v[4:5]
	v_lshl_add_u64 v[60:61], v[60:61], 0, v[6:7]
	s_mov_b32 m0, s23
	s_nop 0
	global_load_lds_dwordx4 v[60:61], off
	s_waitcnt vmcnt(6)
	s_barrier
	v_mfma_f32_16x16x32_bf16 v[24:27], v[94:97], v[114:117], v[24:27]
	v_mfma_f32_16x16x32_bf16 v[28:31], v[222:225], v[114:117], v[28:31]
	v_mfma_f32_16x16x32_bf16 v[60:63], v[94:97], v[146:149], v[62:65]
	v_mfma_f32_16x16x32_bf16 v[106:109], v[222:225], v[146:149], v[118:121]
	v_mfma_f32_16x16x32_bf16 v[110:113], v[94:97], v[198:201], v[122:125]
	v_mfma_f32_16x16x32_bf16 v[114:117], v[222:225], v[198:201], v[130:133]
	v_mfma_f32_16x16x32_bf16 v[94:97], v[94:97], v[206:209], v[98:101]
	v_mfma_f32_16x16x32_bf16 v[98:101], v[222:225], v[206:209], v[102:105]
	v_mfma_f32_16x16x32_bf16 v[24:27], v[218:221], v[142:145], v[24:27]
	v_mfma_f32_16x16x32_bf16 v[28:31], v[226:229], v[142:145], v[28:31]
	v_mfma_f32_16x16x32_bf16 v[60:63], v[218:221], v[174:177], v[60:63]
	v_mfma_f32_16x16x32_bf16 v[106:109], v[226:229], v[174:177], v[106:109]
	v_mfma_f32_16x16x32_bf16 v[110:113], v[218:221], v[202:205], v[110:113]
	v_mfma_f32_16x16x32_bf16 v[114:117], v[226:229], v[202:205], v[114:117]
	v_mfma_f32_16x16x32_bf16 v[94:97], v[218:221], v[210:213], v[94:97]
	v_mfma_f32_16x16x32_bf16 v[98:101], v[226:229], v[210:213], v[98:101]
	v_lshl_add_u64 v[0:1], s[6:7], 0, v[0:1]
	s_mov_b32 m0, s66
	v_lshl_add_u64 v[0:1], v[0:1], 0, v[2:3]
	s_barrier
; #define WAIT_V(n) asm volatile("s_waitcnt vmcnt(" #n ")" ::: "memory")
; #define WAIT_L(n) asm volatile("s_waitcnt lgkmcnt(" #n ")" ::: "memory")
; #define BAR __builtin_amdgcn_s_barrier()
; #define LDA(dst, b, h)                                                                            \
;   _Pragma("unroll") for (int m = 0; m < 4; ++m) _Pragma("unroll") for (int k = 0; k < 2; ++k)                                         \
;     dst[m][k] = *reinterpret_cast<const bf16x8*>((char*)SA(b, h) + lds_byte(wr * 64 + m * 16 + fr, k * 32 + fq * 8))
; #define LDB(dst, b, h)                                                                            \
;   _Pragma("unroll") for (int n = 0; n < 2; ++n) _Pragma("unroll") for (int k = 0; k < 2; ++k)                                         \
;     dst[n][k] = *reinterpret_cast<const bf16x8*>((char*)SB(b, h) + lds_byte(wc * 32 + n * 16 + fr, k * 32 + fq * 8))
; template <int K, bool SWAP>
; __device__ __forceinline__ void gemm_kloop(const bf16* __restrict__ A, const bf16* __restrict__ Bt,
;                                            f32x4 (&acc)[2][2][4][2], bool pref = false) {
;     ...
;   { LDB(B0, 0, 0); LDA(At, 0, 0); STAGE(SA(1, 1), A, HALF, nt - 1);
;     BAR; WAIT_L(0); MMA(0, 0, At, B0); BAR;
;     LDB(B1, 0, 1); BAR; WAIT_L(0); MMA(0, 1, At, B1); BAR;
;     LDA(At, 0, 1); WAIT_V(4); BAR; WAIT_L(0); MMA(1, 0, At, B0); MMA(1, 1, At, B1); BAR; }
;   { LDB(B0, 1, 0); LDA(At, 1, 0); WAIT_V(2); BAR; WAIT_L(0); MMA(0, 0, At, B0); BAR;
;     LDB(B1, 1, 1); WAIT_V(0); BAR; WAIT_L(0); MMA(0, 1, At, B1); BAR;
	ds_read_b128 v[102:105], v129
	ds_read_b128 v[118:121], v129 offset:1024
	ds_read_b128 v[122:125], v129 offset:2048
	ds_read_b128 v[130:133], v129 offset:3072
	ds_read_b128 v[134:137], v178
	ds_read_b128 v[138:141], v178 offset:1024
	ds_read_b128 v[142:145], v179 offset:2048
	ds_read_b128 v[146:149], v179 offset:3072
	ds_read_b128 v[174:177], v179 offset:4096
	ds_read_b128 v[198:201], v179 offset:5120
	ds_read_b128 v[202:205], v179 offset:6144
	ds_read_b128 v[206:209], v179 offset:7168
	global_load_lds_dwordx4 v[0:1], off
	v_lshl_add_u64 v[0:1], s[6:7], 0, v[4:5]
	v_lshl_add_u64 v[0:1], v[0:1], 0, v[6:7]
	s_mov_b32 m0, s64
	s_nop 0
	global_load_lds_dwordx4 v[0:1], off
	s_barrier
	s_waitcnt lgkmcnt(0)
	s_waitcnt lgkmcnt(0)
	v_mfma_f32_16x16x32_bf16 v[0:3], v[102:105], v[134:137], v[12:15]
	v_mfma_f32_16x16x32_bf16 v[4:7], v[122:125], v[134:137], v[66:69]
	v_mfma_f32_16x16x32_bf16 v[12:15], v[102:105], v[142:145], v[70:73]
	v_mfma_f32_16x16x32_bf16 v[64:67], v[122:125], v[142:145], v[74:77]
	v_mfma_f32_16x16x32_bf16 v[68:71], v[102:105], v[174:177], v[78:81]
	v_mfma_f32_16x16x32_bf16 v[72:75], v[122:125], v[174:177], v[82:85]
	v_mfma_f32_16x16x32_bf16 v[76:79], v[102:105], v[202:205], v[86:89]
	v_mfma_f32_16x16x32_bf16 v[80:83], v[122:125], v[202:205], v[90:93]
	v_mfma_f32_16x16x32_bf16 v[0:3], v[118:121], v[138:141], v[0:3]
	v_mfma_f32_16x16x32_bf16 v[4:7], v[130:133], v[138:141], v[4:7]
	v_mfma_f32_16x16x32_bf16 v[12:15], v[118:121], v[146:149], v[12:15]
	v_mfma_f32_16x16x32_bf16 v[64:67], v[130:133], v[146:149], v[64:67]
	v_mfma_f32_16x16x32_bf16 v[68:71], v[118:121], v[198:201], v[68:71]
	v_mfma_f32_16x16x32_bf16 v[72:75], v[130:133], v[198:201], v[72:75]
	v_mfma_f32_16x16x32_bf16 v[76:79], v[118:121], v[206:209], v[76:79]
	v_mfma_f32_16x16x32_bf16 v[84:87], v[130:133], v[206:209], v[80:83]
	s_barrier
	s_nop 0
	ds_read_b128 v[80:83], v186
	ds_read_b128 v[88:91], v186 offset:1024
	ds_read_b128 v[210:213], v186 offset:2048
	ds_read_b128 v[214:217], v186 offset:3072
	s_barrier
	s_waitcnt lgkmcnt(0)
	s_waitcnt lgkmcnt(0)
	v_mfma_f32_16x16x32_bf16 v[40:43], v[210:213], v[142:145], v[40:43]
	v_mfma_f32_16x16x32_bf16 v[8:11], v[80:83], v[134:137], v[8:11]
	v_mfma_f32_16x16x32_bf16 v[32:35], v[210:213], v[134:137], v[32:35]
	v_mfma_f32_16x16x32_bf16 v[134:137], v[214:217], v[146:149], v[40:43]
	v_mfma_f32_16x16x32_bf16 v[40:43], v[80:83], v[174:177], v[44:47]
	v_mfma_f32_16x16x32_bf16 v[44:47], v[88:91], v[198:201], v[40:43]
	v_mfma_f32_16x16x32_bf16 v[40:43], v[210:213], v[174:177], v[48:51]
	v_mfma_f32_16x16x32_bf16 v[8:11], v[88:91], v[138:141], v[8:11]
	v_mfma_f32_16x16x32_bf16 v[32:35], v[214:217], v[138:141], v[32:35]
	v_mfma_f32_16x16x32_bf16 v[36:39], v[80:83], v[142:145], v[36:39]
	v_mfma_f32_16x16x32_bf16 v[138:141], v[214:217], v[198:201], v[40:43]
	v_mfma_f32_16x16x32_bf16 v[40:43], v[80:83], v[202:205], v[52:55]
	v_mfma_f32_16x16x32_bf16 v[36:39], v[88:91], v[146:149], v[36:39]
	v_mfma_f32_16x16x32_bf16 v[52:55], v[88:91], v[206:209], v[40:43]
	v_mfma_f32_16x16x32_bf16 v[40:43], v[210:213], v[202:205], v[56:59]
	v_mfma_f32_16x16x32_bf16 v[142:145], v[214:217], v[206:209], v[40:43]
	s_barrier
	s_nop 4
	ds_read_b128 v[40:43], v178 offset:16384
	ds_read_b128 v[48:51], v178 offset:17408
	ds_read_b128 v[56:59], v179 offset:18432
	ds_read_b128 v[146:149], v179 offset:19456
	ds_read_b128 v[174:177], v179 offset:20480
	ds_read_b128 v[198:201], v179 offset:21504
	ds_read_b128 v[202:205], v179 offset:22528
	ds_read_b128 v[206:209], v179 offset:23552
	s_waitcnt vmcnt(4)
	s_barrier
	s_waitcnt lgkmcnt(0)
	s_waitcnt lgkmcnt(0)
	v_mfma_f32_16x16x32_bf16 v[16:19], v[102:105], v[202:205], v[16:19]
	v_mfma_f32_16x16x32_bf16 v[218:221], v[118:121], v[206:209], v[16:19]
	v_mfma_f32_16x16x32_bf16 v[16:19], v[122:125], v[202:205], v[20:23]
	v_mfma_f32_16x16x32_bf16 v[150:153], v[102:105], v[40:43], v[150:153]
	v_mfma_f32_16x16x32_bf16 v[154:157], v[122:125], v[40:43], v[154:157]
	v_mfma_f32_16x16x32_bf16 v[158:161], v[102:105], v[56:59], v[158:161]
	v_mfma_f32_16x16x32_bf16 v[162:165], v[122:125], v[56:59], v[162:165]
	v_mfma_f32_16x16x32_bf16 v[166:169], v[102:105], v[174:177], v[166:169]
	v_mfma_f32_16x16x32_bf16 v[170:173], v[122:125], v[174:177], v[170:173]
	v_mfma_f32_16x16x32_bf16 v[20:23], v[130:133], v[206:209], v[16:19]
	v_mfma_f32_16x16x32_bf16 v[150:153], v[118:121], v[48:51], v[150:153]
	v_mfma_f32_16x16x32_bf16 v[154:157], v[130:133], v[48:51], v[154:157]
	v_mfma_f32_16x16x32_bf16 v[158:161], v[118:121], v[146:149], v[158:161]
	v_mfma_f32_16x16x32_bf16 v[162:165], v[130:133], v[146:149], v[162:165]
	v_mfma_f32_16x16x32_bf16 v[166:169], v[118:121], v[198:201], v[166:169]
	v_mfma_f32_16x16x32_bf16 v[170:173], v[130:133], v[198:201], v[170:173]
	v_mfma_f32_16x16x32_bf16 v[16:19], v[80:83], v[40:43], v[24:27]
	v_mfma_f32_16x16x32_bf16 v[130:133], v[88:91], v[48:51], v[16:19]
	v_mfma_f32_16x16x32_bf16 v[16:19], v[210:213], v[40:43], v[28:31]
	v_mfma_f32_16x16x32_bf16 v[28:31], v[214:217], v[48:51], v[16:19]
	v_mfma_f32_16x16x32_bf16 v[16:19], v[80:83], v[56:59], v[60:63]
	v_mfma_f32_16x16x32_bf16 v[222:225], v[88:91], v[146:149], v[16:19]
	v_mfma_f32_16x16x32_bf16 v[16:19], v[210:213], v[56:59], v[106:109]
	v_mfma_f32_16x16x32_bf16 v[146:149], v[214:217], v[146:149], v[16:19]
	v_mfma_f32_16x16x32_bf16 v[16:19], v[80:83], v[174:177], v[110:113]
	v_mfma_f32_16x16x32_bf16 v[226:229], v[88:91], v[198:201], v[16:19]
	v_mfma_f32_16x16x32_bf16 v[16:19], v[210:213], v[174:177], v[114:117]
	v_mfma_f32_16x16x32_bf16 v[174:177], v[214:217], v[198:201], v[16:19]
	v_mfma_f32_16x16x32_bf16 v[16:19], v[80:83], v[202:205], v[94:97]
	v_mfma_f32_16x16x32_bf16 v[198:201], v[88:91], v[206:209], v[16:19]
	v_mfma_f32_16x16x32_bf16 v[16:19], v[210:213], v[202:205], v[98:101]
	v_mfma_f32_16x16x32_bf16 v[202:205], v[214:217], v[206:209], v[16:19]
	s_barrier
; #define WAIT_V(n) asm volatile("s_waitcnt vmcnt(" #n ")" ::: "memory")
; #define WAIT_L(n) asm volatile("s_waitcnt lgkmcnt(" #n ")" ::: "memory")
; #define BAR __builtin_amdgcn_s_barrier()
; #define SCHED __builtin_amdgcn_sched_barrier(0)
; #define LDA(dst, b, h)                                                                            \
;   _Pragma("unroll") for (int m = 0; m < 4; ++m) _Pragma("unroll") for (int k = 0; k < 2; ++k)                                         \
;     dst[m][k] = *reinterpret_cast<const bf16x8*>((char*)SA(b, h) + lds_byte(wr * 64 + m * 16 + fr, k * 32 + fq * 8))
; #define LDB(dst, b, h)                                                                            \
;   _Pragma("unroll") for (int n = 0; n < 2; ++n) _Pragma("unroll") for (int k = 0; k < 2; ++k)                                         \
;     dst[n][k] = *reinterpret_cast<const bf16x8*>((char*)SB(b, h) + lds_byte(wc * 32 + n * 16 + fr, k * 32 + fq * 8))
; template <int K, bool SWAP>
; __device__ __forceinline__ void gemm_kloop(const bf16* __restrict__ A, const bf16* __restrict__ Bt,
;                                            f32x4 (&acc)[2][2][4][2], bool pref = false) {
;     ...
;   { LDB(B0, 1, 0); LDA(At, 1, 0); WAIT_V(2); BAR; WAIT_L(0); MMA(0, 0, At, B0); BAR;
;     LDB(B1, 1, 1); WAIT_V(0); BAR; WAIT_L(0); MMA(0, 1, At, B1); BAR;
;     LDA(At, 1, 1); BAR; WAIT_L(0); MMA(1, 0, At, B0); MMA(1, 1, At, B1); BAR; }
;   if (wr == 0) BAR;
;   SCHED;
	ds_read_b128 v[60:63], v188
	ds_read_b128 v[206:209], v188 offset:1024
	ds_read_b128 v[210:213], v188 offset:2048
	ds_read_b128 v[214:217], v188 offset:3072
	s_nop 0
	ds_read_b128 v[16:19], v178 offset:32768
	ds_read_b128 v[24:27], v178 offset:33792
	ds_read_b128 v[92:95], v179 offset:34816
	ds_read_b128 v[100:103], v179 offset:35840
	ds_read_b128 v[108:111], v179 offset:36864
	ds_read_b128 v[116:119], v179 offset:37888
	ds_read_b128 v[124:127], v179 offset:38912
	ds_read_b128 v[230:233], v179 offset:39936
	s_waitcnt vmcnt(2)
	s_barrier
	s_waitcnt lgkmcnt(0)
	s_waitcnt lgkmcnt(0)
	v_mfma_f32_16x16x32_bf16 v[0:3], v[60:63], v[16:19], v[0:3]
	v_mfma_f32_16x16x32_bf16 v[120:123], v[206:209], v[24:27], v[0:3]
	v_mfma_f32_16x16x32_bf16 v[0:3], v[210:213], v[16:19], v[4:7]
	v_mfma_f32_16x16x32_bf16 v[112:115], v[214:217], v[24:27], v[0:3]
	v_mfma_f32_16x16x32_bf16 v[0:3], v[60:63], v[92:95], v[12:15]
	v_mfma_f32_16x16x32_bf16 v[104:107], v[206:209], v[100:103], v[0:3]
	v_mfma_f32_16x16x32_bf16 v[0:3], v[210:213], v[92:95], v[64:67]
	v_mfma_f32_16x16x32_bf16 v[96:99], v[214:217], v[100:103], v[0:3]
	v_mfma_f32_16x16x32_bf16 v[0:3], v[60:63], v[108:111], v[68:71]
	v_mfma_f32_16x16x32_bf16 v[88:91], v[206:209], v[116:119], v[0:3]
	v_mfma_f32_16x16x32_bf16 v[0:3], v[210:213], v[108:111], v[72:75]
	v_mfma_f32_16x16x32_bf16 v[80:83], v[214:217], v[116:119], v[0:3]
	v_mfma_f32_16x16x32_bf16 v[0:3], v[60:63], v[124:127], v[76:79]
	v_mfma_f32_16x16x32_bf16 v[72:75], v[206:209], v[230:233], v[0:3]
	v_mfma_f32_16x16x32_bf16 v[0:3], v[210:213], v[124:127], v[84:87]
	v_mfma_f32_16x16x32_bf16 v[64:67], v[214:217], v[230:233], v[0:3]
	s_barrier
	ds_read_b128 v[4:7], v189
	ds_read_b128 v[12:15], v189 offset:1024
	ds_read_b128 v[234:237], v189 offset:2048
	ds_read_b128 v[238:241], v189 offset:3072
	s_waitcnt vmcnt(0)
	s_barrier
	s_waitcnt lgkmcnt(0)
	s_waitcnt lgkmcnt(0)
	v_mfma_f32_16x16x32_bf16 v[0:3], v[4:7], v[16:19], v[8:11]
	v_mfma_f32_16x16x32_bf16 v[56:59], v[12:15], v[24:27], v[0:3]
	v_mfma_f32_16x16x32_bf16 v[0:3], v[234:237], v[16:19], v[32:35]
	v_mfma_f32_16x16x32_bf16 v[48:51], v[238:241], v[24:27], v[0:3]
	v_mfma_f32_16x16x32_bf16 v[0:3], v[4:7], v[92:95], v[36:39]
	v_mfma_f32_16x16x32_bf16 v[40:43], v[12:15], v[100:103], v[0:3]
	v_mfma_f32_16x16x32_bf16 v[0:3], v[234:237], v[92:95], v[134:137]
	v_mfma_f32_16x16x32_bf16 v[32:35], v[238:241], v[100:103], v[0:3]
	v_mfma_f32_16x16x32_bf16 v[0:3], v[4:7], v[108:111], v[44:47]
	v_mfma_f32_16x16x32_bf16 v[24:27], v[12:15], v[116:119], v[0:3]
	v_mfma_f32_16x16x32_bf16 v[0:3], v[234:237], v[108:111], v[138:141]
	v_mfma_f32_16x16x32_bf16 v[16:19], v[238:241], v[116:119], v[0:3]
	v_mfma_f32_16x16x32_bf16 v[0:3], v[4:7], v[124:127], v[52:55]
	v_mfma_f32_16x16x32_bf16 v[8:11], v[12:15], v[230:233], v[0:3]
	v_mfma_f32_16x16x32_bf16 v[0:3], v[234:237], v[124:127], v[142:145]
	v_mfma_f32_16x16x32_bf16 v[0:3], v[238:241], v[230:233], v[0:3]
	s_barrier
	ds_read_b128 v[36:39], v178 offset:49152
	ds_read_b128 v[44:47], v178 offset:50176
	ds_read_b128 v[134:137], v179 offset:51200
	ds_read_b128 v[138:141], v179 offset:52224
	ds_read_b128 v[142:145], v179 offset:53248
	ds_read_b128 v[230:233], v179 offset:54272
	ds_read_b128 v[242:245], v179 offset:55296
	ds_read_b128 v[246:249], v179 offset:56320
	s_barrier
	s_waitcnt lgkmcnt(0)
	s_waitcnt lgkmcnt(0)
	v_mfma_f32_16x16x32_bf16 v[52:55], v[60:63], v[36:39], v[150:153]
	v_mfma_f32_16x16x32_bf16 v[124:127], v[206:209], v[44:47], v[52:55]
	v_mfma_f32_16x16x32_bf16 v[52:55], v[210:213], v[36:39], v[154:157]
	v_mfma_f32_16x16x32_bf16 v[116:119], v[214:217], v[44:47], v[52:55]
	v_mfma_f32_16x16x32_bf16 v[52:55], v[60:63], v[134:137], v[158:161]
	v_mfma_f32_16x16x32_bf16 v[108:111], v[206:209], v[138:141], v[52:55]
	v_mfma_f32_16x16x32_bf16 v[52:55], v[210:213], v[134:137], v[162:165]
	v_mfma_f32_16x16x32_bf16 v[100:103], v[214:217], v[138:141], v[52:55]
	v_mfma_f32_16x16x32_bf16 v[52:55], v[60:63], v[142:145], v[166:169]
	v_mfma_f32_16x16x32_bf16 v[92:95], v[206:209], v[230:233], v[52:55]
	v_mfma_f32_16x16x32_bf16 v[52:55], v[210:213], v[142:145], v[170:173]
	v_mfma_f32_16x16x32_bf16 v[84:87], v[214:217], v[230:233], v[52:55]
	v_mfma_f32_16x16x32_bf16 v[52:55], v[60:63], v[242:245], v[218:221]
	v_mfma_f32_16x16x32_bf16 v[20:23], v[210:213], v[242:245], v[20:23]
	v_mfma_f32_16x16x32_bf16 v[76:79], v[206:209], v[246:249], v[52:55]
	v_mfma_f32_16x16x32_bf16 v[68:71], v[214:217], v[246:249], v[20:23]
	v_mfma_f32_16x16x32_bf16 v[20:23], v[4:7], v[36:39], v[130:133]
	v_mfma_f32_16x16x32_bf16 v[60:63], v[12:15], v[44:47], v[20:23]
	v_mfma_f32_16x16x32_bf16 v[20:23], v[234:237], v[36:39], v[28:31]
	v_mfma_f32_16x16x32_bf16 v[52:55], v[238:241], v[44:47], v[20:23]
	v_mfma_f32_16x16x32_bf16 v[20:23], v[4:7], v[134:137], v[222:225]
	v_mfma_f32_16x16x32_bf16 v[44:47], v[12:15], v[138:141], v[20:23]
	v_mfma_f32_16x16x32_bf16 v[20:23], v[234:237], v[134:137], v[146:149]
	v_mfma_f32_16x16x32_bf16 v[36:39], v[238:241], v[138:141], v[20:23]
	v_mfma_f32_16x16x32_bf16 v[20:23], v[4:7], v[142:145], v[226:229]
	v_mfma_f32_16x16x32_bf16 v[4:7], v[4:7], v[242:245], v[198:201]
	v_mfma_f32_16x16x32_bf16 v[28:31], v[12:15], v[230:233], v[20:23]
	v_mfma_f32_16x16x32_bf16 v[20:23], v[234:237], v[142:145], v[174:177]
	v_mfma_f32_16x16x32_bf16 v[12:15], v[12:15], v[246:249], v[4:7]
	v_mfma_f32_16x16x32_bf16 v[4:7], v[234:237], v[242:245], v[202:205]
	v_mfma_f32_16x16x32_bf16 v[20:23], v[238:241], v[230:233], v[20:23]
	v_mfma_f32_16x16x32_bf16 v[4:7], v[238:241], v[246:249], v[4:7]
	s_movk_i32 s0, 0x100
	v_cmp_gt_u32_e32 vcc, s0, v128
	s_barrier
	s_and_saveexec_b64 s[0:1], vcc
	s_cbranch_execz .LBB0_673
	s_barrier

; #define WAIT_V(n) asm volatile("s_waitcnt vmcnt(" #n ")" ::: "memory")
; #define WAIT_L(n) asm volatile("s_waitcnt lgkmcnt(" #n ")" ::: "memory")
; #define BAR __builtin_amdgcn_s_barrier()
; #define SCHED __builtin_amdgcn_sched_barrier(0)
; #define LDA(dst, b, h)                                                                            \
;   _Pragma("unroll") for (int m = 0; m < 4; ++m) _Pragma("unroll") for (int k = 0; k < 2; ++k)                                         \
;     dst[m][k] = *reinterpret_cast<const bf16x8*>((char*)SA(b, h) + lds_byte(wr * 64 + m * 16 + fr, k * 32 + fq * 8))
; #define LDB(dst, b, h)                                                                            \
;   _Pragma("unroll") for (int n = 0; n < 2; ++n) _Pragma("unroll") for (int k = 0; k < 2; ++k)                                         \
;     dst[n][k] = *reinterpret_cast<const bf16x8*>((char*)SB(b, h) + lds_byte(wc * 32 + n * 16 + fr, k * 32 + fq * 8))
; template <int K, bool SWAP>
; __device__ __forceinline__ void gemm_kloop(const bf16* __restrict__ A, const bf16* __restrict__ Bt,
;                                            f32x4 (&acc)[2][2][4][2], bool pref = false) {
;     ...
;   if (!pref) {
;     STAGE(SB(0, 0), Bt, 0, 0); STAGE(SA(0, 0), A, 0, 0);
;     STAGE(SB(0, 1), Bt, HALF, 0); STAGE(SA(0, 1), A, HALF, 0);
;   }
;   if (wr == 1) BAR;
;   WAIT_V(4); BAR;
;   STAGE(SB(1, 0), Bt, 0, 1); STAGE(SA(1, 0), A, 0, 1); STAGE(SB(1, 1), Bt, HALF, 1);
;   WAIT_V(6); BAR;
;   for (int t = 0; t < nt - 2; t += 2) {
;     LDB(B0, 0, 0); SCHED; LDA(At, 0, 0); STAGE(SA(1, 1), A, HALF, t + 1);
;     WAIT_L(8); BAR; WAIT_L(0); MMA(0, 0, At, B0); BAR; SCHED;
.LBB0_719:
	s_or_b64 exec, exec, s[66:67]
	v_add_u32_e32 v0, v15, v0
	v_and_b32_e32 v0, 0xfffffc00, v0
	v_sub_u32_e32 v0, v15, v0
	v_lshrrev_b32_e32 v2, 4, v0
	v_bitop3_b32 v2, v2, v0, 32 bitop3:0x6c
	v_ashrrev_i32_e32 v3, 31, v2
	v_add_u32_e32 v1, v64, v1
	v_lshrrev_b32_e32 v3, 26, v3
	v_ashrrev_i32_e32 v1, 6, v1
	v_add_u32_e32 v3, v2, v3
	v_lshlrev_b32_e32 v0, 3, v1
	v_ashrrev_i32_e32 v4, 6, v3
	v_and_b32_e32 v3, 0xc0, v3
	v_and_b32_e32 v0, -16, v0
	v_lshlrev_b32_e32 v1, 5, v1
	v_sub_u32_e32 v2, v2, v3
	v_add_u32_e32 v0, v4, v0
	v_and_b32_e32 v1, 32, v1
	v_ashrrev_i16_sdwa v2, v193, sext(v2) dst_sel:DWORD dst_unused:UNUSED_PAD src0_sel:DWORD src1_sel:BYTE_0
	v_add_u32_sdwa v2, v1, sext(v2) dst_sel:DWORD dst_unused:UNUSED_PAD src0_sel:DWORD src1_sel:WORD_0
	v_ashrrev_i32_e32 v1, 31, v0
	v_lshlrev_b64 v[0:1], 9, v[0:1]
	v_ashrrev_i32_e32 v3, 31, v2
	v_readlane_b32 s68, v254, 33
	v_lshl_add_u64 v[4:5], s[62:63], 0, v[0:1]
	v_lshlrev_b64 v[2:3], 1, v[2:3]
	v_add_u32_e32 v6, s68, v15
	v_lshl_add_u64 v[8:9], v[4:5], 0, v[2:3]
	s_mov_b64 s[4:5], 0x80
	v_readfirstlane_b32 s20, v6
	v_lshl_add_u64 v[4:5], v[8:9], 0, s[4:5]
	s_mov_b32 m0, s20
	s_waitcnt vmcnt(4)
	s_barrier
	global_load_lds_dwordx4 v[4:5], off
	v_ashrrev_i32_e32 v4, 31, v13
	v_lshrrev_b32_e32 v4, 22, v4
	v_add_u32_e32 v4, v13, v4
	v_ashrrev_i32_e32 v5, 10, v4
	v_mul_i32_i24_e32 v4, 0x400, v5
	v_sub_u32_e32 v4, v13, v4
	v_lshrrev_b32_e32 v6, 4, v4
	v_bitop3_b32 v6, v6, v4, 32 bitop3:0x6c
	v_ashrrev_i32_e32 v7, 31, v6
	v_lshrrev_b32_e32 v7, 26, v7
	v_add_u32_e32 v7, v6, v7
	v_lshlrev_b32_e32 v4, 3, v5
	v_ashrrev_i32_e32 v10, 6, v7
	v_and_b32_e32 v7, 0xc0, v7
	v_and_b32_e32 v4, -16, v4
	v_lshlrev_b32_e32 v5, 5, v5
	v_sub_u32_e32 v6, v6, v7
	v_add_u32_e32 v4, v10, v4
	v_and_b32_e32 v5, 32, v5
	v_ashrrev_i16_sdwa v6, v193, sext(v6) dst_sel:DWORD dst_unused:UNUSED_PAD src0_sel:DWORD src1_sel:BYTE_0
	v_add_u32_sdwa v6, v5, sext(v6) dst_sel:DWORD dst_unused:UNUSED_PAD src0_sel:DWORD src1_sel:WORD_0
	v_ashrrev_i32_e32 v5, 31, v4
	v_lshlrev_b64 v[4:5], 9, v[4:5]
	v_ashrrev_i32_e32 v7, 31, v6
	v_lshl_add_u64 v[10:11], s[62:63], 0, v[4:5]
	v_lshlrev_b64 v[6:7], 1, v[6:7]
	v_add_u32_e32 v17, s68, v13
	v_lshl_add_u64 v[10:11], v[10:11], 0, v[6:7]
	v_readfirstlane_b32 s73, v17
	v_lshl_add_u64 v[18:19], v[10:11], 0, s[4:5]
	s_mov_b32 m0, s73
	v_add_u32_e32 v17, 0x8000, v12
	global_load_lds_dwordx4 v[18:19], off
	v_lshl_add_u64 v[18:19], s[12:13], 0, v[0:1]
	v_readfirstlane_b32 s72, v17
	v_lshl_add_u64 v[18:19], v[18:19], 0, v[2:3]
	s_mov_b32 m0, s72
	v_add_u32_e32 v17, 0xa000, v12
	global_load_lds_dwordx4 v[18:19], off
	v_lshl_add_u64 v[18:19], s[12:13], 0, v[4:5]
	v_readfirstlane_b32 s66, v17
	s_add_u32 vcc_lo, s62, 0x10080
	v_readlane_b32 s5, v254, 34
	v_lshl_add_u64 v[18:19], v[18:19], 0, v[6:7]
	s_mov_b32 m0, s66
	s_addc_u32 vcc_hi, s63, 0
	v_add_u32_e32 v17, s5, v15
	global_load_lds_dwordx4 v[18:19], off
	v_lshl_add_u64 v[18:19], vcc, 0, v[0:1]
	v_readfirstlane_b32 s71, v17
	v_lshl_add_u64 v[18:19], v[18:19], 0, v[2:3]
	s_mov_b32 m0, s71
	v_add_u32_e32 v17, s5, v13
	global_load_lds_dwordx4 v[18:19], off
	v_lshl_add_u64 v[18:19], vcc, 0, v[4:5]
	v_readfirstlane_b32 s67, v17
	v_lshl_add_u64 v[18:19], v[18:19], 0, v[6:7]
	s_mov_b32 m0, s67
	v_and_b32_e32 v17, 15, v64
	global_load_lds_dwordx4 v[18:19], off
	v_lshlrev_b32_e32 v18, 2, v64
	v_and_b32_e32 v42, 48, v64
	v_lshlrev_b32_e32 v17, 6, v17
	v_and_b32_e32 v43, 32, v18
	v_bitop3_b32 v65, v17, v43, v42 bitop3:0x36
	v_lshlrev_b32_e32 v17, 6, v64
	s_add_i32 s65, 0, 0x10000
	v_and_b32_e32 v130, 0x3000, v17
	v_add3_u32 v131, s65, v65, v130
	s_waitcnt vmcnt(6)
	s_barrier
	ds_read_b128 v[18:21], v131
	ds_read_b128 v[22:25], v131 offset:1024
	ds_read_b128 v[26:29], v131 offset:2048
	ds_read_b128 v[30:33], v131 offset:3072
	s_add_u32 vcc_lo, s62, 0x10180
	s_addc_u32 vcc_hi, s63, 0
	v_and_b32_e32 v17, 0x3c0, v17
	v_lshlrev_b32_e32 v16, 13, v16
	v_bitop3_b32 v17, v17, v43, v42 bitop3:0x36
	v_add_u32_e32 v62, 0xc000, v12
	v_add3_u32 v132, 0, v65, v16
	v_add3_u32 v138, 0, v17, v16
	v_lshl_add_u64 v[16:17], s[14:15], 0, v[0:1]
	v_readfirstlane_b32 s70, v62
	v_lshl_add_u64 v[16:17], v[16:17], 0, v[2:3]
	s_mov_b32 m0, s70
	v_add_u32_e32 v62, 0xe000, v12
	ds_read_b128 v[34:37], v132
	ds_read_b128 v[38:41], v132 offset:1024
	ds_read_b128 v[42:45], v138 offset:2048
	ds_read_b128 v[46:49], v138 offset:3072
	ds_read_b128 v[50:53], v138 offset:4096
	ds_read_b128 v[54:57], v138 offset:5120
	ds_read_b128 v[58:61], v138 offset:6144
	ds_read_b128 v[66:69], v138 offset:7168
	global_load_lds_dwordx4 v[16:17], off
	v_lshl_add_u64 v[16:17], s[14:15], 0, v[4:5]
	v_readfirstlane_b32 s41, v62
	v_lshl_add_u64 v[16:17], v[16:17], 0, v[6:7]
	s_mov_b32 m0, s41
	s_add_u32 s62, s62, 0x10100
	global_load_lds_dwordx4 v[16:17], off
	s_waitcnt lgkmcnt(8)
	s_barrier
	s_waitcnt lgkmcnt(0)
	s_addc_u32 s63, s63, 0
	s_waitcnt lgkmcnt(0)
	v_mfma_f32_16x16x32_bf16 v[70:73], v[18:21], v[34:37], 0
	v_mfma_f32_16x16x32_bf16 v[78:81], v[18:21], v[42:45], 0
	v_mfma_f32_16x16x32_bf16 v[86:89], v[18:21], v[50:53], 0
	v_mfma_f32_16x16x32_bf16 v[16:19], v[18:21], v[58:61], 0
	v_mfma_f32_16x16x32_bf16 v[70:73], v[22:25], v[38:41], v[70:73]
	v_mfma_f32_16x16x32_bf16 v[78:81], v[22:25], v[46:49], v[78:81]
	v_mfma_f32_16x16x32_bf16 v[86:89], v[22:25], v[54:57], v[86:89]
	v_mfma_f32_16x16x32_bf16 v[16:19], v[22:25], v[66:69], v[16:19]
	v_mfma_f32_16x16x32_bf16 v[20:23], v[26:29], v[58:61], 0
	v_mfma_f32_16x16x32_bf16 v[74:77], v[26:29], v[34:37], 0
	v_mfma_f32_16x16x32_bf16 v[82:85], v[26:29], v[42:45], 0
	v_mfma_f32_16x16x32_bf16 v[90:93], v[26:29], v[50:53], 0
	v_mfma_f32_16x16x32_bf16 v[20:23], v[30:33], v[66:69], v[20:23]
	v_mfma_f32_16x16x32_bf16 v[74:77], v[30:33], v[38:41], v[74:77]
	v_mfma_f32_16x16x32_bf16 v[82:85], v[30:33], v[46:49], v[82:85]
	v_mfma_f32_16x16x32_bf16 v[90:93], v[30:33], v[54:57], v[90:93]
	s_barrier
; #define WAIT_V(n) asm volatile("s_waitcnt vmcnt(" #n ")" ::: "memory")
; #define WAIT_L(n) asm volatile("s_waitcnt lgkmcnt(" #n ")" ::: "memory")
; #define BAR __builtin_amdgcn_s_barrier()
; #define SCHED __builtin_amdgcn_sched_barrier(0)
; #define LDA(dst, b, h)                                                                            \
;   _Pragma("unroll") for (int m = 0; m < 4; ++m) _Pragma("unroll") for (int k = 0; k < 2; ++k)                                         \
;     dst[m][k] = *reinterpret_cast<const bf16x8*>((char*)SA(b, h) + lds_byte(wr * 64 + m * 16 + fr, k * 32 + fq * 8))
; #define LDB(dst, b, h)                                                                            \
;   _Pragma("unroll") for (int n = 0; n < 2; ++n) _Pragma("unroll") for (int k = 0; k < 2; ++k)                                         \
;     dst[n][k] = *reinterpret_cast<const bf16x8*>((char*)SB(b, h) + lds_byte(wc * 32 + n * 16 + fr, k * 32 + fq * 8))
; template <int K, bool SWAP>
; __device__ __forceinline__ void gemm_kloop(const bf16* __restrict__ A, const bf16* __restrict__ Bt,
;                                            f32x4 (&acc)[2][2][4][2], bool pref = false) {
;     ...
;     LDB(B0, 0, 0); SCHED; LDA(At, 0, 0); STAGE(SA(1, 1), A, HALF, t + 1);
;     WAIT_L(8); BAR; WAIT_L(0); MMA(0, 0, At, B0); BAR; SCHED;
;     LDB(B1, 0, 1); STAGE(SB(0, 0), Bt, 0, t + 2);
;     BAR; WAIT_L(0); MMA(0, 1, At, B1); BAR;
;     LDA(At, 0, 1); STAGE(SA(0, 0), A, 0, t + 2);
;     BAR; WAIT_L(0); MMA(1, 0, At, B0); BAR; SCHED;
;     STAGE(SB(0, 1), Bt, HALF, t + 2);
;     WAIT_V(6); BAR; MMA(1, 1, At, B1); BAR;
;     LDB(B0, 1, 0); SCHED; LDA(At, 1, 0); STAGE(SA(0, 1), A, HALF, t + 2);
;     WAIT_L(8); BAR; WAIT_L(0); MMA(0, 0, At, B0); BAR; SCHED;
;     LDB(B1, 1, 1); STAGE(SB(1, 0), Bt, 0, t + 3);
;     BAR; WAIT_L(0); MMA(0, 1, At, B1); BAR;
;     LDA(At, 1, 1); STAGE(SA(1, 0), A, 0, t + 3);
;     BAR; WAIT_L(0); MMA(1, 0, At, B0); BAR; SCHED;
;     STAGE(SB(1, 1), Bt, HALF, t + 3);
;     WAIT_V(6); BAR; MMA(1, 1, At, B1); BAR;
	v_add_u32_e32 v15, s65, v15
	v_add3_u32 v133, s33, v65, v130
	v_readfirstlane_b32 s4, v15
	v_add_u32_e32 v15, s65, v13
	v_lshl_add_u64 v[32:33], v[8:9], 0, s[44:45]
	s_mov_b32 m0, s4
	v_readfirstlane_b32 s4, v15
	ds_read_b128 v[24:27], v133
	ds_read_b128 v[28:31], v133 offset:1024
	ds_read_b128 v[94:97], v133 offset:2048
	ds_read_b128 v[98:101], v133 offset:3072
	global_load_lds_dwordx4 v[32:33], off
	v_lshl_add_u64 v[32:33], v[10:11], 0, s[44:45]
	s_mov_b32 m0, s4
	s_nop 0
	global_load_lds_dwordx4 v[32:33], off
	s_barrier
	s_waitcnt lgkmcnt(0)
	s_waitcnt lgkmcnt(0)
	v_mfma_f32_16x16x32_bf16 v[102:105], v[24:27], v[34:37], 0
	v_mfma_f32_16x16x32_bf16 v[32:35], v[94:97], v[34:37], 0
	v_mfma_f32_16x16x32_bf16 v[102:105], v[28:31], v[38:41], v[102:105]
	v_mfma_f32_16x16x32_bf16 v[32:35], v[98:101], v[38:41], v[32:35]
	v_mfma_f32_16x16x32_bf16 v[36:39], v[24:27], v[42:45], 0
	v_mfma_f32_16x16x32_bf16 v[40:43], v[94:97], v[42:45], 0
	v_mfma_f32_16x16x32_bf16 v[36:39], v[28:31], v[46:49], v[36:39]
	v_mfma_f32_16x16x32_bf16 v[40:43], v[98:101], v[46:49], v[40:43]
	v_mfma_f32_16x16x32_bf16 v[44:47], v[24:27], v[50:53], 0
	v_mfma_f32_16x16x32_bf16 v[24:27], v[24:27], v[58:61], 0
	v_mfma_f32_16x16x32_bf16 v[44:47], v[28:31], v[54:57], v[44:47]
	v_mfma_f32_16x16x32_bf16 v[48:51], v[94:97], v[50:53], 0
	v_mfma_f32_16x16x32_bf16 v[24:27], v[28:31], v[66:69], v[24:27]
	v_mfma_f32_16x16x32_bf16 v[28:31], v[94:97], v[58:61], 0
	v_mfma_f32_16x16x32_bf16 v[48:51], v[98:101], v[54:57], v[48:51]
	v_mfma_f32_16x16x32_bf16 v[28:31], v[98:101], v[66:69], v[28:31]
	v_lshl_add_u64 v[52:53], s[22:23], 0, v[0:1]
	v_readfirstlane_b32 s4, v12
	v_lshl_add_u64 v[52:53], v[52:53], 0, v[2:3]
	s_mov_b32 m0, s4
	v_add_u32_e32 v15, 0x2000, v12
	s_barrier
	global_load_lds_dwordx4 v[52:53], off
	v_lshl_add_u64 v[52:53], s[22:23], 0, v[4:5]
	v_readfirstlane_b32 s4, v15
	v_lshl_add_u64 v[52:53], v[52:53], 0, v[6:7]
	s_mov_b32 m0, s4
	s_nop 0
	global_load_lds_dwordx4 v[52:53], off
	s_barrier
	s_waitcnt lgkmcnt(0)
	s_barrier
	v_lshl_add_u64 v[52:53], s[62:63], 0, v[0:1]
	v_readfirstlane_b32 s4, v14
	v_add_u32_e32 v13, s33, v13
	v_lshl_add_u64 v[52:53], v[52:53], 0, v[2:3]
	s_mov_b32 m0, s4
	v_lshl_add_u64 v[14:15], s[62:63], 0, v[4:5]
	v_readfirstlane_b32 s4, v13
	global_load_lds_dwordx4 v[52:53], off
	v_lshl_add_u64 v[14:15], v[14:15], 0, v[6:7]
	s_mov_b32 m0, s4
	s_nop 0
	global_load_lds_dwordx4 v[14:15], off
	s_waitcnt vmcnt(6)
	s_barrier
	v_add3_u32 v134, s68, v65, v130
	s_barrier
	ds_read_b128 v[52:55], v134
	ds_read_b128 v[56:59], v134 offset:1024
	ds_read_b128 v[60:63], v134 offset:2048
	ds_read_b128 v[66:69], v134 offset:3072
	v_add_u32_e32 v13, 0x4000, v12
	v_lshl_add_u64 v[14:15], s[58:59], 0, v[0:1]
	v_readfirstlane_b32 s4, v13
	v_lshl_add_u64 v[14:15], v[14:15], 0, v[2:3]
	s_mov_b32 m0, s4
	v_add_u32_e32 v12, 0x6000, v12
	ds_read_b128 v[94:97], v132 offset:32768
	ds_read_b128 v[98:101], v132 offset:33792
	ds_read_b128 v[106:109], v138 offset:34816
	ds_read_b128 v[110:113], v138 offset:35840
	ds_read_b128 v[114:117], v138 offset:36864
	ds_read_b128 v[118:121], v138 offset:37888
	ds_read_b128 v[122:125], v138 offset:38912
	ds_read_b128 v[126:129], v138 offset:39936
	global_load_lds_dwordx4 v[14:15], off
	v_lshl_add_u64 v[14:15], s[58:59], 0, v[4:5]
	v_readfirstlane_b32 s4, v12
	v_lshl_add_u64 v[14:15], v[14:15], 0, v[6:7]
	s_mov_b32 m0, s4
	s_nop 0
	global_load_lds_dwordx4 v[14:15], off
	s_waitcnt lgkmcnt(8)
	s_barrier
	s_waitcnt lgkmcnt(0)
	s_waitcnt lgkmcnt(0)
	v_mfma_f32_16x16x32_bf16 v[12:15], v[52:55], v[94:97], v[70:73]
	v_mfma_f32_16x16x32_bf16 v[16:19], v[52:55], v[122:125], v[16:19]
	v_mfma_f32_16x16x32_bf16 v[20:23], v[60:63], v[122:125], v[20:23]
	v_mfma_f32_16x16x32_bf16 v[12:15], v[56:59], v[98:101], v[12:15]
	v_mfma_f32_16x16x32_bf16 v[70:73], v[60:63], v[94:97], v[74:77]
	v_mfma_f32_16x16x32_bf16 v[74:77], v[52:55], v[106:109], v[78:81]
	v_mfma_f32_16x16x32_bf16 v[78:81], v[60:63], v[106:109], v[82:85]
	v_mfma_f32_16x16x32_bf16 v[82:85], v[52:55], v[114:117], v[86:89]
	v_mfma_f32_16x16x32_bf16 v[86:89], v[60:63], v[114:117], v[90:93]
	v_mfma_f32_16x16x32_bf16 v[16:19], v[56:59], v[126:129], v[16:19]
	v_mfma_f32_16x16x32_bf16 v[20:23], v[66:69], v[126:129], v[20:23]
	v_mfma_f32_16x16x32_bf16 v[70:73], v[66:69], v[98:101], v[70:73]
	v_mfma_f32_16x16x32_bf16 v[74:77], v[56:59], v[110:113], v[74:77]
	v_mfma_f32_16x16x32_bf16 v[78:81], v[66:69], v[110:113], v[78:81]
	v_mfma_f32_16x16x32_bf16 v[82:85], v[56:59], v[118:121], v[82:85]
	v_mfma_f32_16x16x32_bf16 v[86:89], v[66:69], v[118:121], v[86:89]
	s_barrier
	s_mov_b32 m0, s20
	v_add3_u32 v65, s5, v65, v130
	v_lshl_add_u64 v[8:9], v[8:9], 0, s[52:53]
	ds_read_b128 v[52:55], v65
	ds_read_b128 v[56:59], v65 offset:1024
	ds_read_b128 v[60:63], v65 offset:2048
	ds_read_b128 v[66:69], v65 offset:3072
	global_load_lds_dwordx4 v[8:9], off
	v_lshl_add_u64 v[8:9], v[10:11], 0, s[52:53]
	s_mov_b32 m0, s73
	s_nop 0
	global_load_lds_dwordx4 v[8:9], off
	s_barrier
	s_waitcnt lgkmcnt(0)
	s_waitcnt lgkmcnt(0)
	v_mfma_f32_16x16x32_bf16 v[8:11], v[52:55], v[94:97], v[102:105]
	v_mfma_f32_16x16x32_bf16 v[32:35], v[60:63], v[94:97], v[32:35]
	v_mfma_f32_16x16x32_bf16 v[36:39], v[52:55], v[106:109], v[36:39]
	v_mfma_f32_16x16x32_bf16 v[40:43], v[60:63], v[106:109], v[40:43]
	v_mfma_f32_16x16x32_bf16 v[44:47], v[52:55], v[114:117], v[44:47]
	v_mfma_f32_16x16x32_bf16 v[48:51], v[60:63], v[114:117], v[48:51]
	v_mfma_f32_16x16x32_bf16 v[24:27], v[52:55], v[122:125], v[24:27]
	v_mfma_f32_16x16x32_bf16 v[28:31], v[60:63], v[122:125], v[28:31]
	v_mfma_f32_16x16x32_bf16 v[8:11], v[56:59], v[98:101], v[8:11]
	v_mfma_f32_16x16x32_bf16 v[32:35], v[66:69], v[98:101], v[32:35]
	v_mfma_f32_16x16x32_bf16 v[36:39], v[56:59], v[110:113], v[36:39]
	v_mfma_f32_16x16x32_bf16 v[40:43], v[66:69], v[110:113], v[40:43]
	v_mfma_f32_16x16x32_bf16 v[44:47], v[56:59], v[118:121], v[44:47]
	v_mfma_f32_16x16x32_bf16 v[48:51], v[66:69], v[118:121], v[48:51]
	v_mfma_f32_16x16x32_bf16 v[24:27], v[56:59], v[126:129], v[24:27]
	v_mfma_f32_16x16x32_bf16 v[28:31], v[66:69], v[126:129], v[28:31]
	v_lshl_add_u64 v[52:53], s[0:1], 0, v[0:1]
	s_mov_b32 m0, s72
	v_lshl_add_u64 v[52:53], v[52:53], 0, v[2:3]
	s_barrier
; #define WAIT_V(n) asm volatile("s_waitcnt vmcnt(" #n ")" ::: "memory")
; #define WAIT_L(n) asm volatile("s_waitcnt lgkmcnt(" #n ")" ::: "memory")
; #define BAR __builtin_amdgcn_s_barrier()
; #define SCHED __builtin_amdgcn_sched_barrier(0)
; #define LDA(dst, b, h)                                                                            \
;   _Pragma("unroll") for (int m = 0; m < 4; ++m) _Pragma("unroll") for (int k = 0; k < 2; ++k)                                         \
;     dst[m][k] = *reinterpret_cast<const bf16x8*>((char*)SA(b, h) + lds_byte(wr * 64 + m * 16 + fr, k * 32 + fq * 8))
; #define LDB(dst, b, h)                                                                            \
;   _Pragma("unroll") for (int n = 0; n < 2; ++n) _Pragma("unroll") for (int k = 0; k < 2; ++k)                                         \
;     dst[n][k] = *reinterpret_cast<const bf16x8*>((char*)SB(b, h) + lds_byte(wc * 32 + n * 16 + fr, k * 32 + fq * 8))
; template <int K, bool SWAP>
; __device__ __forceinline__ void gemm_kloop(const bf16* __restrict__ A, const bf16* __restrict__ Bt,
;                                            f32x4 (&acc)[2][2][4][2], bool pref = false) {
;     ...
;     LDA(At, 1, 1); STAGE(SA(1, 0), A, 0, t + 3);
;     BAR; WAIT_L(0); MMA(1, 0, At, B0); BAR; SCHED;
;     STAGE(SB(1, 1), Bt, HALF, t + 3);
;     WAIT_V(6); BAR; MMA(1, 1, At, B1); BAR;
;   }
;   { LDB(B0, 0, 0); LDA(At, 0, 0); STAGE(SA(1, 1), A, HALF, nt - 1);
;     BAR; WAIT_L(0); MMA(0, 0, At, B0); BAR;
;     LDB(B1, 0, 1); BAR; WAIT_L(0); MMA(0, 1, At, B1); BAR;
;     LDA(At, 0, 1); WAIT_V(4); BAR; WAIT_L(0); MMA(1, 0, At, B0); MMA(1, 1, At, B1); BAR; }
;   { LDB(B0, 1, 0); LDA(At, 1, 0); WAIT_V(2); BAR; WAIT_L(0); MMA(0, 0, At, B0); BAR;
;     LDB(B1, 1, 1); WAIT_V(0); BAR; WAIT_L(0); MMA(0, 1, At, B1); BAR;
;     LDA(At, 1, 1); BAR; WAIT_L(0); MMA(1, 0, At, B0); MMA(1, 1, At, B1); BAR; }
;   if (wr == 0) BAR;
	global_load_lds_dwordx4 v[52:53], off
	v_lshl_add_u64 v[52:53], s[0:1], 0, v[4:5]
	v_lshl_add_u64 v[52:53], v[52:53], 0, v[6:7]
	s_mov_b32 m0, s66
	s_nop 0
	global_load_lds_dwordx4 v[52:53], off
	s_barrier
	s_waitcnt lgkmcnt(0)
	s_barrier
	v_lshl_add_u64 v[52:53], vcc, 0, v[0:1]
	s_mov_b32 m0, s71
	v_lshl_add_u64 v[52:53], v[52:53], 0, v[2:3]
	global_load_lds_dwordx4 v[52:53], off
	v_lshl_add_u64 v[52:53], vcc, 0, v[4:5]
	v_lshl_add_u64 v[52:53], v[52:53], 0, v[6:7]
	s_mov_b32 m0, s67
	s_nop 0
	global_load_lds_dwordx4 v[52:53], off
	s_waitcnt vmcnt(6)
	s_barrier
	v_lshl_add_u64 v[0:1], s[60:61], 0, v[0:1]
	s_mov_b32 m0, s70
	v_lshl_add_u64 v[0:1], v[0:1], 0, v[2:3]
	s_barrier
	ds_read_b128 v[52:55], v131
	ds_read_b128 v[56:59], v131 offset:1024
	ds_read_b128 v[60:63], v131 offset:2048
	ds_read_b128 v[66:69], v131 offset:3072
	ds_read_b128 v[90:93], v132
	ds_read_b128 v[94:97], v132 offset:1024
	ds_read_b128 v[98:101], v138 offset:2048
	ds_read_b128 v[102:105], v138 offset:3072
	ds_read_b128 v[106:109], v138 offset:4096
	ds_read_b128 v[110:113], v138 offset:5120
	ds_read_b128 v[114:117], v138 offset:6144
	ds_read_b128 v[118:121], v138 offset:7168
	global_load_lds_dwordx4 v[0:1], off
	v_lshl_add_u64 v[0:1], s[60:61], 0, v[4:5]
	v_lshl_add_u64 v[0:1], v[0:1], 0, v[6:7]
	s_mov_b32 m0, s41
	s_nop 0
	global_load_lds_dwordx4 v[0:1], off
	s_barrier
	s_waitcnt lgkmcnt(0)
	s_waitcnt lgkmcnt(0)
	v_mfma_f32_16x16x32_bf16 v[0:3], v[52:55], v[90:93], v[12:15]
	v_mfma_f32_16x16x32_bf16 v[4:7], v[60:63], v[90:93], v[70:73]
	v_mfma_f32_16x16x32_bf16 v[12:15], v[52:55], v[98:101], v[74:77]
	v_mfma_f32_16x16x32_bf16 v[16:19], v[52:55], v[114:117], v[16:19]
	v_mfma_f32_16x16x32_bf16 v[20:23], v[60:63], v[114:117], v[20:23]
	v_mfma_f32_16x16x32_bf16 v[0:3], v[56:59], v[94:97], v[0:3]
	v_mfma_f32_16x16x32_bf16 v[4:7], v[66:69], v[94:97], v[4:7]
	v_mfma_f32_16x16x32_bf16 v[12:15], v[56:59], v[102:105], v[12:15]
	v_mfma_f32_16x16x32_bf16 v[70:73], v[60:63], v[98:101], v[78:81]
	v_mfma_f32_16x16x32_bf16 v[74:77], v[52:55], v[106:109], v[82:85]
	v_mfma_f32_16x16x32_bf16 v[78:81], v[60:63], v[106:109], v[86:89]
	v_mfma_f32_16x16x32_bf16 v[16:19], v[56:59], v[118:121], v[16:19]
	v_mfma_f32_16x16x32_bf16 v[20:23], v[66:69], v[118:121], v[20:23]
	v_mfma_f32_16x16x32_bf16 v[70:73], v[66:69], v[102:105], v[70:73]
	v_mfma_f32_16x16x32_bf16 v[74:77], v[56:59], v[110:113], v[74:77]
	v_mfma_f32_16x16x32_bf16 v[78:81], v[66:69], v[110:113], v[78:81]
	s_barrier
	ds_read_b128 v[52:55], v133
	ds_read_b128 v[56:59], v133 offset:1024
	ds_read_b128 v[60:63], v133 offset:2048
	ds_read_b128 v[66:69], v133 offset:3072
	s_barrier
	s_waitcnt lgkmcnt(0)
	s_waitcnt lgkmcnt(0)
	v_mfma_f32_16x16x32_bf16 v[32:35], v[60:63], v[90:93], v[32:35]
	v_mfma_f32_16x16x32_bf16 v[82:85], v[66:69], v[94:97], v[32:35]
	v_mfma_f32_16x16x32_bf16 v[32:35], v[52:55], v[98:101], v[36:39]
	v_mfma_f32_16x16x32_bf16 v[86:89], v[56:59], v[102:105], v[32:35]
	v_mfma_f32_16x16x32_bf16 v[32:35], v[60:63], v[98:101], v[40:43]
	v_mfma_f32_16x16x32_bf16 v[8:11], v[52:55], v[90:93], v[8:11]
	v_mfma_f32_16x16x32_bf16 v[90:93], v[66:69], v[102:105], v[32:35]
	v_mfma_f32_16x16x32_bf16 v[32:35], v[52:55], v[106:109], v[44:47]
	v_mfma_f32_16x16x32_bf16 v[24:27], v[52:55], v[114:117], v[24:27]
	v_mfma_f32_16x16x32_bf16 v[8:11], v[56:59], v[94:97], v[8:11]
	v_mfma_f32_16x16x32_bf16 v[94:97], v[56:59], v[110:113], v[32:35]
	v_mfma_f32_16x16x32_bf16 v[32:35], v[60:63], v[106:109], v[48:51]
	v_mfma_f32_16x16x32_bf16 v[102:105], v[56:59], v[118:121], v[24:27]
	v_mfma_f32_16x16x32_bf16 v[24:27], v[60:63], v[114:117], v[28:31]
	v_mfma_f32_16x16x32_bf16 v[98:101], v[66:69], v[110:113], v[32:35]
	v_mfma_f32_16x16x32_bf16 v[66:69], v[66:69], v[118:121], v[24:27]
	s_barrier
	s_waitcnt vmcnt(4)
	s_barrier
	s_waitcnt lgkmcnt(0)
	s_barrier
	ds_read_b128 v[24:27], v134
	ds_read_b128 v[28:31], v134 offset:1024
	ds_read_b128 v[32:35], v134 offset:2048
	ds_read_b128 v[106:109], v134 offset:3072
	ds_read_b128 v[110:113], v132 offset:32768
	ds_read_b128 v[114:117], v132 offset:33792
	ds_read_b128 v[118:121], v138 offset:34816
	ds_read_b128 v[122:125], v138 offset:35840
	ds_read_b128 v[126:129], v138 offset:36864
	ds_read_b128 v[130:133], v138 offset:37888
	ds_read_b128 v[134:137], v138 offset:38912
	ds_read_b128 v[138:141], v138 offset:39936
	s_waitcnt vmcnt(2)
	s_barrier
	s_waitcnt lgkmcnt(0)
	s_waitcnt lgkmcnt(0)
	v_mfma_f32_16x16x32_bf16 v[0:3], v[24:27], v[110:113], v[0:3]
	v_mfma_f32_16x16x32_bf16 v[60:63], v[28:31], v[114:117], v[0:3]
	v_mfma_f32_16x16x32_bf16 v[0:3], v[32:35], v[110:113], v[4:7]
	v_mfma_f32_16x16x32_bf16 v[56:59], v[106:109], v[114:117], v[0:3]
	v_mfma_f32_16x16x32_bf16 v[0:3], v[24:27], v[118:121], v[12:15]
	v_mfma_f32_16x16x32_bf16 v[52:55], v[28:31], v[122:125], v[0:3]
	v_mfma_f32_16x16x32_bf16 v[0:3], v[32:35], v[118:121], v[70:73]
	v_mfma_f32_16x16x32_bf16 v[48:51], v[106:109], v[122:125], v[0:3]
	v_mfma_f32_16x16x32_bf16 v[0:3], v[24:27], v[126:129], v[74:77]
	v_mfma_f32_16x16x32_bf16 v[44:47], v[28:31], v[130:133], v[0:3]
	v_mfma_f32_16x16x32_bf16 v[0:3], v[32:35], v[126:129], v[78:81]
	v_mfma_f32_16x16x32_bf16 v[40:43], v[106:109], v[130:133], v[0:3]
	v_mfma_f32_16x16x32_bf16 v[0:3], v[24:27], v[134:137], v[16:19]
	v_mfma_f32_16x16x32_bf16 v[36:39], v[28:31], v[138:141], v[0:3]
	v_mfma_f32_16x16x32_bf16 v[0:3], v[32:35], v[134:137], v[20:23]
	v_mfma_f32_16x16x32_bf16 v[32:35], v[106:109], v[138:141], v[0:3]
	s_barrier
	s_nop 4
	ds_read_b128 v[0:3], v65
	ds_read_b128 v[4:7], v65 offset:1024
	ds_read_b128 v[70:73], v65 offset:2048
	ds_read_b128 v[74:77], v65 offset:3072
	s_waitcnt vmcnt(0)
	s_barrier
	s_waitcnt lgkmcnt(0)
	s_waitcnt lgkmcnt(0)
	v_mfma_f32_16x16x32_bf16 v[8:11], v[0:3], v[110:113], v[8:11]
	v_mfma_f32_16x16x32_bf16 v[28:31], v[4:7], v[114:117], v[8:11]
	v_mfma_f32_16x16x32_bf16 v[8:11], v[70:73], v[110:113], v[82:85]
	v_mfma_f32_16x16x32_bf16 v[24:27], v[74:77], v[114:117], v[8:11]
	v_mfma_f32_16x16x32_bf16 v[8:11], v[0:3], v[118:121], v[86:89]
	v_mfma_f32_16x16x32_bf16 v[20:23], v[4:7], v[122:125], v[8:11]
	v_mfma_f32_16x16x32_bf16 v[8:11], v[70:73], v[118:121], v[90:93]
	v_mfma_f32_16x16x32_bf16 v[16:19], v[74:77], v[122:125], v[8:11]
	v_mfma_f32_16x16x32_bf16 v[8:11], v[0:3], v[126:129], v[94:97]
	v_mfma_f32_16x16x32_bf16 v[0:3], v[0:3], v[134:137], v[102:105]
	v_mfma_f32_16x16x32_bf16 v[12:15], v[4:7], v[130:133], v[8:11]
	v_mfma_f32_16x16x32_bf16 v[8:11], v[70:73], v[126:129], v[98:101]
	v_mfma_f32_16x16x32_bf16 v[4:7], v[4:7], v[138:141], v[0:3]
	v_mfma_f32_16x16x32_bf16 v[0:3], v[70:73], v[134:137], v[66:69]
	v_mfma_f32_16x16x32_bf16 v[8:11], v[74:77], v[130:133], v[8:11]
	v_mfma_f32_16x16x32_bf16 v[0:3], v[74:77], v[138:141], v[0:3]
	s_barrier
	s_barrier
	s_waitcnt lgkmcnt(0)
	s_movk_i32 s4, 0x100
	v_cmp_gt_u32_e32 vcc, s4, v64
	s_barrier
	s_and_saveexec_b64 s[62:63], vcc
	s_cbranch_execz .LBB0_721
	s_barrier

; #define WAIT_L(n) asm volatile("s_waitcnt lgkmcnt(" #n ")" ::: "memory")
; #define BAR __builtin_amdgcn_s_barrier()
; #define SCHED __builtin_amdgcn_sched_barrier(0)
; #define LDA(dst, b, h)                                                                            \
;   _Pragma("unroll") for (int m = 0; m < 4; ++m) _Pragma("unroll") for (int k = 0; k < 2; ++k)                                         \
;     dst[m][k] = *reinterpret_cast<const bf16x8*>((char*)SA(b, h) + lds_byte(wr * 64 + m * 16 + fr, k * 32 + fq * 8))
; #define LDB(dst, b, h)                                                                            \
;   _Pragma("unroll") for (int n = 0; n < 2; ++n) _Pragma("unroll") for (int k = 0; k < 2; ++k)                                         \
;     dst[n][k] = *reinterpret_cast<const bf16x8*>((char*)SB(b, h) + lds_byte(wc * 32 + n * 16 + fr, k * 32 + fq * 8))
; template <int K, bool SWAP>
; __device__ __forceinline__ void gemm_kloop(const bf16* __restrict__ A, const bf16* __restrict__ Bt,
;                                            f32x4 (&acc)[2][2][4][2], bool pref = false) {
;     ...
;     LDB(B0, 0, 0); SCHED; LDA(At, 0, 0); STAGE(SA(1, 1), A, HALF, t + 1);
;     WAIT_L(8); BAR; WAIT_L(0); MMA(0, 0, At, B0); BAR; SCHED;
;     LDB(B1, 0, 1); STAGE(SB(0, 0), Bt, 0, t + 2);
;     BAR; WAIT_L(0); MMA(0, 1, At, B1); BAR;
;     LDA(At, 0, 1); STAGE(SA(0, 0), A, 0, t + 2);
;     BAR; WAIT_L(0); MMA(1, 0, At, B0); BAR; SCHED;
.LBB0_791:
	ds_read_b128 v[162:165], v159
	ds_read_b128 v[166:169], v159 offset:1024
	ds_read_b128 v[170:173], v159 offset:2048
	ds_read_b128 v[174:177], v159 offset:3072
	v_add_u32_e32 v160, 0xc000, v145
	v_lshl_add_u64 v[178:179], s[6:7], 0, v[140:141]
	v_readfirstlane_b32 s13, v160
	v_lshl_add_u64 v[188:189], v[178:179], 0, s[74:75]
	s_mov_b32 m0, s13
	v_add_u32_e32 v161, 0xe000, v145
	ds_read_b128 v[198:201], v156
	ds_read_b128 v[202:205], v156 offset:1024
	ds_read_b128 v[206:209], v151
	ds_read_b128 v[210:213], v151 offset:1024
	ds_read_b128 v[214:217], v150
	ds_read_b128 v[218:221], v150 offset:1024
	ds_read_b128 v[222:225], v149
	ds_read_b128 v[226:229], v149 offset:1024
	global_load_lds_dwordx4 v[188:189], off
	v_lshl_add_u64 v[188:189], s[6:7], 0, v[142:143]
	v_readfirstlane_b32 s13, v161
	v_lshl_add_u64 v[230:231], v[188:189], 0, s[74:75]
	s_mov_b32 m0, s13
	s_nop 0
	global_load_lds_dwordx4 v[230:231], off
	s_waitcnt lgkmcnt(8)
	s_barrier
	s_waitcnt lgkmcnt(0)
	s_waitcnt lgkmcnt(0)
	v_mfma_f32_16x16x32_bf16 v[124:127], v[162:165], v[198:201], v[124:127]
	v_mfma_f32_16x16x32_bf16 v[120:123], v[170:173], v[198:201], v[120:123]
	v_mfma_f32_16x16x32_bf16 v[112:115], v[170:173], v[206:209], v[112:115]
	v_mfma_f32_16x16x32_bf16 v[116:119], v[162:165], v[206:209], v[116:119]
	v_mfma_f32_16x16x32_bf16 v[108:111], v[162:165], v[214:217], v[108:111]
	v_mfma_f32_16x16x32_bf16 v[104:107], v[170:173], v[214:217], v[104:107]
	v_mfma_f32_16x16x32_bf16 v[96:99], v[170:173], v[222:225], v[96:99]
	v_mfma_f32_16x16x32_bf16 v[100:103], v[162:165], v[222:225], v[100:103]
	v_mfma_f32_16x16x32_bf16 v[124:127], v[166:169], v[202:205], v[124:127]
	v_mfma_f32_16x16x32_bf16 v[120:123], v[174:177], v[202:205], v[120:123]
	v_mfma_f32_16x16x32_bf16 v[112:115], v[174:177], v[210:213], v[112:115]
	v_mfma_f32_16x16x32_bf16 v[116:119], v[166:169], v[210:213], v[116:119]
	v_mfma_f32_16x16x32_bf16 v[108:111], v[166:169], v[218:221], v[108:111]
	v_mfma_f32_16x16x32_bf16 v[104:107], v[174:177], v[218:221], v[104:107]
	v_mfma_f32_16x16x32_bf16 v[96:99], v[174:177], v[226:229], v[96:99]
	v_mfma_f32_16x16x32_bf16 v[100:103], v[166:169], v[226:229], v[100:103]
	s_barrier
	v_add_u32_e32 v186, s9, v144
	v_lshl_add_u64 v[246:247], s[6:7], 0, v[136:137]
	v_readfirstlane_b32 s13, v186
	v_lshl_add_u64 v[248:249], v[246:247], 0, s[76:77]
	s_mov_b32 m0, s13
	v_add_u32_e32 v186, 0x2000, v186
	ds_read_b128 v[230:233], v158
	ds_read_b128 v[234:237], v158 offset:1024
	ds_read_b128 v[238:241], v158 offset:2048
	ds_read_b128 v[242:245], v158 offset:3072
	global_load_lds_dwordx4 v[248:249], off
	v_lshl_add_u64 v[248:249], s[6:7], 0, v[138:139]
	v_readfirstlane_b32 s13, v186
	v_lshl_add_u64 v[250:251], v[248:249], 0, s[76:77]
	s_mov_b32 m0, s13
	s_nop 0
	global_load_lds_dwordx4 v[250:251], off
	s_barrier
	s_waitcnt lgkmcnt(0)
	s_waitcnt lgkmcnt(0)
	v_mfma_f32_16x16x32_bf16 v[92:95], v[230:233], v[198:201], v[92:95]
	v_mfma_f32_16x16x32_bf16 v[88:91], v[238:241], v[198:201], v[88:91]
	v_mfma_f32_16x16x32_bf16 v[80:83], v[238:241], v[206:209], v[80:83]
	v_mfma_f32_16x16x32_bf16 v[84:87], v[230:233], v[206:209], v[84:87]
	v_mfma_f32_16x16x32_bf16 v[76:79], v[230:233], v[214:217], v[76:79]
	v_mfma_f32_16x16x32_bf16 v[72:75], v[238:241], v[214:217], v[72:75]
	v_mfma_f32_16x16x32_bf16 v[64:67], v[238:241], v[222:225], v[64:67]
	v_mfma_f32_16x16x32_bf16 v[68:71], v[230:233], v[222:225], v[68:71]
	v_mfma_f32_16x16x32_bf16 v[92:95], v[234:237], v[202:205], v[92:95]
	v_mfma_f32_16x16x32_bf16 v[88:91], v[242:245], v[202:205], v[88:91]
	v_mfma_f32_16x16x32_bf16 v[80:83], v[242:245], v[210:213], v[80:83]
	v_mfma_f32_16x16x32_bf16 v[84:87], v[234:237], v[210:213], v[84:87]
	v_mfma_f32_16x16x32_bf16 v[76:79], v[234:237], v[218:221], v[76:79]
	v_mfma_f32_16x16x32_bf16 v[72:75], v[242:245], v[218:221], v[72:75]
	v_mfma_f32_16x16x32_bf16 v[64:67], v[242:245], v[226:229], v[64:67]
	v_mfma_f32_16x16x32_bf16 v[68:71], v[234:237], v[226:229], v[68:71]
	v_readfirstlane_b32 s13, v145
	v_add_u32_e32 v186, 0x2000, v145
	v_lshl_add_u64 v[250:251], v[178:179], 0, s[46:47]
	s_mov_b32 m0, s13
	v_readfirstlane_b32 s13, v186
	s_barrier
	ds_read_b128 v[198:201], v156 offset:16384
	ds_read_b128 v[202:205], v156 offset:17408
	ds_read_b128 v[206:209], v151 offset:16384
	ds_read_b128 v[210:213], v151 offset:17408
	ds_read_b128 v[214:217], v150 offset:16384
	ds_read_b128 v[218:221], v150 offset:17408
	ds_read_b128 v[222:225], v149 offset:16384
	ds_read_b128 v[226:229], v149 offset:17408
	global_load_lds_dwordx4 v[250:251], off
	v_lshl_add_u64 v[250:251], v[188:189], 0, s[46:47]
	s_mov_b32 m0, s13
	s_nop 0
	global_load_lds_dwordx4 v[250:251], off
	s_barrier
	s_waitcnt lgkmcnt(0)
	s_waitcnt lgkmcnt(0)
	v_mfma_f32_16x16x32_bf16 v[60:63], v[162:165], v[198:201], v[60:63]
	v_mfma_f32_16x16x32_bf16 v[56:59], v[170:173], v[198:201], v[56:59]
	v_mfma_f32_16x16x32_bf16 v[48:51], v[170:173], v[206:209], v[48:51]
	v_mfma_f32_16x16x32_bf16 v[52:55], v[162:165], v[206:209], v[52:55]
	v_mfma_f32_16x16x32_bf16 v[44:47], v[162:165], v[214:217], v[44:47]
	v_mfma_f32_16x16x32_bf16 v[40:43], v[170:173], v[214:217], v[40:43]
	v_mfma_f32_16x16x32_bf16 v[32:35], v[170:173], v[222:225], v[32:35]
	v_mfma_f32_16x16x32_bf16 v[36:39], v[162:165], v[222:225], v[36:39]
	v_mfma_f32_16x16x32_bf16 v[60:63], v[166:169], v[202:205], v[60:63]
	v_mfma_f32_16x16x32_bf16 v[56:59], v[174:177], v[202:205], v[56:59]
	v_mfma_f32_16x16x32_bf16 v[48:51], v[174:177], v[210:213], v[48:51]
	v_mfma_f32_16x16x32_bf16 v[52:55], v[166:169], v[210:213], v[52:55]
	v_mfma_f32_16x16x32_bf16 v[44:47], v[166:169], v[218:221], v[44:47]
	v_mfma_f32_16x16x32_bf16 v[40:43], v[174:177], v[218:221], v[40:43]
	v_mfma_f32_16x16x32_bf16 v[32:35], v[174:177], v[226:229], v[32:35]
	v_mfma_f32_16x16x32_bf16 v[36:39], v[166:169], v[226:229], v[36:39]
	s_barrier
; #define WAIT_V(n) asm volatile("s_waitcnt vmcnt(" #n ")" ::: "memory")
; #define WAIT_L(n) asm volatile("s_waitcnt lgkmcnt(" #n ")" ::: "memory")
; #define BAR __builtin_amdgcn_s_barrier()
; #define SCHED __builtin_amdgcn_sched_barrier(0)
; #define LDA(dst, b, h)                                                                            \
;   _Pragma("unroll") for (int m = 0; m < 4; ++m) _Pragma("unroll") for (int k = 0; k < 2; ++k)                                         \
;     dst[m][k] = *reinterpret_cast<const bf16x8*>((char*)SA(b, h) + lds_byte(wr * 64 + m * 16 + fr, k * 32 + fq * 8))
; #define LDB(dst, b, h)                                                                            \
;   _Pragma("unroll") for (int n = 0; n < 2; ++n) _Pragma("unroll") for (int k = 0; k < 2; ++k)                                         \
;     dst[n][k] = *reinterpret_cast<const bf16x8*>((char*)SB(b, h) + lds_byte(wc * 32 + n * 16 + fr, k * 32 + fq * 8))
; template <int K, bool SWAP>
; __device__ __forceinline__ void gemm_kloop(const bf16* __restrict__ A, const bf16* __restrict__ Bt,
;                                            f32x4 (&acc)[2][2][4][2], bool pref = false) {
;     ...
;     STAGE(SB(0, 1), Bt, HALF, t + 2);
;     WAIT_V(6); BAR; MMA(1, 1, At, B1); BAR;
;     LDB(B0, 1, 0); SCHED; LDA(At, 1, 0); STAGE(SA(0, 1), A, HALF, t + 2);
;     WAIT_L(8); BAR; WAIT_L(0); MMA(0, 0, At, B0); BAR; SCHED;
;     LDB(B1, 1, 1); STAGE(SB(1, 0), Bt, 0, t + 3);
;     BAR; WAIT_L(0); MMA(0, 1, At, B1); BAR;
;     LDA(At, 1, 1); STAGE(SA(1, 0), A, 0, t + 3);
	v_readfirstlane_b32 s13, v146
	v_add_u32_e32 v164, 0x2000, v146
	v_lshl_add_u64 v[162:163], v[246:247], 0, s[78:79]
	s_mov_b32 m0, s13
	v_readfirstlane_b32 s13, v164
	global_load_lds_dwordx4 v[162:163], off
	v_lshl_add_u64 v[162:163], v[248:249], 0, s[78:79]
	s_mov_b32 m0, s13
	s_nop 0
	global_load_lds_dwordx4 v[162:163], off
	s_waitcnt vmcnt(6)
	s_barrier
	v_mfma_f32_16x16x32_bf16 v[28:31], v[230:233], v[198:201], v[28:31]
	v_mfma_f32_16x16x32_bf16 v[24:27], v[238:241], v[198:201], v[24:27]
	v_mfma_f32_16x16x32_bf16 v[16:19], v[238:241], v[206:209], v[16:19]
	v_mfma_f32_16x16x32_bf16 v[20:23], v[230:233], v[206:209], v[20:23]
	v_mfma_f32_16x16x32_bf16 v[12:15], v[230:233], v[214:217], v[12:15]
	v_mfma_f32_16x16x32_bf16 v[8:11], v[238:241], v[214:217], v[8:11]
	v_mfma_f32_16x16x32_bf16 v[0:3], v[238:241], v[222:225], v[0:3]
	v_mfma_f32_16x16x32_bf16 v[4:7], v[230:233], v[222:225], v[4:7]
	v_mfma_f32_16x16x32_bf16 v[28:31], v[234:237], v[202:205], v[28:31]
	v_mfma_f32_16x16x32_bf16 v[24:27], v[242:245], v[202:205], v[24:27]
	v_mfma_f32_16x16x32_bf16 v[16:19], v[242:245], v[210:213], v[16:19]
	v_mfma_f32_16x16x32_bf16 v[20:23], v[234:237], v[210:213], v[20:23]
	v_mfma_f32_16x16x32_bf16 v[12:15], v[234:237], v[218:221], v[12:15]
	v_mfma_f32_16x16x32_bf16 v[8:11], v[242:245], v[218:221], v[8:11]
	v_mfma_f32_16x16x32_bf16 v[0:3], v[242:245], v[226:229], v[0:3]
	v_mfma_f32_16x16x32_bf16 v[4:7], v[234:237], v[226:229], v[4:7]
	s_barrier
	ds_read_b128 v[162:165], v147
	ds_read_b128 v[166:169], v147 offset:1024
	ds_read_b128 v[170:173], v147 offset:2048
	ds_read_b128 v[174:177], v147 offset:3072
	v_add_u32_e32 v186, 0x4000, v145
	v_lshl_add_u64 v[230:231], v[178:179], 0, s[80:81]
	v_readfirstlane_b32 s13, v186
	v_add_u32_e32 v186, 0x6000, v145
	s_mov_b32 m0, s13
	v_readfirstlane_b32 s13, v186
	ds_read_b128 v[198:201], v156 offset:32768
	ds_read_b128 v[202:205], v156 offset:33792
	ds_read_b128 v[206:209], v151 offset:32768
	ds_read_b128 v[210:213], v151 offset:33792
	ds_read_b128 v[214:217], v150 offset:32768
	ds_read_b128 v[218:221], v150 offset:33792
	ds_read_b128 v[222:225], v149 offset:32768
	ds_read_b128 v[226:229], v149 offset:33792
	global_load_lds_dwordx4 v[230:231], off
	v_lshl_add_u64 v[230:231], v[188:189], 0, s[80:81]
	s_mov_b32 m0, s13
	s_nop 0
	global_load_lds_dwordx4 v[230:231], off
	s_waitcnt lgkmcnt(8)
	s_barrier
	s_waitcnt lgkmcnt(0)
	s_waitcnt lgkmcnt(0)
	v_mfma_f32_16x16x32_bf16 v[124:127], v[162:165], v[198:201], v[124:127]
	v_mfma_f32_16x16x32_bf16 v[120:123], v[170:173], v[198:201], v[120:123]
	v_mfma_f32_16x16x32_bf16 v[112:115], v[170:173], v[206:209], v[112:115]
	v_mfma_f32_16x16x32_bf16 v[116:119], v[162:165], v[206:209], v[116:119]
	v_mfma_f32_16x16x32_bf16 v[108:111], v[162:165], v[214:217], v[108:111]
	v_mfma_f32_16x16x32_bf16 v[104:107], v[170:173], v[214:217], v[104:107]
	v_mfma_f32_16x16x32_bf16 v[96:99], v[170:173], v[222:225], v[96:99]
	v_mfma_f32_16x16x32_bf16 v[100:103], v[162:165], v[222:225], v[100:103]
	v_mfma_f32_16x16x32_bf16 v[124:127], v[166:169], v[202:205], v[124:127]
	v_mfma_f32_16x16x32_bf16 v[120:123], v[174:177], v[202:205], v[120:123]
	v_mfma_f32_16x16x32_bf16 v[112:115], v[174:177], v[210:213], v[112:115]
	v_mfma_f32_16x16x32_bf16 v[116:119], v[166:169], v[210:213], v[116:119]
	v_mfma_f32_16x16x32_bf16 v[108:111], v[166:169], v[218:221], v[108:111]
	v_mfma_f32_16x16x32_bf16 v[104:107], v[174:177], v[218:221], v[104:107]
	v_mfma_f32_16x16x32_bf16 v[96:99], v[174:177], v[226:229], v[96:99]
	v_mfma_f32_16x16x32_bf16 v[100:103], v[166:169], v[226:229], v[100:103]
	s_barrier
	v_readfirstlane_b32 s13, v152
	v_add_u32_e32 v186, 0x2000, v152
	v_lshl_add_u64 v[250:251], v[246:247], 0, s[82:83]
	s_mov_b32 m0, s13
	v_readfirstlane_b32 s13, v186
	ds_read_b128 v[230:233], v157
	ds_read_b128 v[234:237], v157 offset:1024
	ds_read_b128 v[238:241], v157 offset:2048
	ds_read_b128 v[242:245], v157 offset:3072
	global_load_lds_dwordx4 v[250:251], off
	v_lshl_add_u64 v[250:251], v[248:249], 0, s[82:83]
	s_mov_b32 m0, s13
	s_nop 0
	global_load_lds_dwordx4 v[250:251], off
	s_barrier
	s_waitcnt lgkmcnt(0)
	s_waitcnt lgkmcnt(0)
	v_mfma_f32_16x16x32_bf16 v[92:95], v[230:233], v[198:201], v[92:95]
	v_mfma_f32_16x16x32_bf16 v[88:91], v[238:241], v[198:201], v[88:91]
	v_mfma_f32_16x16x32_bf16 v[80:83], v[238:241], v[206:209], v[80:83]
	v_mfma_f32_16x16x32_bf16 v[84:87], v[230:233], v[206:209], v[84:87]
	v_mfma_f32_16x16x32_bf16 v[76:79], v[230:233], v[214:217], v[76:79]
	v_mfma_f32_16x16x32_bf16 v[72:75], v[238:241], v[214:217], v[72:75]
	v_mfma_f32_16x16x32_bf16 v[64:67], v[238:241], v[222:225], v[64:67]
	v_mfma_f32_16x16x32_bf16 v[68:71], v[230:233], v[222:225], v[68:71]
	v_mfma_f32_16x16x32_bf16 v[92:95], v[234:237], v[202:205], v[92:95]
	v_mfma_f32_16x16x32_bf16 v[88:91], v[242:245], v[202:205], v[88:91]
	v_mfma_f32_16x16x32_bf16 v[80:83], v[242:245], v[210:213], v[80:83]
	v_mfma_f32_16x16x32_bf16 v[84:87], v[234:237], v[210:213], v[84:87]
	v_mfma_f32_16x16x32_bf16 v[76:79], v[234:237], v[218:221], v[76:79]
	v_mfma_f32_16x16x32_bf16 v[72:75], v[242:245], v[218:221], v[72:75]
	v_mfma_f32_16x16x32_bf16 v[64:67], v[242:245], v[226:229], v[64:67]
	v_mfma_f32_16x16x32_bf16 v[68:71], v[234:237], v[226:229], v[68:71]
	v_readfirstlane_b32 s13, v153
	v_lshl_add_u64 v[178:179], v[178:179], 0, s[54:55]
	s_mov_b32 m0, s13
	v_readfirstlane_b32 s13, v154
	s_barrier
	ds_read_b128 v[198:201], v156 offset:49152
	ds_read_b128 v[202:205], v156 offset:50176
	ds_read_b128 v[206:209], v151 offset:49152
	ds_read_b128 v[210:213], v151 offset:50176
	ds_read_b128 v[214:217], v150 offset:49152
	ds_read_b128 v[218:221], v150 offset:50176
	ds_read_b128 v[222:225], v149 offset:49152
	ds_read_b128 v[226:229], v149 offset:50176
	global_load_lds_dwordx4 v[178:179], off
	v_lshl_add_u64 v[178:179], v[188:189], 0, s[54:55]
	s_mov_b32 m0, s13
	s_nop 0
	global_load_lds_dwordx4 v[178:179], off
	s_barrier
; #define WAIT_V(n) asm volatile("s_waitcnt vmcnt(" #n ")" ::: "memory")
; #define WAIT_L(n) asm volatile("s_waitcnt lgkmcnt(" #n ")" ::: "memory")
; #define BAR __builtin_amdgcn_s_barrier()
; #define SCHED __builtin_amdgcn_sched_barrier(0)
; #define LDA(dst, b, h)                                                                            \
;   _Pragma("unroll") for (int m = 0; m < 4; ++m) _Pragma("unroll") for (int k = 0; k < 2; ++k)                                         \
;     dst[m][k] = *reinterpret_cast<const bf16x8*>((char*)SA(b, h) + lds_byte(wr * 64 + m * 16 + fr, k * 32 + fq * 8))
; #define LDB(dst, b, h)                                                                            \
;   _Pragma("unroll") for (int n = 0; n < 2; ++n) _Pragma("unroll") for (int k = 0; k < 2; ++k)                                         \
;     dst[n][k] = *reinterpret_cast<const bf16x8*>((char*)SB(b, h) + lds_byte(wc * 32 + n * 16 + fr, k * 32 + fq * 8))
; template <int K, bool SWAP>
; __device__ __forceinline__ void gemm_kloop(const bf16* __restrict__ A, const bf16* __restrict__ Bt,
;                                            f32x4 (&acc)[2][2][4][2], bool pref = false) {
;     ...
;     BAR; WAIT_L(0); MMA(1, 0, At, B0); BAR; SCHED;
;     STAGE(SB(1, 1), Bt, HALF, t + 3);
;     WAIT_V(6); BAR; MMA(1, 1, At, B1); BAR;
;   }
;   { LDB(B0, 0, 0); LDA(At, 0, 0); STAGE(SA(1, 1), A, HALF, nt - 1);
;     BAR; WAIT_L(0); MMA(0, 0, At, B0); BAR;
;     LDB(B1, 0, 1); BAR; WAIT_L(0); MMA(0, 1, At, B1); BAR;
	s_waitcnt lgkmcnt(0)
	s_waitcnt lgkmcnt(0)
	v_mfma_f32_16x16x32_bf16 v[60:63], v[162:165], v[198:201], v[60:63]
	v_mfma_f32_16x16x32_bf16 v[56:59], v[170:173], v[198:201], v[56:59]
	v_mfma_f32_16x16x32_bf16 v[48:51], v[170:173], v[206:209], v[48:51]
	v_mfma_f32_16x16x32_bf16 v[52:55], v[162:165], v[206:209], v[52:55]
	v_mfma_f32_16x16x32_bf16 v[44:47], v[162:165], v[214:217], v[44:47]
	v_mfma_f32_16x16x32_bf16 v[40:43], v[170:173], v[214:217], v[40:43]
	v_mfma_f32_16x16x32_bf16 v[32:35], v[170:173], v[222:225], v[32:35]
	v_mfma_f32_16x16x32_bf16 v[36:39], v[162:165], v[222:225], v[36:39]
	v_mfma_f32_16x16x32_bf16 v[60:63], v[166:169], v[202:205], v[60:63]
	v_mfma_f32_16x16x32_bf16 v[56:59], v[174:177], v[202:205], v[56:59]
	v_mfma_f32_16x16x32_bf16 v[48:51], v[174:177], v[210:213], v[48:51]
	v_mfma_f32_16x16x32_bf16 v[52:55], v[166:169], v[210:213], v[52:55]
	v_mfma_f32_16x16x32_bf16 v[44:47], v[166:169], v[218:221], v[44:47]
	v_mfma_f32_16x16x32_bf16 v[40:43], v[174:177], v[218:221], v[40:43]
	v_mfma_f32_16x16x32_bf16 v[32:35], v[174:177], v[226:229], v[32:35]
	v_mfma_f32_16x16x32_bf16 v[36:39], v[166:169], v[226:229], v[36:39]
	s_barrier
	v_readfirstlane_b32 s13, v155
	v_add_u32_e32 v164, 0x2000, v155
	v_lshl_add_u64 v[162:163], v[246:247], 0, s[84:85]
	s_mov_b32 m0, s13
	v_readfirstlane_b32 s13, v164
	global_load_lds_dwordx4 v[162:163], off
	v_lshl_add_u64 v[162:163], v[248:249], 0, s[84:85]
	s_mov_b32 m0, s13
	s_nop 0
	global_load_lds_dwordx4 v[162:163], off
	s_waitcnt vmcnt(6)
	s_barrier
	v_mfma_f32_16x16x32_bf16 v[28:31], v[230:233], v[198:201], v[28:31]
	v_mfma_f32_16x16x32_bf16 v[24:27], v[238:241], v[198:201], v[24:27]
	v_mfma_f32_16x16x32_bf16 v[16:19], v[238:241], v[206:209], v[16:19]
	v_mfma_f32_16x16x32_bf16 v[20:23], v[230:233], v[206:209], v[20:23]
	v_mfma_f32_16x16x32_bf16 v[12:15], v[230:233], v[214:217], v[12:15]
	v_mfma_f32_16x16x32_bf16 v[8:11], v[238:241], v[214:217], v[8:11]
	v_mfma_f32_16x16x32_bf16 v[0:3], v[238:241], v[222:225], v[0:3]
	v_mfma_f32_16x16x32_bf16 v[4:7], v[230:233], v[222:225], v[4:7]
	v_mfma_f32_16x16x32_bf16 v[28:31], v[234:237], v[202:205], v[28:31]
	v_mfma_f32_16x16x32_bf16 v[24:27], v[242:245], v[202:205], v[24:27]
	v_mfma_f32_16x16x32_bf16 v[16:19], v[242:245], v[210:213], v[16:19]
	v_mfma_f32_16x16x32_bf16 v[20:23], v[234:237], v[210:213], v[20:23]
	v_mfma_f32_16x16x32_bf16 v[12:15], v[234:237], v[218:221], v[12:15]
	v_mfma_f32_16x16x32_bf16 v[8:11], v[242:245], v[218:221], v[8:11]
	v_mfma_f32_16x16x32_bf16 v[0:3], v[242:245], v[226:229], v[0:3]
	v_mfma_f32_16x16x32_bf16 v[4:7], v[234:237], v[226:229], v[4:7]
	s_add_i32 s12, s12, 2
	v_lshl_add_u64 v[136:137], v[136:137], 0, s[44:45]
	v_lshl_add_u64 v[138:139], v[138:139], 0, s[44:45]
	v_lshl_add_u64 v[140:141], v[140:141], 0, s[44:45]
	s_cmp_lt_u32 s12, 4
	v_lshl_add_u64 v[142:143], v[142:143], 0, s[44:45]
	s_barrier
	s_cbranch_scc1 .LBB0_791
	s_add_u32 s0, s0, 0x20380
	s_addc_u32 s1, s1, 0
	v_lshl_add_u64 v[130:131], s[0:1], 0, v[130:131]
	v_readfirstlane_b32 s12, v160
	v_lshl_add_u64 v[128:129], v[128:129], 1, v[130:131]
	s_mov_b32 m0, s12
	ds_read_b128 v[136:139], v159
	ds_read_b128 v[140:143], v159 offset:1024
	ds_read_b128 v[152:155], v159 offset:2048
	ds_read_b128 v[162:165], v159 offset:3072
	ds_read_b128 v[166:169], v156
	ds_read_b128 v[170:173], v156 offset:1024
	ds_read_b128 v[174:177], v151
	ds_read_b128 v[198:201], v151 offset:1024
	ds_read_b128 v[202:205], v150
	ds_read_b128 v[206:209], v150 offset:1024
	ds_read_b128 v[210:213], v149
	ds_read_b128 v[214:217], v149 offset:1024
	global_load_lds_dwordx4 v[128:129], off
	v_lshl_add_u64 v[128:129], s[0:1], 0, v[134:135]
	v_readfirstlane_b32 s0, v161
	v_lshl_add_u64 v[128:129], v[132:133], 1, v[128:129]
	s_mov_b32 m0, s0
	s_nop 0
	global_load_lds_dwordx4 v[128:129], off
	s_barrier
	s_waitcnt lgkmcnt(0)
	s_waitcnt lgkmcnt(0)
	v_mfma_f32_16x16x32_bf16 v[124:127], v[136:139], v[166:169], v[124:127]
	v_mfma_f32_16x16x32_bf16 v[120:123], v[152:155], v[166:169], v[120:123]
	v_mfma_f32_16x16x32_bf16 v[112:115], v[152:155], v[174:177], v[112:115]
	v_mfma_f32_16x16x32_bf16 v[108:111], v[136:139], v[202:205], v[108:111]
	v_mfma_f32_16x16x32_bf16 v[100:103], v[136:139], v[210:213], v[100:103]
	v_mfma_f32_16x16x32_bf16 v[96:99], v[152:155], v[210:213], v[96:99]
	v_mfma_f32_16x16x32_bf16 v[124:127], v[140:143], v[170:173], v[124:127]
	v_mfma_f32_16x16x32_bf16 v[120:123], v[162:165], v[170:173], v[120:123]
	v_mfma_f32_16x16x32_bf16 v[116:119], v[136:139], v[174:177], v[116:119]
	v_mfma_f32_16x16x32_bf16 v[112:115], v[162:165], v[198:201], v[112:115]
	v_mfma_f32_16x16x32_bf16 v[108:111], v[140:143], v[206:209], v[108:111]
	v_mfma_f32_16x16x32_bf16 v[104:107], v[152:155], v[202:205], v[104:107]
	v_mfma_f32_16x16x32_bf16 v[100:103], v[140:143], v[214:217], v[100:103]
	v_mfma_f32_16x16x32_bf16 v[96:99], v[162:165], v[214:217], v[96:99]
	v_mfma_f32_16x16x32_bf16 v[116:119], v[140:143], v[198:201], v[116:119]
	v_mfma_f32_16x16x32_bf16 v[104:107], v[162:165], v[206:209], v[104:107]
	s_barrier
	ds_read_b128 v[128:131], v158
	ds_read_b128 v[132:135], v158 offset:1024
	ds_read_b128 v[218:221], v158 offset:2048
	ds_read_b128 v[158:161], v158 offset:3072
	s_barrier
; #define WAIT_V(n) asm volatile("s_waitcnt vmcnt(" #n ")" ::: "memory")
; #define WAIT_L(n) asm volatile("s_waitcnt lgkmcnt(" #n ")" ::: "memory")
; #define BAR __builtin_amdgcn_s_barrier()
; #define LDA(dst, b, h)                                                                            \
;   _Pragma("unroll") for (int m = 0; m < 4; ++m) _Pragma("unroll") for (int k = 0; k < 2; ++k)                                         \
;     dst[m][k] = *reinterpret_cast<const bf16x8*>((char*)SA(b, h) + lds_byte(wr * 64 + m * 16 + fr, k * 32 + fq * 8))
; #define LDB(dst, b, h)                                                                            \
;   _Pragma("unroll") for (int n = 0; n < 2; ++n) _Pragma("unroll") for (int k = 0; k < 2; ++k)                                         \
;     dst[n][k] = *reinterpret_cast<const bf16x8*>((char*)SB(b, h) + lds_byte(wc * 32 + n * 16 + fr, k * 32 + fq * 8))
; template <int K, bool SWAP>
; __device__ __forceinline__ void gemm_kloop(const bf16* __restrict__ A, const bf16* __restrict__ Bt,
;                                            f32x4 (&acc)[2][2][4][2], bool pref = false) {
;     ...
;     LDB(B1, 0, 1); BAR; WAIT_L(0); MMA(0, 1, At, B1); BAR;
;     LDA(At, 0, 1); WAIT_V(4); BAR; WAIT_L(0); MMA(1, 0, At, B0); MMA(1, 1, At, B1); BAR; }
;   { LDB(B0, 1, 0); LDA(At, 1, 0); WAIT_V(2); BAR; WAIT_L(0); MMA(0, 0, At, B0); BAR;
	s_waitcnt lgkmcnt(0)
	s_waitcnt lgkmcnt(0)
	v_mfma_f32_16x16x32_bf16 v[88:91], v[218:221], v[166:169], v[88:91]
	v_mfma_f32_16x16x32_bf16 v[84:87], v[128:131], v[174:177], v[84:87]
	v_mfma_f32_16x16x32_bf16 v[76:79], v[128:131], v[202:205], v[76:79]
	v_mfma_f32_16x16x32_bf16 v[72:75], v[218:221], v[202:205], v[72:75]
	v_mfma_f32_16x16x32_bf16 v[68:71], v[128:131], v[210:213], v[68:71]
	v_mfma_f32_16x16x32_bf16 v[64:67], v[218:221], v[210:213], v[64:67]
	v_mfma_f32_16x16x32_bf16 v[92:95], v[128:131], v[166:169], v[92:95]
	v_mfma_f32_16x16x32_bf16 v[88:91], v[158:161], v[170:173], v[88:91]
	v_mfma_f32_16x16x32_bf16 v[84:87], v[132:135], v[198:201], v[84:87]
	v_mfma_f32_16x16x32_bf16 v[80:83], v[218:221], v[174:177], v[80:83]
	v_mfma_f32_16x16x32_bf16 v[76:79], v[132:135], v[206:209], v[76:79]
	v_mfma_f32_16x16x32_bf16 v[72:75], v[158:161], v[206:209], v[72:75]
	v_mfma_f32_16x16x32_bf16 v[68:71], v[132:135], v[214:217], v[68:71]
	v_mfma_f32_16x16x32_bf16 v[64:67], v[158:161], v[214:217], v[64:67]
	v_mfma_f32_16x16x32_bf16 v[92:95], v[132:135], v[170:173], v[92:95]
	v_mfma_f32_16x16x32_bf16 v[80:83], v[158:161], v[198:201], v[80:83]
	s_barrier
	ds_read_b128 v[166:169], v156 offset:16384
	ds_read_b128 v[170:173], v156 offset:17408
	ds_read_b128 v[174:177], v151 offset:16384
	ds_read_b128 v[198:201], v151 offset:17408
	ds_read_b128 v[202:205], v150 offset:16384
	ds_read_b128 v[206:209], v150 offset:17408
	ds_read_b128 v[210:213], v149 offset:16384
	ds_read_b128 v[214:217], v149 offset:17408
	s_waitcnt vmcnt(4)
	s_barrier
	s_waitcnt lgkmcnt(0)
	s_waitcnt lgkmcnt(0)
	v_mfma_f32_16x16x32_bf16 v[60:63], v[136:139], v[166:169], v[60:63]
	v_mfma_f32_16x16x32_bf16 v[56:59], v[152:155], v[166:169], v[56:59]
	v_mfma_f32_16x16x32_bf16 v[48:51], v[152:155], v[174:177], v[48:51]
	v_mfma_f32_16x16x32_bf16 v[52:55], v[136:139], v[174:177], v[52:55]
	v_mfma_f32_16x16x32_bf16 v[44:47], v[136:139], v[202:205], v[44:47]
	v_mfma_f32_16x16x32_bf16 v[40:43], v[152:155], v[202:205], v[40:43]
	v_mfma_f32_16x16x32_bf16 v[32:35], v[152:155], v[210:213], v[32:35]
	v_mfma_f32_16x16x32_bf16 v[36:39], v[136:139], v[210:213], v[36:39]
	v_mfma_f32_16x16x32_bf16 v[60:63], v[140:143], v[170:173], v[60:63]
	v_mfma_f32_16x16x32_bf16 v[56:59], v[162:165], v[170:173], v[56:59]
	v_mfma_f32_16x16x32_bf16 v[48:51], v[162:165], v[198:201], v[48:51]
	v_mfma_f32_16x16x32_bf16 v[52:55], v[140:143], v[198:201], v[52:55]
	v_mfma_f32_16x16x32_bf16 v[44:47], v[140:143], v[206:209], v[44:47]
	v_mfma_f32_16x16x32_bf16 v[40:43], v[162:165], v[206:209], v[40:43]
	v_mfma_f32_16x16x32_bf16 v[32:35], v[162:165], v[214:217], v[32:35]
	v_mfma_f32_16x16x32_bf16 v[36:39], v[140:143], v[214:217], v[36:39]
	v_mfma_f32_16x16x32_bf16 v[28:31], v[128:131], v[166:169], v[28:31]
	v_mfma_f32_16x16x32_bf16 v[24:27], v[218:221], v[166:169], v[24:27]
	v_mfma_f32_16x16x32_bf16 v[16:19], v[218:221], v[174:177], v[16:19]
	v_mfma_f32_16x16x32_bf16 v[20:23], v[128:131], v[174:177], v[20:23]
	v_mfma_f32_16x16x32_bf16 v[12:15], v[128:131], v[202:205], v[12:15]
	v_mfma_f32_16x16x32_bf16 v[8:11], v[218:221], v[202:205], v[8:11]
	v_mfma_f32_16x16x32_bf16 v[0:3], v[218:221], v[210:213], v[0:3]
	v_mfma_f32_16x16x32_bf16 v[4:7], v[128:131], v[210:213], v[4:7]
	v_mfma_f32_16x16x32_bf16 v[28:31], v[132:135], v[170:173], v[28:31]
	v_mfma_f32_16x16x32_bf16 v[24:27], v[158:161], v[170:173], v[24:27]
	v_mfma_f32_16x16x32_bf16 v[16:19], v[158:161], v[198:201], v[16:19]
	v_mfma_f32_16x16x32_bf16 v[20:23], v[132:135], v[198:201], v[20:23]
	v_mfma_f32_16x16x32_bf16 v[12:15], v[132:135], v[206:209], v[12:15]
	v_mfma_f32_16x16x32_bf16 v[8:11], v[158:161], v[206:209], v[8:11]
	v_mfma_f32_16x16x32_bf16 v[0:3], v[158:161], v[214:217], v[0:3]
	v_mfma_f32_16x16x32_bf16 v[4:7], v[132:135], v[214:217], v[4:7]
	s_barrier
	ds_read_b128 v[128:131], v147
	ds_read_b128 v[140:143], v147 offset:1024
	ds_read_b128 v[158:161], v147 offset:2048
	ds_read_b128 v[162:165], v147 offset:3072
	ds_read_b128 v[166:169], v156 offset:32768
	ds_read_b128 v[170:173], v156 offset:33792
	ds_read_b128 v[174:177], v151 offset:32768
	ds_read_b128 v[198:201], v151 offset:33792
	ds_read_b128 v[202:205], v150 offset:32768
	ds_read_b128 v[206:209], v150 offset:33792
	ds_read_b128 v[210:213], v149 offset:32768
	ds_read_b128 v[214:217], v149 offset:33792
	s_waitcnt vmcnt(2)
	s_barrier
; #define WAIT_V(n) asm volatile("s_waitcnt vmcnt(" #n ")" ::: "memory")
; #define WAIT_L(n) asm volatile("s_waitcnt lgkmcnt(" #n ")" ::: "memory")
; #define BAR __builtin_amdgcn_s_barrier()
; #define LDA(dst, b, h)                                                                            \
;   _Pragma("unroll") for (int m = 0; m < 4; ++m) _Pragma("unroll") for (int k = 0; k < 2; ++k)                                         \
;     dst[m][k] = *reinterpret_cast<const bf16x8*>((char*)SA(b, h) + lds_byte(wr * 64 + m * 16 + fr, k * 32 + fq * 8))
; #define LDB(dst, b, h)                                                                            \
;   _Pragma("unroll") for (int n = 0; n < 2; ++n) _Pragma("unroll") for (int k = 0; k < 2; ++k)                                         \
;     dst[n][k] = *reinterpret_cast<const bf16x8*>((char*)SB(b, h) + lds_byte(wc * 32 + n * 16 + fr, k * 32 + fq * 8))
; template <int K, bool SWAP>
; __device__ __forceinline__ void gemm_kloop(const bf16* __restrict__ A, const bf16* __restrict__ Bt,
;                                            f32x4 (&acc)[2][2][4][2], bool pref = false) {
;     ...
;   { LDB(B0, 1, 0); LDA(At, 1, 0); WAIT_V(2); BAR; WAIT_L(0); MMA(0, 0, At, B0); BAR;
;     LDB(B1, 1, 1); WAIT_V(0); BAR; WAIT_L(0); MMA(0, 1, At, B1); BAR;
;     LDA(At, 1, 1); BAR; WAIT_L(0); MMA(1, 0, At, B0); MMA(1, 1, At, B1); BAR; }
;   if (wr == 0) BAR;
	s_waitcnt lgkmcnt(0)
	s_waitcnt lgkmcnt(0)
	v_mfma_f32_16x16x32_bf16 v[124:127], v[128:131], v[166:169], v[124:127]
	v_mfma_f32_16x16x32_bf16 v[120:123], v[158:161], v[166:169], v[120:123]
	v_mfma_f32_16x16x32_bf16 v[116:119], v[128:131], v[174:177], v[116:119]
	v_mfma_f32_16x16x32_bf16 v[112:115], v[158:161], v[174:177], v[112:115]
	v_mfma_f32_16x16x32_bf16 v[108:111], v[128:131], v[202:205], v[108:111]
	v_mfma_f32_16x16x32_bf16 v[104:107], v[158:161], v[202:205], v[104:107]
	v_mfma_f32_16x16x32_bf16 v[100:103], v[128:131], v[210:213], v[100:103]
	v_mfma_f32_16x16x32_bf16 v[96:99], v[158:161], v[210:213], v[96:99]
	v_mfma_f32_16x16x32_bf16 v[152:155], v[140:143], v[170:173], v[124:127]
	v_mfma_f32_16x16x32_bf16 v[144:147], v[162:165], v[170:173], v[120:123]
	v_mfma_f32_16x16x32_bf16 v[136:139], v[140:143], v[198:201], v[116:119]
	v_mfma_f32_16x16x32_bf16 v[132:135], v[162:165], v[198:201], v[112:115]
	v_mfma_f32_16x16x32_bf16 v[124:127], v[140:143], v[206:209], v[108:111]
	v_mfma_f32_16x16x32_bf16 v[120:123], v[162:165], v[206:209], v[104:107]
	v_mfma_f32_16x16x32_bf16 v[112:115], v[140:143], v[214:217], v[100:103]
	v_mfma_f32_16x16x32_bf16 v[108:111], v[162:165], v[214:217], v[96:99]
	s_barrier
	ds_read_b128 v[104:107], v157
	ds_read_b128 v[116:119], v157 offset:1024
	ds_read_b128 v[218:221], v157 offset:2048
	ds_read_b128 v[222:225], v157 offset:3072
	s_waitcnt vmcnt(0)
	s_barrier
	s_waitcnt lgkmcnt(0)
	s_waitcnt lgkmcnt(0)
	v_mfma_f32_16x16x32_bf16 v[92:95], v[104:107], v[166:169], v[92:95]
	v_mfma_f32_16x16x32_bf16 v[88:91], v[218:221], v[166:169], v[88:91]
	v_mfma_f32_16x16x32_bf16 v[84:87], v[104:107], v[174:177], v[84:87]
	v_mfma_f32_16x16x32_bf16 v[80:83], v[218:221], v[174:177], v[80:83]
	v_mfma_f32_16x16x32_bf16 v[76:79], v[104:107], v[202:205], v[76:79]
	v_mfma_f32_16x16x32_bf16 v[72:75], v[218:221], v[202:205], v[72:75]
	v_mfma_f32_16x16x32_bf16 v[68:71], v[104:107], v[210:213], v[68:71]
	v_mfma_f32_16x16x32_bf16 v[64:67], v[218:221], v[210:213], v[64:67]
	v_mfma_f32_16x16x32_bf16 v[100:103], v[116:119], v[170:173], v[92:95]
	v_mfma_f32_16x16x32_bf16 v[96:99], v[222:225], v[170:173], v[88:91]
	v_mfma_f32_16x16x32_bf16 v[88:91], v[116:119], v[198:201], v[84:87]
	v_mfma_f32_16x16x32_bf16 v[84:87], v[222:225], v[198:201], v[80:83]
	v_mfma_f32_16x16x32_bf16 v[76:79], v[116:119], v[206:209], v[76:79]
	v_mfma_f32_16x16x32_bf16 v[72:75], v[222:225], v[206:209], v[72:75]
	v_mfma_f32_16x16x32_bf16 v[68:71], v[116:119], v[214:217], v[68:71]
	v_mfma_f32_16x16x32_bf16 v[64:67], v[222:225], v[214:217], v[64:67]
	s_barrier
	ds_read_b128 v[80:83], v156 offset:49152
	ds_read_b128 v[92:95], v156 offset:50176
	ds_read_b128 v[166:169], v151 offset:49152
	ds_read_b128 v[170:173], v151 offset:50176
	ds_read_b128 v[174:177], v150 offset:49152
	ds_read_b128 v[198:201], v150 offset:50176
	ds_read_b128 v[202:205], v149 offset:49152
	ds_read_b128 v[206:209], v149 offset:50176
	s_barrier
	s_waitcnt lgkmcnt(0)
	s_waitcnt lgkmcnt(0)
	v_mfma_f32_16x16x32_bf16 v[60:63], v[128:131], v[80:83], v[60:63]
	v_mfma_f32_16x16x32_bf16 v[56:59], v[158:161], v[80:83], v[56:59]
	v_mfma_f32_16x16x32_bf16 v[48:51], v[158:161], v[166:169], v[48:51]
	v_mfma_f32_16x16x32_bf16 v[52:55], v[128:131], v[166:169], v[52:55]
	v_mfma_f32_16x16x32_bf16 v[44:47], v[128:131], v[174:177], v[44:47]
	v_mfma_f32_16x16x32_bf16 v[40:43], v[158:161], v[174:177], v[40:43]
	v_mfma_f32_16x16x32_bf16 v[32:35], v[158:161], v[202:205], v[32:35]
	v_mfma_f32_16x16x32_bf16 v[36:39], v[128:131], v[202:205], v[36:39]
	v_mfma_f32_16x16x32_bf16 v[60:63], v[140:143], v[92:95], v[60:63]
	v_mfma_f32_16x16x32_bf16 v[56:59], v[162:165], v[92:95], v[56:59]
	v_mfma_f32_16x16x32_bf16 v[48:51], v[162:165], v[170:173], v[48:51]
	v_mfma_f32_16x16x32_bf16 v[52:55], v[140:143], v[170:173], v[52:55]
	v_mfma_f32_16x16x32_bf16 v[44:47], v[140:143], v[198:201], v[44:47]
	v_mfma_f32_16x16x32_bf16 v[40:43], v[162:165], v[198:201], v[40:43]
	v_mfma_f32_16x16x32_bf16 v[32:35], v[162:165], v[206:209], v[32:35]
	v_mfma_f32_16x16x32_bf16 v[36:39], v[140:143], v[206:209], v[36:39]
	v_mfma_f32_16x16x32_bf16 v[28:31], v[104:107], v[80:83], v[28:31]
	v_mfma_f32_16x16x32_bf16 v[24:27], v[218:221], v[80:83], v[24:27]
	v_mfma_f32_16x16x32_bf16 v[16:19], v[218:221], v[166:169], v[16:19]
	v_mfma_f32_16x16x32_bf16 v[20:23], v[104:107], v[166:169], v[20:23]
	v_mfma_f32_16x16x32_bf16 v[12:15], v[104:107], v[174:177], v[12:15]
	v_mfma_f32_16x16x32_bf16 v[8:11], v[218:221], v[174:177], v[8:11]
	v_mfma_f32_16x16x32_bf16 v[0:3], v[218:221], v[202:205], v[0:3]
	v_mfma_f32_16x16x32_bf16 v[4:7], v[104:107], v[202:205], v[4:7]
	v_mfma_f32_16x16x32_bf16 v[28:31], v[116:119], v[92:95], v[28:31]
	v_mfma_f32_16x16x32_bf16 v[24:27], v[222:225], v[92:95], v[24:27]
	v_mfma_f32_16x16x32_bf16 v[16:19], v[222:225], v[170:173], v[16:19]
	v_mfma_f32_16x16x32_bf16 v[20:23], v[116:119], v[170:173], v[20:23]
	v_mfma_f32_16x16x32_bf16 v[12:15], v[116:119], v[198:201], v[12:15]
	v_mfma_f32_16x16x32_bf16 v[8:11], v[222:225], v[198:201], v[8:11]
	v_mfma_f32_16x16x32_bf16 v[0:3], v[222:225], v[206:209], v[0:3]
	v_mfma_f32_16x16x32_bf16 v[4:7], v[116:119], v[206:209], v[4:7]
	s_movk_i32 s0, 0x100
	v_cmp_gt_u32_e32 vcc, s0, v148
	s_barrier
	s_and_saveexec_b64 s[0:1], vcc
	s_cbranch_execz .LBB0_794
	s_barrier

; #define WAIT_L(n) asm volatile("s_waitcnt lgkmcnt(" #n ")" ::: "memory")
; #define BAR __builtin_amdgcn_s_barrier()
; #define SCHED __builtin_amdgcn_sched_barrier(0)
; #define LDA(dst, b, h)                                                                            \
;   _Pragma("unroll") for (int m = 0; m < 4; ++m) _Pragma("unroll") for (int k = 0; k < 2; ++k)                                         \
;     dst[m][k] = *reinterpret_cast<const bf16x8*>((char*)SA(b, h) + lds_byte(wr * 64 + m * 16 + fr, k * 32 + fq * 8))
; #define LDB(dst, b, h)                                                                            \
;   _Pragma("unroll") for (int n = 0; n < 2; ++n) _Pragma("unroll") for (int k = 0; k < 2; ++k)                                         \
;     dst[n][k] = *reinterpret_cast<const bf16x8*>((char*)SB(b, h) + lds_byte(wc * 32 + n * 16 + fr, k * 32 + fq * 8))
; template <int K, bool SWAP>
; __device__ __forceinline__ void gemm_kloop(const bf16* __restrict__ A, const bf16* __restrict__ Bt,
;                                            f32x4 (&acc)[2][2][4][2], bool pref = false) {
;     ...
;     LDB(B0, 0, 0); SCHED; LDA(At, 0, 0); STAGE(SA(1, 1), A, HALF, t + 1);
;     WAIT_L(8); BAR; WAIT_L(0); MMA(0, 0, At, B0); BAR; SCHED;
;     LDB(B1, 0, 1); STAGE(SB(0, 0), Bt, 0, t + 2);
;     BAR; WAIT_L(0); MMA(0, 1, At, B1); BAR;
;     LDA(At, 0, 1); STAGE(SA(0, 0), A, 0, t + 2);
;     BAR; WAIT_L(0); MMA(1, 0, At, B0); BAR; SCHED;
.LBB0_797:
	ds_read_b128 v[162:165], v158
	ds_read_b128 v[166:169], v158 offset:1024
	ds_read_b128 v[170:173], v158 offset:2048
	ds_read_b128 v[174:177], v158 offset:3072
	v_add_u32_e32 v159, 0xc000, v153
	v_lshl_add_u64 v[178:179], s[6:7], 0, v[140:141]
	v_readfirstlane_b32 s5, v159
	v_lshl_add_u64 v[160:161], v[178:179], 0, s[86:87]
	s_mov_b32 m0, s5
	ds_read_b128 v[198:201], v148
	ds_read_b128 v[202:205], v148 offset:1024
	ds_read_b128 v[206:209], v147
	ds_read_b128 v[210:213], v147 offset:1024
	ds_read_b128 v[214:217], v146
	ds_read_b128 v[218:221], v146 offset:1024
	ds_read_b128 v[222:225], v145
	ds_read_b128 v[226:229], v145 offset:1024
	global_load_lds_dwordx4 v[160:161], off
	v_add_u32_e32 v160, 0xe000, v153
	v_lshl_add_u64 v[188:189], s[6:7], 0, v[142:143]
	v_readfirstlane_b32 s5, v160
	v_lshl_add_u64 v[230:231], v[188:189], 0, s[86:87]
	s_mov_b32 m0, s5
	s_nop 0
	global_load_lds_dwordx4 v[230:231], off
	s_waitcnt lgkmcnt(8)
	s_barrier
	s_waitcnt lgkmcnt(0)
	s_waitcnt lgkmcnt(0)
	v_mfma_f32_16x16x32_bf16 v[124:127], v[162:165], v[198:201], v[124:127]
	v_mfma_f32_16x16x32_bf16 v[120:123], v[170:173], v[198:201], v[120:123]
	v_mfma_f32_16x16x32_bf16 v[112:115], v[170:173], v[206:209], v[112:115]
	v_mfma_f32_16x16x32_bf16 v[116:119], v[162:165], v[206:209], v[116:119]
	v_mfma_f32_16x16x32_bf16 v[108:111], v[162:165], v[214:217], v[108:111]
	v_mfma_f32_16x16x32_bf16 v[104:107], v[170:173], v[214:217], v[104:107]
	v_mfma_f32_16x16x32_bf16 v[96:99], v[170:173], v[222:225], v[96:99]
	v_mfma_f32_16x16x32_bf16 v[100:103], v[162:165], v[222:225], v[100:103]
	v_mfma_f32_16x16x32_bf16 v[124:127], v[166:169], v[202:205], v[124:127]
	v_mfma_f32_16x16x32_bf16 v[120:123], v[174:177], v[202:205], v[120:123]
	v_mfma_f32_16x16x32_bf16 v[112:115], v[174:177], v[210:213], v[112:115]
	v_mfma_f32_16x16x32_bf16 v[116:119], v[166:169], v[210:213], v[116:119]
	v_mfma_f32_16x16x32_bf16 v[108:111], v[166:169], v[218:221], v[108:111]
	v_mfma_f32_16x16x32_bf16 v[104:107], v[174:177], v[218:221], v[104:107]
	v_mfma_f32_16x16x32_bf16 v[96:99], v[174:177], v[226:229], v[96:99]
	v_mfma_f32_16x16x32_bf16 v[100:103], v[166:169], v[226:229], v[100:103]
	s_barrier
	v_add_u32_e32 v161, s9, v150
	v_lshl_add_u64 v[246:247], s[6:7], 0, v[136:137]
	v_readfirstlane_b32 s5, v161
	v_lshl_add_u64 v[248:249], v[246:247], 0, s[88:89]
	s_mov_b32 m0, s5
	v_add_u32_e32 v161, 0x2000, v161
	ds_read_b128 v[230:233], v157
	ds_read_b128 v[234:237], v157 offset:1024
	ds_read_b128 v[238:241], v157 offset:2048
	ds_read_b128 v[242:245], v157 offset:3072
	global_load_lds_dwordx4 v[248:249], off
	v_lshl_add_u64 v[248:249], s[6:7], 0, v[138:139]
	v_readfirstlane_b32 s5, v161
	v_lshl_add_u64 v[250:251], v[248:249], 0, s[88:89]
	s_mov_b32 m0, s5
	s_nop 0
	global_load_lds_dwordx4 v[250:251], off
	s_barrier
	s_waitcnt lgkmcnt(0)
	s_waitcnt lgkmcnt(0)
	v_mfma_f32_16x16x32_bf16 v[92:95], v[230:233], v[198:201], v[92:95]
	v_mfma_f32_16x16x32_bf16 v[88:91], v[238:241], v[198:201], v[88:91]
	v_mfma_f32_16x16x32_bf16 v[80:83], v[238:241], v[206:209], v[80:83]
	v_mfma_f32_16x16x32_bf16 v[84:87], v[230:233], v[206:209], v[84:87]
	v_mfma_f32_16x16x32_bf16 v[76:79], v[230:233], v[214:217], v[76:79]
	v_mfma_f32_16x16x32_bf16 v[72:75], v[238:241], v[214:217], v[72:75]
	v_mfma_f32_16x16x32_bf16 v[64:67], v[238:241], v[222:225], v[64:67]
	v_mfma_f32_16x16x32_bf16 v[68:71], v[230:233], v[222:225], v[68:71]
	v_mfma_f32_16x16x32_bf16 v[92:95], v[234:237], v[202:205], v[92:95]
	v_mfma_f32_16x16x32_bf16 v[88:91], v[242:245], v[202:205], v[88:91]
	v_mfma_f32_16x16x32_bf16 v[80:83], v[242:245], v[210:213], v[80:83]
	v_mfma_f32_16x16x32_bf16 v[84:87], v[234:237], v[210:213], v[84:87]
	v_mfma_f32_16x16x32_bf16 v[76:79], v[234:237], v[218:221], v[76:79]
	v_mfma_f32_16x16x32_bf16 v[72:75], v[242:245], v[218:221], v[72:75]
	v_mfma_f32_16x16x32_bf16 v[64:67], v[242:245], v[226:229], v[64:67]
	v_mfma_f32_16x16x32_bf16 v[68:71], v[234:237], v[226:229], v[68:71]
	v_readfirstlane_b32 s5, v153
	v_add_u32_e32 v161, 0x2000, v153
	v_lshl_add_u64 v[250:251], v[178:179], 0, s[90:91]
	s_mov_b32 m0, s5
	v_readfirstlane_b32 s5, v161
	s_barrier
	ds_read_b128 v[198:201], v148 offset:16384
	ds_read_b128 v[202:205], v148 offset:17408
	ds_read_b128 v[206:209], v147 offset:16384
	ds_read_b128 v[210:213], v147 offset:17408
	ds_read_b128 v[214:217], v146 offset:16384
	ds_read_b128 v[218:221], v146 offset:17408
	ds_read_b128 v[222:225], v145 offset:16384
	ds_read_b128 v[226:229], v145 offset:17408
	global_load_lds_dwordx4 v[250:251], off
	v_lshl_add_u64 v[250:251], v[188:189], 0, s[90:91]
	s_mov_b32 m0, s5
	s_nop 0
	global_load_lds_dwordx4 v[250:251], off
	s_barrier
	s_waitcnt lgkmcnt(0)
	s_waitcnt lgkmcnt(0)
	v_mfma_f32_16x16x32_bf16 v[60:63], v[162:165], v[198:201], v[60:63]
	v_mfma_f32_16x16x32_bf16 v[56:59], v[170:173], v[198:201], v[56:59]
	v_mfma_f32_16x16x32_bf16 v[48:51], v[170:173], v[206:209], v[48:51]
	v_mfma_f32_16x16x32_bf16 v[52:55], v[162:165], v[206:209], v[52:55]
	v_mfma_f32_16x16x32_bf16 v[44:47], v[162:165], v[214:217], v[44:47]
	v_mfma_f32_16x16x32_bf16 v[40:43], v[170:173], v[214:217], v[40:43]
	v_mfma_f32_16x16x32_bf16 v[32:35], v[170:173], v[222:225], v[32:35]
	v_mfma_f32_16x16x32_bf16 v[36:39], v[162:165], v[222:225], v[36:39]
	v_mfma_f32_16x16x32_bf16 v[60:63], v[166:169], v[202:205], v[60:63]
	v_mfma_f32_16x16x32_bf16 v[56:59], v[174:177], v[202:205], v[56:59]
	v_mfma_f32_16x16x32_bf16 v[48:51], v[174:177], v[210:213], v[48:51]
	v_mfma_f32_16x16x32_bf16 v[52:55], v[166:169], v[210:213], v[52:55]
	v_mfma_f32_16x16x32_bf16 v[44:47], v[166:169], v[218:221], v[44:47]
	v_mfma_f32_16x16x32_bf16 v[40:43], v[174:177], v[218:221], v[40:43]
	v_mfma_f32_16x16x32_bf16 v[32:35], v[174:177], v[226:229], v[32:35]
	v_mfma_f32_16x16x32_bf16 v[36:39], v[166:169], v[226:229], v[36:39]
	s_barrier
; #define WAIT_V(n) asm volatile("s_waitcnt vmcnt(" #n ")" ::: "memory")
; #define WAIT_L(n) asm volatile("s_waitcnt lgkmcnt(" #n ")" ::: "memory")
; #define BAR __builtin_amdgcn_s_barrier()
; #define SCHED __builtin_amdgcn_sched_barrier(0)
; #define LDA(dst, b, h)                                                                            \
;   _Pragma("unroll") for (int m = 0; m < 4; ++m) _Pragma("unroll") for (int k = 0; k < 2; ++k)                                         \
;     dst[m][k] = *reinterpret_cast<const bf16x8*>((char*)SA(b, h) + lds_byte(wr * 64 + m * 16 + fr, k * 32 + fq * 8))
; #define LDB(dst, b, h)                                                                            \
;   _Pragma("unroll") for (int n = 0; n < 2; ++n) _Pragma("unroll") for (int k = 0; k < 2; ++k)                                         \
;     dst[n][k] = *reinterpret_cast<const bf16x8*>((char*)SB(b, h) + lds_byte(wc * 32 + n * 16 + fr, k * 32 + fq * 8))
; template <int K, bool SWAP>
; __device__ __forceinline__ void gemm_kloop(const bf16* __restrict__ A, const bf16* __restrict__ Bt,
;                                            f32x4 (&acc)[2][2][4][2], bool pref = false) {
;     ...
;     STAGE(SB(0, 1), Bt, HALF, t + 2);
;     WAIT_V(6); BAR; MMA(1, 1, At, B1); BAR;
;     LDB(B0, 1, 0); SCHED; LDA(At, 1, 0); STAGE(SA(0, 1), A, HALF, t + 2);
;     WAIT_L(8); BAR; WAIT_L(0); MMA(0, 0, At, B0); BAR; SCHED;
;     LDB(B1, 1, 1); STAGE(SB(1, 0), Bt, 0, t + 3);
;     BAR; WAIT_L(0); MMA(0, 1, At, B1); BAR;
;     LDA(At, 1, 1); STAGE(SA(1, 0), A, 0, t + 3);
	v_add_u32_e32 v161, s33, v150
	v_lshl_add_u64 v[162:163], v[246:247], 0, s[92:93]
	v_readfirstlane_b32 s5, v161
	v_add_u32_e32 v161, 0x2000, v161
	s_mov_b32 m0, s5
	v_readfirstlane_b32 s5, v161
	global_load_lds_dwordx4 v[162:163], off
	v_lshl_add_u64 v[162:163], v[248:249], 0, s[92:93]
	s_mov_b32 m0, s5
	s_nop 0
	global_load_lds_dwordx4 v[162:163], off
	s_waitcnt vmcnt(6)
	s_barrier
	v_mfma_f32_16x16x32_bf16 v[28:31], v[230:233], v[198:201], v[28:31]
	v_mfma_f32_16x16x32_bf16 v[24:27], v[238:241], v[198:201], v[24:27]
	v_mfma_f32_16x16x32_bf16 v[16:19], v[238:241], v[206:209], v[16:19]
	v_mfma_f32_16x16x32_bf16 v[20:23], v[230:233], v[206:209], v[20:23]
	v_mfma_f32_16x16x32_bf16 v[12:15], v[230:233], v[214:217], v[12:15]
	v_mfma_f32_16x16x32_bf16 v[8:11], v[238:241], v[214:217], v[8:11]
	v_mfma_f32_16x16x32_bf16 v[0:3], v[238:241], v[222:225], v[0:3]
	v_mfma_f32_16x16x32_bf16 v[4:7], v[230:233], v[222:225], v[4:7]
	v_mfma_f32_16x16x32_bf16 v[28:31], v[234:237], v[202:205], v[28:31]
	v_mfma_f32_16x16x32_bf16 v[24:27], v[242:245], v[202:205], v[24:27]
	v_mfma_f32_16x16x32_bf16 v[16:19], v[242:245], v[210:213], v[16:19]
	v_mfma_f32_16x16x32_bf16 v[20:23], v[234:237], v[210:213], v[20:23]
	v_mfma_f32_16x16x32_bf16 v[12:15], v[234:237], v[218:221], v[12:15]
	v_mfma_f32_16x16x32_bf16 v[8:11], v[242:245], v[218:221], v[8:11]
	v_mfma_f32_16x16x32_bf16 v[0:3], v[242:245], v[226:229], v[0:3]
	v_mfma_f32_16x16x32_bf16 v[4:7], v[234:237], v[226:229], v[4:7]
	s_barrier
	ds_read_b128 v[162:165], v151
	ds_read_b128 v[166:169], v151 offset:1024
	ds_read_b128 v[170:173], v151 offset:2048
	ds_read_b128 v[174:177], v151 offset:3072
	v_add_u32_e32 v161, 0x4000, v153
	v_lshl_add_u64 v[230:231], v[178:179], 0, s[94:95]
	v_readfirstlane_b32 s5, v161
	v_add_u32_e32 v161, 0x6000, v153
	s_mov_b32 m0, s5
	v_readfirstlane_b32 s5, v161
	ds_read_b128 v[198:201], v148 offset:32768
	ds_read_b128 v[202:205], v148 offset:33792
	ds_read_b128 v[206:209], v147 offset:32768
	ds_read_b128 v[210:213], v147 offset:33792
	ds_read_b128 v[214:217], v146 offset:32768
	ds_read_b128 v[218:221], v146 offset:33792
	ds_read_b128 v[222:225], v145 offset:32768
	ds_read_b128 v[226:229], v145 offset:33792
	global_load_lds_dwordx4 v[230:231], off
	v_lshl_add_u64 v[230:231], v[188:189], 0, s[94:95]
	s_mov_b32 m0, s5
	s_nop 0
	global_load_lds_dwordx4 v[230:231], off
	s_waitcnt lgkmcnt(8)
	s_barrier
	s_waitcnt lgkmcnt(0)
	s_waitcnt lgkmcnt(0)
	v_mfma_f32_16x16x32_bf16 v[124:127], v[162:165], v[198:201], v[124:127]
	v_mfma_f32_16x16x32_bf16 v[120:123], v[170:173], v[198:201], v[120:123]
	v_mfma_f32_16x16x32_bf16 v[112:115], v[170:173], v[206:209], v[112:115]
	v_mfma_f32_16x16x32_bf16 v[116:119], v[162:165], v[206:209], v[116:119]
	v_mfma_f32_16x16x32_bf16 v[108:111], v[162:165], v[214:217], v[108:111]
	v_mfma_f32_16x16x32_bf16 v[104:107], v[170:173], v[214:217], v[104:107]
	v_mfma_f32_16x16x32_bf16 v[96:99], v[170:173], v[222:225], v[96:99]
	v_mfma_f32_16x16x32_bf16 v[100:103], v[162:165], v[222:225], v[100:103]
	v_mfma_f32_16x16x32_bf16 v[124:127], v[166:169], v[202:205], v[124:127]
	v_mfma_f32_16x16x32_bf16 v[120:123], v[174:177], v[202:205], v[120:123]
	v_mfma_f32_16x16x32_bf16 v[112:115], v[174:177], v[210:213], v[112:115]
	v_mfma_f32_16x16x32_bf16 v[116:119], v[166:169], v[210:213], v[116:119]
	v_mfma_f32_16x16x32_bf16 v[108:111], v[166:169], v[218:221], v[108:111]
	v_mfma_f32_16x16x32_bf16 v[104:107], v[174:177], v[218:221], v[104:107]
	v_mfma_f32_16x16x32_bf16 v[96:99], v[174:177], v[226:229], v[96:99]
	v_mfma_f32_16x16x32_bf16 v[100:103], v[166:169], v[226:229], v[100:103]
	s_barrier
	v_readfirstlane_b32 s5, v152
	v_add_u32_e32 v161, 0x2000, v152
	v_lshl_add_u64 v[250:251], v[246:247], 0, s[96:97]
	s_mov_b32 m0, s5
	v_readfirstlane_b32 s5, v161
	ds_read_b128 v[230:233], v149
	ds_read_b128 v[234:237], v149 offset:1024
	ds_read_b128 v[238:241], v149 offset:2048
	ds_read_b128 v[242:245], v149 offset:3072
	global_load_lds_dwordx4 v[250:251], off
	v_lshl_add_u64 v[250:251], v[248:249], 0, s[96:97]
	s_mov_b32 m0, s5
	s_nop 0
	global_load_lds_dwordx4 v[250:251], off
	s_barrier
	s_waitcnt lgkmcnt(0)
	s_waitcnt lgkmcnt(0)
	v_mfma_f32_16x16x32_bf16 v[92:95], v[230:233], v[198:201], v[92:95]
	v_mfma_f32_16x16x32_bf16 v[88:91], v[238:241], v[198:201], v[88:91]
	v_mfma_f32_16x16x32_bf16 v[80:83], v[238:241], v[206:209], v[80:83]
	v_mfma_f32_16x16x32_bf16 v[84:87], v[230:233], v[206:209], v[84:87]
	v_mfma_f32_16x16x32_bf16 v[76:79], v[230:233], v[214:217], v[76:79]
	v_mfma_f32_16x16x32_bf16 v[72:75], v[238:241], v[214:217], v[72:75]
	v_mfma_f32_16x16x32_bf16 v[64:67], v[238:241], v[222:225], v[64:67]
	v_mfma_f32_16x16x32_bf16 v[68:71], v[230:233], v[222:225], v[68:71]
	v_mfma_f32_16x16x32_bf16 v[92:95], v[234:237], v[202:205], v[92:95]
	v_mfma_f32_16x16x32_bf16 v[88:91], v[242:245], v[202:205], v[88:91]
	v_mfma_f32_16x16x32_bf16 v[80:83], v[242:245], v[210:213], v[80:83]
	v_mfma_f32_16x16x32_bf16 v[84:87], v[234:237], v[210:213], v[84:87]
	v_mfma_f32_16x16x32_bf16 v[76:79], v[234:237], v[218:221], v[76:79]
	v_mfma_f32_16x16x32_bf16 v[72:75], v[242:245], v[218:221], v[72:75]
	v_mfma_f32_16x16x32_bf16 v[64:67], v[242:245], v[226:229], v[64:67]
	v_mfma_f32_16x16x32_bf16 v[68:71], v[234:237], v[226:229], v[68:71]
	v_readfirstlane_b32 s5, v154
	v_lshl_add_u64 v[178:179], v[178:179], 0, s[34:35]
	s_mov_b32 m0, s5
	v_readfirstlane_b32 s5, v155
	s_barrier
; #define WAIT_V(n) asm volatile("s_waitcnt vmcnt(" #n ")" ::: "memory")
; #define WAIT_L(n) asm volatile("s_waitcnt lgkmcnt(" #n ")" ::: "memory")
; #define BAR __builtin_amdgcn_s_barrier()
; #define SCHED __builtin_amdgcn_sched_barrier(0)
; #define LDA(dst, b, h)                                                                            \
;   _Pragma("unroll") for (int m = 0; m < 4; ++m) _Pragma("unroll") for (int k = 0; k < 2; ++k)                                         \
;     dst[m][k] = *reinterpret_cast<const bf16x8*>((char*)SA(b, h) + lds_byte(wr * 64 + m * 16 + fr, k * 32 + fq * 8))
; #define LDB(dst, b, h)                                                                            \
;   _Pragma("unroll") for (int n = 0; n < 2; ++n) _Pragma("unroll") for (int k = 0; k < 2; ++k)                                         \
;     dst[n][k] = *reinterpret_cast<const bf16x8*>((char*)SB(b, h) + lds_byte(wc * 32 + n * 16 + fr, k * 32 + fq * 8))
; template <int K, bool SWAP>
; __device__ __forceinline__ void gemm_kloop(const bf16* __restrict__ A, const bf16* __restrict__ Bt,
;                                            f32x4 (&acc)[2][2][4][2], bool pref = false) {
;     ...
;     LDA(At, 1, 1); STAGE(SA(1, 0), A, 0, t + 3);
;     BAR; WAIT_L(0); MMA(1, 0, At, B0); BAR; SCHED;
;     STAGE(SB(1, 1), Bt, HALF, t + 3);
;     WAIT_V(6); BAR; MMA(1, 1, At, B1); BAR;
;   }
;   { LDB(B0, 0, 0); LDA(At, 0, 0); STAGE(SA(1, 1), A, HALF, nt - 1);
;     BAR; WAIT_L(0); MMA(0, 0, At, B0); BAR;
;     LDB(B1, 0, 1); BAR; WAIT_L(0); MMA(0, 1, At, B1); BAR;
	ds_read_b128 v[198:201], v148 offset:49152
	ds_read_b128 v[202:205], v148 offset:50176
	ds_read_b128 v[206:209], v147 offset:49152
	ds_read_b128 v[210:213], v147 offset:50176
	ds_read_b128 v[214:217], v146 offset:49152
	ds_read_b128 v[218:221], v146 offset:50176
	ds_read_b128 v[222:225], v145 offset:49152
	ds_read_b128 v[226:229], v145 offset:50176
	global_load_lds_dwordx4 v[178:179], off
	v_lshl_add_u64 v[178:179], v[188:189], 0, s[34:35]
	s_mov_b32 m0, s5
	s_nop 0
	global_load_lds_dwordx4 v[178:179], off
	s_barrier
	s_waitcnt lgkmcnt(0)
	s_waitcnt lgkmcnt(0)
	v_mfma_f32_16x16x32_bf16 v[60:63], v[162:165], v[198:201], v[60:63]
	v_mfma_f32_16x16x32_bf16 v[56:59], v[170:173], v[198:201], v[56:59]
	v_mfma_f32_16x16x32_bf16 v[48:51], v[170:173], v[206:209], v[48:51]
	v_mfma_f32_16x16x32_bf16 v[52:55], v[162:165], v[206:209], v[52:55]
	v_mfma_f32_16x16x32_bf16 v[44:47], v[162:165], v[214:217], v[44:47]
	v_mfma_f32_16x16x32_bf16 v[40:43], v[170:173], v[214:217], v[40:43]
	v_mfma_f32_16x16x32_bf16 v[32:35], v[170:173], v[222:225], v[32:35]
	v_mfma_f32_16x16x32_bf16 v[36:39], v[162:165], v[222:225], v[36:39]
	v_mfma_f32_16x16x32_bf16 v[60:63], v[166:169], v[202:205], v[60:63]
	v_mfma_f32_16x16x32_bf16 v[56:59], v[174:177], v[202:205], v[56:59]
	v_mfma_f32_16x16x32_bf16 v[48:51], v[174:177], v[210:213], v[48:51]
	v_mfma_f32_16x16x32_bf16 v[52:55], v[166:169], v[210:213], v[52:55]
	v_mfma_f32_16x16x32_bf16 v[44:47], v[166:169], v[218:221], v[44:47]
	v_mfma_f32_16x16x32_bf16 v[40:43], v[174:177], v[218:221], v[40:43]
	v_mfma_f32_16x16x32_bf16 v[32:35], v[174:177], v[226:229], v[32:35]
	v_mfma_f32_16x16x32_bf16 v[36:39], v[166:169], v[226:229], v[36:39]
	s_barrier
	v_readfirstlane_b32 s5, v156
	v_add_u32_e32 v161, 0x2000, v156
	v_lshl_add_u64 v[162:163], v[246:247], 0, s[36:37]
	s_mov_b32 m0, s5
	v_readfirstlane_b32 s5, v161
	global_load_lds_dwordx4 v[162:163], off
	v_lshl_add_u64 v[162:163], v[248:249], 0, s[36:37]
	s_mov_b32 m0, s5
	s_nop 0
	global_load_lds_dwordx4 v[162:163], off
	s_waitcnt vmcnt(6)
	s_barrier
	v_mfma_f32_16x16x32_bf16 v[28:31], v[230:233], v[198:201], v[28:31]
	v_mfma_f32_16x16x32_bf16 v[24:27], v[238:241], v[198:201], v[24:27]
	v_mfma_f32_16x16x32_bf16 v[16:19], v[238:241], v[206:209], v[16:19]
	v_mfma_f32_16x16x32_bf16 v[20:23], v[230:233], v[206:209], v[20:23]
	v_mfma_f32_16x16x32_bf16 v[12:15], v[230:233], v[214:217], v[12:15]
	v_mfma_f32_16x16x32_bf16 v[8:11], v[238:241], v[214:217], v[8:11]
	v_mfma_f32_16x16x32_bf16 v[0:3], v[238:241], v[222:225], v[0:3]
	v_mfma_f32_16x16x32_bf16 v[4:7], v[230:233], v[222:225], v[4:7]
	v_mfma_f32_16x16x32_bf16 v[28:31], v[234:237], v[202:205], v[28:31]
	v_mfma_f32_16x16x32_bf16 v[24:27], v[242:245], v[202:205], v[24:27]
	v_mfma_f32_16x16x32_bf16 v[16:19], v[242:245], v[210:213], v[16:19]
	v_mfma_f32_16x16x32_bf16 v[20:23], v[234:237], v[210:213], v[20:23]
	v_mfma_f32_16x16x32_bf16 v[12:15], v[234:237], v[218:221], v[12:15]
	v_mfma_f32_16x16x32_bf16 v[8:11], v[242:245], v[218:221], v[8:11]
	v_mfma_f32_16x16x32_bf16 v[0:3], v[242:245], v[226:229], v[0:3]
	v_mfma_f32_16x16x32_bf16 v[4:7], v[234:237], v[226:229], v[4:7]
	s_add_i32 s1, s1, 2
	v_lshl_add_u64 v[136:137], v[136:137], 0, s[44:45]
	v_lshl_add_u64 v[138:139], v[138:139], 0, s[44:45]
	v_lshl_add_u64 v[140:141], v[140:141], 0, s[44:45]
	s_cmp_lt_u32 s1, 12
	v_lshl_add_u64 v[142:143], v[142:143], 0, s[44:45]
	s_barrier
	s_cbranch_scc1 .LBB0_797
	s_add_u32 s14, s14, 0x40780
	s_addc_u32 s15, s15, 0
	v_lshl_add_u64 v[130:131], s[14:15], 0, v[130:131]
	v_readfirstlane_b32 s1, v159
	v_lshl_add_u64 v[128:129], v[128:129], 1, v[130:131]
	s_mov_b32 m0, s1
	ds_read_b128 v[136:139], v158
	ds_read_b128 v[140:143], v158 offset:1024
	ds_read_b128 v[152:155], v158 offset:2048
	ds_read_b128 v[162:165], v158 offset:3072
	ds_read_b128 v[166:169], v148
	ds_read_b128 v[170:173], v148 offset:1024
	ds_read_b128 v[174:177], v147
	ds_read_b128 v[198:201], v147 offset:1024
	ds_read_b128 v[202:205], v146
	ds_read_b128 v[206:209], v146 offset:1024
	ds_read_b128 v[210:213], v145
	ds_read_b128 v[214:217], v145 offset:1024
	global_load_lds_dwordx4 v[128:129], off
	v_lshl_add_u64 v[128:129], s[14:15], 0, v[134:135]
	v_readfirstlane_b32 s1, v160
	v_lshl_add_u64 v[128:129], v[132:133], 1, v[128:129]
	s_mov_b32 m0, s1
	s_nop 0
	global_load_lds_dwordx4 v[128:129], off
	s_barrier
	s_waitcnt lgkmcnt(0)
	s_waitcnt lgkmcnt(0)
	v_mfma_f32_16x16x32_bf16 v[116:119], v[136:139], v[174:177], v[116:119]
	v_mfma_f32_16x16x32_bf16 v[112:115], v[152:155], v[174:177], v[112:115]
	v_mfma_f32_16x16x32_bf16 v[104:107], v[152:155], v[202:205], v[104:107]
	v_mfma_f32_16x16x32_bf16 v[108:111], v[136:139], v[202:205], v[108:111]
	v_mfma_f32_16x16x32_bf16 v[100:103], v[136:139], v[210:213], v[100:103]
	v_mfma_f32_16x16x32_bf16 v[96:99], v[152:155], v[210:213], v[96:99]
	v_mfma_f32_16x16x32_bf16 v[120:123], v[152:155], v[166:169], v[120:123]
	v_mfma_f32_16x16x32_bf16 v[124:127], v[136:139], v[166:169], v[124:127]
	v_mfma_f32_16x16x32_bf16 v[116:119], v[140:143], v[198:201], v[116:119]
	v_mfma_f32_16x16x32_bf16 v[112:115], v[162:165], v[198:201], v[112:115]
	v_mfma_f32_16x16x32_bf16 v[104:107], v[162:165], v[206:209], v[104:107]
	v_mfma_f32_16x16x32_bf16 v[108:111], v[140:143], v[206:209], v[108:111]
	v_mfma_f32_16x16x32_bf16 v[100:103], v[140:143], v[214:217], v[100:103]
	v_mfma_f32_16x16x32_bf16 v[96:99], v[162:165], v[214:217], v[96:99]
	v_mfma_f32_16x16x32_bf16 v[120:123], v[162:165], v[170:173], v[120:123]
	v_mfma_f32_16x16x32_bf16 v[124:127], v[140:143], v[170:173], v[124:127]
	s_barrier
	ds_read_b128 v[128:131], v157
	ds_read_b128 v[132:135], v157 offset:1024
	ds_read_b128 v[158:161], v157 offset:2048
	ds_read_b128 v[218:221], v157 offset:3072
	s_barrier
; #define WAIT_V(n) asm volatile("s_waitcnt vmcnt(" #n ")" ::: "memory")
; #define WAIT_L(n) asm volatile("s_waitcnt lgkmcnt(" #n ")" ::: "memory")
; #define BAR __builtin_amdgcn_s_barrier()
; #define LDA(dst, b, h)                                                                            \
;   _Pragma("unroll") for (int m = 0; m < 4; ++m) _Pragma("unroll") for (int k = 0; k < 2; ++k)                                         \
;     dst[m][k] = *reinterpret_cast<const bf16x8*>((char*)SA(b, h) + lds_byte(wr * 64 + m * 16 + fr, k * 32 + fq * 8))
; #define LDB(dst, b, h)                                                                            \
;   _Pragma("unroll") for (int n = 0; n < 2; ++n) _Pragma("unroll") for (int k = 0; k < 2; ++k)                                         \
;     dst[n][k] = *reinterpret_cast<const bf16x8*>((char*)SB(b, h) + lds_byte(wc * 32 + n * 16 + fr, k * 32 + fq * 8))
; template <int K, bool SWAP>
; __device__ __forceinline__ void gemm_kloop(const bf16* __restrict__ A, const bf16* __restrict__ Bt,
;                                            f32x4 (&acc)[2][2][4][2], bool pref = false) {
;     ...
;     LDB(B1, 0, 1); BAR; WAIT_L(0); MMA(0, 1, At, B1); BAR;
;     LDA(At, 0, 1); WAIT_V(4); BAR; WAIT_L(0); MMA(1, 0, At, B0); MMA(1, 1, At, B1); BAR; }
;   { LDB(B0, 1, 0); LDA(At, 1, 0); WAIT_V(2); BAR; WAIT_L(0); MMA(0, 0, At, B0); BAR;
	s_waitcnt lgkmcnt(0)
	s_waitcnt lgkmcnt(0)
	v_mfma_f32_16x16x32_bf16 v[92:95], v[128:131], v[166:169], v[92:95]
	v_mfma_f32_16x16x32_bf16 v[88:91], v[158:161], v[166:169], v[88:91]
	v_mfma_f32_16x16x32_bf16 v[80:83], v[158:161], v[174:177], v[80:83]
	v_mfma_f32_16x16x32_bf16 v[84:87], v[128:131], v[174:177], v[84:87]
	v_mfma_f32_16x16x32_bf16 v[76:79], v[128:131], v[202:205], v[76:79]
	v_mfma_f32_16x16x32_bf16 v[72:75], v[158:161], v[202:205], v[72:75]
	v_mfma_f32_16x16x32_bf16 v[64:67], v[158:161], v[210:213], v[64:67]
	v_mfma_f32_16x16x32_bf16 v[68:71], v[128:131], v[210:213], v[68:71]
	v_mfma_f32_16x16x32_bf16 v[92:95], v[132:135], v[170:173], v[92:95]
	v_mfma_f32_16x16x32_bf16 v[88:91], v[218:221], v[170:173], v[88:91]
	v_mfma_f32_16x16x32_bf16 v[80:83], v[218:221], v[198:201], v[80:83]
	v_mfma_f32_16x16x32_bf16 v[84:87], v[132:135], v[198:201], v[84:87]
	v_mfma_f32_16x16x32_bf16 v[76:79], v[132:135], v[206:209], v[76:79]
	v_mfma_f32_16x16x32_bf16 v[72:75], v[218:221], v[206:209], v[72:75]
	v_mfma_f32_16x16x32_bf16 v[64:67], v[218:221], v[214:217], v[64:67]
	v_mfma_f32_16x16x32_bf16 v[68:71], v[132:135], v[214:217], v[68:71]
	s_barrier
	ds_read_b128 v[166:169], v148 offset:16384
	ds_read_b128 v[170:173], v148 offset:17408
	ds_read_b128 v[174:177], v147 offset:16384
	ds_read_b128 v[198:201], v147 offset:17408
	ds_read_b128 v[202:205], v146 offset:16384
	ds_read_b128 v[206:209], v146 offset:17408
	ds_read_b128 v[210:213], v145 offset:16384
	ds_read_b128 v[214:217], v145 offset:17408
	s_waitcnt vmcnt(4)
	s_barrier
	s_waitcnt lgkmcnt(0)
	s_waitcnt lgkmcnt(0)
	v_mfma_f32_16x16x32_bf16 v[60:63], v[136:139], v[166:169], v[60:63]
	v_mfma_f32_16x16x32_bf16 v[56:59], v[152:155], v[166:169], v[56:59]
	v_mfma_f32_16x16x32_bf16 v[48:51], v[152:155], v[174:177], v[48:51]
	v_mfma_f32_16x16x32_bf16 v[52:55], v[136:139], v[174:177], v[52:55]
	v_mfma_f32_16x16x32_bf16 v[44:47], v[136:139], v[202:205], v[44:47]
	v_mfma_f32_16x16x32_bf16 v[40:43], v[152:155], v[202:205], v[40:43]
	v_mfma_f32_16x16x32_bf16 v[32:35], v[152:155], v[210:213], v[32:35]
	v_mfma_f32_16x16x32_bf16 v[36:39], v[136:139], v[210:213], v[36:39]
	v_mfma_f32_16x16x32_bf16 v[60:63], v[140:143], v[170:173], v[60:63]
	v_mfma_f32_16x16x32_bf16 v[56:59], v[162:165], v[170:173], v[56:59]
	v_mfma_f32_16x16x32_bf16 v[48:51], v[162:165], v[198:201], v[48:51]
	v_mfma_f32_16x16x32_bf16 v[52:55], v[140:143], v[198:201], v[52:55]
	v_mfma_f32_16x16x32_bf16 v[44:47], v[140:143], v[206:209], v[44:47]
	v_mfma_f32_16x16x32_bf16 v[40:43], v[162:165], v[206:209], v[40:43]
	v_mfma_f32_16x16x32_bf16 v[32:35], v[162:165], v[214:217], v[32:35]
	v_mfma_f32_16x16x32_bf16 v[36:39], v[140:143], v[214:217], v[36:39]
	v_mfma_f32_16x16x32_bf16 v[28:31], v[128:131], v[166:169], v[28:31]
	v_mfma_f32_16x16x32_bf16 v[24:27], v[158:161], v[166:169], v[24:27]
	v_mfma_f32_16x16x32_bf16 v[16:19], v[158:161], v[174:177], v[16:19]
	v_mfma_f32_16x16x32_bf16 v[20:23], v[128:131], v[174:177], v[20:23]
	v_mfma_f32_16x16x32_bf16 v[12:15], v[128:131], v[202:205], v[12:15]
	v_mfma_f32_16x16x32_bf16 v[8:11], v[158:161], v[202:205], v[8:11]
	v_mfma_f32_16x16x32_bf16 v[0:3], v[158:161], v[210:213], v[0:3]
	v_mfma_f32_16x16x32_bf16 v[4:7], v[128:131], v[210:213], v[4:7]
	v_mfma_f32_16x16x32_bf16 v[28:31], v[132:135], v[170:173], v[28:31]
	v_mfma_f32_16x16x32_bf16 v[24:27], v[218:221], v[170:173], v[24:27]
	v_mfma_f32_16x16x32_bf16 v[16:19], v[218:221], v[198:201], v[16:19]
	v_mfma_f32_16x16x32_bf16 v[20:23], v[132:135], v[198:201], v[20:23]
	v_mfma_f32_16x16x32_bf16 v[12:15], v[132:135], v[206:209], v[12:15]
	v_mfma_f32_16x16x32_bf16 v[8:11], v[218:221], v[206:209], v[8:11]
	v_mfma_f32_16x16x32_bf16 v[0:3], v[218:221], v[214:217], v[0:3]
	v_mfma_f32_16x16x32_bf16 v[4:7], v[132:135], v[214:217], v[4:7]
	s_barrier
	ds_read_b128 v[136:139], v151
	ds_read_b128 v[140:143], v151 offset:1024
	ds_read_b128 v[152:155], v151 offset:2048
	ds_read_b128 v[156:159], v151 offset:3072
	ds_read_b128 v[160:163], v148 offset:32768
	ds_read_b128 v[164:167], v148 offset:33792
	ds_read_b128 v[168:171], v147 offset:32768
	ds_read_b128 v[172:175], v147 offset:33792
	ds_read_b128 v[176:179], v146 offset:32768
	ds_read_b128 v[198:201], v146 offset:33792
	ds_read_b128 v[202:205], v145 offset:32768
	ds_read_b128 v[206:209], v145 offset:33792
	s_waitcnt vmcnt(2)
	s_barrier
; #define WAIT_V(n) asm volatile("s_waitcnt vmcnt(" #n ")" ::: "memory")
; #define WAIT_L(n) asm volatile("s_waitcnt lgkmcnt(" #n ")" ::: "memory")
; #define BAR __builtin_amdgcn_s_barrier()
; #define LDA(dst, b, h)                                                                            \
;   _Pragma("unroll") for (int m = 0; m < 4; ++m) _Pragma("unroll") for (int k = 0; k < 2; ++k)                                         \
;     dst[m][k] = *reinterpret_cast<const bf16x8*>((char*)SA(b, h) + lds_byte(wr * 64 + m * 16 + fr, k * 32 + fq * 8))
; #define LDB(dst, b, h)                                                                            \
;   _Pragma("unroll") for (int n = 0; n < 2; ++n) _Pragma("unroll") for (int k = 0; k < 2; ++k)                                         \
;     dst[n][k] = *reinterpret_cast<const bf16x8*>((char*)SB(b, h) + lds_byte(wc * 32 + n * 16 + fr, k * 32 + fq * 8))
; template <int K, bool SWAP>
; __device__ __forceinline__ void gemm_kloop(const bf16* __restrict__ A, const bf16* __restrict__ Bt,
;                                            f32x4 (&acc)[2][2][4][2], bool pref = false) {
;     ...
;   { LDB(B0, 1, 0); LDA(At, 1, 0); WAIT_V(2); BAR; WAIT_L(0); MMA(0, 0, At, B0); BAR;
;     LDB(B1, 1, 1); WAIT_V(0); BAR; WAIT_L(0); MMA(0, 1, At, B1); BAR;
;     LDA(At, 1, 1); BAR; WAIT_L(0); MMA(1, 0, At, B0); MMA(1, 1, At, B1); BAR; }
;   if (wr == 0) BAR;
	s_waitcnt lgkmcnt(0)
	s_waitcnt lgkmcnt(0)
	v_mfma_f32_16x16x32_bf16 v[124:127], v[136:139], v[160:163], v[124:127]
	v_mfma_f32_16x16x32_bf16 v[120:123], v[152:155], v[160:163], v[120:123]
	v_mfma_f32_16x16x32_bf16 v[116:119], v[136:139], v[168:171], v[116:119]
	v_mfma_f32_16x16x32_bf16 v[112:115], v[152:155], v[168:171], v[112:115]
	v_mfma_f32_16x16x32_bf16 v[108:111], v[136:139], v[176:179], v[108:111]
	v_mfma_f32_16x16x32_bf16 v[104:107], v[152:155], v[176:179], v[104:107]
	v_mfma_f32_16x16x32_bf16 v[100:103], v[136:139], v[202:205], v[100:103]
	v_mfma_f32_16x16x32_bf16 v[96:99], v[152:155], v[202:205], v[96:99]
	v_mfma_f32_16x16x32_bf16 v[132:135], v[140:143], v[164:167], v[124:127]
	v_mfma_f32_16x16x32_bf16 v[128:131], v[156:159], v[164:167], v[120:123]
	v_mfma_f32_16x16x32_bf16 v[116:119], v[140:143], v[172:175], v[116:119]
	v_mfma_f32_16x16x32_bf16 v[112:115], v[156:159], v[172:175], v[112:115]
	v_mfma_f32_16x16x32_bf16 v[108:111], v[140:143], v[198:201], v[108:111]
	v_mfma_f32_16x16x32_bf16 v[104:107], v[156:159], v[198:201], v[104:107]
	v_mfma_f32_16x16x32_bf16 v[100:103], v[140:143], v[206:209], v[100:103]
	v_mfma_f32_16x16x32_bf16 v[96:99], v[156:159], v[206:209], v[96:99]
	s_barrier
	ds_read_b128 v[120:123], v149
	ds_read_b128 v[124:127], v149 offset:1024
	ds_read_b128 v[210:213], v149 offset:2048
	ds_read_b128 v[214:217], v149 offset:3072
	s_waitcnt vmcnt(0)
	s_barrier
	s_waitcnt lgkmcnt(0)
	s_waitcnt lgkmcnt(0)
	v_mfma_f32_16x16x32_bf16 v[92:95], v[120:123], v[160:163], v[92:95]
	v_mfma_f32_16x16x32_bf16 v[88:91], v[210:213], v[160:163], v[88:91]
	v_mfma_f32_16x16x32_bf16 v[80:83], v[210:213], v[168:171], v[80:83]
	v_mfma_f32_16x16x32_bf16 v[84:87], v[120:123], v[168:171], v[84:87]
	v_mfma_f32_16x16x32_bf16 v[76:79], v[120:123], v[176:179], v[76:79]
	v_mfma_f32_16x16x32_bf16 v[72:75], v[210:213], v[176:179], v[72:75]
	v_mfma_f32_16x16x32_bf16 v[64:67], v[210:213], v[202:205], v[64:67]
	v_mfma_f32_16x16x32_bf16 v[68:71], v[120:123], v[202:205], v[68:71]
	v_mfma_f32_16x16x32_bf16 v[92:95], v[124:127], v[164:167], v[92:95]
	v_mfma_f32_16x16x32_bf16 v[88:91], v[214:217], v[164:167], v[88:91]
	v_mfma_f32_16x16x32_bf16 v[80:83], v[214:217], v[172:175], v[80:83]
	v_mfma_f32_16x16x32_bf16 v[84:87], v[124:127], v[172:175], v[84:87]
	v_mfma_f32_16x16x32_bf16 v[76:79], v[124:127], v[198:201], v[76:79]
	v_mfma_f32_16x16x32_bf16 v[72:75], v[214:217], v[198:201], v[72:75]
	v_mfma_f32_16x16x32_bf16 v[64:67], v[214:217], v[206:209], v[64:67]
	v_mfma_f32_16x16x32_bf16 v[68:71], v[124:127], v[206:209], v[68:71]
	s_barrier
	ds_read_b128 v[160:163], v148 offset:49152
	ds_read_b128 v[148:151], v148 offset:50176
	ds_read_b128 v[164:167], v147 offset:49152
	ds_read_b128 v[168:171], v147 offset:50176
	ds_read_b128 v[172:175], v146 offset:49152
	ds_read_b128 v[176:179], v146 offset:50176
	ds_read_b128 v[198:201], v145 offset:49152
	ds_read_b128 v[202:205], v145 offset:50176
	s_barrier
	s_waitcnt lgkmcnt(0)
	s_waitcnt lgkmcnt(0)
	v_mfma_f32_16x16x32_bf16 v[60:63], v[136:139], v[160:163], v[60:63]
	v_mfma_f32_16x16x32_bf16 v[56:59], v[152:155], v[160:163], v[56:59]
	v_mfma_f32_16x16x32_bf16 v[48:51], v[152:155], v[164:167], v[48:51]
	v_mfma_f32_16x16x32_bf16 v[52:55], v[136:139], v[164:167], v[52:55]
	v_mfma_f32_16x16x32_bf16 v[44:47], v[136:139], v[172:175], v[44:47]
	v_mfma_f32_16x16x32_bf16 v[40:43], v[152:155], v[172:175], v[40:43]
	v_mfma_f32_16x16x32_bf16 v[32:35], v[152:155], v[198:201], v[32:35]
	v_mfma_f32_16x16x32_bf16 v[36:39], v[136:139], v[198:201], v[36:39]
	v_mfma_f32_16x16x32_bf16 v[60:63], v[140:143], v[148:151], v[60:63]
	v_mfma_f32_16x16x32_bf16 v[56:59], v[156:159], v[148:151], v[56:59]
	v_mfma_f32_16x16x32_bf16 v[48:51], v[156:159], v[168:171], v[48:51]
	v_mfma_f32_16x16x32_bf16 v[52:55], v[140:143], v[168:171], v[52:55]
	v_mfma_f32_16x16x32_bf16 v[44:47], v[140:143], v[176:179], v[44:47]
	v_mfma_f32_16x16x32_bf16 v[40:43], v[156:159], v[176:179], v[40:43]
	v_mfma_f32_16x16x32_bf16 v[32:35], v[156:159], v[202:205], v[32:35]
	v_mfma_f32_16x16x32_bf16 v[36:39], v[140:143], v[202:205], v[36:39]
	v_mfma_f32_16x16x32_bf16 v[28:31], v[120:123], v[160:163], v[28:31]
	v_mfma_f32_16x16x32_bf16 v[24:27], v[210:213], v[160:163], v[24:27]
	v_mfma_f32_16x16x32_bf16 v[16:19], v[210:213], v[164:167], v[16:19]
	v_mfma_f32_16x16x32_bf16 v[20:23], v[120:123], v[164:167], v[20:23]
	v_mfma_f32_16x16x32_bf16 v[12:15], v[120:123], v[172:175], v[12:15]
	v_mfma_f32_16x16x32_bf16 v[8:11], v[210:213], v[172:175], v[8:11]
	v_mfma_f32_16x16x32_bf16 v[0:3], v[210:213], v[198:201], v[0:3]
	v_mfma_f32_16x16x32_bf16 v[4:7], v[120:123], v[198:201], v[4:7]
	v_mfma_f32_16x16x32_bf16 v[28:31], v[124:127], v[148:151], v[28:31]
	v_mfma_f32_16x16x32_bf16 v[24:27], v[214:217], v[148:151], v[24:27]
	v_mfma_f32_16x16x32_bf16 v[16:19], v[214:217], v[168:171], v[16:19]
	v_mfma_f32_16x16x32_bf16 v[20:23], v[124:127], v[168:171], v[20:23]
	v_mfma_f32_16x16x32_bf16 v[12:15], v[124:127], v[176:179], v[12:15]
	v_mfma_f32_16x16x32_bf16 v[8:11], v[214:217], v[176:179], v[8:11]
	v_mfma_f32_16x16x32_bf16 v[0:3], v[214:217], v[202:205], v[0:3]
	v_mfma_f32_16x16x32_bf16 v[4:7], v[124:127], v[202:205], v[4:7]
	s_movk_i32 s1, 0x100
	v_cmp_gt_u32_e32 vcc, s1, v144
	s_barrier
	s_and_saveexec_b64 s[14:15], vcc
	s_mov_b32 s62, s68
	s_mov_b32 s63, s69
	s_cbranch_execz .LBB0_800
	s_barrier

; #define WAIT_L(n) asm volatile("s_waitcnt lgkmcnt(" #n ")" ::: "memory")
; #define BAR __builtin_amdgcn_s_barrier()
; #define SCHED __builtin_amdgcn_sched_barrier(0)
; #define LDA(dst, b, h)                                                                            \
;   _Pragma("unroll") for (int m = 0; m < 4; ++m) _Pragma("unroll") for (int k = 0; k < 2; ++k)                                         \
;     dst[m][k] = *reinterpret_cast<const bf16x8*>((char*)SA(b, h) + lds_byte(wr * 64 + m * 16 + fr, k * 32 + fq * 8))
; #define LDB(dst, b, h)                                                                            \
;   _Pragma("unroll") for (int n = 0; n < 2; ++n) _Pragma("unroll") for (int k = 0; k < 2; ++k)                                         \
;     dst[n][k] = *reinterpret_cast<const bf16x8*>((char*)SB(b, h) + lds_byte(wc * 32 + n * 16 + fr, k * 32 + fq * 8))
; template <int K, bool SWAP>
; __device__ __forceinline__ void gemm_kloop(const bf16* __restrict__ A, const bf16* __restrict__ Bt,
;                                            f32x4 (&acc)[2][2][4][2], bool pref = false) {
;     ...
;     LDB(B0, 0, 0); SCHED; LDA(At, 0, 0); STAGE(SA(1, 1), A, HALF, t + 1);
;     WAIT_L(8); BAR; WAIT_L(0); MMA(0, 0, At, B0); BAR; SCHED;
;     LDB(B1, 0, 1); STAGE(SB(0, 0), Bt, 0, t + 2);
;     BAR; WAIT_L(0); MMA(0, 1, At, B1); BAR;
;     LDA(At, 0, 1); STAGE(SA(0, 0), A, 0, t + 2);
;     BAR; WAIT_L(0); MMA(1, 0, At, B0); BAR; SCHED;
.LBB0_844:
	ds_read_b128 v[162:165], v159
	ds_read_b128 v[166:169], v159 offset:1024
	ds_read_b128 v[170:173], v159 offset:2048
	ds_read_b128 v[174:177], v159 offset:3072
	v_add_u32_e32 v160, 0xc000, v146
	v_lshl_add_u64 v[178:179], s[6:7], 0, v[140:141]
	v_readfirstlane_b32 s14, v160
	v_lshl_add_u64 v[188:189], v[178:179], 0, s[38:39]
	s_mov_b32 m0, s14
	v_add_u32_e32 v161, 0xe000, v146
	ds_read_b128 v[198:201], v151
	ds_read_b128 v[202:205], v151 offset:1024
	ds_read_b128 v[206:209], v150
	ds_read_b128 v[210:213], v150 offset:1024
	ds_read_b128 v[214:217], v149
	ds_read_b128 v[218:221], v149 offset:1024
	ds_read_b128 v[222:225], v148
	ds_read_b128 v[226:229], v148 offset:1024
	global_load_lds_dwordx4 v[188:189], off
	v_lshl_add_u64 v[188:189], s[6:7], 0, v[142:143]
	v_readfirstlane_b32 s14, v161
	v_lshl_add_u64 v[230:231], v[188:189], 0, s[38:39]
	s_mov_b32 m0, s14
	s_nop 0
	global_load_lds_dwordx4 v[230:231], off
	s_waitcnt lgkmcnt(8)
	s_barrier
	s_waitcnt lgkmcnt(0)
	s_waitcnt lgkmcnt(0)
	v_mfma_f32_16x16x32_bf16 v[124:127], v[162:165], v[198:201], v[124:127]
	v_mfma_f32_16x16x32_bf16 v[120:123], v[170:173], v[198:201], v[120:123]
	v_mfma_f32_16x16x32_bf16 v[112:115], v[170:173], v[206:209], v[112:115]
	v_mfma_f32_16x16x32_bf16 v[116:119], v[162:165], v[206:209], v[116:119]
	v_mfma_f32_16x16x32_bf16 v[108:111], v[162:165], v[214:217], v[108:111]
	v_mfma_f32_16x16x32_bf16 v[104:107], v[170:173], v[214:217], v[104:107]
	v_mfma_f32_16x16x32_bf16 v[96:99], v[170:173], v[222:225], v[96:99]
	v_mfma_f32_16x16x32_bf16 v[100:103], v[162:165], v[222:225], v[100:103]
	v_mfma_f32_16x16x32_bf16 v[124:127], v[166:169], v[202:205], v[124:127]
	v_mfma_f32_16x16x32_bf16 v[120:123], v[174:177], v[202:205], v[120:123]
	v_mfma_f32_16x16x32_bf16 v[112:115], v[174:177], v[210:213], v[112:115]
	v_mfma_f32_16x16x32_bf16 v[116:119], v[166:169], v[210:213], v[116:119]
	v_mfma_f32_16x16x32_bf16 v[108:111], v[166:169], v[218:221], v[108:111]
	v_mfma_f32_16x16x32_bf16 v[104:107], v[174:177], v[218:221], v[104:107]
	v_mfma_f32_16x16x32_bf16 v[96:99], v[174:177], v[226:229], v[96:99]
	v_mfma_f32_16x16x32_bf16 v[100:103], v[166:169], v[226:229], v[100:103]
	s_barrier
	v_add_u32_e32 v186, s9, v145
	v_lshl_add_u64 v[246:247], s[6:7], 0, v[136:137]
	v_readfirstlane_b32 s14, v186
	v_lshl_add_u64 v[248:249], v[246:247], 0, s[18:19]
	s_mov_b32 m0, s14
	v_add_u32_e32 v186, 0x2000, v186
	ds_read_b128 v[230:233], v158
	ds_read_b128 v[234:237], v158 offset:1024
	ds_read_b128 v[238:241], v158 offset:2048
	ds_read_b128 v[242:245], v158 offset:3072
	global_load_lds_dwordx4 v[248:249], off
	v_lshl_add_u64 v[248:249], s[6:7], 0, v[138:139]
	v_readfirstlane_b32 s14, v186
	v_lshl_add_u64 v[250:251], v[248:249], 0, s[18:19]
	s_mov_b32 m0, s14
	s_nop 0
	global_load_lds_dwordx4 v[250:251], off
	s_barrier
	s_waitcnt lgkmcnt(0)
	s_waitcnt lgkmcnt(0)
	v_mfma_f32_16x16x32_bf16 v[92:95], v[230:233], v[198:201], v[92:95]
	v_mfma_f32_16x16x32_bf16 v[88:91], v[238:241], v[198:201], v[88:91]
	v_mfma_f32_16x16x32_bf16 v[80:83], v[238:241], v[206:209], v[80:83]
	v_mfma_f32_16x16x32_bf16 v[84:87], v[230:233], v[206:209], v[84:87]
	v_mfma_f32_16x16x32_bf16 v[76:79], v[230:233], v[214:217], v[76:79]
	v_mfma_f32_16x16x32_bf16 v[72:75], v[238:241], v[214:217], v[72:75]
	v_mfma_f32_16x16x32_bf16 v[64:67], v[238:241], v[222:225], v[64:67]
	v_mfma_f32_16x16x32_bf16 v[68:71], v[230:233], v[222:225], v[68:71]
	v_mfma_f32_16x16x32_bf16 v[92:95], v[234:237], v[202:205], v[92:95]
	v_mfma_f32_16x16x32_bf16 v[88:91], v[242:245], v[202:205], v[88:91]
	v_mfma_f32_16x16x32_bf16 v[80:83], v[242:245], v[210:213], v[80:83]
	v_mfma_f32_16x16x32_bf16 v[84:87], v[234:237], v[210:213], v[84:87]
	v_mfma_f32_16x16x32_bf16 v[76:79], v[234:237], v[218:221], v[76:79]
	v_mfma_f32_16x16x32_bf16 v[72:75], v[242:245], v[218:221], v[72:75]
	v_mfma_f32_16x16x32_bf16 v[64:67], v[242:245], v[226:229], v[64:67]
	v_mfma_f32_16x16x32_bf16 v[68:71], v[234:237], v[226:229], v[68:71]
	v_readfirstlane_b32 s14, v146
	v_add_u32_e32 v186, 0x2000, v146
	v_lshl_add_u64 v[250:251], v[178:179], 0, s[26:27]
	s_mov_b32 m0, s14
	v_readfirstlane_b32 s14, v186
	s_barrier
	ds_read_b128 v[198:201], v151 offset:16384
	ds_read_b128 v[202:205], v151 offset:17408
	ds_read_b128 v[206:209], v150 offset:16384
	ds_read_b128 v[210:213], v150 offset:17408
	ds_read_b128 v[214:217], v149 offset:16384
	ds_read_b128 v[218:221], v149 offset:17408
	ds_read_b128 v[222:225], v148 offset:16384
	ds_read_b128 v[226:229], v148 offset:17408
	global_load_lds_dwordx4 v[250:251], off
	v_lshl_add_u64 v[250:251], v[188:189], 0, s[26:27]
	s_mov_b32 m0, s14
	s_nop 0
	global_load_lds_dwordx4 v[250:251], off
	s_barrier
	s_waitcnt lgkmcnt(0)
	s_waitcnt lgkmcnt(0)
	v_mfma_f32_16x16x32_bf16 v[60:63], v[162:165], v[198:201], v[60:63]
	v_mfma_f32_16x16x32_bf16 v[56:59], v[170:173], v[198:201], v[56:59]
	v_mfma_f32_16x16x32_bf16 v[48:51], v[170:173], v[206:209], v[48:51]
	v_mfma_f32_16x16x32_bf16 v[52:55], v[162:165], v[206:209], v[52:55]
	v_mfma_f32_16x16x32_bf16 v[44:47], v[162:165], v[214:217], v[44:47]
	v_mfma_f32_16x16x32_bf16 v[40:43], v[170:173], v[214:217], v[40:43]
	v_mfma_f32_16x16x32_bf16 v[32:35], v[170:173], v[222:225], v[32:35]
	v_mfma_f32_16x16x32_bf16 v[36:39], v[162:165], v[222:225], v[36:39]
	v_mfma_f32_16x16x32_bf16 v[60:63], v[166:169], v[202:205], v[60:63]
	v_mfma_f32_16x16x32_bf16 v[56:59], v[174:177], v[202:205], v[56:59]
	v_mfma_f32_16x16x32_bf16 v[48:51], v[174:177], v[210:213], v[48:51]
	v_mfma_f32_16x16x32_bf16 v[52:55], v[166:169], v[210:213], v[52:55]
	v_mfma_f32_16x16x32_bf16 v[44:47], v[166:169], v[218:221], v[44:47]
	v_mfma_f32_16x16x32_bf16 v[40:43], v[174:177], v[218:221], v[40:43]
	v_mfma_f32_16x16x32_bf16 v[32:35], v[174:177], v[226:229], v[32:35]
	v_mfma_f32_16x16x32_bf16 v[36:39], v[166:169], v[226:229], v[36:39]
	s_barrier
; #define WAIT_V(n) asm volatile("s_waitcnt vmcnt(" #n ")" ::: "memory")
; #define WAIT_L(n) asm volatile("s_waitcnt lgkmcnt(" #n ")" ::: "memory")
; #define BAR __builtin_amdgcn_s_barrier()
; #define SCHED __builtin_amdgcn_sched_barrier(0)
; #define LDA(dst, b, h)                                                                            \
;   _Pragma("unroll") for (int m = 0; m < 4; ++m) _Pragma("unroll") for (int k = 0; k < 2; ++k)                                         \
;     dst[m][k] = *reinterpret_cast<const bf16x8*>((char*)SA(b, h) + lds_byte(wr * 64 + m * 16 + fr, k * 32 + fq * 8))
; #define LDB(dst, b, h)                                                                            \
;   _Pragma("unroll") for (int n = 0; n < 2; ++n) _Pragma("unroll") for (int k = 0; k < 2; ++k)                                         \
;     dst[n][k] = *reinterpret_cast<const bf16x8*>((char*)SB(b, h) + lds_byte(wc * 32 + n * 16 + fr, k * 32 + fq * 8))
; template <int K, bool SWAP>
; __device__ __forceinline__ void gemm_kloop(const bf16* __restrict__ A, const bf16* __restrict__ Bt,
;                                            f32x4 (&acc)[2][2][4][2], bool pref = false) {
;     ...
;     STAGE(SB(0, 1), Bt, HALF, t + 2);
;     WAIT_V(6); BAR; MMA(1, 1, At, B1); BAR;
;     LDB(B0, 1, 0); SCHED; LDA(At, 1, 0); STAGE(SA(0, 1), A, HALF, t + 2);
;     WAIT_L(8); BAR; WAIT_L(0); MMA(0, 0, At, B0); BAR; SCHED;
;     LDB(B1, 1, 1); STAGE(SB(1, 0), Bt, 0, t + 3);
;     BAR; WAIT_L(0); MMA(0, 1, At, B1); BAR;
;     LDA(At, 1, 1); STAGE(SA(1, 0), A, 0, t + 3);
	v_readfirstlane_b32 s14, v147
	v_add_u32_e32 v164, 0x2000, v147
	v_lshl_add_u64 v[162:163], v[246:247], 0, s[30:31]
	s_mov_b32 m0, s14
	v_readfirstlane_b32 s14, v164
	global_load_lds_dwordx4 v[162:163], off
	v_lshl_add_u64 v[162:163], v[248:249], 0, s[30:31]
	s_mov_b32 m0, s14
	s_nop 0
	global_load_lds_dwordx4 v[162:163], off
	s_waitcnt vmcnt(6)
	s_barrier
	v_mfma_f32_16x16x32_bf16 v[28:31], v[230:233], v[198:201], v[28:31]
	v_mfma_f32_16x16x32_bf16 v[24:27], v[238:241], v[198:201], v[24:27]
	v_mfma_f32_16x16x32_bf16 v[16:19], v[238:241], v[206:209], v[16:19]
	v_mfma_f32_16x16x32_bf16 v[20:23], v[230:233], v[206:209], v[20:23]
	v_mfma_f32_16x16x32_bf16 v[12:15], v[230:233], v[214:217], v[12:15]
	v_mfma_f32_16x16x32_bf16 v[8:11], v[238:241], v[214:217], v[8:11]
	v_mfma_f32_16x16x32_bf16 v[0:3], v[238:241], v[222:225], v[0:3]
	v_mfma_f32_16x16x32_bf16 v[4:7], v[230:233], v[222:225], v[4:7]
	v_mfma_f32_16x16x32_bf16 v[28:31], v[234:237], v[202:205], v[28:31]
	v_mfma_f32_16x16x32_bf16 v[24:27], v[242:245], v[202:205], v[24:27]
	v_mfma_f32_16x16x32_bf16 v[16:19], v[242:245], v[210:213], v[16:19]
	v_mfma_f32_16x16x32_bf16 v[20:23], v[234:237], v[210:213], v[20:23]
	v_mfma_f32_16x16x32_bf16 v[12:15], v[234:237], v[218:221], v[12:15]
	v_mfma_f32_16x16x32_bf16 v[8:11], v[242:245], v[218:221], v[8:11]
	v_mfma_f32_16x16x32_bf16 v[0:3], v[242:245], v[226:229], v[0:3]
	v_mfma_f32_16x16x32_bf16 v[4:7], v[234:237], v[226:229], v[4:7]
	s_barrier
	ds_read_b128 v[162:165], v153
	ds_read_b128 v[166:169], v153 offset:1024
	ds_read_b128 v[170:173], v153 offset:2048
	ds_read_b128 v[174:177], v153 offset:3072
	v_add_u32_e32 v186, 0x4000, v146
	v_lshl_add_u64 v[230:231], v[178:179], 0, s[16:17]
	v_readfirstlane_b32 s14, v186
	v_add_u32_e32 v186, 0x6000, v146
	s_mov_b32 m0, s14
	v_readfirstlane_b32 s14, v186
	ds_read_b128 v[198:201], v151 offset:32768
	ds_read_b128 v[202:205], v151 offset:33792
	ds_read_b128 v[206:209], v150 offset:32768
	ds_read_b128 v[210:213], v150 offset:33792
	ds_read_b128 v[214:217], v149 offset:32768
	ds_read_b128 v[218:221], v149 offset:33792
	ds_read_b128 v[222:225], v148 offset:32768
	ds_read_b128 v[226:229], v148 offset:33792
	global_load_lds_dwordx4 v[230:231], off
	v_lshl_add_u64 v[230:231], v[188:189], 0, s[16:17]
	s_mov_b32 m0, s14
	s_nop 0
	global_load_lds_dwordx4 v[230:231], off
	s_waitcnt lgkmcnt(8)
	s_barrier
	s_waitcnt lgkmcnt(0)
	s_waitcnt lgkmcnt(0)
	v_mfma_f32_16x16x32_bf16 v[124:127], v[162:165], v[198:201], v[124:127]
	v_mfma_f32_16x16x32_bf16 v[120:123], v[170:173], v[198:201], v[120:123]
	v_mfma_f32_16x16x32_bf16 v[112:115], v[170:173], v[206:209], v[112:115]
	v_mfma_f32_16x16x32_bf16 v[116:119], v[162:165], v[206:209], v[116:119]
	v_mfma_f32_16x16x32_bf16 v[108:111], v[162:165], v[214:217], v[108:111]
	v_mfma_f32_16x16x32_bf16 v[104:107], v[170:173], v[214:217], v[104:107]
	v_mfma_f32_16x16x32_bf16 v[96:99], v[170:173], v[222:225], v[96:99]
	v_mfma_f32_16x16x32_bf16 v[100:103], v[162:165], v[222:225], v[100:103]
	v_mfma_f32_16x16x32_bf16 v[124:127], v[166:169], v[202:205], v[124:127]
	v_mfma_f32_16x16x32_bf16 v[120:123], v[174:177], v[202:205], v[120:123]
	v_mfma_f32_16x16x32_bf16 v[112:115], v[174:177], v[210:213], v[112:115]
	v_mfma_f32_16x16x32_bf16 v[116:119], v[166:169], v[210:213], v[116:119]
	v_mfma_f32_16x16x32_bf16 v[108:111], v[166:169], v[218:221], v[108:111]
	v_mfma_f32_16x16x32_bf16 v[104:107], v[174:177], v[218:221], v[104:107]
	v_mfma_f32_16x16x32_bf16 v[96:99], v[174:177], v[226:229], v[96:99]
	v_mfma_f32_16x16x32_bf16 v[100:103], v[166:169], v[226:229], v[100:103]
	s_barrier
	v_readfirstlane_b32 s14, v154
	v_add_u32_e32 v186, 0x2000, v154
	v_lshl_add_u64 v[250:251], v[246:247], 0, s[28:29]
	s_mov_b32 m0, s14
	v_readfirstlane_b32 s14, v186
	ds_read_b128 v[230:233], v152
	ds_read_b128 v[234:237], v152 offset:1024
	ds_read_b128 v[238:241], v152 offset:2048
	ds_read_b128 v[242:245], v152 offset:3072
	global_load_lds_dwordx4 v[250:251], off
	v_lshl_add_u64 v[250:251], v[248:249], 0, s[28:29]
	s_mov_b32 m0, s14
	s_nop 0
	global_load_lds_dwordx4 v[250:251], off
	s_barrier
	s_waitcnt lgkmcnt(0)
	s_waitcnt lgkmcnt(0)
	v_mfma_f32_16x16x32_bf16 v[92:95], v[230:233], v[198:201], v[92:95]
	v_mfma_f32_16x16x32_bf16 v[88:91], v[238:241], v[198:201], v[88:91]
	v_mfma_f32_16x16x32_bf16 v[80:83], v[238:241], v[206:209], v[80:83]
	v_mfma_f32_16x16x32_bf16 v[84:87], v[230:233], v[206:209], v[84:87]
	v_mfma_f32_16x16x32_bf16 v[76:79], v[230:233], v[214:217], v[76:79]
	v_mfma_f32_16x16x32_bf16 v[72:75], v[238:241], v[214:217], v[72:75]
	v_mfma_f32_16x16x32_bf16 v[64:67], v[238:241], v[222:225], v[64:67]
	v_mfma_f32_16x16x32_bf16 v[68:71], v[230:233], v[222:225], v[68:71]
	v_mfma_f32_16x16x32_bf16 v[92:95], v[234:237], v[202:205], v[92:95]
	v_mfma_f32_16x16x32_bf16 v[88:91], v[242:245], v[202:205], v[88:91]
	v_mfma_f32_16x16x32_bf16 v[80:83], v[242:245], v[210:213], v[80:83]
	v_mfma_f32_16x16x32_bf16 v[84:87], v[234:237], v[210:213], v[84:87]
	v_mfma_f32_16x16x32_bf16 v[76:79], v[234:237], v[218:221], v[76:79]
	v_mfma_f32_16x16x32_bf16 v[72:75], v[242:245], v[218:221], v[72:75]
	v_mfma_f32_16x16x32_bf16 v[64:67], v[242:245], v[226:229], v[64:67]
	v_mfma_f32_16x16x32_bf16 v[68:71], v[234:237], v[226:229], v[68:71]
	v_readfirstlane_b32 s14, v155
	v_lshl_add_u64 v[178:179], v[178:179], 0, s[24:25]
	s_mov_b32 m0, s14
	v_readfirstlane_b32 s14, v156
	s_barrier
	ds_read_b128 v[198:201], v151 offset:49152
	ds_read_b128 v[202:205], v151 offset:50176
	ds_read_b128 v[206:209], v150 offset:49152
	ds_read_b128 v[210:213], v150 offset:50176
	ds_read_b128 v[214:217], v149 offset:49152
	ds_read_b128 v[218:221], v149 offset:50176
	ds_read_b128 v[222:225], v148 offset:49152
	ds_read_b128 v[226:229], v148 offset:50176
	global_load_lds_dwordx4 v[178:179], off
	v_lshl_add_u64 v[178:179], v[188:189], 0, s[24:25]
	s_mov_b32 m0, s14
	s_nop 0
	global_load_lds_dwordx4 v[178:179], off
	s_barrier
; #define WAIT_V(n) asm volatile("s_waitcnt vmcnt(" #n ")" ::: "memory")
; #define WAIT_L(n) asm volatile("s_waitcnt lgkmcnt(" #n ")" ::: "memory")
; #define BAR __builtin_amdgcn_s_barrier()
; #define SCHED __builtin_amdgcn_sched_barrier(0)
; #define LDA(dst, b, h)                                                                            \
;   _Pragma("unroll") for (int m = 0; m < 4; ++m) _Pragma("unroll") for (int k = 0; k < 2; ++k)                                         \
;     dst[m][k] = *reinterpret_cast<const bf16x8*>((char*)SA(b, h) + lds_byte(wr * 64 + m * 16 + fr, k * 32 + fq * 8))
; #define LDB(dst, b, h)                                                                            \
;   _Pragma("unroll") for (int n = 0; n < 2; ++n) _Pragma("unroll") for (int k = 0; k < 2; ++k)                                         \
;     dst[n][k] = *reinterpret_cast<const bf16x8*>((char*)SB(b, h) + lds_byte(wc * 32 + n * 16 + fr, k * 32 + fq * 8))
; template <int K, bool SWAP>
; __device__ __forceinline__ void gemm_kloop(const bf16* __restrict__ A, const bf16* __restrict__ Bt,
;                                            f32x4 (&acc)[2][2][4][2], bool pref = false) {
;     ...
;     BAR; WAIT_L(0); MMA(1, 0, At, B0); BAR; SCHED;
;     STAGE(SB(1, 1), Bt, HALF, t + 3);
;     WAIT_V(6); BAR; MMA(1, 1, At, B1); BAR;
;   }
;   { LDB(B0, 0, 0); LDA(At, 0, 0); STAGE(SA(1, 1), A, HALF, nt - 1);
;     BAR; WAIT_L(0); MMA(0, 0, At, B0); BAR;
;     LDB(B1, 0, 1); BAR; WAIT_L(0); MMA(0, 1, At, B1); BAR;
	s_waitcnt lgkmcnt(0)
	s_waitcnt lgkmcnt(0)
	v_mfma_f32_16x16x32_bf16 v[60:63], v[162:165], v[198:201], v[60:63]
	v_mfma_f32_16x16x32_bf16 v[56:59], v[170:173], v[198:201], v[56:59]
	v_mfma_f32_16x16x32_bf16 v[48:51], v[170:173], v[206:209], v[48:51]
	v_mfma_f32_16x16x32_bf16 v[52:55], v[162:165], v[206:209], v[52:55]
	v_mfma_f32_16x16x32_bf16 v[44:47], v[162:165], v[214:217], v[44:47]
	v_mfma_f32_16x16x32_bf16 v[40:43], v[170:173], v[214:217], v[40:43]
	v_mfma_f32_16x16x32_bf16 v[32:35], v[170:173], v[222:225], v[32:35]
	v_mfma_f32_16x16x32_bf16 v[36:39], v[162:165], v[222:225], v[36:39]
	v_mfma_f32_16x16x32_bf16 v[60:63], v[166:169], v[202:205], v[60:63]
	v_mfma_f32_16x16x32_bf16 v[56:59], v[174:177], v[202:205], v[56:59]
	v_mfma_f32_16x16x32_bf16 v[48:51], v[174:177], v[210:213], v[48:51]
	v_mfma_f32_16x16x32_bf16 v[52:55], v[166:169], v[210:213], v[52:55]
	v_mfma_f32_16x16x32_bf16 v[44:47], v[166:169], v[218:221], v[44:47]
	v_mfma_f32_16x16x32_bf16 v[40:43], v[174:177], v[218:221], v[40:43]
	v_mfma_f32_16x16x32_bf16 v[32:35], v[174:177], v[226:229], v[32:35]
	v_mfma_f32_16x16x32_bf16 v[36:39], v[166:169], v[226:229], v[36:39]
	s_barrier
	v_readfirstlane_b32 s14, v157
	v_add_u32_e32 v164, 0x2000, v157
	v_lshl_add_u64 v[162:163], v[246:247], 0, s[2:3]
	s_mov_b32 m0, s14
	v_readfirstlane_b32 s14, v164
	global_load_lds_dwordx4 v[162:163], off
	v_lshl_add_u64 v[162:163], v[248:249], 0, s[2:3]
	s_mov_b32 m0, s14
	s_nop 0
	global_load_lds_dwordx4 v[162:163], off
	s_waitcnt vmcnt(6)
	s_barrier
	v_mfma_f32_16x16x32_bf16 v[28:31], v[230:233], v[198:201], v[28:31]
	v_mfma_f32_16x16x32_bf16 v[24:27], v[238:241], v[198:201], v[24:27]
	v_mfma_f32_16x16x32_bf16 v[16:19], v[238:241], v[206:209], v[16:19]
	v_mfma_f32_16x16x32_bf16 v[20:23], v[230:233], v[206:209], v[20:23]
	v_mfma_f32_16x16x32_bf16 v[12:15], v[230:233], v[214:217], v[12:15]
	v_mfma_f32_16x16x32_bf16 v[8:11], v[238:241], v[214:217], v[8:11]
	v_mfma_f32_16x16x32_bf16 v[0:3], v[238:241], v[222:225], v[0:3]
	v_mfma_f32_16x16x32_bf16 v[4:7], v[230:233], v[222:225], v[4:7]
	v_mfma_f32_16x16x32_bf16 v[28:31], v[234:237], v[202:205], v[28:31]
	v_mfma_f32_16x16x32_bf16 v[24:27], v[242:245], v[202:205], v[24:27]
	v_mfma_f32_16x16x32_bf16 v[16:19], v[242:245], v[210:213], v[16:19]
	v_mfma_f32_16x16x32_bf16 v[20:23], v[234:237], v[210:213], v[20:23]
	v_mfma_f32_16x16x32_bf16 v[12:15], v[234:237], v[218:221], v[12:15]
	v_mfma_f32_16x16x32_bf16 v[8:11], v[242:245], v[218:221], v[8:11]
	v_mfma_f32_16x16x32_bf16 v[0:3], v[242:245], v[226:229], v[0:3]
	v_mfma_f32_16x16x32_bf16 v[4:7], v[234:237], v[226:229], v[4:7]
	s_add_i32 s11, s11, 2
	v_lshl_add_u64 v[136:137], v[136:137], 0, s[44:45]
	v_lshl_add_u64 v[138:139], v[138:139], 0, s[44:45]
	v_lshl_add_u64 v[140:141], v[140:141], 0, s[44:45]
	s_cmp_lt_u32 s11, 12
	v_lshl_add_u64 v[142:143], v[142:143], 0, s[44:45]
	s_barrier
	s_cbranch_scc1 .LBB0_844
	s_add_u32 s12, s12, 0x40780
	s_addc_u32 s13, s13, 0
	v_lshl_add_u64 v[130:131], s[12:13], 0, v[130:131]
	v_readfirstlane_b32 s11, v160
	v_lshl_add_u64 v[128:129], v[128:129], 1, v[130:131]
	s_mov_b32 m0, s11
	ds_read_b128 v[136:139], v159
	ds_read_b128 v[140:143], v159 offset:1024
	ds_read_b128 v[154:157], v159 offset:2048
	ds_read_b128 v[162:165], v159 offset:3072
	ds_read_b128 v[166:169], v151
	ds_read_b128 v[170:173], v151 offset:1024
	ds_read_b128 v[174:177], v150
	ds_read_b128 v[198:201], v150 offset:1024
	ds_read_b128 v[202:205], v149
	ds_read_b128 v[206:209], v149 offset:1024
	ds_read_b128 v[210:213], v148
	ds_read_b128 v[214:217], v148 offset:1024
	global_load_lds_dwordx4 v[128:129], off
	v_lshl_add_u64 v[128:129], s[12:13], 0, v[134:135]
	v_readfirstlane_b32 s11, v161
	v_lshl_add_u64 v[128:129], v[132:133], 1, v[128:129]
	s_mov_b32 m0, s11
	s_nop 0
	global_load_lds_dwordx4 v[128:129], off
	s_barrier
	s_waitcnt lgkmcnt(0)
	s_waitcnt lgkmcnt(0)
	v_mfma_f32_16x16x32_bf16 v[124:127], v[136:139], v[166:169], v[124:127]
	v_mfma_f32_16x16x32_bf16 v[120:123], v[154:157], v[166:169], v[120:123]
	v_mfma_f32_16x16x32_bf16 v[112:115], v[154:157], v[174:177], v[112:115]
	v_mfma_f32_16x16x32_bf16 v[116:119], v[136:139], v[174:177], v[116:119]
	v_mfma_f32_16x16x32_bf16 v[108:111], v[136:139], v[202:205], v[108:111]
	v_mfma_f32_16x16x32_bf16 v[104:107], v[154:157], v[202:205], v[104:107]
	v_mfma_f32_16x16x32_bf16 v[96:99], v[154:157], v[210:213], v[96:99]
	v_mfma_f32_16x16x32_bf16 v[100:103], v[136:139], v[210:213], v[100:103]
	v_mfma_f32_16x16x32_bf16 v[124:127], v[140:143], v[170:173], v[124:127]
	v_mfma_f32_16x16x32_bf16 v[120:123], v[162:165], v[170:173], v[120:123]
	v_mfma_f32_16x16x32_bf16 v[112:115], v[162:165], v[198:201], v[112:115]
	v_mfma_f32_16x16x32_bf16 v[116:119], v[140:143], v[198:201], v[116:119]
	v_mfma_f32_16x16x32_bf16 v[108:111], v[140:143], v[206:209], v[108:111]
	v_mfma_f32_16x16x32_bf16 v[104:107], v[162:165], v[206:209], v[104:107]
	v_mfma_f32_16x16x32_bf16 v[96:99], v[162:165], v[214:217], v[96:99]
	v_mfma_f32_16x16x32_bf16 v[100:103], v[140:143], v[214:217], v[100:103]
	s_barrier
	ds_read_b128 v[128:131], v158
	ds_read_b128 v[132:135], v158 offset:1024
	ds_read_b128 v[218:221], v158 offset:2048
	ds_read_b128 v[158:161], v158 offset:3072
	s_barrier
; #define WAIT_V(n) asm volatile("s_waitcnt vmcnt(" #n ")" ::: "memory")
; #define WAIT_L(n) asm volatile("s_waitcnt lgkmcnt(" #n ")" ::: "memory")
; #define BAR __builtin_amdgcn_s_barrier()
; #define LDA(dst, b, h)                                                                            \
;   _Pragma("unroll") for (int m = 0; m < 4; ++m) _Pragma("unroll") for (int k = 0; k < 2; ++k)                                         \
;     dst[m][k] = *reinterpret_cast<const bf16x8*>((char*)SA(b, h) + lds_byte(wr * 64 + m * 16 + fr, k * 32 + fq * 8))
; #define LDB(dst, b, h)                                                                            \
;   _Pragma("unroll") for (int n = 0; n < 2; ++n) _Pragma("unroll") for (int k = 0; k < 2; ++k)                                         \
;     dst[n][k] = *reinterpret_cast<const bf16x8*>((char*)SB(b, h) + lds_byte(wc * 32 + n * 16 + fr, k * 32 + fq * 8))
; template <int K, bool SWAP>
; __device__ __forceinline__ void gemm_kloop(const bf16* __restrict__ A, const bf16* __restrict__ Bt,
;                                            f32x4 (&acc)[2][2][4][2], bool pref = false) {
;     ...
;     LDB(B1, 0, 1); BAR; WAIT_L(0); MMA(0, 1, At, B1); BAR;
;     LDA(At, 0, 1); WAIT_V(4); BAR; WAIT_L(0); MMA(1, 0, At, B0); MMA(1, 1, At, B1); BAR; }
;   { LDB(B0, 1, 0); LDA(At, 1, 0); WAIT_V(2); BAR; WAIT_L(0); MMA(0, 0, At, B0); BAR;
	s_waitcnt lgkmcnt(0)
	s_waitcnt lgkmcnt(0)
	v_mfma_f32_16x16x32_bf16 v[88:91], v[218:221], v[166:169], v[88:91]
	v_mfma_f32_16x16x32_bf16 v[84:87], v[128:131], v[174:177], v[84:87]
	v_mfma_f32_16x16x32_bf16 v[80:83], v[218:221], v[174:177], v[80:83]
	v_mfma_f32_16x16x32_bf16 v[76:79], v[128:131], v[202:205], v[76:79]
	v_mfma_f32_16x16x32_bf16 v[72:75], v[218:221], v[202:205], v[72:75]
	v_mfma_f32_16x16x32_bf16 v[68:71], v[128:131], v[210:213], v[68:71]
	v_mfma_f32_16x16x32_bf16 v[64:67], v[218:221], v[210:213], v[64:67]
	v_mfma_f32_16x16x32_bf16 v[92:95], v[128:131], v[166:169], v[92:95]
	v_mfma_f32_16x16x32_bf16 v[88:91], v[158:161], v[170:173], v[88:91]
	v_mfma_f32_16x16x32_bf16 v[84:87], v[132:135], v[198:201], v[84:87]
	v_mfma_f32_16x16x32_bf16 v[80:83], v[158:161], v[198:201], v[80:83]
	v_mfma_f32_16x16x32_bf16 v[76:79], v[132:135], v[206:209], v[76:79]
	v_mfma_f32_16x16x32_bf16 v[72:75], v[158:161], v[206:209], v[72:75]
	v_mfma_f32_16x16x32_bf16 v[68:71], v[132:135], v[214:217], v[68:71]
	v_mfma_f32_16x16x32_bf16 v[64:67], v[158:161], v[214:217], v[64:67]
	v_mfma_f32_16x16x32_bf16 v[222:225], v[132:135], v[170:173], v[92:95]
	s_barrier
	s_nop 0
	ds_read_b128 v[92:95], v151 offset:16384
	ds_read_b128 v[166:169], v151 offset:17408
	ds_read_b128 v[170:173], v150 offset:16384
	ds_read_b128 v[174:177], v150 offset:17408
	ds_read_b128 v[198:201], v149 offset:16384
	ds_read_b128 v[202:205], v149 offset:17408
	ds_read_b128 v[206:209], v148 offset:16384
	ds_read_b128 v[210:213], v148 offset:17408
	s_waitcnt vmcnt(4)
	s_barrier
	s_waitcnt lgkmcnt(0)
	s_waitcnt lgkmcnt(0)
	v_mfma_f32_16x16x32_bf16 v[60:63], v[136:139], v[92:95], v[60:63]
	v_mfma_f32_16x16x32_bf16 v[56:59], v[154:157], v[92:95], v[56:59]
	v_mfma_f32_16x16x32_bf16 v[48:51], v[154:157], v[170:173], v[48:51]
	v_mfma_f32_16x16x32_bf16 v[52:55], v[136:139], v[170:173], v[52:55]
	v_mfma_f32_16x16x32_bf16 v[44:47], v[136:139], v[198:201], v[44:47]
	v_mfma_f32_16x16x32_bf16 v[40:43], v[154:157], v[198:201], v[40:43]
	v_mfma_f32_16x16x32_bf16 v[32:35], v[154:157], v[206:209], v[32:35]
	v_mfma_f32_16x16x32_bf16 v[36:39], v[136:139], v[206:209], v[36:39]
	v_mfma_f32_16x16x32_bf16 v[60:63], v[140:143], v[166:169], v[60:63]
	v_mfma_f32_16x16x32_bf16 v[56:59], v[162:165], v[166:169], v[56:59]
	v_mfma_f32_16x16x32_bf16 v[48:51], v[162:165], v[174:177], v[48:51]
	v_mfma_f32_16x16x32_bf16 v[52:55], v[140:143], v[174:177], v[52:55]
	v_mfma_f32_16x16x32_bf16 v[44:47], v[140:143], v[202:205], v[44:47]
	v_mfma_f32_16x16x32_bf16 v[40:43], v[162:165], v[202:205], v[40:43]
	v_mfma_f32_16x16x32_bf16 v[32:35], v[162:165], v[210:213], v[32:35]
	v_mfma_f32_16x16x32_bf16 v[36:39], v[140:143], v[210:213], v[36:39]
	v_mfma_f32_16x16x32_bf16 v[28:31], v[128:131], v[92:95], v[28:31]
	v_mfma_f32_16x16x32_bf16 v[24:27], v[218:221], v[92:95], v[24:27]
	v_mfma_f32_16x16x32_bf16 v[16:19], v[218:221], v[170:173], v[16:19]
	v_mfma_f32_16x16x32_bf16 v[20:23], v[128:131], v[170:173], v[20:23]
	v_mfma_f32_16x16x32_bf16 v[12:15], v[128:131], v[198:201], v[12:15]
	v_mfma_f32_16x16x32_bf16 v[8:11], v[218:221], v[198:201], v[8:11]
	v_mfma_f32_16x16x32_bf16 v[0:3], v[218:221], v[206:209], v[0:3]
	v_mfma_f32_16x16x32_bf16 v[4:7], v[128:131], v[206:209], v[4:7]
	v_mfma_f32_16x16x32_bf16 v[28:31], v[132:135], v[166:169], v[28:31]
	v_mfma_f32_16x16x32_bf16 v[24:27], v[158:161], v[166:169], v[24:27]
	v_mfma_f32_16x16x32_bf16 v[16:19], v[158:161], v[174:177], v[16:19]
	v_mfma_f32_16x16x32_bf16 v[20:23], v[132:135], v[174:177], v[20:23]
	v_mfma_f32_16x16x32_bf16 v[12:15], v[132:135], v[202:205], v[12:15]
	v_mfma_f32_16x16x32_bf16 v[8:11], v[158:161], v[202:205], v[8:11]
	v_mfma_f32_16x16x32_bf16 v[0:3], v[158:161], v[210:213], v[0:3]
	v_mfma_f32_16x16x32_bf16 v[4:7], v[132:135], v[210:213], v[4:7]
	s_barrier
	ds_read_b128 v[128:131], v153
	ds_read_b128 v[132:135], v153 offset:1024
	ds_read_b128 v[136:139], v153 offset:2048
	ds_read_b128 v[140:143], v153 offset:3072
	ds_read_b128 v[154:157], v151 offset:32768
	ds_read_b128 v[158:161], v151 offset:33792
	ds_read_b128 v[162:165], v150 offset:32768
	ds_read_b128 v[166:169], v150 offset:33792
	ds_read_b128 v[170:173], v149 offset:32768
	ds_read_b128 v[174:177], v149 offset:33792
	ds_read_b128 v[198:201], v148 offset:32768
	ds_read_b128 v[202:205], v148 offset:33792
	s_waitcnt vmcnt(2)
	s_barrier
; #define WAIT_V(n) asm volatile("s_waitcnt vmcnt(" #n ")" ::: "memory")
; #define WAIT_L(n) asm volatile("s_waitcnt lgkmcnt(" #n ")" ::: "memory")
; #define BAR __builtin_amdgcn_s_barrier()
; #define LDA(dst, b, h)                                                                            \
;   _Pragma("unroll") for (int m = 0; m < 4; ++m) _Pragma("unroll") for (int k = 0; k < 2; ++k)                                         \
;     dst[m][k] = *reinterpret_cast<const bf16x8*>((char*)SA(b, h) + lds_byte(wr * 64 + m * 16 + fr, k * 32 + fq * 8))
; #define LDB(dst, b, h)                                                                            \
;   _Pragma("unroll") for (int n = 0; n < 2; ++n) _Pragma("unroll") for (int k = 0; k < 2; ++k)                                         \
;     dst[n][k] = *reinterpret_cast<const bf16x8*>((char*)SB(b, h) + lds_byte(wc * 32 + n * 16 + fr, k * 32 + fq * 8))
; template <int K, bool SWAP>
; __device__ __forceinline__ void gemm_kloop(const bf16* __restrict__ A, const bf16* __restrict__ Bt,
;                                            f32x4 (&acc)[2][2][4][2], bool pref = false) {
;     ...
;   { LDB(B0, 1, 0); LDA(At, 1, 0); WAIT_V(2); BAR; WAIT_L(0); MMA(0, 0, At, B0); BAR;
;     LDB(B1, 1, 1); WAIT_V(0); BAR; WAIT_L(0); MMA(0, 1, At, B1); BAR;
;     LDA(At, 1, 1); BAR; WAIT_L(0); MMA(1, 0, At, B0); MMA(1, 1, At, B1); BAR; }
;   if (wr == 0) BAR;
	s_waitcnt lgkmcnt(0)
	s_waitcnt lgkmcnt(0)
	v_mfma_f32_16x16x32_bf16 v[92:95], v[128:131], v[154:157], v[124:127]
	v_mfma_f32_16x16x32_bf16 v[124:127], v[132:135], v[158:161], v[92:95]
	v_mfma_f32_16x16x32_bf16 v[92:95], v[136:139], v[154:157], v[120:123]
	v_mfma_f32_16x16x32_bf16 v[120:123], v[140:143], v[158:161], v[92:95]
	v_mfma_f32_16x16x32_bf16 v[92:95], v[128:131], v[162:165], v[116:119]
	v_mfma_f32_16x16x32_bf16 v[116:119], v[132:135], v[166:169], v[92:95]
	v_mfma_f32_16x16x32_bf16 v[92:95], v[136:139], v[162:165], v[112:115]
	v_mfma_f32_16x16x32_bf16 v[112:115], v[140:143], v[166:169], v[92:95]
	v_mfma_f32_16x16x32_bf16 v[92:95], v[128:131], v[170:173], v[108:111]
	v_mfma_f32_16x16x32_bf16 v[108:111], v[132:135], v[174:177], v[92:95]
	v_mfma_f32_16x16x32_bf16 v[92:95], v[136:139], v[170:173], v[104:107]
	v_mfma_f32_16x16x32_bf16 v[104:107], v[140:143], v[174:177], v[92:95]
	v_mfma_f32_16x16x32_bf16 v[92:95], v[128:131], v[198:201], v[100:103]
	v_mfma_f32_16x16x32_bf16 v[100:103], v[132:135], v[202:205], v[92:95]
	v_mfma_f32_16x16x32_bf16 v[92:95], v[136:139], v[198:201], v[96:99]
	v_mfma_f32_16x16x32_bf16 v[92:95], v[140:143], v[202:205], v[92:95]
	s_barrier
	ds_read_b128 v[206:209], v152
	ds_read_b128 v[210:213], v152 offset:1024
	ds_read_b128 v[214:217], v152 offset:2048
	ds_read_b128 v[218:221], v152 offset:3072
	s_waitcnt vmcnt(0)
	s_barrier
	s_waitcnt lgkmcnt(0)
	s_waitcnt lgkmcnt(0)
	v_mfma_f32_16x16x32_bf16 v[96:99], v[206:209], v[154:157], v[222:225]
	v_mfma_f32_16x16x32_bf16 v[88:91], v[214:217], v[154:157], v[88:91]
	v_mfma_f32_16x16x32_bf16 v[84:87], v[206:209], v[162:165], v[84:87]
	v_mfma_f32_16x16x32_bf16 v[80:83], v[214:217], v[162:165], v[80:83]
	v_mfma_f32_16x16x32_bf16 v[76:79], v[206:209], v[170:173], v[76:79]
	v_mfma_f32_16x16x32_bf16 v[72:75], v[214:217], v[170:173], v[72:75]
	v_mfma_f32_16x16x32_bf16 v[68:71], v[206:209], v[198:201], v[68:71]
	v_mfma_f32_16x16x32_bf16 v[64:67], v[214:217], v[198:201], v[64:67]
	v_mfma_f32_16x16x32_bf16 v[96:99], v[210:213], v[158:161], v[96:99]
	v_mfma_f32_16x16x32_bf16 v[88:91], v[218:221], v[158:161], v[88:91]
	v_mfma_f32_16x16x32_bf16 v[84:87], v[210:213], v[166:169], v[84:87]
	v_mfma_f32_16x16x32_bf16 v[80:83], v[218:221], v[166:169], v[80:83]
	v_mfma_f32_16x16x32_bf16 v[76:79], v[210:213], v[174:177], v[76:79]
	v_mfma_f32_16x16x32_bf16 v[72:75], v[218:221], v[174:177], v[72:75]
	v_mfma_f32_16x16x32_bf16 v[68:71], v[210:213], v[202:205], v[68:71]
	v_mfma_f32_16x16x32_bf16 v[64:67], v[218:221], v[202:205], v[64:67]
	s_barrier
	ds_read_b128 v[152:155], v151 offset:49152
	ds_read_b128 v[156:159], v151 offset:50176
	ds_read_b128 v[160:163], v150 offset:49152
	ds_read_b128 v[164:167], v150 offset:50176
	ds_read_b128 v[168:171], v149 offset:49152
	ds_read_b128 v[172:175], v149 offset:50176
	ds_read_b128 v[176:179], v148 offset:49152
	ds_read_b128 v[146:149], v148 offset:50176
	s_barrier
	s_waitcnt lgkmcnt(0)
	s_waitcnt lgkmcnt(0)
	v_mfma_f32_16x16x32_bf16 v[60:63], v[128:131], v[152:155], v[60:63]
	v_mfma_f32_16x16x32_bf16 v[56:59], v[136:139], v[152:155], v[56:59]
	v_mfma_f32_16x16x32_bf16 v[48:51], v[136:139], v[160:163], v[48:51]
	v_mfma_f32_16x16x32_bf16 v[52:55], v[128:131], v[160:163], v[52:55]
	v_mfma_f32_16x16x32_bf16 v[44:47], v[128:131], v[168:171], v[44:47]
	v_mfma_f32_16x16x32_bf16 v[40:43], v[136:139], v[168:171], v[40:43]
	v_mfma_f32_16x16x32_bf16 v[32:35], v[136:139], v[176:179], v[32:35]
	v_mfma_f32_16x16x32_bf16 v[36:39], v[128:131], v[176:179], v[36:39]
	v_mfma_f32_16x16x32_bf16 v[60:63], v[132:135], v[156:159], v[60:63]
	v_mfma_f32_16x16x32_bf16 v[56:59], v[140:143], v[156:159], v[56:59]
	v_mfma_f32_16x16x32_bf16 v[48:51], v[140:143], v[164:167], v[48:51]
	v_mfma_f32_16x16x32_bf16 v[52:55], v[132:135], v[164:167], v[52:55]
	v_mfma_f32_16x16x32_bf16 v[44:47], v[132:135], v[172:175], v[44:47]
	v_mfma_f32_16x16x32_bf16 v[40:43], v[140:143], v[172:175], v[40:43]
	v_mfma_f32_16x16x32_bf16 v[32:35], v[140:143], v[146:149], v[32:35]
	v_mfma_f32_16x16x32_bf16 v[36:39], v[132:135], v[146:149], v[36:39]
	v_mfma_f32_16x16x32_bf16 v[28:31], v[206:209], v[152:155], v[28:31]
	v_mfma_f32_16x16x32_bf16 v[24:27], v[214:217], v[152:155], v[24:27]
	v_mfma_f32_16x16x32_bf16 v[16:19], v[214:217], v[160:163], v[16:19]
	v_mfma_f32_16x16x32_bf16 v[20:23], v[206:209], v[160:163], v[20:23]
	v_mfma_f32_16x16x32_bf16 v[12:15], v[206:209], v[168:171], v[12:15]
	v_mfma_f32_16x16x32_bf16 v[8:11], v[214:217], v[168:171], v[8:11]
	v_mfma_f32_16x16x32_bf16 v[0:3], v[214:217], v[176:179], v[0:3]
	v_mfma_f32_16x16x32_bf16 v[4:7], v[206:209], v[176:179], v[4:7]
	v_mfma_f32_16x16x32_bf16 v[28:31], v[210:213], v[156:159], v[28:31]
	v_mfma_f32_16x16x32_bf16 v[24:27], v[218:221], v[156:159], v[24:27]
	v_mfma_f32_16x16x32_bf16 v[16:19], v[218:221], v[164:167], v[16:19]
	v_mfma_f32_16x16x32_bf16 v[20:23], v[210:213], v[164:167], v[20:23]
	v_mfma_f32_16x16x32_bf16 v[12:15], v[210:213], v[172:175], v[12:15]
	v_mfma_f32_16x16x32_bf16 v[8:11], v[218:221], v[172:175], v[8:11]
	v_mfma_f32_16x16x32_bf16 v[0:3], v[218:221], v[146:149], v[0:3]
	v_mfma_f32_16x16x32_bf16 v[4:7], v[210:213], v[146:149], v[4:7]
	s_movk_i32 s11, 0x100
	v_cmp_gt_u32_e32 vcc, s11, v144
	s_barrier
	s_and_saveexec_b64 s[12:13], vcc
	s_cbranch_execz .LBB0_847
	s_barrier
